# combination on v20: MLA store/prefetch segment at step tail, GEMM K-loops with the last two iterations peeled (no useless clamped prefetch), DPP adds for the first four butterfly steps of the SSQ redu
# speedup vs baseline: 1.0033x; 1.0033x over previous
.LBB0_168:
	v_add_u32_e32 v194, v158, v129
	ds_read_b128 v[178:181], v147
	ds_read_b128 v[182:185], v147 offset:4096
	ds_read_b128 v[186:189], v147 offset:8192
	ds_read_b128 v[190:193], v194 offset:24576
	ds_read_b128 v[194:197], v194 offset:28672
	s_add_i32 s29, s28, 2
	s_min_u32 s30, s1, 0xf80
	s_add_i32 s98, s1, 0x80
	s_min_u32 s98, s98, 0xf80
	s_addk_i32 s1, 0x100
	v_add_u32_e32 v240, s30, v130
	v_add_u32_e32 v241, 0x40000, v240
	v_add_u32_e32 v242, 0x80000, v240
	v_add_u32_e32 v243, 0xc0000, v240
	s_waitcnt lgkmcnt(1)
	v_mfma_f32_32x32x16_bf16 v[80:95], v[178:181], v[190:193], v[80:95]
	v_add_u32_e32 v206, v158, v162
	v_add_u32_e32 v132, v167, v129
	s_waitcnt lgkmcnt(0)
	v_mfma_f32_32x32x16_bf16 v[64:79], v[178:181], v[194:197], v[64:79]
	ds_read_b128 v[178:181], v161
	s_waitcnt vmcnt(13)
	ds_write_b128 v127, v[96:99] offset:57344
	global_load_dwordx4 v[96:99], v240, s[6:7]
	v_mfma_f32_32x32x16_bf16 v[48:63], v[182:185], v[190:193], v[48:63]
	v_mfma_f32_32x32x16_bf16 v[32:47], v[182:185], v[194:197], v[32:47]
	s_waitcnt vmcnt(13)
	ds_write_b128 v159, v[100:103] offset:8192
	global_load_dwordx4 v[100:103], v241, s[6:7]
	v_mfma_f32_32x32x16_bf16 v[0:15], v[186:189], v[194:197], v[0:15]
	v_add_u32_e32 v194, v158, v160
	v_mfma_f32_32x32x16_bf16 v[16:31], v[186:189], v[190:193], v[16:31]
	ds_read_b128 v[182:185], v194 offset:24576
	ds_read_b128 v[186:189], v161 offset:4096
	ds_read_b128 v[190:193], v165 offset:8192
	ds_read_b128 v[194:197], v194 offset:28672
	ds_read_b128 v[202:205], v206 offset:24576
	s_waitcnt vmcnt(13)
	ds_write_b128 v159, v[108:111] offset:16384
	global_load_dwordx4 v[108:111], v242, s[6:7]
	s_waitcnt lgkmcnt(5)
	v_mfma_f32_32x32x16_bf16 v[80:95], v[178:181], v[182:185], v[80:95]
	s_waitcnt lgkmcnt(2)
	v_mfma_f32_32x32x16_bf16 v[64:79], v[178:181], v[194:197], v[64:79]
	s_waitcnt vmcnt(13)
	ds_write_b128 v159, v[104:107] offset:24576
	global_load_dwordx4 v[104:107], v240, s[76:77]
	v_mfma_f32_32x32x16_bf16 v[48:63], v[186:189], v[182:185], v[48:63]
	v_mfma_f32_32x32x16_bf16 v[32:47], v[186:189], v[194:197], v[32:47]
	ds_read_b128 v[178:181], v161 offset:8192
	ds_read_b128 v[186:189], v163
	s_waitcnt vmcnt(13)
	ds_write_b128 v159, v[112:115] offset:32768
	global_load_dwordx4 v[112:115], v241, s[76:77]
	s_waitcnt lgkmcnt(2)
	v_mfma_f32_32x32x16_bf16 v[16:31], v[178:181], v[182:185], v[16:31]
	v_mfma_f32_32x32x16_bf16 v[0:15], v[178:181], v[194:197], v[0:15]
	ds_read_b128 v[178:181], v206 offset:28672
	v_add_u32_e32 v206, v158, v164
	ds_read_b128 v[182:185], v206 offset:24576
	s_waitcnt vmcnt(13)
	ds_write_b128 v159, v[116:119] offset:40960
	global_load_dwordx4 v[116:119], v242, s[76:77]
	s_waitcnt lgkmcnt(4)
	v_mfma_f32_32x32x16_bf16 v[80:95], v[186:189], v[202:205], v[80:95]
	s_waitcnt lgkmcnt(2)
	v_mfma_f32_32x32x16_bf16 v[64:79], v[186:189], v[178:181], v[64:79]
	ds_read_b128 v[186:189], v163 offset:4096
	ds_read_b128 v[194:197], v163 offset:8192
	s_waitcnt vmcnt(13)
	ds_write_b128 v159, v[120:123] offset:49152
	global_load_dwordx4 v[120:123], v243, s[76:77]
	s_waitcnt lgkmcnt(2)
	v_mfma_f32_32x32x16_bf16 v[48:63], v[186:189], v[202:205], v[48:63]
	v_mfma_f32_32x32x16_bf16 v[32:47], v[186:189], v[178:181], v[32:47]
	s_waitcnt lgkmcnt(1)
	v_mfma_f32_32x32x16_bf16 v[16:31], v[194:197], v[202:205], v[16:31]
	v_mfma_f32_32x32x16_bf16 v[0:15], v[194:197], v[178:181], v[0:15]
	ds_read_b128 v[178:181], v165
	ds_read_b128 v[186:189], v165 offset:4096
	ds_read_b128 v[194:197], v206 offset:28672
	s_waitcnt lgkmcnt(0)
	s_barrier
	v_mfma_f32_32x32x16_bf16 v[80:95], v[178:181], v[182:185], v[80:95]
	v_mfma_f32_32x32x16_bf16 v[64:79], v[178:181], v[194:197], v[64:79]
	v_mfma_f32_32x32x16_bf16 v[48:63], v[186:189], v[182:185], v[48:63]
	v_mfma_f32_32x32x16_bf16 v[32:47], v[186:189], v[194:197], v[32:47]
	ds_read_b128 v[178:181], v147 offset:57344
	ds_read_b128 v[186:189], v147 offset:61440
	ds_read_b128 v[202:205], v166 offset:8192
	ds_read_b128 v[206:209], v173
	v_mfma_f32_32x32x16_bf16 v[16:31], v[190:193], v[182:185], v[16:31]
	ds_read_b128 v[182:185], v132 offset:4096
	v_add_u32_e32 v240, s98, v130
	v_add_u32_e32 v241, 0x40000, v240
	v_add_u32_e32 v242, 0x80000, v240
	v_add_u32_e32 v243, 0xc0000, v240
	s_waitcnt vmcnt(13)
	ds_write_b128 v127, v[212:215]
	global_load_dwordx4 v[212:215], v240, s[6:7]
	v_mfma_f32_32x32x16_bf16 v[0:15], v[190:193], v[194:197], v[0:15]
	s_waitcnt lgkmcnt(2)
	v_mfma_f32_32x32x16_bf16 v[80:95], v[178:181], v[206:209], v[80:95]
	v_add_u32_e32 v194, v167, v160
	s_mov_b32 s28, s29
	s_waitcnt lgkmcnt(1)
	v_mfma_f32_32x32x16_bf16 v[64:79], v[178:181], v[182:185], v[64:79]
	s_waitcnt vmcnt(13)
	ds_write_b128 v127, v[216:219] offset:8192
	global_load_dwordx4 v[216:219], v241, s[6:7]
	v_mfma_f32_32x32x16_bf16 v[48:63], v[186:189], v[206:209], v[48:63]
	v_mfma_f32_32x32x16_bf16 v[32:47], v[186:189], v[182:185], v[32:47]
	s_waitcnt vmcnt(13)
	ds_write_b128 v127, v[220:223] offset:16384
	global_load_dwordx4 v[220:223], v242, s[6:7]
	v_mfma_f32_32x32x16_bf16 v[16:31], v[202:205], v[206:209], v[16:31]
	v_mfma_f32_32x32x16_bf16 v[0:15], v[202:205], v[182:185], v[0:15]
	ds_read_b128 v[178:181], v161 offset:57344
	ds_read_b128 v[182:185], v174
	ds_read_b128 v[186:189], v161 offset:61440
	ds_read_b128 v[190:193], v170 offset:8192
	ds_read_b128 v[194:197], v194 offset:4096
	ds_read_b128 v[202:205], v175
	s_waitcnt vmcnt(13)
	ds_write_b128 v127, v[224:227] offset:24576
	global_load_dwordx4 v[224:227], v240, s[76:77]
	s_waitcnt lgkmcnt(5)
	v_mfma_f32_32x32x16_bf16 v[80:95], v[178:181], v[182:185], v[80:95]
	s_waitcnt lgkmcnt(2)
	v_mfma_f32_32x32x16_bf16 v[64:79], v[178:181], v[194:197], v[64:79]
	s_waitcnt vmcnt(13)
; template <int MT, bool PIN, class Epi>
; __device__ __forceinline__ void gemm_phase(const Params& P, const bf16_t* __restrict__ A, const bf16_t* __restrict__ Bt, int nM, int nN, int K, const Epi epi, char* lds) {
;     ...
;         for (int kt = 0; kt < nk; kt += 2) { G_STEP(0, kt); G_STEP(1, kt + 1); }
	ds_write_b128 v127, v[228:231] offset:32768
	global_load_dwordx4 v[228:231], v241, s[76:77]
	v_mfma_f32_32x32x16_bf16 v[48:63], v[186:189], v[182:185], v[48:63]
	v_mfma_f32_32x32x16_bf16 v[32:47], v[186:189], v[194:197], v[32:47]
	ds_read_b128 v[178:181], v168 offset:8192
	ds_read_b128 v[186:189], v169 offset:8192
	s_waitcnt vmcnt(13)
	ds_write_b128 v127, v[232:235] offset:40960
	global_load_dwordx4 v[232:235], v242, s[76:77]
	s_waitcnt lgkmcnt(2)
	v_mfma_f32_32x32x16_bf16 v[16:31], v[178:181], v[182:185], v[16:31]
	v_mfma_f32_32x32x16_bf16 v[0:15], v[178:181], v[194:197], v[0:15]
	ds_read_b128 v[178:181], v163 offset:57344
	ds_read_b128 v[182:185], v163 offset:61440
	v_add_u32_e32 v194, v167, v162
	ds_read_b128 v[194:197], v194 offset:4096
	ds_read_b128 v[206:209], v176
	s_waitcnt vmcnt(13)
	ds_write_b128 v127, v[236:239] offset:49152
	global_load_dwordx4 v[236:239], v243, s[76:77]
	s_waitcnt lgkmcnt(4)
	v_mfma_f32_32x32x16_bf16 v[80:95], v[178:181], v[202:205], v[80:95]
	s_waitcnt lgkmcnt(2)
	v_mfma_f32_32x32x16_bf16 v[64:79], v[178:181], v[194:197], v[64:79]
	v_mfma_f32_32x32x16_bf16 v[48:63], v[182:185], v[202:205], v[48:63]
	v_mfma_f32_32x32x16_bf16 v[32:47], v[182:185], v[194:197], v[32:47]
	ds_read_b128 v[178:181], v165 offset:57344
	ds_read_b128 v[182:185], v165 offset:61440
	v_mfma_f32_32x32x16_bf16 v[16:31], v[186:189], v[202:205], v[16:31]
	v_mfma_f32_32x32x16_bf16 v[0:15], v[186:189], v[194:197], v[0:15]
	v_add_u32_e32 v186, v167, v164
	ds_read_b128 v[186:189], v186 offset:4096
	s_waitcnt lgkmcnt(0)
	s_barrier
	v_mfma_f32_32x32x16_bf16 v[80:95], v[178:181], v[206:209], v[80:95]
	v_mfma_f32_32x32x16_bf16 v[64:79], v[178:181], v[186:189], v[64:79]
	v_mfma_f32_32x32x16_bf16 v[48:63], v[182:185], v[206:209], v[48:63]
	v_mfma_f32_32x32x16_bf16 v[32:47], v[182:185], v[186:189], v[32:47]
	v_mfma_f32_32x32x16_bf16 v[16:31], v[190:193], v[206:209], v[16:31]
	v_mfma_f32_32x32x16_bf16 v[0:15], v[190:193], v[186:189], v[0:15]
	s_cmp_lt_u32 s28, 28
	s_cbranch_scc1 .LBB0_168
	v_add_u32_e32 v194, v158, v129
	ds_read_b128 v[178:181], v147
	ds_read_b128 v[182:185], v147 offset:4096
	ds_read_b128 v[186:189], v147 offset:8192
	ds_read_b128 v[190:193], v194 offset:24576
	ds_read_b128 v[194:197], v194 offset:28672
	s_add_i32 s29, s28, 2
	s_min_u32 s30, s1, 0xf80
	s_add_i32 s98, s1, 0x80
	s_min_u32 s98, s98, 0xf80
	s_addk_i32 s1, 0x100
	v_add_u32_e32 v240, s30, v130
	v_add_u32_e32 v241, 0x40000, v240
	v_add_u32_e32 v242, 0x80000, v240
	v_add_u32_e32 v243, 0xc0000, v240
	s_waitcnt lgkmcnt(1)
	v_mfma_f32_32x32x16_bf16 v[80:95], v[178:181], v[190:193], v[80:95]
	v_add_u32_e32 v206, v158, v162
	v_add_u32_e32 v132, v167, v129
	s_waitcnt lgkmcnt(0)
	v_mfma_f32_32x32x16_bf16 v[64:79], v[178:181], v[194:197], v[64:79]
	ds_read_b128 v[178:181], v161
	s_waitcnt vmcnt(13)
	ds_write_b128 v127, v[96:99] offset:57344
	global_load_dwordx4 v[96:99], v240, s[6:7]
	v_mfma_f32_32x32x16_bf16 v[48:63], v[182:185], v[190:193], v[48:63]
	v_mfma_f32_32x32x16_bf16 v[32:47], v[182:185], v[194:197], v[32:47]
	s_waitcnt vmcnt(13)
	ds_write_b128 v159, v[100:103] offset:8192
	global_load_dwordx4 v[100:103], v241, s[6:7]
	v_mfma_f32_32x32x16_bf16 v[0:15], v[186:189], v[194:197], v[0:15]
	v_add_u32_e32 v194, v158, v160
	v_mfma_f32_32x32x16_bf16 v[16:31], v[186:189], v[190:193], v[16:31]
	ds_read_b128 v[182:185], v194 offset:24576
	ds_read_b128 v[186:189], v161 offset:4096
	ds_read_b128 v[190:193], v165 offset:8192
	ds_read_b128 v[194:197], v194 offset:28672
	ds_read_b128 v[202:205], v206 offset:24576
	s_waitcnt vmcnt(13)
	ds_write_b128 v159, v[108:111] offset:16384
	global_load_dwordx4 v[108:111], v242, s[6:7]
	s_waitcnt lgkmcnt(5)
	v_mfma_f32_32x32x16_bf16 v[80:95], v[178:181], v[182:185], v[80:95]
	s_waitcnt lgkmcnt(2)
	v_mfma_f32_32x32x16_bf16 v[64:79], v[178:181], v[194:197], v[64:79]
	s_waitcnt vmcnt(13)
	ds_write_b128 v159, v[104:107] offset:24576
	global_load_dwordx4 v[104:107], v240, s[76:77]
	v_mfma_f32_32x32x16_bf16 v[48:63], v[186:189], v[182:185], v[48:63]
	v_mfma_f32_32x32x16_bf16 v[32:47], v[186:189], v[194:197], v[32:47]
	ds_read_b128 v[178:181], v161 offset:8192
	ds_read_b128 v[186:189], v163
	s_waitcnt vmcnt(13)
	ds_write_b128 v159, v[112:115] offset:32768
	global_load_dwordx4 v[112:115], v241, s[76:77]
	s_waitcnt lgkmcnt(2)
	v_mfma_f32_32x32x16_bf16 v[16:31], v[178:181], v[182:185], v[16:31]
	v_mfma_f32_32x32x16_bf16 v[0:15], v[178:181], v[194:197], v[0:15]
	ds_read_b128 v[178:181], v206 offset:28672
	v_add_u32_e32 v206, v158, v164
	ds_read_b128 v[182:185], v206 offset:24576
	s_waitcnt vmcnt(13)
	ds_write_b128 v159, v[116:119] offset:40960
	global_load_dwordx4 v[116:119], v242, s[76:77]
	s_waitcnt lgkmcnt(4)
	v_mfma_f32_32x32x16_bf16 v[80:95], v[186:189], v[202:205], v[80:95]
	s_waitcnt lgkmcnt(2)
	v_mfma_f32_32x32x16_bf16 v[64:79], v[186:189], v[178:181], v[64:79]
	ds_read_b128 v[186:189], v163 offset:4096
	ds_read_b128 v[194:197], v163 offset:8192
	s_waitcnt vmcnt(13)
	ds_write_b128 v159, v[120:123] offset:49152
	global_load_dwordx4 v[120:123], v243, s[76:77]
	s_waitcnt lgkmcnt(2)
	v_mfma_f32_32x32x16_bf16 v[48:63], v[186:189], v[202:205], v[48:63]
	v_mfma_f32_32x32x16_bf16 v[32:47], v[186:189], v[178:181], v[32:47]
	s_waitcnt lgkmcnt(1)
	v_mfma_f32_32x32x16_bf16 v[16:31], v[194:197], v[202:205], v[16:31]
	v_mfma_f32_32x32x16_bf16 v[0:15], v[194:197], v[178:181], v[0:15]
	ds_read_b128 v[178:181], v165
	ds_read_b128 v[186:189], v165 offset:4096
	ds_read_b128 v[194:197], v206 offset:28672
	s_waitcnt lgkmcnt(0)
	s_barrier
; template <int MT, bool PIN, class Epi>
; __device__ __forceinline__ void gemm_phase(const Params& P, const bf16_t* __restrict__ A, const bf16_t* __restrict__ Bt, int nM, int nN, int K, const Epi epi, char* lds) {
;     ...
;         for (int kt = 0; kt < nk; kt += 2) { G_STEP(0, kt); G_STEP(1, kt + 1); }
	v_mfma_f32_32x32x16_bf16 v[80:95], v[178:181], v[182:185], v[80:95]
	v_mfma_f32_32x32x16_bf16 v[64:79], v[178:181], v[194:197], v[64:79]
	v_mfma_f32_32x32x16_bf16 v[48:63], v[186:189], v[182:185], v[48:63]
	v_mfma_f32_32x32x16_bf16 v[32:47], v[186:189], v[194:197], v[32:47]
	ds_read_b128 v[178:181], v147 offset:57344
	ds_read_b128 v[186:189], v147 offset:61440
	ds_read_b128 v[202:205], v166 offset:8192
	ds_read_b128 v[206:209], v173
	v_mfma_f32_32x32x16_bf16 v[16:31], v[190:193], v[182:185], v[16:31]
	ds_read_b128 v[182:185], v132 offset:4096
	v_add_u32_e32 v240, s98, v130
	v_add_u32_e32 v241, 0x40000, v240
	v_add_u32_e32 v242, 0x80000, v240
	v_add_u32_e32 v243, 0xc0000, v240
	s_waitcnt vmcnt(13)
	ds_write_b128 v127, v[212:215]
	v_mfma_f32_32x32x16_bf16 v[0:15], v[190:193], v[194:197], v[0:15]
	s_waitcnt lgkmcnt(2)
	v_mfma_f32_32x32x16_bf16 v[80:95], v[178:181], v[206:209], v[80:95]
	v_add_u32_e32 v194, v167, v160
	s_mov_b32 s28, s29
	s_waitcnt lgkmcnt(1)
	v_mfma_f32_32x32x16_bf16 v[64:79], v[178:181], v[182:185], v[64:79]
	s_waitcnt vmcnt(12)
	ds_write_b128 v127, v[216:219] offset:8192
	v_mfma_f32_32x32x16_bf16 v[48:63], v[186:189], v[206:209], v[48:63]
	v_mfma_f32_32x32x16_bf16 v[32:47], v[186:189], v[182:185], v[32:47]
	s_waitcnt vmcnt(11)
	ds_write_b128 v127, v[220:223] offset:16384
	v_mfma_f32_32x32x16_bf16 v[16:31], v[202:205], v[206:209], v[16:31]
	v_mfma_f32_32x32x16_bf16 v[0:15], v[202:205], v[182:185], v[0:15]
	ds_read_b128 v[178:181], v161 offset:57344
	ds_read_b128 v[182:185], v174
	ds_read_b128 v[186:189], v161 offset:61440
	ds_read_b128 v[190:193], v170 offset:8192
	ds_read_b128 v[194:197], v194 offset:4096
	ds_read_b128 v[202:205], v175
	s_waitcnt vmcnt(10)
	ds_write_b128 v127, v[224:227] offset:24576
	s_waitcnt lgkmcnt(5)
	v_mfma_f32_32x32x16_bf16 v[80:95], v[178:181], v[182:185], v[80:95]
	s_waitcnt lgkmcnt(2)
	v_mfma_f32_32x32x16_bf16 v[64:79], v[178:181], v[194:197], v[64:79]
	s_waitcnt vmcnt(9)
	ds_write_b128 v127, v[228:231] offset:32768
	v_mfma_f32_32x32x16_bf16 v[48:63], v[186:189], v[182:185], v[48:63]
	v_mfma_f32_32x32x16_bf16 v[32:47], v[186:189], v[194:197], v[32:47]
	ds_read_b128 v[178:181], v168 offset:8192
	ds_read_b128 v[186:189], v169 offset:8192
	s_waitcnt vmcnt(8)
	ds_write_b128 v127, v[232:235] offset:40960
	s_waitcnt lgkmcnt(2)
	v_mfma_f32_32x32x16_bf16 v[16:31], v[178:181], v[182:185], v[16:31]
	v_mfma_f32_32x32x16_bf16 v[0:15], v[178:181], v[194:197], v[0:15]
	ds_read_b128 v[178:181], v163 offset:57344
	ds_read_b128 v[182:185], v163 offset:61440
	v_add_u32_e32 v194, v167, v162
	ds_read_b128 v[194:197], v194 offset:4096
	ds_read_b128 v[206:209], v176
	s_waitcnt vmcnt(7)
	ds_write_b128 v127, v[236:239] offset:49152
	s_waitcnt lgkmcnt(4)
	v_mfma_f32_32x32x16_bf16 v[80:95], v[178:181], v[202:205], v[80:95]
	s_waitcnt lgkmcnt(2)
	v_mfma_f32_32x32x16_bf16 v[64:79], v[178:181], v[194:197], v[64:79]
	v_mfma_f32_32x32x16_bf16 v[48:63], v[182:185], v[202:205], v[48:63]
	v_mfma_f32_32x32x16_bf16 v[32:47], v[182:185], v[194:197], v[32:47]
	ds_read_b128 v[178:181], v165 offset:57344
	ds_read_b128 v[182:185], v165 offset:61440
	v_mfma_f32_32x32x16_bf16 v[16:31], v[186:189], v[202:205], v[16:31]
	v_mfma_f32_32x32x16_bf16 v[0:15], v[186:189], v[194:197], v[0:15]
	v_add_u32_e32 v186, v167, v164
	ds_read_b128 v[186:189], v186 offset:4096
	s_waitcnt lgkmcnt(0)
	s_barrier
	v_mfma_f32_32x32x16_bf16 v[80:95], v[178:181], v[206:209], v[80:95]
	v_mfma_f32_32x32x16_bf16 v[64:79], v[178:181], v[186:189], v[64:79]
	v_mfma_f32_32x32x16_bf16 v[48:63], v[182:185], v[206:209], v[48:63]
	v_mfma_f32_32x32x16_bf16 v[32:47], v[182:185], v[186:189], v[32:47]
	v_mfma_f32_32x32x16_bf16 v[16:31], v[190:193], v[206:209], v[16:31]
	v_mfma_f32_32x32x16_bf16 v[0:15], v[190:193], v[186:189], v[0:15]
	v_add_u32_e32 v194, v158, v129
	ds_read_b128 v[178:181], v147
	ds_read_b128 v[182:185], v147 offset:4096
	ds_read_b128 v[186:189], v147 offset:8192
	ds_read_b128 v[190:193], v194 offset:24576
	ds_read_b128 v[194:197], v194 offset:28672
	s_add_i32 s29, s28, 2
	s_min_u32 s30, s1, 0xf80
	s_add_i32 s98, s1, 0x80
	s_min_u32 s98, s98, 0xf80
	s_addk_i32 s1, 0x100
	v_add_u32_e32 v240, s30, v130
	v_add_u32_e32 v241, 0x40000, v240
	v_add_u32_e32 v242, 0x80000, v240
	v_add_u32_e32 v243, 0xc0000, v240
	s_waitcnt lgkmcnt(1)
	v_mfma_f32_32x32x16_bf16 v[80:95], v[178:181], v[190:193], v[80:95]
	v_add_u32_e32 v206, v158, v162
	v_add_u32_e32 v132, v167, v129
	s_waitcnt lgkmcnt(0)
	v_mfma_f32_32x32x16_bf16 v[64:79], v[178:181], v[194:197], v[64:79]
	ds_read_b128 v[178:181], v161
	s_waitcnt vmcnt(6)
	ds_write_b128 v127, v[96:99] offset:57344
	v_mfma_f32_32x32x16_bf16 v[48:63], v[182:185], v[190:193], v[48:63]
	v_mfma_f32_32x32x16_bf16 v[32:47], v[182:185], v[194:197], v[32:47]
	s_waitcnt vmcnt(5)
	ds_write_b128 v159, v[100:103] offset:8192
	v_mfma_f32_32x32x16_bf16 v[0:15], v[186:189], v[194:197], v[0:15]
	v_add_u32_e32 v194, v158, v160
	v_mfma_f32_32x32x16_bf16 v[16:31], v[186:189], v[190:193], v[16:31]
	ds_read_b128 v[182:185], v194 offset:24576
	ds_read_b128 v[186:189], v161 offset:4096
	ds_read_b128 v[190:193], v165 offset:8192
	ds_read_b128 v[194:197], v194 offset:28672
	ds_read_b128 v[202:205], v206 offset:24576
	s_waitcnt vmcnt(4)
	ds_write_b128 v159, v[108:111] offset:16384
	s_waitcnt lgkmcnt(5)
	v_mfma_f32_32x32x16_bf16 v[80:95], v[178:181], v[182:185], v[80:95]
	s_waitcnt lgkmcnt(2)
	v_mfma_f32_32x32x16_bf16 v[64:79], v[178:181], v[194:197], v[64:79]
	s_waitcnt vmcnt(3)
	ds_write_b128 v159, v[104:107] offset:24576
	v_mfma_f32_32x32x16_bf16 v[48:63], v[186:189], v[182:185], v[48:63]
	v_mfma_f32_32x32x16_bf16 v[32:47], v[186:189], v[194:197], v[32:47]
	ds_read_b128 v[178:181], v161 offset:8192
	ds_read_b128 v[186:189], v163
	s_waitcnt vmcnt(2)
	ds_write_b128 v159, v[112:115] offset:32768
	s_waitcnt lgkmcnt(2)
	v_mfma_f32_32x32x16_bf16 v[16:31], v[178:181], v[182:185], v[16:31]
	v_mfma_f32_32x32x16_bf16 v[0:15], v[178:181], v[194:197], v[0:15]
	ds_read_b128 v[178:181], v206 offset:28672
	v_add_u32_e32 v206, v158, v164
	ds_read_b128 v[182:185], v206 offset:24576
	s_waitcnt vmcnt(1)
	ds_write_b128 v159, v[116:119] offset:40960
	s_waitcnt lgkmcnt(4)
	v_mfma_f32_32x32x16_bf16 v[80:95], v[186:189], v[202:205], v[80:95]
	s_waitcnt lgkmcnt(2)
	v_mfma_f32_32x32x16_bf16 v[64:79], v[186:189], v[178:181], v[64:79]
	ds_read_b128 v[186:189], v163 offset:4096
	ds_read_b128 v[194:197], v163 offset:8192
	s_waitcnt vmcnt(0)
	ds_write_b128 v159, v[120:123] offset:49152
	s_waitcnt lgkmcnt(2)
	v_mfma_f32_32x32x16_bf16 v[48:63], v[186:189], v[202:205], v[48:63]
	v_mfma_f32_32x32x16_bf16 v[32:47], v[186:189], v[178:181], v[32:47]
	s_waitcnt lgkmcnt(1)
	v_mfma_f32_32x32x16_bf16 v[16:31], v[194:197], v[202:205], v[16:31]
	v_mfma_f32_32x32x16_bf16 v[0:15], v[194:197], v[178:181], v[0:15]
	ds_read_b128 v[178:181], v165
	ds_read_b128 v[186:189], v165 offset:4096
	ds_read_b128 v[194:197], v206 offset:28672
	s_waitcnt lgkmcnt(0)
	s_barrier
;     template <int MT> __device__ __forceinline__ void run(const Params& P, f32x16 (&acc)[MT][2], int rbase, int pn, int wc, int lane) const {
;     ...
;             if (wc == 0 && n < 16) { float* WI = (float*)(ws + OFF_WI);
; #pragma unroll
;                 for (int mt = 0; mt < MT; ++mt)
; #pragma unroll
;                     for (int rg = 0; rg < 16; ++rg) { const int r = ROWOF(rb, mt, rg); WI[(size_t)r * 16 + n] = acc[mt][0][rg] * 0.03125f; } }
	v_mfma_f32_32x32x16_bf16 v[80:95], v[178:181], v[182:185], v[80:95]
	v_mfma_f32_32x32x16_bf16 v[64:79], v[178:181], v[194:197], v[64:79]
	v_mfma_f32_32x32x16_bf16 v[48:63], v[186:189], v[182:185], v[48:63]
	v_mfma_f32_32x32x16_bf16 v[32:47], v[186:189], v[194:197], v[32:47]
	ds_read_b128 v[178:181], v147 offset:57344
	ds_read_b128 v[186:189], v147 offset:61440
	ds_read_b128 v[202:205], v166 offset:8192
	ds_read_b128 v[206:209], v173
	v_mfma_f32_32x32x16_bf16 v[16:31], v[190:193], v[182:185], v[16:31]
	ds_read_b128 v[182:185], v132 offset:4096
	v_add_u32_e32 v240, s98, v130
	v_add_u32_e32 v241, 0x40000, v240
	v_add_u32_e32 v242, 0x80000, v240
	v_add_u32_e32 v243, 0xc0000, v240
	v_mfma_f32_32x32x16_bf16 v[0:15], v[190:193], v[194:197], v[0:15]
	s_waitcnt lgkmcnt(1)
	v_mfma_f32_32x32x16_bf16 v[80:95], v[178:181], v[206:209], v[80:95]
	v_add_u32_e32 v194, v167, v160
	s_mov_b32 s28, s29
	s_waitcnt lgkmcnt(0)
	v_mfma_f32_32x32x16_bf16 v[64:79], v[178:181], v[182:185], v[64:79]
	v_mfma_f32_32x32x16_bf16 v[48:63], v[186:189], v[206:209], v[48:63]
	v_mfma_f32_32x32x16_bf16 v[32:47], v[186:189], v[182:185], v[32:47]
	v_mfma_f32_32x32x16_bf16 v[16:31], v[202:205], v[206:209], v[16:31]
	v_mfma_f32_32x32x16_bf16 v[0:15], v[202:205], v[182:185], v[0:15]
	ds_read_b128 v[178:181], v161 offset:57344
	ds_read_b128 v[182:185], v174
	ds_read_b128 v[186:189], v161 offset:61440
	ds_read_b128 v[190:193], v170 offset:8192
	ds_read_b128 v[194:197], v194 offset:4096
	ds_read_b128 v[202:205], v175
	s_waitcnt lgkmcnt(4)
	v_mfma_f32_32x32x16_bf16 v[80:95], v[178:181], v[182:185], v[80:95]
	s_waitcnt lgkmcnt(1)
	v_mfma_f32_32x32x16_bf16 v[64:79], v[178:181], v[194:197], v[64:79]
	v_mfma_f32_32x32x16_bf16 v[48:63], v[186:189], v[182:185], v[48:63]
	v_mfma_f32_32x32x16_bf16 v[32:47], v[186:189], v[194:197], v[32:47]
	ds_read_b128 v[178:181], v168 offset:8192
	ds_read_b128 v[186:189], v169 offset:8192
	s_waitcnt lgkmcnt(1)
	v_mfma_f32_32x32x16_bf16 v[16:31], v[178:181], v[182:185], v[16:31]
	v_mfma_f32_32x32x16_bf16 v[0:15], v[178:181], v[194:197], v[0:15]
	ds_read_b128 v[178:181], v163 offset:57344
	ds_read_b128 v[182:185], v163 offset:61440
	v_add_u32_e32 v194, v167, v162
	ds_read_b128 v[194:197], v194 offset:4096
	ds_read_b128 v[206:209], v176
	s_waitcnt lgkmcnt(3)
	v_mfma_f32_32x32x16_bf16 v[80:95], v[178:181], v[202:205], v[80:95]
	s_waitcnt lgkmcnt(1)
	v_mfma_f32_32x32x16_bf16 v[64:79], v[178:181], v[194:197], v[64:79]
	v_mfma_f32_32x32x16_bf16 v[48:63], v[182:185], v[202:205], v[48:63]
	v_mfma_f32_32x32x16_bf16 v[32:47], v[182:185], v[194:197], v[32:47]
	ds_read_b128 v[178:181], v165 offset:57344
	ds_read_b128 v[182:185], v165 offset:61440
	v_mfma_f32_32x32x16_bf16 v[16:31], v[186:189], v[202:205], v[16:31]
	v_mfma_f32_32x32x16_bf16 v[0:15], v[186:189], v[194:197], v[0:15]
	v_add_u32_e32 v186, v167, v164
	ds_read_b128 v[186:189], v186 offset:4096
	s_waitcnt lgkmcnt(0)
	s_barrier
	v_mfma_f32_32x32x16_bf16 v[80:95], v[178:181], v[206:209], v[80:95]
	v_mfma_f32_32x32x16_bf16 v[64:79], v[178:181], v[186:189], v[64:79]
	v_mfma_f32_32x32x16_bf16 v[48:63], v[182:185], v[206:209], v[48:63]
	v_mfma_f32_32x32x16_bf16 v[32:47], v[182:185], v[186:189], v[32:47]
	v_mfma_f32_32x32x16_bf16 v[16:31], v[190:193], v[206:209], v[16:31]
	v_mfma_f32_32x32x16_bf16 v[0:15], v[190:193], v[186:189], v[0:15]
	s_nop 1
	s_mul_i32 s39, s24, 0xc0
	v_readlane_b32 s1, v252, 38
	s_lshl_b32 s6, s0, 1
	v_readlane_b32 s0, v252, 40
	s_add_i32 s39, s39, s1
	s_or_b32 s38, s6, s0
	s_waitcnt vmcnt(0)
	v_or_b32_e32 v96, s39, v171
	s_cmp_gt_i32 s38, 3
	s_mov_b64 s[0:1], -1
	s_cbranch_scc0 .LBB0_887
	s_cmp_gt_u32 s6, 7
	s_cbranch_scc0 .LBB0_692
	s_cmp_lg_u32 s38, 8
	s_cbranch_scc0 .LBB0_474
	s_cmp_gt_u32 s38, 18
	s_cbranch_scc0 .LBB0_280
	s_cmp_gt_u32 s38, 20
	s_cbranch_scc0 .LBB0_181
	s_cmp_gt_u32 s38, 28
	s_cbranch_scc0 .LBB0_178
	s_mov_b64 s[0:1], exec
	v_readlane_b32 s6, v252, 43
	v_readlane_b32 s7, v252, 44
	s_and_b64 s[6:7], s[0:1], s[6:7]
	s_mov_b64 exec, s[6:7]
	s_cbranch_execz .LBB0_177
	v_ashrrev_i32_e32 v97, 31, v96
	v_lshlrev_b64 v[98:99], 6, v[96:97]
	s_waitcnt vmcnt(4)
	v_mul_f32_e32 v100, 0x3d000000, v80
	v_lshl_add_u64 v[98:99], v[152:153], 0, v[98:99]
	global_store_dword v[98:99], v100, off
	v_or_b32_e32 v100, 1, v96
	v_ashrrev_i32_e32 v101, 31, v100
	v_lshlrev_b64 v[100:101], 6, v[100:101]
	v_mul_f32_e32 v97, 0x3d000000, v81
	v_lshl_add_u64 v[100:101], v[152:153], 0, v[100:101]
	global_store_dword v[100:101], v97, off
	v_or_b32_e32 v100, 2, v96
	v_ashrrev_i32_e32 v101, 31, v100
	v_lshlrev_b64 v[100:101], 6, v[100:101]
	v_mul_f32_e32 v97, 0x3d000000, v82
	v_lshl_add_u64 v[100:101], v[152:153], 0, v[100:101]
	global_store_dword v[100:101], v97, off
	v_or_b32_e32 v100, 3, v96
	v_ashrrev_i32_e32 v101, 31, v100
	v_lshlrev_b64 v[100:101], 6, v[100:101]
	v_mul_f32_e32 v97, 0x3d000000, v83
	v_lshl_add_u64 v[100:101], v[152:153], 0, v[100:101]
	global_store_dword v[100:101], v97, off
	v_or_b32_e32 v100, 8, v96
	v_ashrrev_i32_e32 v101, 31, v100
	v_lshlrev_b64 v[100:101], 6, v[100:101]
	v_mul_f32_e32 v97, 0x3d000000, v84
	v_lshl_add_u64 v[100:101], v[152:153], 0, v[100:101]
	global_store_dword v[100:101], v97, off
	v_or_b32_e32 v100, 9, v96
	v_ashrrev_i32_e32 v101, 31, v100
	v_lshlrev_b64 v[100:101], 6, v[100:101]
	v_mul_f32_e32 v97, 0x3d000000, v85
	v_lshl_add_u64 v[100:101], v[152:153], 0, v[100:101]
	global_store_dword v[100:101], v97, off
	v_or_b32_e32 v100, 10, v96
	v_ashrrev_i32_e32 v101, 31, v100
	v_lshlrev_b64 v[100:101], 6, v[100:101]
	v_mul_f32_e32 v97, 0x3d000000, v86
	v_lshl_add_u64 v[100:101], v[152:153], 0, v[100:101]
	global_store_dword v[100:101], v97, off
	v_or_b32_e32 v100, 11, v96
;     template <int MT> __device__ __forceinline__ void run(const Params& P, f32x16 (&acc)[MT][2], int rbase, int pn, int wc, int lane) const {
;     ...
;             if (wc == 0 && n < 16) { float* WI = (float*)(ws + OFF_WI);
; #pragma unroll
;                 for (int mt = 0; mt < MT; ++mt)
; #pragma unroll
;                     for (int rg = 0; rg < 16; ++rg) { const int r = ROWOF(rb, mt, rg); WI[(size_t)r * 16 + n] = acc[mt][0][rg] * 0.03125f; } }
	v_ashrrev_i32_e32 v101, 31, v100
	v_lshlrev_b64 v[100:101], 6, v[100:101]
	v_mul_f32_e32 v97, 0x3d000000, v87
	v_lshl_add_u64 v[100:101], v[152:153], 0, v[100:101]
	global_store_dword v[100:101], v97, off
	v_or_b32_e32 v100, 16, v96
	v_ashrrev_i32_e32 v101, 31, v100
	v_lshlrev_b64 v[100:101], 6, v[100:101]
	v_mul_f32_e32 v97, 0x3d000000, v88
	v_lshl_add_u64 v[100:101], v[152:153], 0, v[100:101]
	global_store_dword v[100:101], v97, off
	v_or_b32_e32 v100, 17, v96
	v_ashrrev_i32_e32 v101, 31, v100
	v_lshlrev_b64 v[100:101], 6, v[100:101]
	v_mul_f32_e32 v97, 0x3d000000, v89
	v_lshl_add_u64 v[100:101], v[152:153], 0, v[100:101]
	global_store_dword v[100:101], v97, off
	v_or_b32_e32 v100, 18, v96
	v_ashrrev_i32_e32 v101, 31, v100
	v_lshlrev_b64 v[100:101], 6, v[100:101]
	v_mul_f32_e32 v97, 0x3d000000, v90
	v_lshl_add_u64 v[100:101], v[152:153], 0, v[100:101]
	global_store_dword v[100:101], v97, off
	v_or_b32_e32 v100, 19, v96
	v_ashrrev_i32_e32 v101, 31, v100
	v_lshlrev_b64 v[100:101], 6, v[100:101]
	v_mul_f32_e32 v97, 0x3d000000, v91
	v_lshl_add_u64 v[100:101], v[152:153], 0, v[100:101]
	global_store_dword v[100:101], v97, off
	v_or_b32_e32 v100, 24, v96
	v_ashrrev_i32_e32 v101, 31, v100
	v_lshlrev_b64 v[100:101], 6, v[100:101]
	v_mul_f32_e32 v97, 0x3d000000, v92
	v_lshl_add_u64 v[100:101], v[152:153], 0, v[100:101]
	global_store_dword v[100:101], v97, off
	v_or_b32_e32 v100, 25, v96
	v_ashrrev_i32_e32 v101, 31, v100
	v_lshlrev_b64 v[100:101], 6, v[100:101]
	v_mul_f32_e32 v97, 0x3d000000, v93
	v_lshl_add_u64 v[100:101], v[152:153], 0, v[100:101]
	global_store_dword v[100:101], v97, off
	v_or_b32_e32 v100, 26, v96
	v_ashrrev_i32_e32 v101, 31, v100
	v_lshlrev_b64 v[100:101], 6, v[100:101]
	v_mul_f32_e32 v97, 0x3d000000, v94
	v_lshl_add_u64 v[100:101], v[152:153], 0, v[100:101]
	global_store_dword v[100:101], v97, off
	v_or_b32_e32 v100, 27, v96
	v_ashrrev_i32_e32 v101, 31, v100
	v_lshlrev_b64 v[100:101], 6, v[100:101]
	v_mul_f32_e32 v97, 0x3d000000, v95
	v_lshl_add_u64 v[100:101], v[152:153], 0, v[100:101]
	global_store_dword v[100:101], v97, off
	v_add_u32_e32 v100, 33, v96
	v_ashrrev_i32_e32 v101, 31, v100
	v_mul_f32_e32 v97, 0x3d000000, v48
	v_lshlrev_b64 v[100:101], 6, v[100:101]
	global_store_dword v[98:99], v97, off offset:2048
	v_mul_f32_e32 v97, 0x3d000000, v49
	v_lshl_add_u64 v[100:101], v[152:153], 0, v[100:101]
	global_store_dword v[100:101], v97, off
	v_add_u32_e32 v100, 34, v96
	v_ashrrev_i32_e32 v101, 31, v100
	v_lshlrev_b64 v[100:101], 6, v[100:101]
	v_mul_f32_e32 v97, 0x3d000000, v50
	v_lshl_add_u64 v[100:101], v[152:153], 0, v[100:101]
	global_store_dword v[100:101], v97, off
	v_add_u32_e32 v100, 35, v96
	v_ashrrev_i32_e32 v101, 31, v100
	v_lshlrev_b64 v[100:101], 6, v[100:101]
	v_mul_f32_e32 v97, 0x3d000000, v51
	v_lshl_add_u64 v[100:101], v[152:153], 0, v[100:101]
	global_store_dword v[100:101], v97, off
	v_add_u32_e32 v100, 40, v96
	v_ashrrev_i32_e32 v101, 31, v100
	v_lshlrev_b64 v[100:101], 6, v[100:101]
	v_mul_f32_e32 v97, 0x3d000000, v52
	v_lshl_add_u64 v[100:101], v[152:153], 0, v[100:101]
	global_store_dword v[100:101], v97, off
	v_add_u32_e32 v100, 41, v96
	v_ashrrev_i32_e32 v101, 31, v100
	v_lshlrev_b64 v[100:101], 6, v[100:101]
	v_mul_f32_e32 v97, 0x3d000000, v53
	v_lshl_add_u64 v[100:101], v[152:153], 0, v[100:101]
	global_store_dword v[100:101], v97, off
	v_add_u32_e32 v100, 42, v96
	v_ashrrev_i32_e32 v101, 31, v100
	v_lshlrev_b64 v[100:101], 6, v[100:101]
	v_mul_f32_e32 v97, 0x3d000000, v54
	v_lshl_add_u64 v[100:101], v[152:153], 0, v[100:101]
	global_store_dword v[100:101], v97, off
	v_add_u32_e32 v100, 43, v96
	v_ashrrev_i32_e32 v101, 31, v100
	v_lshlrev_b64 v[100:101], 6, v[100:101]
	v_mul_f32_e32 v97, 0x3d000000, v55
	v_lshl_add_u64 v[100:101], v[152:153], 0, v[100:101]
	global_store_dword v[100:101], v97, off
	v_add_u32_e32 v100, 48, v96
	v_ashrrev_i32_e32 v101, 31, v100
	v_lshlrev_b64 v[100:101], 6, v[100:101]
	v_mul_f32_e32 v97, 0x3d000000, v56
	v_lshl_add_u64 v[100:101], v[152:153], 0, v[100:101]
	global_store_dword v[100:101], v97, off
	v_add_u32_e32 v100, 49, v96
	v_ashrrev_i32_e32 v101, 31, v100
	v_lshlrev_b64 v[100:101], 6, v[100:101]
	v_mul_f32_e32 v97, 0x3d000000, v57
	v_lshl_add_u64 v[100:101], v[152:153], 0, v[100:101]
	global_store_dword v[100:101], v97, off
	v_add_u32_e32 v100, 50, v96
	v_ashrrev_i32_e32 v101, 31, v100
	v_lshlrev_b64 v[100:101], 6, v[100:101]
	v_mul_f32_e32 v97, 0x3d000000, v58
	v_lshl_add_u64 v[100:101], v[152:153], 0, v[100:101]
	global_store_dword v[100:101], v97, off
	v_add_u32_e32 v100, 51, v96
	v_ashrrev_i32_e32 v101, 31, v100
	v_lshlrev_b64 v[100:101], 6, v[100:101]
;     template <int MT> __device__ __forceinline__ void run(const Params& P, f32x16 (&acc)[MT][2], int rbase, int pn, int wc, int lane) const {
;     ...
;             if (wc == 0 && n < 16) { float* WI = (float*)(ws + OFF_WI);
; #pragma unroll
;                 for (int mt = 0; mt < MT; ++mt)
; #pragma unroll
;                     for (int rg = 0; rg < 16; ++rg) { const int r = ROWOF(rb, mt, rg); WI[(size_t)r * 16 + n] = acc[mt][0][rg] * 0.03125f; } }
	v_mul_f32_e32 v97, 0x3d000000, v59
	v_lshl_add_u64 v[100:101], v[152:153], 0, v[100:101]
	global_store_dword v[100:101], v97, off
	v_add_u32_e32 v100, 56, v96
	v_ashrrev_i32_e32 v101, 31, v100
	v_lshlrev_b64 v[100:101], 6, v[100:101]
	v_mul_f32_e32 v97, 0x3d000000, v60
	v_lshl_add_u64 v[100:101], v[152:153], 0, v[100:101]
	global_store_dword v[100:101], v97, off
	v_add_u32_e32 v100, 57, v96
	v_ashrrev_i32_e32 v101, 31, v100
	v_lshlrev_b64 v[100:101], 6, v[100:101]
	v_mul_f32_e32 v97, 0x3d000000, v61
	v_lshl_add_u64 v[100:101], v[152:153], 0, v[100:101]
	global_store_dword v[100:101], v97, off
	v_add_u32_e32 v100, 58, v96
	v_ashrrev_i32_e32 v101, 31, v100
	v_lshlrev_b64 v[100:101], 6, v[100:101]
	v_mul_f32_e32 v97, 0x3d000000, v62
	v_lshl_add_u64 v[100:101], v[152:153], 0, v[100:101]
	global_store_dword v[100:101], v97, off
	v_add_u32_e32 v100, 59, v96
	v_ashrrev_i32_e32 v101, 31, v100
	v_lshlrev_b64 v[100:101], 6, v[100:101]
	s_movk_i32 s6, 0x1000
	v_mul_f32_e32 v97, 0x3d000000, v63
	v_lshl_add_u64 v[100:101], v[152:153], 0, v[100:101]
	v_add_co_u32_e32 v98, vcc, s6, v98
	global_store_dword v[100:101], v97, off
	v_mul_f32_e32 v97, 0x3d000000, v16
	v_addc_co_u32_e32 v99, vcc, 0, v99, vcc
	global_store_dword v[98:99], v97, off
	v_add_u32_e32 v98, 0x41, v96
	v_ashrrev_i32_e32 v99, 31, v98
	v_lshlrev_b64 v[98:99], 6, v[98:99]
	v_mul_f32_e32 v97, 0x3d000000, v17
	v_lshl_add_u64 v[98:99], v[152:153], 0, v[98:99]
	global_store_dword v[98:99], v97, off
	v_add_u32_e32 v98, 0x42, v96
	v_ashrrev_i32_e32 v99, 31, v98
	v_lshlrev_b64 v[98:99], 6, v[98:99]
	v_mul_f32_e32 v97, 0x3d000000, v18
	v_lshl_add_u64 v[98:99], v[152:153], 0, v[98:99]
	global_store_dword v[98:99], v97, off
	v_add_u32_e32 v98, 0x43, v96
	v_ashrrev_i32_e32 v99, 31, v98
	v_lshlrev_b64 v[98:99], 6, v[98:99]
	v_mul_f32_e32 v97, 0x3d000000, v19
	v_lshl_add_u64 v[98:99], v[152:153], 0, v[98:99]
	global_store_dword v[98:99], v97, off
	v_add_u32_e32 v98, 0x48, v96
	v_ashrrev_i32_e32 v99, 31, v98
	v_lshlrev_b64 v[98:99], 6, v[98:99]
	v_mul_f32_e32 v97, 0x3d000000, v20
	v_lshl_add_u64 v[98:99], v[152:153], 0, v[98:99]
	global_store_dword v[98:99], v97, off
	v_add_u32_e32 v98, 0x49, v96
	v_ashrrev_i32_e32 v99, 31, v98
	v_lshlrev_b64 v[98:99], 6, v[98:99]
	v_mul_f32_e32 v97, 0x3d000000, v21
	v_lshl_add_u64 v[98:99], v[152:153], 0, v[98:99]
	global_store_dword v[98:99], v97, off
	v_add_u32_e32 v98, 0x4a, v96
	v_ashrrev_i32_e32 v99, 31, v98
	v_lshlrev_b64 v[98:99], 6, v[98:99]
	v_mul_f32_e32 v97, 0x3d000000, v22
	v_lshl_add_u64 v[98:99], v[152:153], 0, v[98:99]
	global_store_dword v[98:99], v97, off
	v_add_u32_e32 v98, 0x4b, v96
	v_ashrrev_i32_e32 v99, 31, v98
	v_lshlrev_b64 v[98:99], 6, v[98:99]
	v_mul_f32_e32 v97, 0x3d000000, v23
	v_lshl_add_u64 v[98:99], v[152:153], 0, v[98:99]
	global_store_dword v[98:99], v97, off
	v_add_u32_e32 v98, 0x50, v96
	v_ashrrev_i32_e32 v99, 31, v98
	v_lshlrev_b64 v[98:99], 6, v[98:99]
	v_mul_f32_e32 v97, 0x3d000000, v24
	v_lshl_add_u64 v[98:99], v[152:153], 0, v[98:99]
	global_store_dword v[98:99], v97, off
	v_add_u32_e32 v98, 0x51, v96
	v_ashrrev_i32_e32 v99, 31, v98
	v_lshlrev_b64 v[98:99], 6, v[98:99]
	v_mul_f32_e32 v97, 0x3d000000, v25
	v_lshl_add_u64 v[98:99], v[152:153], 0, v[98:99]
	global_store_dword v[98:99], v97, off
	v_add_u32_e32 v98, 0x52, v96
	v_ashrrev_i32_e32 v99, 31, v98
	v_lshlrev_b64 v[98:99], 6, v[98:99]
	v_mul_f32_e32 v97, 0x3d000000, v26
	v_lshl_add_u64 v[98:99], v[152:153], 0, v[98:99]
	global_store_dword v[98:99], v97, off
	v_add_u32_e32 v98, 0x53, v96
	v_ashrrev_i32_e32 v99, 31, v98
	v_lshlrev_b64 v[98:99], 6, v[98:99]
	v_mul_f32_e32 v97, 0x3d000000, v27
	v_lshl_add_u64 v[98:99], v[152:153], 0, v[98:99]
	global_store_dword v[98:99], v97, off
	v_add_u32_e32 v98, 0x58, v96
	v_ashrrev_i32_e32 v99, 31, v98
	v_lshlrev_b64 v[98:99], 6, v[98:99]
	v_mul_f32_e32 v97, 0x3d000000, v28
	v_lshl_add_u64 v[98:99], v[152:153], 0, v[98:99]
	global_store_dword v[98:99], v97, off
	v_add_u32_e32 v98, 0x59, v96
	v_ashrrev_i32_e32 v99, 31, v98
	v_lshlrev_b64 v[98:99], 6, v[98:99]
	v_mul_f32_e32 v97, 0x3d000000, v29
	v_lshl_add_u64 v[98:99], v[152:153], 0, v[98:99]
	global_store_dword v[98:99], v97, off
	v_add_u32_e32 v98, 0x5a, v96
	v_ashrrev_i32_e32 v99, 31, v98
	v_lshlrev_b64 v[98:99], 6, v[98:99]
	v_mul_f32_e32 v97, 0x3d000000, v30
	v_lshl_add_u64 v[98:99], v[152:153], 0, v[98:99]
	global_store_dword v[98:99], v97, off
	v_add_u32_e32 v98, 0x5b, v96
	v_ashrrev_i32_e32 v99, 31, v98
	v_lshlrev_b64 v[98:99], 6, v[98:99]
	v_mul_f32_e32 v97, 0x3d000000, v31
	v_lshl_add_u64 v[98:99], v[152:153], 0, v[98:99]
	global_store_dword v[98:99], v97, off

; __device__ __forceinline__ bf16_t f2bf(float f) { return (bf16_t)(pk_bf16(f, f) & 0xffffu); }
; __device__ __forceinline__ float halfsum32(float s) {
;     s += __shfl_xor(s, 1); s += __shfl_xor(s, 2); s += __shfl_xor(s, 4); s += __shfl_xor(s, 8); s += __shfl_xor(s, 16); return s;
;     template <int MT> __device__ __forceinline__ void run(const Params& P, f32x16 (&acc)[MT][2], int rbase, int pn, int wc, int lane) const {
;     ...
;             bf16_t* CK = (bf16_t*)(ws + OFF_CKVA); float* SSQ = (float*)(ws + OFF_SSQK);
;             const int c0 = (pn - 4) * 128 + wc * 64 + n, c1 = c0 + 32; const float g0 = P.gkv[c0], g1 = P.gkv[c1];
; #pragma unroll
;             for (int mt = 0; mt < MT; ++mt)
; #pragma unroll
;                 for (int rg = 0; rg < 16; ++rg) { const int r = ROWOF(rb, mt, rg); const float v0 = acc[mt][0][rg], v1 = acc[mt][1][rg];
;                     float* o = (r < NPR) ? out + O_PCKV + (size_t)r * 512 : out + O_SCKV + (size_t)(r - NPR) * 512;
;                     o[c0] = v0 * g0; o[c1] = v1 * g1;
;                     const size_t kr = tok_keyrow(r);
;                     CK[kr * 512 + c0] = f2bf(v0 * g0); CK[kr * 512 + c1] = f2bf(v1 * g1);
;                     const float s = halfsum32(v0 * v0 + v1 * v1); if (n == 0) atomicAdd(SSQ + r, s); }
.LBB0_697:
	s_or_b64 exec, exec, s[0:1]
	v_or_b32_e32 v98, 1, v96
	s_waitcnt lgkmcnt(0)
	v_ashrrev_i32_e32 v99, 31, v98
	v_add_u32_e32 v97, 0xffffc001, v96
	v_cmp_gt_i32_e64 s[0:1], s40, v98
	v_mov_b32_e32 v109, s13
	v_mov_b32_e32 v110, s15
	v_cndmask_b32_e64 v101, 0, v99, s[0:1]
	v_cndmask_b32_e64 v100, v97, v98, s[0:1]
	v_cndmask_b32_e64 v111, v109, v110, s[0:1]
	v_mov_b32_e32 v109, s12
	v_mov_b32_e32 v110, s14
	v_cndmask_b32_e64 v110, v109, v110, s[0:1]
	v_lshlrev_b64 v[100:101], 11, v[100:101]
	v_lshl_add_u64 v[100:101], v[110:111], 0, v[100:101]
	v_mul_f32_e32 v110, v81, v103
	v_lshl_add_u64 v[100:101], v[132:133], 2, v[100:101]
	v_mul_f32_e32 v109, v65, v102
	v_cmp_lt_i32_e32 vcc, s41, v98
	global_store_dword v[100:101], v110, off
	global_store_dword v[100:101], v109, off offset:128
	v_mov_b64_e32 v[100:101], v[98:99]
	s_and_saveexec_b64 s[0:1], vcc
	s_mov_b64 s[68:69], 0x156a0c80
	v_lshrrev_b32_e32 v97, 6, v97
	v_mul_lo_u32 v97, v97, s54
	v_and_or_b32 v97, v98, 37, v97
	v_add_u32_e32 v100, 0x4400, v97
	v_mov_b32_e32 v101, v133
	s_or_b64 exec, exec, s[0:1]
	v_lshlrev_b64 v[100:101], 10, v[100:101]
	v_lshl_add_u64 v[100:101], s[8:9], 0, v[100:101]
	v_cvt_pk_bf16_f32 v97, v110, v110
	v_lshl_add_u64 v[100:101], v[132:133], 1, v[100:101]
	global_store_short v[100:101], v97, off
	v_cvt_pk_bf16_f32 v97, v109, v109
	global_store_short v[100:101], v97, off offset:64
	v_mul_f32_e32 v97, v65, v65
	v_fmac_f32_e32 v97, v81, v81
	s_nop 1
	v_add_f32_dpp v97, v97, v97 quad_perm:[1,0,3,2] row_mask:0xf bank_mask:0xf
	s_nop 1
	v_add_f32_dpp v97, v97, v97 quad_perm:[2,3,0,1] row_mask:0xf bank_mask:0xf
	s_nop 1
	v_add_f32_dpp v97, v97, v97 row_half_mirror row_mask:0xf bank_mask:0xf
	s_nop 1
	v_add_f32_dpp v97, v97, v97 row_mirror row_mask:0xf bank_mask:0xf
	ds_bpermute_b32 v100, v108, v97
	s_and_saveexec_b64 s[0:1], s[4:5]
	s_cbranch_execz .LBB0_701
	v_lshl_add_u64 v[98:99], v[98:99], 2, s[10:11]
	s_waitcnt lgkmcnt(0)
	v_add_f32_e32 v97, v97, v100
	global_atomic_add_f32 v[98:99], v97, off
.LBB0_701:
	s_or_b64 exec, exec, s[0:1]
	v_or_b32_e32 v98, 2, v96
	v_ashrrev_i32_e32 v99, 31, v98
	v_add_u32_e32 v97, 0xffffc002, v96
	v_cmp_gt_i32_e64 s[0:1], s40, v98
	v_mov_b32_e32 v109, s13
	v_mov_b32_e32 v110, s15
	v_cndmask_b32_e64 v101, 0, v99, s[0:1]
	s_waitcnt lgkmcnt(0)
	v_cndmask_b32_e64 v100, v97, v98, s[0:1]
	v_cndmask_b32_e64 v111, v109, v110, s[0:1]
	v_mov_b32_e32 v109, s12
	v_mov_b32_e32 v110, s14
	v_cndmask_b32_e64 v110, v109, v110, s[0:1]
	v_lshlrev_b64 v[100:101], 11, v[100:101]
	v_lshl_add_u64 v[100:101], v[110:111], 0, v[100:101]
	v_mul_f32_e32 v110, v82, v103
	v_lshl_add_u64 v[100:101], v[132:133], 2, v[100:101]
	v_mul_f32_e32 v109, v66, v102
	v_cmp_lt_i32_e32 vcc, s41, v98
	global_store_dword v[100:101], v110, off
	global_store_dword v[100:101], v109, off offset:128
	v_mov_b64_e32 v[100:101], v[98:99]
	s_and_saveexec_b64 s[0:1], vcc
	v_lshrrev_b32_e32 v97, 6, v97
	v_mul_lo_u32 v97, v97, s54
	v_and_or_b32 v97, v98, 38, v97
	v_add_u32_e32 v100, 0x4400, v97
	v_mov_b32_e32 v101, v133
	s_or_b64 exec, exec, s[0:1]
	v_lshlrev_b64 v[100:101], 10, v[100:101]
	v_lshl_add_u64 v[100:101], s[8:9], 0, v[100:101]
	v_cvt_pk_bf16_f32 v97, v110, v110
	v_lshl_add_u64 v[100:101], v[132:133], 1, v[100:101]
	global_store_short v[100:101], v97, off
	v_cvt_pk_bf16_f32 v97, v109, v109
	global_store_short v[100:101], v97, off offset:64
	v_mul_f32_e32 v97, v66, v66
	v_fmac_f32_e32 v97, v82, v82
	s_nop 1
	v_add_f32_dpp v97, v97, v97 quad_perm:[1,0,3,2] row_mask:0xf bank_mask:0xf
	s_nop 1
	v_add_f32_dpp v97, v97, v97 quad_perm:[2,3,0,1] row_mask:0xf bank_mask:0xf
	s_nop 1
	v_add_f32_dpp v97, v97, v97 row_half_mirror row_mask:0xf bank_mask:0xf
	s_nop 1
	v_add_f32_dpp v97, v97, v97 row_mirror row_mask:0xf bank_mask:0xf
	ds_bpermute_b32 v100, v108, v97
	s_and_saveexec_b64 s[0:1], s[4:5]
	s_cbranch_execz .LBB0_705
	v_lshl_add_u64 v[98:99], v[98:99], 2, s[10:11]
	s_waitcnt lgkmcnt(0)
	v_add_f32_e32 v97, v97, v100
	global_atomic_add_f32 v[98:99], v97, off
.LBB0_705:
	s_or_b64 exec, exec, s[0:1]
	v_or_b32_e32 v98, 3, v96
	v_ashrrev_i32_e32 v99, 31, v98
	v_add_u32_e32 v97, 0xffffc003, v96
	v_cmp_gt_i32_e64 s[0:1], s40, v98
	v_mov_b32_e32 v109, s13
	v_mov_b32_e32 v110, s15
	v_cndmask_b32_e64 v101, 0, v99, s[0:1]
	s_waitcnt lgkmcnt(0)
	v_cndmask_b32_e64 v100, v97, v98, s[0:1]
	v_cndmask_b32_e64 v111, v109, v110, s[0:1]
	v_mov_b32_e32 v109, s12
	v_mov_b32_e32 v110, s14
	v_cndmask_b32_e64 v110, v109, v110, s[0:1]
	v_lshlrev_b64 v[100:101], 11, v[100:101]
	v_lshl_add_u64 v[100:101], v[110:111], 0, v[100:101]
	v_mul_f32_e32 v110, v83, v103
	v_lshl_add_u64 v[100:101], v[132:133], 2, v[100:101]
	v_mul_f32_e32 v109, v67, v102
	v_cmp_lt_i32_e32 vcc, s41, v98
	global_store_dword v[100:101], v110, off
	global_store_dword v[100:101], v109, off offset:128
	v_mov_b64_e32 v[100:101], v[98:99]
	s_and_saveexec_b64 s[0:1], vcc
	v_lshrrev_b32_e32 v97, 6, v97
	v_mul_lo_u32 v97, v97, s54
	v_and_or_b32 v97, v98, 39, v97
	v_add_u32_e32 v100, 0x4400, v97
	v_mov_b32_e32 v101, v133
	s_or_b64 exec, exec, s[0:1]
	v_lshlrev_b64 v[100:101], 10, v[100:101]
	v_lshl_add_u64 v[100:101], s[8:9], 0, v[100:101]
	v_cvt_pk_bf16_f32 v97, v110, v110
	v_lshl_add_u64 v[100:101], v[132:133], 1, v[100:101]
	global_store_short v[100:101], v97, off
	v_cvt_pk_bf16_f32 v97, v109, v109
	global_store_short v[100:101], v97, off offset:64
	v_mul_f32_e32 v97, v67, v67
	v_fmac_f32_e32 v97, v83, v83
	s_nop 1
	v_add_f32_dpp v97, v97, v97 quad_perm:[1,0,3,2] row_mask:0xf bank_mask:0xf
	s_nop 1
	v_add_f32_dpp v97, v97, v97 quad_perm:[2,3,0,1] row_mask:0xf bank_mask:0xf
	s_nop 1
	v_add_f32_dpp v97, v97, v97 row_half_mirror row_mask:0xf bank_mask:0xf
	s_nop 1
	v_add_f32_dpp v97, v97, v97 row_mirror row_mask:0xf bank_mask:0xf
	ds_bpermute_b32 v100, v108, v97
	s_and_saveexec_b64 s[0:1], s[4:5]
	s_cbranch_execz .LBB0_709
	v_lshl_add_u64 v[98:99], v[98:99], 2, s[10:11]
	s_waitcnt lgkmcnt(0)
	v_add_f32_e32 v97, v97, v100
	global_atomic_add_f32 v[98:99], v97, off
; __device__ __forceinline__ bf16_t f2bf(float f) { return (bf16_t)(pk_bf16(f, f) & 0xffffu); }
; __device__ __forceinline__ float halfsum32(float s) {
;     s += __shfl_xor(s, 1); s += __shfl_xor(s, 2); s += __shfl_xor(s, 4); s += __shfl_xor(s, 8); s += __shfl_xor(s, 16); return s;
;     template <int MT> __device__ __forceinline__ void run(const Params& P, f32x16 (&acc)[MT][2], int rbase, int pn, int wc, int lane) const {
;     ...
;             bf16_t* CK = (bf16_t*)(ws + OFF_CKVA); float* SSQ = (float*)(ws + OFF_SSQK);
;             const int c0 = (pn - 4) * 128 + wc * 64 + n, c1 = c0 + 32; const float g0 = P.gkv[c0], g1 = P.gkv[c1];
; #pragma unroll
;             for (int mt = 0; mt < MT; ++mt)
; #pragma unroll
;                 for (int rg = 0; rg < 16; ++rg) { const int r = ROWOF(rb, mt, rg); const float v0 = acc[mt][0][rg], v1 = acc[mt][1][rg];
;                     float* o = (r < NPR) ? out + O_PCKV + (size_t)r * 512 : out + O_SCKV + (size_t)(r - NPR) * 512;
;                     o[c0] = v0 * g0; o[c1] = v1 * g1;
;                     const size_t kr = tok_keyrow(r);
;                     CK[kr * 512 + c0] = f2bf(v0 * g0); CK[kr * 512 + c1] = f2bf(v1 * g1);
;                     const float s = halfsum32(v0 * v0 + v1 * v1); if (n == 0) atomicAdd(SSQ + r, s); }
.LBB0_709:
	s_or_b64 exec, exec, s[0:1]
	v_or_b32_e32 v98, 8, v96
	v_ashrrev_i32_e32 v99, 31, v98
	v_add_u32_e32 v97, 0xffffc008, v96
	v_cmp_gt_i32_e64 s[0:1], s40, v98
	v_mov_b32_e32 v109, s13
	v_mov_b32_e32 v110, s15
	v_cndmask_b32_e64 v101, 0, v99, s[0:1]
	s_waitcnt lgkmcnt(0)
	v_cndmask_b32_e64 v100, v97, v98, s[0:1]
	v_cndmask_b32_e64 v111, v109, v110, s[0:1]
	v_mov_b32_e32 v109, s12
	v_mov_b32_e32 v110, s14
	v_cndmask_b32_e64 v110, v109, v110, s[0:1]
	v_lshlrev_b64 v[100:101], 11, v[100:101]
	v_lshl_add_u64 v[100:101], v[110:111], 0, v[100:101]
	v_mul_f32_e32 v110, v84, v103
	v_lshl_add_u64 v[100:101], v[132:133], 2, v[100:101]
	v_mul_f32_e32 v109, v68, v102
	v_cmp_lt_i32_e32 vcc, s41, v98
	global_store_dword v[100:101], v110, off
	global_store_dword v[100:101], v109, off offset:128
	v_mov_b64_e32 v[100:101], v[98:99]
	s_and_saveexec_b64 s[0:1], vcc
	v_lshrrev_b32_e32 v97, 6, v97
	v_mul_lo_u32 v97, v97, s54
	v_and_or_b32 v97, v98, 44, v97
	v_add_u32_e32 v100, 0x4400, v97
	v_mov_b32_e32 v101, v133
	s_or_b64 exec, exec, s[0:1]
	v_lshlrev_b64 v[100:101], 10, v[100:101]
	v_lshl_add_u64 v[100:101], s[8:9], 0, v[100:101]
	v_cvt_pk_bf16_f32 v97, v110, v110
	v_lshl_add_u64 v[100:101], v[132:133], 1, v[100:101]
	global_store_short v[100:101], v97, off
	v_cvt_pk_bf16_f32 v97, v109, v109
	global_store_short v[100:101], v97, off offset:64
	v_mul_f32_e32 v97, v68, v68
	v_fmac_f32_e32 v97, v84, v84
	s_nop 1
	v_add_f32_dpp v97, v97, v97 quad_perm:[1,0,3,2] row_mask:0xf bank_mask:0xf
	s_nop 1
	v_add_f32_dpp v97, v97, v97 quad_perm:[2,3,0,1] row_mask:0xf bank_mask:0xf
	s_nop 1
	v_add_f32_dpp v97, v97, v97 row_half_mirror row_mask:0xf bank_mask:0xf
	s_nop 1
	v_add_f32_dpp v97, v97, v97 row_mirror row_mask:0xf bank_mask:0xf
	ds_bpermute_b32 v100, v108, v97
	s_and_saveexec_b64 s[0:1], s[4:5]
	s_cbranch_execz .LBB0_713
	v_lshl_add_u64 v[98:99], v[98:99], 2, s[10:11]
	s_waitcnt lgkmcnt(0)
	v_add_f32_e32 v97, v97, v100
	global_atomic_add_f32 v[98:99], v97, off
.LBB0_713:
	s_or_b64 exec, exec, s[0:1]
	v_or_b32_e32 v98, 9, v96
	v_ashrrev_i32_e32 v99, 31, v98
	v_add_u32_e32 v97, 0xffffc009, v96
	v_cmp_gt_i32_e64 s[0:1], s40, v98
	v_mov_b32_e32 v109, s13
	v_mov_b32_e32 v110, s15
	v_cndmask_b32_e64 v101, 0, v99, s[0:1]
	s_waitcnt lgkmcnt(0)
	v_cndmask_b32_e64 v100, v97, v98, s[0:1]
	v_cndmask_b32_e64 v111, v109, v110, s[0:1]
	v_mov_b32_e32 v109, s12
	v_mov_b32_e32 v110, s14
	v_cndmask_b32_e64 v110, v109, v110, s[0:1]
	v_lshlrev_b64 v[100:101], 11, v[100:101]
	v_lshl_add_u64 v[100:101], v[110:111], 0, v[100:101]
	v_mul_f32_e32 v110, v85, v103
	v_lshl_add_u64 v[100:101], v[132:133], 2, v[100:101]
	v_mul_f32_e32 v109, v69, v102
	v_cmp_lt_i32_e32 vcc, s41, v98
	global_store_dword v[100:101], v110, off
	global_store_dword v[100:101], v109, off offset:128
	v_mov_b64_e32 v[100:101], v[98:99]
	s_and_saveexec_b64 s[0:1], vcc
	v_lshrrev_b32_e32 v97, 6, v97
	v_mul_lo_u32 v97, v97, s54
	v_and_or_b32 v97, v98, 45, v97
	v_add_u32_e32 v100, 0x4400, v97
	v_mov_b32_e32 v101, v133
	s_or_b64 exec, exec, s[0:1]
	v_lshlrev_b64 v[100:101], 10, v[100:101]
	v_lshl_add_u64 v[100:101], s[8:9], 0, v[100:101]
	v_cvt_pk_bf16_f32 v97, v110, v110
	v_lshl_add_u64 v[100:101], v[132:133], 1, v[100:101]
	global_store_short v[100:101], v97, off
	v_cvt_pk_bf16_f32 v97, v109, v109
	global_store_short v[100:101], v97, off offset:64
	v_mul_f32_e32 v97, v69, v69
	v_fmac_f32_e32 v97, v85, v85
	s_nop 1
	v_add_f32_dpp v97, v97, v97 quad_perm:[1,0,3,2] row_mask:0xf bank_mask:0xf
	s_nop 1
	v_add_f32_dpp v97, v97, v97 quad_perm:[2,3,0,1] row_mask:0xf bank_mask:0xf
	s_nop 1
	v_add_f32_dpp v97, v97, v97 row_half_mirror row_mask:0xf bank_mask:0xf
	s_nop 1
	v_add_f32_dpp v97, v97, v97 row_mirror row_mask:0xf bank_mask:0xf
	ds_bpermute_b32 v100, v108, v97
	s_and_saveexec_b64 s[0:1], s[4:5]
	s_cbranch_execz .LBB0_717
	v_lshl_add_u64 v[98:99], v[98:99], 2, s[10:11]
	s_waitcnt lgkmcnt(0)
	v_add_f32_e32 v97, v97, v100
	global_atomic_add_f32 v[98:99], v97, off
.LBB0_717:
	s_or_b64 exec, exec, s[0:1]
	v_or_b32_e32 v98, 10, v96
	v_ashrrev_i32_e32 v99, 31, v98
	v_add_u32_e32 v97, 0xffffc00a, v96
	v_cmp_gt_i32_e64 s[0:1], s40, v98
	v_mov_b32_e32 v109, s13
	v_mov_b32_e32 v110, s15
	v_cndmask_b32_e64 v101, 0, v99, s[0:1]
	s_waitcnt lgkmcnt(0)
	v_cndmask_b32_e64 v100, v97, v98, s[0:1]
	v_cndmask_b32_e64 v111, v109, v110, s[0:1]
	v_mov_b32_e32 v109, s12
	v_mov_b32_e32 v110, s14
	v_cndmask_b32_e64 v110, v109, v110, s[0:1]
	v_lshlrev_b64 v[100:101], 11, v[100:101]
	v_lshl_add_u64 v[100:101], v[110:111], 0, v[100:101]
	v_mul_f32_e32 v110, v86, v103
	v_lshl_add_u64 v[100:101], v[132:133], 2, v[100:101]
	v_mul_f32_e32 v109, v70, v102
	v_cmp_lt_i32_e32 vcc, s41, v98
	global_store_dword v[100:101], v110, off
	global_store_dword v[100:101], v109, off offset:128
	v_mov_b64_e32 v[100:101], v[98:99]
	s_and_saveexec_b64 s[0:1], vcc
	v_lshrrev_b32_e32 v97, 6, v97
	v_mul_lo_u32 v97, v97, s54
	v_and_or_b32 v97, v98, 46, v97
	v_add_u32_e32 v100, 0x4400, v97
	v_mov_b32_e32 v101, v133
	s_or_b64 exec, exec, s[0:1]
	v_lshlrev_b64 v[100:101], 10, v[100:101]
	v_lshl_add_u64 v[100:101], s[8:9], 0, v[100:101]
	v_cvt_pk_bf16_f32 v97, v110, v110
	v_lshl_add_u64 v[100:101], v[132:133], 1, v[100:101]
	global_store_short v[100:101], v97, off
	v_cvt_pk_bf16_f32 v97, v109, v109
	global_store_short v[100:101], v97, off offset:64
	v_mul_f32_e32 v97, v70, v70
	v_fmac_f32_e32 v97, v86, v86
	s_nop 1
	v_add_f32_dpp v97, v97, v97 quad_perm:[1,0,3,2] row_mask:0xf bank_mask:0xf
	s_nop 1
	v_add_f32_dpp v97, v97, v97 quad_perm:[2,3,0,1] row_mask:0xf bank_mask:0xf
	s_nop 1
	v_add_f32_dpp v97, v97, v97 row_half_mirror row_mask:0xf bank_mask:0xf
	s_nop 1
	v_add_f32_dpp v97, v97, v97 row_mirror row_mask:0xf bank_mask:0xf
	ds_bpermute_b32 v100, v108, v97
	s_and_saveexec_b64 s[0:1], s[4:5]
	s_cbranch_execz .LBB0_721
	v_lshl_add_u64 v[98:99], v[98:99], 2, s[10:11]
	s_waitcnt lgkmcnt(0)
	v_add_f32_e32 v97, v97, v100
	global_atomic_add_f32 v[98:99], v97, off
; __device__ __forceinline__ bf16_t f2bf(float f) { return (bf16_t)(pk_bf16(f, f) & 0xffffu); }
; __device__ __forceinline__ float halfsum32(float s) {
;     s += __shfl_xor(s, 1); s += __shfl_xor(s, 2); s += __shfl_xor(s, 4); s += __shfl_xor(s, 8); s += __shfl_xor(s, 16); return s;
;     template <int MT> __device__ __forceinline__ void run(const Params& P, f32x16 (&acc)[MT][2], int rbase, int pn, int wc, int lane) const {
;     ...
;             bf16_t* CK = (bf16_t*)(ws + OFF_CKVA); float* SSQ = (float*)(ws + OFF_SSQK);
;             const int c0 = (pn - 4) * 128 + wc * 64 + n, c1 = c0 + 32; const float g0 = P.gkv[c0], g1 = P.gkv[c1];
; #pragma unroll
;             for (int mt = 0; mt < MT; ++mt)
; #pragma unroll
;                 for (int rg = 0; rg < 16; ++rg) { const int r = ROWOF(rb, mt, rg); const float v0 = acc[mt][0][rg], v1 = acc[mt][1][rg];
;                     float* o = (r < NPR) ? out + O_PCKV + (size_t)r * 512 : out + O_SCKV + (size_t)(r - NPR) * 512;
;                     o[c0] = v0 * g0; o[c1] = v1 * g1;
;                     const size_t kr = tok_keyrow(r);
;                     CK[kr * 512 + c0] = f2bf(v0 * g0); CK[kr * 512 + c1] = f2bf(v1 * g1);
;                     const float s = halfsum32(v0 * v0 + v1 * v1); if (n == 0) atomicAdd(SSQ + r, s); }
.LBB0_721:
	s_or_b64 exec, exec, s[0:1]
	v_or_b32_e32 v98, 11, v96
	v_ashrrev_i32_e32 v99, 31, v98
	v_add_u32_e32 v97, 0xffffc00b, v96
	v_cmp_gt_i32_e64 s[0:1], s40, v98
	v_mov_b32_e32 v109, s13
	v_mov_b32_e32 v110, s15
	v_cndmask_b32_e64 v101, 0, v99, s[0:1]
	s_waitcnt lgkmcnt(0)
	v_cndmask_b32_e64 v100, v97, v98, s[0:1]
	v_cndmask_b32_e64 v111, v109, v110, s[0:1]
	v_mov_b32_e32 v109, s12
	v_mov_b32_e32 v110, s14
	v_cndmask_b32_e64 v110, v109, v110, s[0:1]
	v_lshlrev_b64 v[100:101], 11, v[100:101]
	v_lshl_add_u64 v[100:101], v[110:111], 0, v[100:101]
	v_mul_f32_e32 v110, v87, v103
	v_lshl_add_u64 v[100:101], v[132:133], 2, v[100:101]
	v_mul_f32_e32 v109, v71, v102
	v_cmp_lt_i32_e32 vcc, s41, v98
	global_store_dword v[100:101], v110, off
	global_store_dword v[100:101], v109, off offset:128
	v_mov_b64_e32 v[100:101], v[98:99]
	s_and_saveexec_b64 s[0:1], vcc
	v_lshrrev_b32_e32 v97, 6, v97
	v_mul_lo_u32 v97, v97, s54
	v_and_or_b32 v97, v98, 47, v97
	v_add_u32_e32 v100, 0x4400, v97
	v_mov_b32_e32 v101, v133
	s_or_b64 exec, exec, s[0:1]
	v_lshlrev_b64 v[100:101], 10, v[100:101]
	v_lshl_add_u64 v[100:101], s[8:9], 0, v[100:101]
	v_cvt_pk_bf16_f32 v97, v110, v110
	v_lshl_add_u64 v[100:101], v[132:133], 1, v[100:101]
	global_store_short v[100:101], v97, off
	v_cvt_pk_bf16_f32 v97, v109, v109
	global_store_short v[100:101], v97, off offset:64
	v_mul_f32_e32 v97, v71, v71
	v_fmac_f32_e32 v97, v87, v87
	s_nop 1
	v_add_f32_dpp v97, v97, v97 quad_perm:[1,0,3,2] row_mask:0xf bank_mask:0xf
	s_nop 1
	v_add_f32_dpp v97, v97, v97 quad_perm:[2,3,0,1] row_mask:0xf bank_mask:0xf
	s_nop 1
	v_add_f32_dpp v97, v97, v97 row_half_mirror row_mask:0xf bank_mask:0xf
	s_nop 1
	v_add_f32_dpp v97, v97, v97 row_mirror row_mask:0xf bank_mask:0xf
	ds_bpermute_b32 v100, v108, v97
	s_and_saveexec_b64 s[0:1], s[4:5]
	s_cbranch_execz .LBB0_725
	v_lshl_add_u64 v[98:99], v[98:99], 2, s[10:11]
	s_waitcnt lgkmcnt(0)
	v_add_f32_e32 v97, v97, v100
	global_atomic_add_f32 v[98:99], v97, off
.LBB0_725:
	s_or_b64 exec, exec, s[0:1]
	v_or_b32_e32 v98, 16, v96
	v_ashrrev_i32_e32 v99, 31, v98
	v_add_u32_e32 v97, 0xffffc010, v96
	v_cmp_gt_i32_e64 s[0:1], s40, v98
	v_mov_b32_e32 v109, s13
	v_mov_b32_e32 v110, s15
	v_cndmask_b32_e64 v101, 0, v99, s[0:1]
	s_waitcnt lgkmcnt(0)
	v_cndmask_b32_e64 v100, v97, v98, s[0:1]
	v_cndmask_b32_e64 v111, v109, v110, s[0:1]
	v_mov_b32_e32 v109, s12
	v_mov_b32_e32 v110, s14
	v_cndmask_b32_e64 v110, v109, v110, s[0:1]
	v_lshlrev_b64 v[100:101], 11, v[100:101]
	v_lshl_add_u64 v[100:101], v[110:111], 0, v[100:101]
	v_mul_f32_e32 v110, v88, v103
	v_lshl_add_u64 v[100:101], v[132:133], 2, v[100:101]
	v_mul_f32_e32 v109, v72, v102
	v_cmp_lt_i32_e32 vcc, s41, v98
	global_store_dword v[100:101], v110, off
	global_store_dword v[100:101], v109, off offset:128
	v_mov_b64_e32 v[100:101], v[98:99]
	s_and_saveexec_b64 s[0:1], vcc
	v_lshrrev_b32_e32 v97, 6, v97
	v_mul_lo_u32 v97, v97, s54
	v_and_or_b32 v97, v98, 52, v97
	v_add_u32_e32 v100, 0x4400, v97
	v_mov_b32_e32 v101, v133
	s_or_b64 exec, exec, s[0:1]
	v_lshlrev_b64 v[100:101], 10, v[100:101]
	v_lshl_add_u64 v[100:101], s[8:9], 0, v[100:101]
	v_cvt_pk_bf16_f32 v97, v110, v110
	v_lshl_add_u64 v[100:101], v[132:133], 1, v[100:101]
	global_store_short v[100:101], v97, off
	v_cvt_pk_bf16_f32 v97, v109, v109
	global_store_short v[100:101], v97, off offset:64
	v_mul_f32_e32 v97, v72, v72
	v_fmac_f32_e32 v97, v88, v88
	s_nop 1
	v_add_f32_dpp v97, v97, v97 quad_perm:[1,0,3,2] row_mask:0xf bank_mask:0xf
	s_nop 1
	v_add_f32_dpp v97, v97, v97 quad_perm:[2,3,0,1] row_mask:0xf bank_mask:0xf
	s_nop 1
	v_add_f32_dpp v97, v97, v97 row_half_mirror row_mask:0xf bank_mask:0xf
	s_nop 1
	v_add_f32_dpp v97, v97, v97 row_mirror row_mask:0xf bank_mask:0xf
	ds_bpermute_b32 v100, v108, v97
	s_and_saveexec_b64 s[0:1], s[4:5]
	s_cbranch_execz .LBB0_729
	v_lshl_add_u64 v[98:99], v[98:99], 2, s[10:11]
	s_waitcnt lgkmcnt(0)
	v_add_f32_e32 v97, v97, v100
	global_atomic_add_f32 v[98:99], v97, off
.LBB0_729:
	s_or_b64 exec, exec, s[0:1]
	v_or_b32_e32 v98, 17, v96
	v_ashrrev_i32_e32 v99, 31, v98
	v_add_u32_e32 v97, 0xffffc011, v96
	v_cmp_gt_i32_e64 s[0:1], s40, v98
	v_mov_b32_e32 v109, s13
	v_mov_b32_e32 v110, s15
	v_cndmask_b32_e64 v101, 0, v99, s[0:1]
	s_waitcnt lgkmcnt(0)
	v_cndmask_b32_e64 v100, v97, v98, s[0:1]
	v_cndmask_b32_e64 v111, v109, v110, s[0:1]
	v_mov_b32_e32 v109, s12
	v_mov_b32_e32 v110, s14
	v_cndmask_b32_e64 v110, v109, v110, s[0:1]
	v_lshlrev_b64 v[100:101], 11, v[100:101]
	v_lshl_add_u64 v[100:101], v[110:111], 0, v[100:101]
	v_mul_f32_e32 v110, v89, v103
	v_lshl_add_u64 v[100:101], v[132:133], 2, v[100:101]
	v_mul_f32_e32 v109, v73, v102
	v_cmp_lt_i32_e32 vcc, s41, v98
	global_store_dword v[100:101], v110, off
	global_store_dword v[100:101], v109, off offset:128
	v_mov_b64_e32 v[100:101], v[98:99]
	s_and_saveexec_b64 s[0:1], vcc
	v_lshrrev_b32_e32 v97, 6, v97
	v_mul_lo_u32 v97, v97, s54
	v_and_or_b32 v97, v98, 53, v97
	v_add_u32_e32 v100, 0x4400, v97
	v_mov_b32_e32 v101, v133
	s_or_b64 exec, exec, s[0:1]
	v_lshlrev_b64 v[100:101], 10, v[100:101]
	v_lshl_add_u64 v[100:101], s[8:9], 0, v[100:101]
	v_cvt_pk_bf16_f32 v97, v110, v110
	v_lshl_add_u64 v[100:101], v[132:133], 1, v[100:101]
	global_store_short v[100:101], v97, off
	v_cvt_pk_bf16_f32 v97, v109, v109
	global_store_short v[100:101], v97, off offset:64
	v_mul_f32_e32 v97, v73, v73
	v_fmac_f32_e32 v97, v89, v89
	s_nop 1
	v_add_f32_dpp v97, v97, v97 quad_perm:[1,0,3,2] row_mask:0xf bank_mask:0xf
	s_nop 1
	v_add_f32_dpp v97, v97, v97 quad_perm:[2,3,0,1] row_mask:0xf bank_mask:0xf
	s_nop 1
	v_add_f32_dpp v97, v97, v97 row_half_mirror row_mask:0xf bank_mask:0xf
	s_nop 1
	v_add_f32_dpp v97, v97, v97 row_mirror row_mask:0xf bank_mask:0xf
	ds_bpermute_b32 v100, v108, v97
	s_and_saveexec_b64 s[0:1], s[4:5]
	s_cbranch_execz .LBB0_733
	v_lshl_add_u64 v[98:99], v[98:99], 2, s[10:11]
	s_waitcnt lgkmcnt(0)
	v_add_f32_e32 v97, v97, v100
	global_atomic_add_f32 v[98:99], v97, off
; __device__ __forceinline__ bf16_t f2bf(float f) { return (bf16_t)(pk_bf16(f, f) & 0xffffu); }
; __device__ __forceinline__ float halfsum32(float s) {
;     s += __shfl_xor(s, 1); s += __shfl_xor(s, 2); s += __shfl_xor(s, 4); s += __shfl_xor(s, 8); s += __shfl_xor(s, 16); return s;
;     template <int MT> __device__ __forceinline__ void run(const Params& P, f32x16 (&acc)[MT][2], int rbase, int pn, int wc, int lane) const {
;     ...
;             bf16_t* CK = (bf16_t*)(ws + OFF_CKVA); float* SSQ = (float*)(ws + OFF_SSQK);
;             const int c0 = (pn - 4) * 128 + wc * 64 + n, c1 = c0 + 32; const float g0 = P.gkv[c0], g1 = P.gkv[c1];
; #pragma unroll
;             for (int mt = 0; mt < MT; ++mt)
; #pragma unroll
;                 for (int rg = 0; rg < 16; ++rg) { const int r = ROWOF(rb, mt, rg); const float v0 = acc[mt][0][rg], v1 = acc[mt][1][rg];
;                     float* o = (r < NPR) ? out + O_PCKV + (size_t)r * 512 : out + O_SCKV + (size_t)(r - NPR) * 512;
;                     o[c0] = v0 * g0; o[c1] = v1 * g1;
;                     const size_t kr = tok_keyrow(r);
;                     CK[kr * 512 + c0] = f2bf(v0 * g0); CK[kr * 512 + c1] = f2bf(v1 * g1);
;                     const float s = halfsum32(v0 * v0 + v1 * v1); if (n == 0) atomicAdd(SSQ + r, s); }
.LBB0_733:
	s_or_b64 exec, exec, s[0:1]
	v_or_b32_e32 v98, 18, v96
	v_ashrrev_i32_e32 v99, 31, v98
	v_add_u32_e32 v97, 0xffffc012, v96
	v_cmp_gt_i32_e64 s[0:1], s40, v98
	v_mov_b32_e32 v109, s13
	v_mov_b32_e32 v110, s15
	v_cndmask_b32_e64 v101, 0, v99, s[0:1]
	s_waitcnt lgkmcnt(0)
	v_cndmask_b32_e64 v100, v97, v98, s[0:1]
	v_cndmask_b32_e64 v111, v109, v110, s[0:1]
	v_mov_b32_e32 v109, s12
	v_mov_b32_e32 v110, s14
	v_cndmask_b32_e64 v110, v109, v110, s[0:1]
	v_lshlrev_b64 v[100:101], 11, v[100:101]
	v_lshl_add_u64 v[100:101], v[110:111], 0, v[100:101]
	v_mul_f32_e32 v110, v90, v103
	v_lshl_add_u64 v[100:101], v[132:133], 2, v[100:101]
	v_mul_f32_e32 v109, v74, v102
	v_cmp_lt_i32_e32 vcc, s41, v98
	global_store_dword v[100:101], v110, off
	global_store_dword v[100:101], v109, off offset:128
	v_mov_b64_e32 v[100:101], v[98:99]
	s_and_saveexec_b64 s[0:1], vcc
	v_lshrrev_b32_e32 v97, 6, v97
	v_mul_lo_u32 v97, v97, s54
	v_and_or_b32 v97, v98, 54, v97
	v_add_u32_e32 v100, 0x4400, v97
	v_mov_b32_e32 v101, v133
	s_or_b64 exec, exec, s[0:1]
	v_lshlrev_b64 v[100:101], 10, v[100:101]
	v_lshl_add_u64 v[100:101], s[8:9], 0, v[100:101]
	v_cvt_pk_bf16_f32 v97, v110, v110
	v_lshl_add_u64 v[100:101], v[132:133], 1, v[100:101]
	global_store_short v[100:101], v97, off
	v_cvt_pk_bf16_f32 v97, v109, v109
	global_store_short v[100:101], v97, off offset:64
	v_mul_f32_e32 v97, v74, v74
	v_fmac_f32_e32 v97, v90, v90
	s_nop 1
	v_add_f32_dpp v97, v97, v97 quad_perm:[1,0,3,2] row_mask:0xf bank_mask:0xf
	s_nop 1
	v_add_f32_dpp v97, v97, v97 quad_perm:[2,3,0,1] row_mask:0xf bank_mask:0xf
	s_nop 1
	v_add_f32_dpp v97, v97, v97 row_half_mirror row_mask:0xf bank_mask:0xf
	s_nop 1
	v_add_f32_dpp v97, v97, v97 row_mirror row_mask:0xf bank_mask:0xf
	ds_bpermute_b32 v100, v108, v97
	s_and_saveexec_b64 s[0:1], s[4:5]
	s_cbranch_execz .LBB0_737
	v_lshl_add_u64 v[98:99], v[98:99], 2, s[10:11]
	s_waitcnt lgkmcnt(0)
	v_add_f32_e32 v97, v97, v100
	global_atomic_add_f32 v[98:99], v97, off
.LBB0_737:
	s_or_b64 exec, exec, s[0:1]
	v_or_b32_e32 v98, 19, v96
	v_ashrrev_i32_e32 v99, 31, v98
	v_add_u32_e32 v97, 0xffffc013, v96
	v_cmp_gt_i32_e64 s[0:1], s40, v98
	v_mov_b32_e32 v109, s13
	v_mov_b32_e32 v110, s15
	v_cndmask_b32_e64 v101, 0, v99, s[0:1]
	s_waitcnt lgkmcnt(0)
	v_cndmask_b32_e64 v100, v97, v98, s[0:1]
	v_cndmask_b32_e64 v111, v109, v110, s[0:1]
	v_mov_b32_e32 v109, s12
	v_mov_b32_e32 v110, s14
	v_cndmask_b32_e64 v110, v109, v110, s[0:1]
	v_lshlrev_b64 v[100:101], 11, v[100:101]
	v_lshl_add_u64 v[100:101], v[110:111], 0, v[100:101]
	v_mul_f32_e32 v110, v91, v103
	v_lshl_add_u64 v[100:101], v[132:133], 2, v[100:101]
	v_mul_f32_e32 v109, v75, v102
	v_cmp_lt_i32_e32 vcc, s41, v98
	global_store_dword v[100:101], v110, off
	global_store_dword v[100:101], v109, off offset:128
	v_mov_b64_e32 v[100:101], v[98:99]
	s_and_saveexec_b64 s[0:1], vcc
	v_lshrrev_b32_e32 v97, 6, v97
	v_mul_lo_u32 v97, v97, s54
	v_and_or_b32 v97, v98, 55, v97
	v_add_u32_e32 v100, 0x4400, v97
	v_mov_b32_e32 v101, v133
	s_or_b64 exec, exec, s[0:1]
	v_lshlrev_b64 v[100:101], 10, v[100:101]
	v_lshl_add_u64 v[100:101], s[8:9], 0, v[100:101]
	v_cvt_pk_bf16_f32 v97, v110, v110
	v_lshl_add_u64 v[100:101], v[132:133], 1, v[100:101]
	global_store_short v[100:101], v97, off
	v_cvt_pk_bf16_f32 v97, v109, v109
	global_store_short v[100:101], v97, off offset:64
	v_mul_f32_e32 v97, v75, v75
	v_fmac_f32_e32 v97, v91, v91
	s_nop 1
	v_add_f32_dpp v97, v97, v97 quad_perm:[1,0,3,2] row_mask:0xf bank_mask:0xf
	s_nop 1
	v_add_f32_dpp v97, v97, v97 quad_perm:[2,3,0,1] row_mask:0xf bank_mask:0xf
	s_nop 1
	v_add_f32_dpp v97, v97, v97 row_half_mirror row_mask:0xf bank_mask:0xf
	s_nop 1
	v_add_f32_dpp v97, v97, v97 row_mirror row_mask:0xf bank_mask:0xf
	ds_bpermute_b32 v100, v108, v97
	s_and_saveexec_b64 s[0:1], s[4:5]
	s_cbranch_execz .LBB0_741
	v_lshl_add_u64 v[98:99], v[98:99], 2, s[10:11]
	s_waitcnt lgkmcnt(0)
	v_add_f32_e32 v97, v97, v100
	global_atomic_add_f32 v[98:99], v97, off
.LBB0_741:
	s_or_b64 exec, exec, s[0:1]
	v_or_b32_e32 v98, 24, v96
	v_ashrrev_i32_e32 v99, 31, v98
	v_add_u32_e32 v97, 0xffffc018, v96
	v_cmp_gt_i32_e64 s[0:1], s40, v98
	v_mov_b32_e32 v109, s13
	v_mov_b32_e32 v110, s15
	v_cndmask_b32_e64 v101, 0, v99, s[0:1]
	s_waitcnt lgkmcnt(0)
	v_cndmask_b32_e64 v100, v97, v98, s[0:1]
	v_cndmask_b32_e64 v111, v109, v110, s[0:1]
	v_mov_b32_e32 v109, s12
	v_mov_b32_e32 v110, s14
	v_cndmask_b32_e64 v110, v109, v110, s[0:1]
	v_lshlrev_b64 v[100:101], 11, v[100:101]
	v_lshl_add_u64 v[100:101], v[110:111], 0, v[100:101]
	v_mul_f32_e32 v110, v92, v103
	v_lshl_add_u64 v[100:101], v[132:133], 2, v[100:101]
	v_mul_f32_e32 v109, v76, v102
	v_cmp_lt_i32_e32 vcc, s41, v98
	global_store_dword v[100:101], v110, off
	global_store_dword v[100:101], v109, off offset:128
	v_mov_b64_e32 v[100:101], v[98:99]
	s_and_saveexec_b64 s[0:1], vcc
	v_lshrrev_b32_e32 v97, 6, v97
	v_mul_lo_u32 v97, v97, s54
	v_and_or_b32 v97, v98, 60, v97
	v_add_u32_e32 v100, 0x4400, v97
	v_mov_b32_e32 v101, v133
	s_or_b64 exec, exec, s[0:1]
	v_lshlrev_b64 v[100:101], 10, v[100:101]
	v_lshl_add_u64 v[100:101], s[8:9], 0, v[100:101]
	v_cvt_pk_bf16_f32 v97, v110, v110
	v_lshl_add_u64 v[100:101], v[132:133], 1, v[100:101]
	global_store_short v[100:101], v97, off
	v_cvt_pk_bf16_f32 v97, v109, v109
	global_store_short v[100:101], v97, off offset:64
	v_mul_f32_e32 v97, v76, v76
	v_fmac_f32_e32 v97, v92, v92
	s_nop 1
	v_add_f32_dpp v97, v97, v97 quad_perm:[1,0,3,2] row_mask:0xf bank_mask:0xf
	s_nop 1
	v_add_f32_dpp v97, v97, v97 quad_perm:[2,3,0,1] row_mask:0xf bank_mask:0xf
	s_nop 1
	v_add_f32_dpp v97, v97, v97 row_half_mirror row_mask:0xf bank_mask:0xf
	s_nop 1
	v_add_f32_dpp v97, v97, v97 row_mirror row_mask:0xf bank_mask:0xf
	ds_bpermute_b32 v100, v108, v97
	s_and_saveexec_b64 s[0:1], s[4:5]
	s_cbranch_execz .LBB0_745
	v_lshl_add_u64 v[98:99], v[98:99], 2, s[10:11]
	s_waitcnt lgkmcnt(0)
	v_add_f32_e32 v97, v97, v100
	global_atomic_add_f32 v[98:99], v97, off
; __device__ __forceinline__ bf16_t f2bf(float f) { return (bf16_t)(pk_bf16(f, f) & 0xffffu); }
; __device__ __forceinline__ float halfsum32(float s) {
;     s += __shfl_xor(s, 1); s += __shfl_xor(s, 2); s += __shfl_xor(s, 4); s += __shfl_xor(s, 8); s += __shfl_xor(s, 16); return s;
;     template <int MT> __device__ __forceinline__ void run(const Params& P, f32x16 (&acc)[MT][2], int rbase, int pn, int wc, int lane) const {
;     ...
;             bf16_t* CK = (bf16_t*)(ws + OFF_CKVA); float* SSQ = (float*)(ws + OFF_SSQK);
;             const int c0 = (pn - 4) * 128 + wc * 64 + n, c1 = c0 + 32; const float g0 = P.gkv[c0], g1 = P.gkv[c1];
; #pragma unroll
;             for (int mt = 0; mt < MT; ++mt)
; #pragma unroll
;                 for (int rg = 0; rg < 16; ++rg) { const int r = ROWOF(rb, mt, rg); const float v0 = acc[mt][0][rg], v1 = acc[mt][1][rg];
;                     float* o = (r < NPR) ? out + O_PCKV + (size_t)r * 512 : out + O_SCKV + (size_t)(r - NPR) * 512;
;                     o[c0] = v0 * g0; o[c1] = v1 * g1;
;                     const size_t kr = tok_keyrow(r);
;                     CK[kr * 512 + c0] = f2bf(v0 * g0); CK[kr * 512 + c1] = f2bf(v1 * g1);
;                     const float s = halfsum32(v0 * v0 + v1 * v1); if (n == 0) atomicAdd(SSQ + r, s); }
.LBB0_745:
	s_or_b64 exec, exec, s[0:1]
	v_or_b32_e32 v98, 25, v96
	v_ashrrev_i32_e32 v99, 31, v98
	v_add_u32_e32 v97, 0xffffc019, v96
	v_cmp_gt_i32_e64 s[0:1], s40, v98
	v_mov_b32_e32 v109, s13
	v_mov_b32_e32 v110, s15
	v_cndmask_b32_e64 v101, 0, v99, s[0:1]
	s_waitcnt lgkmcnt(0)
	v_cndmask_b32_e64 v100, v97, v98, s[0:1]
	v_cndmask_b32_e64 v111, v109, v110, s[0:1]
	v_mov_b32_e32 v109, s12
	v_mov_b32_e32 v110, s14
	v_cndmask_b32_e64 v110, v109, v110, s[0:1]
	v_lshlrev_b64 v[100:101], 11, v[100:101]
	v_lshl_add_u64 v[100:101], v[110:111], 0, v[100:101]
	v_mul_f32_e32 v110, v93, v103
	v_lshl_add_u64 v[100:101], v[132:133], 2, v[100:101]
	v_mul_f32_e32 v109, v77, v102
	v_cmp_lt_i32_e32 vcc, s41, v98
	global_store_dword v[100:101], v110, off
	global_store_dword v[100:101], v109, off offset:128
	v_mov_b64_e32 v[100:101], v[98:99]
	s_and_saveexec_b64 s[0:1], vcc
	v_lshrrev_b32_e32 v97, 6, v97
	v_mul_lo_u32 v97, v97, s54
	v_and_or_b32 v97, v98, 61, v97
	v_add_u32_e32 v100, 0x4400, v97
	v_mov_b32_e32 v101, v133
	s_or_b64 exec, exec, s[0:1]
	v_lshlrev_b64 v[100:101], 10, v[100:101]
	v_lshl_add_u64 v[100:101], s[8:9], 0, v[100:101]
	v_cvt_pk_bf16_f32 v97, v110, v110
	v_lshl_add_u64 v[100:101], v[132:133], 1, v[100:101]
	global_store_short v[100:101], v97, off
	v_cvt_pk_bf16_f32 v97, v109, v109
	global_store_short v[100:101], v97, off offset:64
	v_mul_f32_e32 v97, v77, v77
	v_fmac_f32_e32 v97, v93, v93
	s_nop 1
	v_add_f32_dpp v97, v97, v97 quad_perm:[1,0,3,2] row_mask:0xf bank_mask:0xf
	s_nop 1
	v_add_f32_dpp v97, v97, v97 quad_perm:[2,3,0,1] row_mask:0xf bank_mask:0xf
	s_nop 1
	v_add_f32_dpp v97, v97, v97 row_half_mirror row_mask:0xf bank_mask:0xf
	s_nop 1
	v_add_f32_dpp v97, v97, v97 row_mirror row_mask:0xf bank_mask:0xf
	ds_bpermute_b32 v100, v108, v97
	s_and_saveexec_b64 s[0:1], s[4:5]
	s_cbranch_execz .LBB0_749
	v_lshl_add_u64 v[98:99], v[98:99], 2, s[10:11]
	s_waitcnt lgkmcnt(0)
	v_add_f32_e32 v97, v97, v100
	global_atomic_add_f32 v[98:99], v97, off
.LBB0_749:
	s_or_b64 exec, exec, s[0:1]
	v_or_b32_e32 v98, 26, v96
	v_ashrrev_i32_e32 v99, 31, v98
	v_add_u32_e32 v97, 0xffffc01a, v96
	v_cmp_gt_i32_e64 s[0:1], s40, v98
	v_mov_b32_e32 v109, s13
	v_mov_b32_e32 v110, s15
	v_cndmask_b32_e64 v101, 0, v99, s[0:1]
	s_waitcnt lgkmcnt(0)
	v_cndmask_b32_e64 v100, v97, v98, s[0:1]
	v_cndmask_b32_e64 v111, v109, v110, s[0:1]
	v_mov_b32_e32 v109, s12
	v_mov_b32_e32 v110, s14
	v_cndmask_b32_e64 v110, v109, v110, s[0:1]
	v_lshlrev_b64 v[100:101], 11, v[100:101]
	v_lshl_add_u64 v[100:101], v[110:111], 0, v[100:101]
	v_mul_f32_e32 v110, v94, v103
	v_lshl_add_u64 v[100:101], v[132:133], 2, v[100:101]
	v_mul_f32_e32 v109, v78, v102
	v_cmp_lt_i32_e32 vcc, s41, v98
	global_store_dword v[100:101], v110, off
	global_store_dword v[100:101], v109, off offset:128
	v_mov_b64_e32 v[100:101], v[98:99]
	s_and_saveexec_b64 s[0:1], vcc
	v_lshrrev_b32_e32 v97, 6, v97
	v_mul_lo_u32 v97, v97, s54
	v_and_or_b32 v97, v98, 62, v97
	v_add_u32_e32 v100, 0x4400, v97
	v_mov_b32_e32 v101, v133
	s_or_b64 exec, exec, s[0:1]
	v_lshlrev_b64 v[100:101], 10, v[100:101]
	v_lshl_add_u64 v[100:101], s[8:9], 0, v[100:101]
	v_cvt_pk_bf16_f32 v97, v110, v110
	v_lshl_add_u64 v[100:101], v[132:133], 1, v[100:101]
	global_store_short v[100:101], v97, off
	v_cvt_pk_bf16_f32 v97, v109, v109
	global_store_short v[100:101], v97, off offset:64
	v_mul_f32_e32 v97, v78, v78
	v_fmac_f32_e32 v97, v94, v94
	s_nop 1
	v_add_f32_dpp v97, v97, v97 quad_perm:[1,0,3,2] row_mask:0xf bank_mask:0xf
	s_nop 1
	v_add_f32_dpp v97, v97, v97 quad_perm:[2,3,0,1] row_mask:0xf bank_mask:0xf
	s_nop 1
	v_add_f32_dpp v97, v97, v97 row_half_mirror row_mask:0xf bank_mask:0xf
	s_nop 1
	v_add_f32_dpp v97, v97, v97 row_mirror row_mask:0xf bank_mask:0xf
	ds_bpermute_b32 v100, v108, v97
	s_and_saveexec_b64 s[0:1], s[4:5]
	s_cbranch_execz .LBB0_753
	v_lshl_add_u64 v[98:99], v[98:99], 2, s[10:11]
	s_waitcnt lgkmcnt(0)
	v_add_f32_e32 v97, v97, v100
	global_atomic_add_f32 v[98:99], v97, off
.LBB0_753:
	s_or_b64 exec, exec, s[0:1]
	v_or_b32_e32 v98, 27, v96
	v_ashrrev_i32_e32 v99, 31, v98
	v_add_u32_e32 v97, 0xffffc01b, v96
	v_cmp_gt_i32_e64 s[0:1], s40, v98
	v_mov_b32_e32 v109, s13
	v_mov_b32_e32 v110, s15
	v_cndmask_b32_e64 v101, 0, v99, s[0:1]
	s_waitcnt lgkmcnt(0)
	v_cndmask_b32_e64 v100, v97, v98, s[0:1]
	v_cndmask_b32_e64 v111, v109, v110, s[0:1]
	v_mov_b32_e32 v109, s12
	v_mov_b32_e32 v110, s14
	v_cndmask_b32_e64 v110, v109, v110, s[0:1]
	v_lshlrev_b64 v[100:101], 11, v[100:101]
	v_lshl_add_u64 v[100:101], v[110:111], 0, v[100:101]
	v_mul_f32_e32 v110, v95, v103
	v_lshl_add_u64 v[100:101], v[132:133], 2, v[100:101]
	v_mul_f32_e32 v109, v79, v102
	v_cmp_lt_i32_e32 vcc, s41, v98
	global_store_dword v[100:101], v110, off
	global_store_dword v[100:101], v109, off offset:128
	v_mov_b64_e32 v[100:101], v[98:99]
	s_and_saveexec_b64 s[0:1], vcc
	v_lshrrev_b32_e32 v97, 6, v97
	v_mul_lo_u32 v97, v97, s54
	v_and_or_b32 v97, v98, 63, v97
	v_add_u32_e32 v100, 0x4400, v97
	v_mov_b32_e32 v101, v133
	s_or_b64 exec, exec, s[0:1]
	v_lshlrev_b64 v[100:101], 10, v[100:101]
	v_lshl_add_u64 v[100:101], s[8:9], 0, v[100:101]
	v_cvt_pk_bf16_f32 v97, v110, v110
	v_lshl_add_u64 v[100:101], v[132:133], 1, v[100:101]
	global_store_short v[100:101], v97, off
	v_cvt_pk_bf16_f32 v97, v109, v109
	global_store_short v[100:101], v97, off offset:64
	v_mul_f32_e32 v97, v79, v79
	v_fmac_f32_e32 v97, v95, v95
	s_nop 1
	v_add_f32_dpp v97, v97, v97 quad_perm:[1,0,3,2] row_mask:0xf bank_mask:0xf
	s_nop 1
	v_add_f32_dpp v97, v97, v97 quad_perm:[2,3,0,1] row_mask:0xf bank_mask:0xf
	s_nop 1
	v_add_f32_dpp v97, v97, v97 row_half_mirror row_mask:0xf bank_mask:0xf
	s_nop 1
	v_add_f32_dpp v97, v97, v97 row_mirror row_mask:0xf bank_mask:0xf
	ds_bpermute_b32 v100, v108, v97
	s_and_saveexec_b64 s[0:1], s[4:5]
	s_cbranch_execz .LBB0_757
	v_lshl_add_u64 v[98:99], v[98:99], 2, s[10:11]
	s_waitcnt lgkmcnt(0)
	v_add_f32_e32 v97, v97, v100
	global_atomic_add_f32 v[98:99], v97, off
; __device__ __forceinline__ bf16_t f2bf(float f) { return (bf16_t)(pk_bf16(f, f) & 0xffffu); }
; __device__ __forceinline__ float halfsum32(float s) {
;     s += __shfl_xor(s, 1); s += __shfl_xor(s, 2); s += __shfl_xor(s, 4); s += __shfl_xor(s, 8); s += __shfl_xor(s, 16); return s;
;     template <int MT> __device__ __forceinline__ void run(const Params& P, f32x16 (&acc)[MT][2], int rbase, int pn, int wc, int lane) const {
;     ...
;             bf16_t* CK = (bf16_t*)(ws + OFF_CKVA); float* SSQ = (float*)(ws + OFF_SSQK);
;             const int c0 = (pn - 4) * 128 + wc * 64 + n, c1 = c0 + 32; const float g0 = P.gkv[c0], g1 = P.gkv[c1];
; #pragma unroll
;             for (int mt = 0; mt < MT; ++mt)
; #pragma unroll
;                 for (int rg = 0; rg < 16; ++rg) { const int r = ROWOF(rb, mt, rg); const float v0 = acc[mt][0][rg], v1 = acc[mt][1][rg];
;                     float* o = (r < NPR) ? out + O_PCKV + (size_t)r * 512 : out + O_SCKV + (size_t)(r - NPR) * 512;
;                     o[c0] = v0 * g0; o[c1] = v1 * g1;
;                     const size_t kr = tok_keyrow(r);
;                     CK[kr * 512 + c0] = f2bf(v0 * g0); CK[kr * 512 + c1] = f2bf(v1 * g1);
;                     const float s = halfsum32(v0 * v0 + v1 * v1); if (n == 0) atomicAdd(SSQ + r, s); }
.LBB0_757:
	s_or_b64 exec, exec, s[0:1]
	s_movk_i32 s0, 0x3fdf
	v_add_u32_e32 v98, 32, v96
	v_cmp_lt_i32_e32 vcc, s0, v96
	s_movk_i32 s0, 0x3fe0
	v_ashrrev_i32_e32 v99, 31, v98
	v_add_u32_e32 v97, 0xffffc020, v96
	v_cmp_gt_i32_e64 s[0:1], s0, v96
	v_mov_b32_e32 v109, s13
	v_mov_b32_e32 v110, s15
	v_cndmask_b32_e64 v101, 0, v99, s[0:1]
	s_waitcnt lgkmcnt(0)
	v_cndmask_b32_e64 v100, v97, v98, s[0:1]
	v_cndmask_b32_e64 v111, v109, v110, s[0:1]
	v_mov_b32_e32 v109, s12
	v_mov_b32_e32 v110, s14
	v_cndmask_b32_e64 v110, v109, v110, s[0:1]
	v_lshlrev_b64 v[100:101], 11, v[100:101]
	v_lshl_add_u64 v[100:101], v[110:111], 0, v[100:101]
	v_mul_f32_e32 v110, v48, v103
	v_lshl_add_u64 v[100:101], v[132:133], 2, v[100:101]
	v_mul_f32_e32 v109, v32, v102
	global_store_dword v[100:101], v110, off
	global_store_dword v[100:101], v109, off offset:128
	v_mov_b64_e32 v[100:101], v[98:99]
	s_and_saveexec_b64 s[0:1], vcc
	v_lshrrev_b32_e32 v97, 6, v97
	v_mul_lo_u32 v97, v97, s54
	v_and_or_b32 v97, v98, 36, v97
	v_add_u32_e32 v100, 0x4400, v97
	v_mov_b32_e32 v101, v133
	s_or_b64 exec, exec, s[0:1]
	v_lshlrev_b64 v[100:101], 10, v[100:101]
	v_lshl_add_u64 v[100:101], s[8:9], 0, v[100:101]
	v_cvt_pk_bf16_f32 v97, v110, v110
	v_lshl_add_u64 v[100:101], v[132:133], 1, v[100:101]
	global_store_short v[100:101], v97, off
	v_cvt_pk_bf16_f32 v97, v109, v109
	global_store_short v[100:101], v97, off offset:64
	v_mul_f32_e32 v97, v32, v32
	v_fmac_f32_e32 v97, v48, v48
	s_nop 1
	v_add_f32_dpp v97, v97, v97 quad_perm:[1,0,3,2] row_mask:0xf bank_mask:0xf
	s_nop 1
	v_add_f32_dpp v97, v97, v97 quad_perm:[2,3,0,1] row_mask:0xf bank_mask:0xf
	s_nop 1
	v_add_f32_dpp v97, v97, v97 row_half_mirror row_mask:0xf bank_mask:0xf
	s_nop 1
	v_add_f32_dpp v97, v97, v97 row_mirror row_mask:0xf bank_mask:0xf
	ds_bpermute_b32 v100, v108, v97
	s_and_saveexec_b64 s[0:1], s[4:5]
	s_cbranch_execz .LBB0_761
	v_lshl_add_u64 v[98:99], v[98:99], 2, s[10:11]
	s_waitcnt lgkmcnt(0)
	v_add_f32_e32 v97, v97, v100
	global_atomic_add_f32 v[98:99], v97, off
.LBB0_761:
	s_or_b64 exec, exec, s[0:1]
	v_add_u32_e32 v98, 33, v96
	v_ashrrev_i32_e32 v99, 31, v98
	v_add_u32_e32 v97, 0xffffc021, v96
	v_cmp_gt_i32_e64 s[0:1], s40, v98
	v_mov_b32_e32 v109, s13
	v_mov_b32_e32 v110, s15
	v_cndmask_b32_e64 v101, 0, v99, s[0:1]
	s_waitcnt lgkmcnt(0)
	v_cndmask_b32_e64 v100, v97, v98, s[0:1]
	v_cndmask_b32_e64 v111, v109, v110, s[0:1]
	v_mov_b32_e32 v109, s12
	v_mov_b32_e32 v110, s14
	v_cndmask_b32_e64 v110, v109, v110, s[0:1]
	v_lshlrev_b64 v[100:101], 11, v[100:101]
	v_lshl_add_u64 v[100:101], v[110:111], 0, v[100:101]
	v_mul_f32_e32 v110, v49, v103
	v_lshl_add_u64 v[100:101], v[132:133], 2, v[100:101]
	v_mul_f32_e32 v109, v33, v102
	v_cmp_lt_i32_e32 vcc, s41, v98
	global_store_dword v[100:101], v110, off
	global_store_dword v[100:101], v109, off offset:128
	v_mov_b64_e32 v[100:101], v[98:99]
	s_and_saveexec_b64 s[0:1], vcc
	v_lshrrev_b32_e32 v97, 6, v97
	v_mul_lo_u32 v97, v97, s54
	v_and_or_b32 v97, v98, 37, v97
	v_add_u32_e32 v100, 0x4400, v97
	v_mov_b32_e32 v101, v133
	s_or_b64 exec, exec, s[0:1]
	v_lshlrev_b64 v[100:101], 10, v[100:101]
	v_lshl_add_u64 v[100:101], s[8:9], 0, v[100:101]
	v_cvt_pk_bf16_f32 v97, v110, v110
	v_lshl_add_u64 v[100:101], v[132:133], 1, v[100:101]
	global_store_short v[100:101], v97, off
	v_cvt_pk_bf16_f32 v97, v109, v109
	global_store_short v[100:101], v97, off offset:64
	v_mul_f32_e32 v97, v33, v33
	v_fmac_f32_e32 v97, v49, v49
	s_nop 1
	v_add_f32_dpp v97, v97, v97 quad_perm:[1,0,3,2] row_mask:0xf bank_mask:0xf
	s_nop 1
	v_add_f32_dpp v97, v97, v97 quad_perm:[2,3,0,1] row_mask:0xf bank_mask:0xf
	s_nop 1
	v_add_f32_dpp v97, v97, v97 row_half_mirror row_mask:0xf bank_mask:0xf
	s_nop 1
	v_add_f32_dpp v97, v97, v97 row_mirror row_mask:0xf bank_mask:0xf
	ds_bpermute_b32 v100, v108, v97
	s_and_saveexec_b64 s[0:1], s[4:5]
	s_cbranch_execz .LBB0_765
	v_lshl_add_u64 v[98:99], v[98:99], 2, s[10:11]
	s_waitcnt lgkmcnt(0)
	v_add_f32_e32 v97, v97, v100
	global_atomic_add_f32 v[98:99], v97, off
.LBB0_765:
	s_or_b64 exec, exec, s[0:1]
	v_add_u32_e32 v98, 34, v96
	v_ashrrev_i32_e32 v99, 31, v98
	v_add_u32_e32 v97, 0xffffc022, v96
	v_cmp_gt_i32_e64 s[0:1], s40, v98
	v_mov_b32_e32 v109, s13
	v_mov_b32_e32 v110, s15
	v_cndmask_b32_e64 v101, 0, v99, s[0:1]
	s_waitcnt lgkmcnt(0)
	v_cndmask_b32_e64 v100, v97, v98, s[0:1]
	v_cndmask_b32_e64 v111, v109, v110, s[0:1]
	v_mov_b32_e32 v109, s12
	v_mov_b32_e32 v110, s14
	v_cndmask_b32_e64 v110, v109, v110, s[0:1]
	v_lshlrev_b64 v[100:101], 11, v[100:101]
	v_lshl_add_u64 v[100:101], v[110:111], 0, v[100:101]
	v_mul_f32_e32 v110, v50, v103
	v_lshl_add_u64 v[100:101], v[132:133], 2, v[100:101]
	v_mul_f32_e32 v109, v34, v102
	v_cmp_lt_i32_e32 vcc, s41, v98
	global_store_dword v[100:101], v110, off
	global_store_dword v[100:101], v109, off offset:128
	v_mov_b64_e32 v[100:101], v[98:99]
	s_and_saveexec_b64 s[0:1], vcc
	v_lshrrev_b32_e32 v97, 6, v97
	v_mul_lo_u32 v97, v97, s54
	v_and_or_b32 v97, v98, 38, v97
	v_add_u32_e32 v100, 0x4400, v97
	v_mov_b32_e32 v101, v133
	s_or_b64 exec, exec, s[0:1]
	v_lshlrev_b64 v[100:101], 10, v[100:101]
	v_lshl_add_u64 v[100:101], s[8:9], 0, v[100:101]
	v_cvt_pk_bf16_f32 v97, v110, v110
	v_lshl_add_u64 v[100:101], v[132:133], 1, v[100:101]
	global_store_short v[100:101], v97, off
	v_cvt_pk_bf16_f32 v97, v109, v109
	global_store_short v[100:101], v97, off offset:64
	v_mul_f32_e32 v97, v34, v34
	v_fmac_f32_e32 v97, v50, v50
	s_nop 1
	v_add_f32_dpp v97, v97, v97 quad_perm:[1,0,3,2] row_mask:0xf bank_mask:0xf
	s_nop 1
	v_add_f32_dpp v97, v97, v97 quad_perm:[2,3,0,1] row_mask:0xf bank_mask:0xf
	s_nop 1
	v_add_f32_dpp v97, v97, v97 row_half_mirror row_mask:0xf bank_mask:0xf
	s_nop 1
	v_add_f32_dpp v97, v97, v97 row_mirror row_mask:0xf bank_mask:0xf
	ds_bpermute_b32 v100, v108, v97
	s_and_saveexec_b64 s[0:1], s[4:5]
	s_cbranch_execz .LBB0_769
	v_lshl_add_u64 v[98:99], v[98:99], 2, s[10:11]
	s_waitcnt lgkmcnt(0)
	v_add_f32_e32 v97, v97, v100
	global_atomic_add_f32 v[98:99], v97, off
; __device__ __forceinline__ bf16_t f2bf(float f) { return (bf16_t)(pk_bf16(f, f) & 0xffffu); }
; __device__ __forceinline__ float halfsum32(float s) {
;     s += __shfl_xor(s, 1); s += __shfl_xor(s, 2); s += __shfl_xor(s, 4); s += __shfl_xor(s, 8); s += __shfl_xor(s, 16); return s;
;     template <int MT> __device__ __forceinline__ void run(const Params& P, f32x16 (&acc)[MT][2], int rbase, int pn, int wc, int lane) const {
;     ...
;             bf16_t* CK = (bf16_t*)(ws + OFF_CKVA); float* SSQ = (float*)(ws + OFF_SSQK);
;             const int c0 = (pn - 4) * 128 + wc * 64 + n, c1 = c0 + 32; const float g0 = P.gkv[c0], g1 = P.gkv[c1];
; #pragma unroll
;             for (int mt = 0; mt < MT; ++mt)
; #pragma unroll
;                 for (int rg = 0; rg < 16; ++rg) { const int r = ROWOF(rb, mt, rg); const float v0 = acc[mt][0][rg], v1 = acc[mt][1][rg];
;                     float* o = (r < NPR) ? out + O_PCKV + (size_t)r * 512 : out + O_SCKV + (size_t)(r - NPR) * 512;
;                     o[c0] = v0 * g0; o[c1] = v1 * g1;
;                     const size_t kr = tok_keyrow(r);
;                     CK[kr * 512 + c0] = f2bf(v0 * g0); CK[kr * 512 + c1] = f2bf(v1 * g1);
;                     const float s = halfsum32(v0 * v0 + v1 * v1); if (n == 0) atomicAdd(SSQ + r, s); }
.LBB0_769:
	s_or_b64 exec, exec, s[0:1]
	v_add_u32_e32 v98, 35, v96
	v_ashrrev_i32_e32 v99, 31, v98
	v_add_u32_e32 v97, 0xffffc023, v96
	v_cmp_gt_i32_e64 s[0:1], s40, v98
	v_mov_b32_e32 v109, s13
	v_mov_b32_e32 v110, s15
	v_cndmask_b32_e64 v101, 0, v99, s[0:1]
	s_waitcnt lgkmcnt(0)
	v_cndmask_b32_e64 v100, v97, v98, s[0:1]
	v_cndmask_b32_e64 v111, v109, v110, s[0:1]
	v_mov_b32_e32 v109, s12
	v_mov_b32_e32 v110, s14
	v_cndmask_b32_e64 v110, v109, v110, s[0:1]
	v_lshlrev_b64 v[100:101], 11, v[100:101]
	v_lshl_add_u64 v[100:101], v[110:111], 0, v[100:101]
	v_mul_f32_e32 v110, v51, v103
	v_lshl_add_u64 v[100:101], v[132:133], 2, v[100:101]
	v_mul_f32_e32 v109, v35, v102
	v_cmp_lt_i32_e32 vcc, s41, v98
	global_store_dword v[100:101], v110, off
	global_store_dword v[100:101], v109, off offset:128
	v_mov_b64_e32 v[100:101], v[98:99]
	s_and_saveexec_b64 s[0:1], vcc
	v_lshrrev_b32_e32 v97, 6, v97
	v_mul_lo_u32 v97, v97, s54
	v_and_or_b32 v97, v98, 39, v97
	v_add_u32_e32 v100, 0x4400, v97
	v_mov_b32_e32 v101, v133
	s_or_b64 exec, exec, s[0:1]
	v_lshlrev_b64 v[100:101], 10, v[100:101]
	v_lshl_add_u64 v[100:101], s[8:9], 0, v[100:101]
	v_cvt_pk_bf16_f32 v97, v110, v110
	v_lshl_add_u64 v[100:101], v[132:133], 1, v[100:101]
	global_store_short v[100:101], v97, off
	v_cvt_pk_bf16_f32 v97, v109, v109
	global_store_short v[100:101], v97, off offset:64
	v_mul_f32_e32 v97, v35, v35
	v_fmac_f32_e32 v97, v51, v51
	s_nop 1
	v_add_f32_dpp v97, v97, v97 quad_perm:[1,0,3,2] row_mask:0xf bank_mask:0xf
	s_nop 1
	v_add_f32_dpp v97, v97, v97 quad_perm:[2,3,0,1] row_mask:0xf bank_mask:0xf
	s_nop 1
	v_add_f32_dpp v97, v97, v97 row_half_mirror row_mask:0xf bank_mask:0xf
	s_nop 1
	v_add_f32_dpp v97, v97, v97 row_mirror row_mask:0xf bank_mask:0xf
	ds_bpermute_b32 v100, v108, v97
	s_and_saveexec_b64 s[0:1], s[4:5]
	s_cbranch_execz .LBB0_773
	v_lshl_add_u64 v[98:99], v[98:99], 2, s[10:11]
	s_waitcnt lgkmcnt(0)
	v_add_f32_e32 v97, v97, v100
	global_atomic_add_f32 v[98:99], v97, off
.LBB0_773:
	s_or_b64 exec, exec, s[0:1]
	v_add_u32_e32 v98, 40, v96
	v_ashrrev_i32_e32 v99, 31, v98
	v_add_u32_e32 v97, 0xffffc028, v96
	v_cmp_gt_i32_e64 s[0:1], s40, v98
	v_mov_b32_e32 v109, s13
	v_mov_b32_e32 v110, s15
	v_cndmask_b32_e64 v101, 0, v99, s[0:1]
	s_waitcnt lgkmcnt(0)
	v_cndmask_b32_e64 v100, v97, v98, s[0:1]
	v_cndmask_b32_e64 v111, v109, v110, s[0:1]
	v_mov_b32_e32 v109, s12
	v_mov_b32_e32 v110, s14
	v_cndmask_b32_e64 v110, v109, v110, s[0:1]
	v_lshlrev_b64 v[100:101], 11, v[100:101]
	v_lshl_add_u64 v[100:101], v[110:111], 0, v[100:101]
	v_mul_f32_e32 v110, v52, v103
	v_lshl_add_u64 v[100:101], v[132:133], 2, v[100:101]
	v_mul_f32_e32 v109, v36, v102
	v_cmp_lt_i32_e32 vcc, s41, v98
	global_store_dword v[100:101], v110, off
	global_store_dword v[100:101], v109, off offset:128
	v_mov_b64_e32 v[100:101], v[98:99]
	s_and_saveexec_b64 s[0:1], vcc
	v_lshrrev_b32_e32 v97, 6, v97
	v_mul_lo_u32 v97, v97, s54
	v_and_or_b32 v97, v98, 44, v97
	v_add_u32_e32 v100, 0x4400, v97
	v_mov_b32_e32 v101, v133
	s_or_b64 exec, exec, s[0:1]
	v_lshlrev_b64 v[100:101], 10, v[100:101]
	v_lshl_add_u64 v[100:101], s[8:9], 0, v[100:101]
	v_cvt_pk_bf16_f32 v97, v110, v110
	v_lshl_add_u64 v[100:101], v[132:133], 1, v[100:101]
	global_store_short v[100:101], v97, off
	v_cvt_pk_bf16_f32 v97, v109, v109
	global_store_short v[100:101], v97, off offset:64
	v_mul_f32_e32 v97, v36, v36
	v_fmac_f32_e32 v97, v52, v52
	s_nop 1
	v_add_f32_dpp v97, v97, v97 quad_perm:[1,0,3,2] row_mask:0xf bank_mask:0xf
	s_nop 1
	v_add_f32_dpp v97, v97, v97 quad_perm:[2,3,0,1] row_mask:0xf bank_mask:0xf
	s_nop 1
	v_add_f32_dpp v97, v97, v97 row_half_mirror row_mask:0xf bank_mask:0xf
	s_nop 1
	v_add_f32_dpp v97, v97, v97 row_mirror row_mask:0xf bank_mask:0xf
	ds_bpermute_b32 v100, v108, v97
	s_and_saveexec_b64 s[0:1], s[4:5]
	s_cbranch_execz .LBB0_777
	v_lshl_add_u64 v[98:99], v[98:99], 2, s[10:11]
	s_waitcnt lgkmcnt(0)
	v_add_f32_e32 v97, v97, v100
	global_atomic_add_f32 v[98:99], v97, off
.LBB0_777:
	s_or_b64 exec, exec, s[0:1]
	v_add_u32_e32 v98, 41, v96
	v_ashrrev_i32_e32 v99, 31, v98
	v_add_u32_e32 v97, 0xffffc029, v96
	v_cmp_gt_i32_e64 s[0:1], s40, v98
	v_mov_b32_e32 v109, s13
	v_mov_b32_e32 v110, s15
	v_cndmask_b32_e64 v101, 0, v99, s[0:1]
	s_waitcnt lgkmcnt(0)
	v_cndmask_b32_e64 v100, v97, v98, s[0:1]
	v_cndmask_b32_e64 v111, v109, v110, s[0:1]
	v_mov_b32_e32 v109, s12
	v_mov_b32_e32 v110, s14
	v_cndmask_b32_e64 v110, v109, v110, s[0:1]
	v_lshlrev_b64 v[100:101], 11, v[100:101]
	v_lshl_add_u64 v[100:101], v[110:111], 0, v[100:101]
	v_mul_f32_e32 v110, v53, v103
	v_lshl_add_u64 v[100:101], v[132:133], 2, v[100:101]
	v_mul_f32_e32 v109, v37, v102
	v_cmp_lt_i32_e32 vcc, s41, v98
	global_store_dword v[100:101], v110, off
	global_store_dword v[100:101], v109, off offset:128
	v_mov_b64_e32 v[100:101], v[98:99]
	s_and_saveexec_b64 s[0:1], vcc
	v_lshrrev_b32_e32 v97, 6, v97
	v_mul_lo_u32 v97, v97, s54
	v_and_or_b32 v97, v98, 45, v97
	v_add_u32_e32 v100, 0x4400, v97
	v_mov_b32_e32 v101, v133
	s_or_b64 exec, exec, s[0:1]
	v_lshlrev_b64 v[100:101], 10, v[100:101]
	v_lshl_add_u64 v[100:101], s[8:9], 0, v[100:101]
	v_cvt_pk_bf16_f32 v97, v110, v110
	v_lshl_add_u64 v[100:101], v[132:133], 1, v[100:101]
	global_store_short v[100:101], v97, off
	v_cvt_pk_bf16_f32 v97, v109, v109
	global_store_short v[100:101], v97, off offset:64
	v_mul_f32_e32 v97, v37, v37
	v_fmac_f32_e32 v97, v53, v53
	s_nop 1
	v_add_f32_dpp v97, v97, v97 quad_perm:[1,0,3,2] row_mask:0xf bank_mask:0xf
	s_nop 1
	v_add_f32_dpp v97, v97, v97 quad_perm:[2,3,0,1] row_mask:0xf bank_mask:0xf
	s_nop 1
	v_add_f32_dpp v97, v97, v97 row_half_mirror row_mask:0xf bank_mask:0xf
	s_nop 1
	v_add_f32_dpp v97, v97, v97 row_mirror row_mask:0xf bank_mask:0xf
	ds_bpermute_b32 v100, v108, v97
	s_and_saveexec_b64 s[0:1], s[4:5]
	s_cbranch_execz .LBB0_781
	v_lshl_add_u64 v[98:99], v[98:99], 2, s[10:11]
	s_waitcnt lgkmcnt(0)
	v_add_f32_e32 v97, v97, v100
	global_atomic_add_f32 v[98:99], v97, off
; __device__ __forceinline__ bf16_t f2bf(float f) { return (bf16_t)(pk_bf16(f, f) & 0xffffu); }
; __device__ __forceinline__ float halfsum32(float s) {
;     s += __shfl_xor(s, 1); s += __shfl_xor(s, 2); s += __shfl_xor(s, 4); s += __shfl_xor(s, 8); s += __shfl_xor(s, 16); return s;
;     template <int MT> __device__ __forceinline__ void run(const Params& P, f32x16 (&acc)[MT][2], int rbase, int pn, int wc, int lane) const {
;     ...
;             bf16_t* CK = (bf16_t*)(ws + OFF_CKVA); float* SSQ = (float*)(ws + OFF_SSQK);
;             const int c0 = (pn - 4) * 128 + wc * 64 + n, c1 = c0 + 32; const float g0 = P.gkv[c0], g1 = P.gkv[c1];
; #pragma unroll
;             for (int mt = 0; mt < MT; ++mt)
; #pragma unroll
;                 for (int rg = 0; rg < 16; ++rg) { const int r = ROWOF(rb, mt, rg); const float v0 = acc[mt][0][rg], v1 = acc[mt][1][rg];
;                     float* o = (r < NPR) ? out + O_PCKV + (size_t)r * 512 : out + O_SCKV + (size_t)(r - NPR) * 512;
;                     o[c0] = v0 * g0; o[c1] = v1 * g1;
;                     const size_t kr = tok_keyrow(r);
;                     CK[kr * 512 + c0] = f2bf(v0 * g0); CK[kr * 512 + c1] = f2bf(v1 * g1);
;                     const float s = halfsum32(v0 * v0 + v1 * v1); if (n == 0) atomicAdd(SSQ + r, s); }
.LBB0_781:
	s_or_b64 exec, exec, s[0:1]
	v_add_u32_e32 v98, 42, v96
	v_ashrrev_i32_e32 v99, 31, v98
	v_add_u32_e32 v97, 0xffffc02a, v96
	v_cmp_gt_i32_e64 s[0:1], s40, v98
	v_mov_b32_e32 v109, s13
	v_mov_b32_e32 v110, s15
	v_cndmask_b32_e64 v101, 0, v99, s[0:1]
	s_waitcnt lgkmcnt(0)
	v_cndmask_b32_e64 v100, v97, v98, s[0:1]
	v_cndmask_b32_e64 v111, v109, v110, s[0:1]
	v_mov_b32_e32 v109, s12
	v_mov_b32_e32 v110, s14
	v_cndmask_b32_e64 v110, v109, v110, s[0:1]
	v_lshlrev_b64 v[100:101], 11, v[100:101]
	v_lshl_add_u64 v[100:101], v[110:111], 0, v[100:101]
	v_mul_f32_e32 v110, v54, v103
	v_lshl_add_u64 v[100:101], v[132:133], 2, v[100:101]
	v_mul_f32_e32 v109, v38, v102
	v_cmp_lt_i32_e32 vcc, s41, v98
	global_store_dword v[100:101], v110, off
	global_store_dword v[100:101], v109, off offset:128
	v_mov_b64_e32 v[100:101], v[98:99]
	s_and_saveexec_b64 s[0:1], vcc
	v_lshrrev_b32_e32 v97, 6, v97
	v_mul_lo_u32 v97, v97, s54
	v_and_or_b32 v97, v98, 46, v97
	v_add_u32_e32 v100, 0x4400, v97
	v_mov_b32_e32 v101, v133
	s_or_b64 exec, exec, s[0:1]
	v_lshlrev_b64 v[100:101], 10, v[100:101]
	v_lshl_add_u64 v[100:101], s[8:9], 0, v[100:101]
	v_cvt_pk_bf16_f32 v97, v110, v110
	v_lshl_add_u64 v[100:101], v[132:133], 1, v[100:101]
	global_store_short v[100:101], v97, off
	v_cvt_pk_bf16_f32 v97, v109, v109
	global_store_short v[100:101], v97, off offset:64
	v_mul_f32_e32 v97, v38, v38
	v_fmac_f32_e32 v97, v54, v54
	s_nop 1
	v_add_f32_dpp v97, v97, v97 quad_perm:[1,0,3,2] row_mask:0xf bank_mask:0xf
	s_nop 1
	v_add_f32_dpp v97, v97, v97 quad_perm:[2,3,0,1] row_mask:0xf bank_mask:0xf
	s_nop 1
	v_add_f32_dpp v97, v97, v97 row_half_mirror row_mask:0xf bank_mask:0xf
	s_nop 1
	v_add_f32_dpp v97, v97, v97 row_mirror row_mask:0xf bank_mask:0xf
	ds_bpermute_b32 v100, v108, v97
	s_and_saveexec_b64 s[0:1], s[4:5]
	s_cbranch_execz .LBB0_785
	v_lshl_add_u64 v[98:99], v[98:99], 2, s[10:11]
	s_waitcnt lgkmcnt(0)
	v_add_f32_e32 v97, v97, v100
	global_atomic_add_f32 v[98:99], v97, off
.LBB0_785:
	s_or_b64 exec, exec, s[0:1]
	v_add_u32_e32 v98, 43, v96
	v_ashrrev_i32_e32 v99, 31, v98
	v_add_u32_e32 v97, 0xffffc02b, v96
	v_cmp_gt_i32_e64 s[0:1], s40, v98
	v_mov_b32_e32 v109, s13
	v_mov_b32_e32 v110, s15
	v_cndmask_b32_e64 v101, 0, v99, s[0:1]
	s_waitcnt lgkmcnt(0)
	v_cndmask_b32_e64 v100, v97, v98, s[0:1]
	v_cndmask_b32_e64 v111, v109, v110, s[0:1]
	v_mov_b32_e32 v109, s12
	v_mov_b32_e32 v110, s14
	v_cndmask_b32_e64 v110, v109, v110, s[0:1]
	v_lshlrev_b64 v[100:101], 11, v[100:101]
	v_lshl_add_u64 v[100:101], v[110:111], 0, v[100:101]
	v_mul_f32_e32 v110, v55, v103
	v_lshl_add_u64 v[100:101], v[132:133], 2, v[100:101]
	v_mul_f32_e32 v109, v39, v102
	v_cmp_lt_i32_e32 vcc, s41, v98
	global_store_dword v[100:101], v110, off
	global_store_dword v[100:101], v109, off offset:128
	v_mov_b64_e32 v[100:101], v[98:99]
	s_and_saveexec_b64 s[0:1], vcc
	v_lshrrev_b32_e32 v97, 6, v97
	v_mul_lo_u32 v97, v97, s54
	v_and_or_b32 v97, v98, 47, v97
	v_add_u32_e32 v100, 0x4400, v97
	v_mov_b32_e32 v101, v133
	s_or_b64 exec, exec, s[0:1]
	v_lshlrev_b64 v[100:101], 10, v[100:101]
	v_lshl_add_u64 v[100:101], s[8:9], 0, v[100:101]
	v_cvt_pk_bf16_f32 v97, v110, v110
	v_lshl_add_u64 v[100:101], v[132:133], 1, v[100:101]
	global_store_short v[100:101], v97, off
	v_cvt_pk_bf16_f32 v97, v109, v109
	global_store_short v[100:101], v97, off offset:64
	v_mul_f32_e32 v97, v39, v39
	v_fmac_f32_e32 v97, v55, v55
	s_nop 1
	v_add_f32_dpp v97, v97, v97 quad_perm:[1,0,3,2] row_mask:0xf bank_mask:0xf
	s_nop 1
	v_add_f32_dpp v97, v97, v97 quad_perm:[2,3,0,1] row_mask:0xf bank_mask:0xf
	s_nop 1
	v_add_f32_dpp v97, v97, v97 row_half_mirror row_mask:0xf bank_mask:0xf
	s_nop 1
	v_add_f32_dpp v97, v97, v97 row_mirror row_mask:0xf bank_mask:0xf
	ds_bpermute_b32 v100, v108, v97
	s_and_saveexec_b64 s[0:1], s[4:5]
	s_cbranch_execz .LBB0_789
	v_lshl_add_u64 v[98:99], v[98:99], 2, s[10:11]
	s_waitcnt lgkmcnt(0)
	v_add_f32_e32 v97, v97, v100
	global_atomic_add_f32 v[98:99], v97, off
.LBB0_789:
	s_or_b64 exec, exec, s[0:1]
	v_add_u32_e32 v98, 48, v96
	v_ashrrev_i32_e32 v99, 31, v98
	v_add_u32_e32 v97, 0xffffc030, v96
	v_cmp_gt_i32_e64 s[0:1], s40, v98
	v_mov_b32_e32 v109, s13
	v_mov_b32_e32 v110, s15
	v_cndmask_b32_e64 v101, 0, v99, s[0:1]
	s_waitcnt lgkmcnt(0)
	v_cndmask_b32_e64 v100, v97, v98, s[0:1]
	v_cndmask_b32_e64 v111, v109, v110, s[0:1]
	v_mov_b32_e32 v109, s12
	v_mov_b32_e32 v110, s14
	v_cndmask_b32_e64 v110, v109, v110, s[0:1]
	v_lshlrev_b64 v[100:101], 11, v[100:101]
	v_lshl_add_u64 v[100:101], v[110:111], 0, v[100:101]
	v_mul_f32_e32 v110, v56, v103
	v_lshl_add_u64 v[100:101], v[132:133], 2, v[100:101]
	v_mul_f32_e32 v109, v40, v102
	v_cmp_lt_i32_e32 vcc, s41, v98
	global_store_dword v[100:101], v110, off
	global_store_dword v[100:101], v109, off offset:128
	v_mov_b64_e32 v[100:101], v[98:99]
	s_and_saveexec_b64 s[0:1], vcc
	v_lshrrev_b32_e32 v97, 6, v97
	v_mul_lo_u32 v97, v97, s54
	v_and_or_b32 v97, v98, 52, v97
	v_add_u32_e32 v100, 0x4400, v97
	v_mov_b32_e32 v101, v133
	s_or_b64 exec, exec, s[0:1]
	v_lshlrev_b64 v[100:101], 10, v[100:101]
	v_lshl_add_u64 v[100:101], s[8:9], 0, v[100:101]
	v_cvt_pk_bf16_f32 v97, v110, v110
	v_lshl_add_u64 v[100:101], v[132:133], 1, v[100:101]
	global_store_short v[100:101], v97, off
	v_cvt_pk_bf16_f32 v97, v109, v109
	global_store_short v[100:101], v97, off offset:64
	v_mul_f32_e32 v97, v40, v40
	v_fmac_f32_e32 v97, v56, v56
	s_nop 1
	v_add_f32_dpp v97, v97, v97 quad_perm:[1,0,3,2] row_mask:0xf bank_mask:0xf
	s_nop 1
	v_add_f32_dpp v97, v97, v97 quad_perm:[2,3,0,1] row_mask:0xf bank_mask:0xf
	s_nop 1
	v_add_f32_dpp v97, v97, v97 row_half_mirror row_mask:0xf bank_mask:0xf
	s_nop 1
	v_add_f32_dpp v97, v97, v97 row_mirror row_mask:0xf bank_mask:0xf
	ds_bpermute_b32 v100, v108, v97
	s_and_saveexec_b64 s[0:1], s[4:5]
	s_cbranch_execz .LBB0_793
	v_lshl_add_u64 v[98:99], v[98:99], 2, s[10:11]
	s_waitcnt lgkmcnt(0)
	v_add_f32_e32 v97, v97, v100
	global_atomic_add_f32 v[98:99], v97, off
; __device__ __forceinline__ bf16_t f2bf(float f) { return (bf16_t)(pk_bf16(f, f) & 0xffffu); }
; __device__ __forceinline__ float halfsum32(float s) {
;     s += __shfl_xor(s, 1); s += __shfl_xor(s, 2); s += __shfl_xor(s, 4); s += __shfl_xor(s, 8); s += __shfl_xor(s, 16); return s;
;     template <int MT> __device__ __forceinline__ void run(const Params& P, f32x16 (&acc)[MT][2], int rbase, int pn, int wc, int lane) const {
;     ...
;             bf16_t* CK = (bf16_t*)(ws + OFF_CKVA); float* SSQ = (float*)(ws + OFF_SSQK);
;             const int c0 = (pn - 4) * 128 + wc * 64 + n, c1 = c0 + 32; const float g0 = P.gkv[c0], g1 = P.gkv[c1];
; #pragma unroll
;             for (int mt = 0; mt < MT; ++mt)
; #pragma unroll
;                 for (int rg = 0; rg < 16; ++rg) { const int r = ROWOF(rb, mt, rg); const float v0 = acc[mt][0][rg], v1 = acc[mt][1][rg];
;                     float* o = (r < NPR) ? out + O_PCKV + (size_t)r * 512 : out + O_SCKV + (size_t)(r - NPR) * 512;
;                     o[c0] = v0 * g0; o[c1] = v1 * g1;
;                     const size_t kr = tok_keyrow(r);
;                     CK[kr * 512 + c0] = f2bf(v0 * g0); CK[kr * 512 + c1] = f2bf(v1 * g1);
;                     const float s = halfsum32(v0 * v0 + v1 * v1); if (n == 0) atomicAdd(SSQ + r, s); }
.LBB0_793:
	s_or_b64 exec, exec, s[0:1]
	v_add_u32_e32 v98, 49, v96
	v_ashrrev_i32_e32 v99, 31, v98
	v_add_u32_e32 v97, 0xffffc031, v96
	v_cmp_gt_i32_e64 s[0:1], s40, v98
	v_mov_b32_e32 v109, s13
	v_mov_b32_e32 v110, s15
	v_cndmask_b32_e64 v101, 0, v99, s[0:1]
	s_waitcnt lgkmcnt(0)
	v_cndmask_b32_e64 v100, v97, v98, s[0:1]
	v_cndmask_b32_e64 v111, v109, v110, s[0:1]
	v_mov_b32_e32 v109, s12
	v_mov_b32_e32 v110, s14
	v_cndmask_b32_e64 v110, v109, v110, s[0:1]
	v_lshlrev_b64 v[100:101], 11, v[100:101]
	v_lshl_add_u64 v[100:101], v[110:111], 0, v[100:101]
	v_mul_f32_e32 v110, v57, v103
	v_lshl_add_u64 v[100:101], v[132:133], 2, v[100:101]
	v_mul_f32_e32 v109, v41, v102
	v_cmp_lt_i32_e32 vcc, s41, v98
	global_store_dword v[100:101], v110, off
	global_store_dword v[100:101], v109, off offset:128
	v_mov_b64_e32 v[100:101], v[98:99]
	s_and_saveexec_b64 s[0:1], vcc
	v_lshrrev_b32_e32 v97, 6, v97
	v_mul_lo_u32 v97, v97, s54
	v_and_or_b32 v97, v98, 53, v97
	v_add_u32_e32 v100, 0x4400, v97
	v_mov_b32_e32 v101, v133
	s_or_b64 exec, exec, s[0:1]
	v_lshlrev_b64 v[100:101], 10, v[100:101]
	v_lshl_add_u64 v[100:101], s[8:9], 0, v[100:101]
	v_cvt_pk_bf16_f32 v97, v110, v110
	v_lshl_add_u64 v[100:101], v[132:133], 1, v[100:101]
	global_store_short v[100:101], v97, off
	v_cvt_pk_bf16_f32 v97, v109, v109
	global_store_short v[100:101], v97, off offset:64
	v_mul_f32_e32 v97, v41, v41
	v_fmac_f32_e32 v97, v57, v57
	s_nop 1
	v_add_f32_dpp v97, v97, v97 quad_perm:[1,0,3,2] row_mask:0xf bank_mask:0xf
	s_nop 1
	v_add_f32_dpp v97, v97, v97 quad_perm:[2,3,0,1] row_mask:0xf bank_mask:0xf
	s_nop 1
	v_add_f32_dpp v97, v97, v97 row_half_mirror row_mask:0xf bank_mask:0xf
	s_nop 1
	v_add_f32_dpp v97, v97, v97 row_mirror row_mask:0xf bank_mask:0xf
	ds_bpermute_b32 v100, v108, v97
	s_and_saveexec_b64 s[0:1], s[4:5]
	s_cbranch_execz .LBB0_797
	v_lshl_add_u64 v[98:99], v[98:99], 2, s[10:11]
	s_waitcnt lgkmcnt(0)
	v_add_f32_e32 v97, v97, v100
	global_atomic_add_f32 v[98:99], v97, off
.LBB0_797:
	s_or_b64 exec, exec, s[0:1]
	v_add_u32_e32 v98, 50, v96
	v_ashrrev_i32_e32 v99, 31, v98
	v_add_u32_e32 v97, 0xffffc032, v96
	v_cmp_gt_i32_e64 s[0:1], s40, v98
	v_mov_b32_e32 v109, s13
	v_mov_b32_e32 v110, s15
	v_cndmask_b32_e64 v101, 0, v99, s[0:1]
	s_waitcnt lgkmcnt(0)
	v_cndmask_b32_e64 v100, v97, v98, s[0:1]
	v_cndmask_b32_e64 v111, v109, v110, s[0:1]
	v_mov_b32_e32 v109, s12
	v_mov_b32_e32 v110, s14
	v_cndmask_b32_e64 v110, v109, v110, s[0:1]
	v_lshlrev_b64 v[100:101], 11, v[100:101]
	v_lshl_add_u64 v[100:101], v[110:111], 0, v[100:101]
	v_mul_f32_e32 v110, v58, v103
	v_lshl_add_u64 v[100:101], v[132:133], 2, v[100:101]
	v_mul_f32_e32 v109, v42, v102
	v_cmp_lt_i32_e32 vcc, s41, v98
	global_store_dword v[100:101], v110, off
	global_store_dword v[100:101], v109, off offset:128
	v_mov_b64_e32 v[100:101], v[98:99]
	s_and_saveexec_b64 s[0:1], vcc
	v_lshrrev_b32_e32 v97, 6, v97
	v_mul_lo_u32 v97, v97, s54
	v_and_or_b32 v97, v98, 54, v97
	v_add_u32_e32 v100, 0x4400, v97
	v_mov_b32_e32 v101, v133
	s_or_b64 exec, exec, s[0:1]
	v_lshlrev_b64 v[100:101], 10, v[100:101]
	v_lshl_add_u64 v[100:101], s[8:9], 0, v[100:101]
	v_cvt_pk_bf16_f32 v97, v110, v110
	v_lshl_add_u64 v[100:101], v[132:133], 1, v[100:101]
	global_store_short v[100:101], v97, off
	v_cvt_pk_bf16_f32 v97, v109, v109
	global_store_short v[100:101], v97, off offset:64
	v_mul_f32_e32 v97, v42, v42
	v_fmac_f32_e32 v97, v58, v58
	s_nop 1
	v_add_f32_dpp v97, v97, v97 quad_perm:[1,0,3,2] row_mask:0xf bank_mask:0xf
	s_nop 1
	v_add_f32_dpp v97, v97, v97 quad_perm:[2,3,0,1] row_mask:0xf bank_mask:0xf
	s_nop 1
	v_add_f32_dpp v97, v97, v97 row_half_mirror row_mask:0xf bank_mask:0xf
	s_nop 1
	v_add_f32_dpp v97, v97, v97 row_mirror row_mask:0xf bank_mask:0xf
	ds_bpermute_b32 v100, v108, v97
	s_and_saveexec_b64 s[0:1], s[4:5]
	s_cbranch_execz .LBB0_801
	v_lshl_add_u64 v[98:99], v[98:99], 2, s[10:11]
	s_waitcnt lgkmcnt(0)
	v_add_f32_e32 v97, v97, v100
	global_atomic_add_f32 v[98:99], v97, off
.LBB0_801:
	s_or_b64 exec, exec, s[0:1]
	v_add_u32_e32 v98, 51, v96
	v_ashrrev_i32_e32 v99, 31, v98
	v_add_u32_e32 v97, 0xffffc033, v96
	v_cmp_gt_i32_e64 s[0:1], s40, v98
	v_mov_b32_e32 v109, s13
	v_mov_b32_e32 v110, s15
	v_cndmask_b32_e64 v101, 0, v99, s[0:1]
	s_waitcnt lgkmcnt(0)
	v_cndmask_b32_e64 v100, v97, v98, s[0:1]
	v_cndmask_b32_e64 v111, v109, v110, s[0:1]
	v_mov_b32_e32 v109, s12
	v_mov_b32_e32 v110, s14
	v_cndmask_b32_e64 v110, v109, v110, s[0:1]
	v_lshlrev_b64 v[100:101], 11, v[100:101]
	v_lshl_add_u64 v[100:101], v[110:111], 0, v[100:101]
	v_mul_f32_e32 v110, v59, v103
	v_lshl_add_u64 v[100:101], v[132:133], 2, v[100:101]
	v_mul_f32_e32 v109, v43, v102
	v_cmp_lt_i32_e32 vcc, s41, v98
	global_store_dword v[100:101], v110, off
	global_store_dword v[100:101], v109, off offset:128
	v_mov_b64_e32 v[100:101], v[98:99]
	s_and_saveexec_b64 s[0:1], vcc
	v_lshrrev_b32_e32 v97, 6, v97
	v_mul_lo_u32 v97, v97, s54
	v_and_or_b32 v97, v98, 55, v97
	v_add_u32_e32 v100, 0x4400, v97
	v_mov_b32_e32 v101, v133
	s_or_b64 exec, exec, s[0:1]
	v_lshlrev_b64 v[100:101], 10, v[100:101]
	v_lshl_add_u64 v[100:101], s[8:9], 0, v[100:101]
	v_cvt_pk_bf16_f32 v97, v110, v110
	v_lshl_add_u64 v[100:101], v[132:133], 1, v[100:101]
	global_store_short v[100:101], v97, off
	v_cvt_pk_bf16_f32 v97, v109, v109
	global_store_short v[100:101], v97, off offset:64
	v_mul_f32_e32 v97, v43, v43
	v_fmac_f32_e32 v97, v59, v59
	s_nop 1
	v_add_f32_dpp v97, v97, v97 quad_perm:[1,0,3,2] row_mask:0xf bank_mask:0xf
	s_nop 1
	v_add_f32_dpp v97, v97, v97 quad_perm:[2,3,0,1] row_mask:0xf bank_mask:0xf
	s_nop 1
	v_add_f32_dpp v97, v97, v97 row_half_mirror row_mask:0xf bank_mask:0xf
	s_nop 1
	v_add_f32_dpp v97, v97, v97 row_mirror row_mask:0xf bank_mask:0xf
	ds_bpermute_b32 v100, v108, v97
	s_and_saveexec_b64 s[0:1], s[4:5]
	s_cbranch_execz .LBB0_805
	v_lshl_add_u64 v[98:99], v[98:99], 2, s[10:11]
	s_waitcnt lgkmcnt(0)
	v_add_f32_e32 v97, v97, v100
	global_atomic_add_f32 v[98:99], v97, off
; __device__ __forceinline__ bf16_t f2bf(float f) { return (bf16_t)(pk_bf16(f, f) & 0xffffu); }
; __device__ __forceinline__ float halfsum32(float s) {
;     s += __shfl_xor(s, 1); s += __shfl_xor(s, 2); s += __shfl_xor(s, 4); s += __shfl_xor(s, 8); s += __shfl_xor(s, 16); return s;
;     template <int MT> __device__ __forceinline__ void run(const Params& P, f32x16 (&acc)[MT][2], int rbase, int pn, int wc, int lane) const {
;     ...
;             bf16_t* CK = (bf16_t*)(ws + OFF_CKVA); float* SSQ = (float*)(ws + OFF_SSQK);
;             const int c0 = (pn - 4) * 128 + wc * 64 + n, c1 = c0 + 32; const float g0 = P.gkv[c0], g1 = P.gkv[c1];
; #pragma unroll
;             for (int mt = 0; mt < MT; ++mt)
; #pragma unroll
;                 for (int rg = 0; rg < 16; ++rg) { const int r = ROWOF(rb, mt, rg); const float v0 = acc[mt][0][rg], v1 = acc[mt][1][rg];
;                     float* o = (r < NPR) ? out + O_PCKV + (size_t)r * 512 : out + O_SCKV + (size_t)(r - NPR) * 512;
;                     o[c0] = v0 * g0; o[c1] = v1 * g1;
;                     const size_t kr = tok_keyrow(r);
;                     CK[kr * 512 + c0] = f2bf(v0 * g0); CK[kr * 512 + c1] = f2bf(v1 * g1);
;                     const float s = halfsum32(v0 * v0 + v1 * v1); if (n == 0) atomicAdd(SSQ + r, s); }
.LBB0_805:
	s_or_b64 exec, exec, s[0:1]
	v_add_u32_e32 v98, 56, v96
	v_ashrrev_i32_e32 v99, 31, v98
	v_add_u32_e32 v97, 0xffffc038, v96
	v_cmp_gt_i32_e64 s[0:1], s40, v98
	v_mov_b32_e32 v109, s13
	v_mov_b32_e32 v110, s15
	v_cndmask_b32_e64 v101, 0, v99, s[0:1]
	s_waitcnt lgkmcnt(0)
	v_cndmask_b32_e64 v100, v97, v98, s[0:1]
	v_cndmask_b32_e64 v111, v109, v110, s[0:1]
	v_mov_b32_e32 v109, s12
	v_mov_b32_e32 v110, s14
	v_cndmask_b32_e64 v110, v109, v110, s[0:1]
	v_lshlrev_b64 v[100:101], 11, v[100:101]
	v_lshl_add_u64 v[100:101], v[110:111], 0, v[100:101]
	v_mul_f32_e32 v110, v60, v103
	v_lshl_add_u64 v[100:101], v[132:133], 2, v[100:101]
	v_mul_f32_e32 v109, v44, v102
	v_cmp_lt_i32_e32 vcc, s41, v98
	global_store_dword v[100:101], v110, off
	global_store_dword v[100:101], v109, off offset:128
	v_mov_b64_e32 v[100:101], v[98:99]
	s_and_saveexec_b64 s[0:1], vcc
	v_lshrrev_b32_e32 v97, 6, v97
	v_mul_lo_u32 v97, v97, s54
	v_and_or_b32 v97, v98, 60, v97
	v_add_u32_e32 v100, 0x4400, v97
	v_mov_b32_e32 v101, v133
	s_or_b64 exec, exec, s[0:1]
	v_lshlrev_b64 v[100:101], 10, v[100:101]
	v_lshl_add_u64 v[100:101], s[8:9], 0, v[100:101]
	v_cvt_pk_bf16_f32 v97, v110, v110
	v_lshl_add_u64 v[100:101], v[132:133], 1, v[100:101]
	global_store_short v[100:101], v97, off
	v_cvt_pk_bf16_f32 v97, v109, v109
	global_store_short v[100:101], v97, off offset:64
	v_mul_f32_e32 v97, v44, v44
	v_fmac_f32_e32 v97, v60, v60
	s_nop 1
	v_add_f32_dpp v97, v97, v97 quad_perm:[1,0,3,2] row_mask:0xf bank_mask:0xf
	s_nop 1
	v_add_f32_dpp v97, v97, v97 quad_perm:[2,3,0,1] row_mask:0xf bank_mask:0xf
	s_nop 1
	v_add_f32_dpp v97, v97, v97 row_half_mirror row_mask:0xf bank_mask:0xf
	s_nop 1
	v_add_f32_dpp v97, v97, v97 row_mirror row_mask:0xf bank_mask:0xf
	ds_bpermute_b32 v100, v108, v97
	s_and_saveexec_b64 s[0:1], s[4:5]
	s_cbranch_execz .LBB0_809
	v_lshl_add_u64 v[98:99], v[98:99], 2, s[10:11]
	s_waitcnt lgkmcnt(0)
	v_add_f32_e32 v97, v97, v100
	global_atomic_add_f32 v[98:99], v97, off
.LBB0_809:
	s_or_b64 exec, exec, s[0:1]
	v_add_u32_e32 v98, 57, v96
	v_ashrrev_i32_e32 v99, 31, v98
	v_add_u32_e32 v97, 0xffffc039, v96
	v_cmp_gt_i32_e64 s[0:1], s40, v98
	v_mov_b32_e32 v109, s13
	v_mov_b32_e32 v110, s15
	v_cndmask_b32_e64 v101, 0, v99, s[0:1]
	s_waitcnt lgkmcnt(0)
	v_cndmask_b32_e64 v100, v97, v98, s[0:1]
	v_cndmask_b32_e64 v111, v109, v110, s[0:1]
	v_mov_b32_e32 v109, s12
	v_mov_b32_e32 v110, s14
	v_cndmask_b32_e64 v110, v109, v110, s[0:1]
	v_lshlrev_b64 v[100:101], 11, v[100:101]
	v_lshl_add_u64 v[100:101], v[110:111], 0, v[100:101]
	v_mul_f32_e32 v110, v61, v103
	v_lshl_add_u64 v[100:101], v[132:133], 2, v[100:101]
	v_mul_f32_e32 v109, v45, v102
	v_cmp_lt_i32_e32 vcc, s41, v98
	global_store_dword v[100:101], v110, off
	global_store_dword v[100:101], v109, off offset:128
	v_mov_b64_e32 v[100:101], v[98:99]
	s_and_saveexec_b64 s[0:1], vcc
	v_lshrrev_b32_e32 v97, 6, v97
	v_mul_lo_u32 v97, v97, s54
	v_and_or_b32 v97, v98, 61, v97
	v_add_u32_e32 v100, 0x4400, v97
	v_mov_b32_e32 v101, v133
	s_or_b64 exec, exec, s[0:1]
	v_lshlrev_b64 v[100:101], 10, v[100:101]
	v_lshl_add_u64 v[100:101], s[8:9], 0, v[100:101]
	v_cvt_pk_bf16_f32 v97, v110, v110
	v_lshl_add_u64 v[100:101], v[132:133], 1, v[100:101]
	global_store_short v[100:101], v97, off
	v_cvt_pk_bf16_f32 v97, v109, v109
	global_store_short v[100:101], v97, off offset:64
	v_mul_f32_e32 v97, v45, v45
	v_fmac_f32_e32 v97, v61, v61
	s_nop 1
	v_add_f32_dpp v97, v97, v97 quad_perm:[1,0,3,2] row_mask:0xf bank_mask:0xf
	s_nop 1
	v_add_f32_dpp v97, v97, v97 quad_perm:[2,3,0,1] row_mask:0xf bank_mask:0xf
	s_nop 1
	v_add_f32_dpp v97, v97, v97 row_half_mirror row_mask:0xf bank_mask:0xf
	s_nop 1
	v_add_f32_dpp v97, v97, v97 row_mirror row_mask:0xf bank_mask:0xf
	ds_bpermute_b32 v100, v108, v97
	s_and_saveexec_b64 s[0:1], s[4:5]
	s_cbranch_execz .LBB0_813
	v_lshl_add_u64 v[98:99], v[98:99], 2, s[10:11]
	s_waitcnt lgkmcnt(0)
	v_add_f32_e32 v97, v97, v100
	global_atomic_add_f32 v[98:99], v97, off
.LBB0_813:
	s_or_b64 exec, exec, s[0:1]
	v_add_u32_e32 v98, 58, v96
	v_ashrrev_i32_e32 v99, 31, v98
	v_add_u32_e32 v97, 0xffffc03a, v96
	v_cmp_gt_i32_e64 s[0:1], s40, v98
	v_mov_b32_e32 v109, s13
	v_mov_b32_e32 v110, s15
	v_cndmask_b32_e64 v101, 0, v99, s[0:1]
	s_waitcnt lgkmcnt(0)
	v_cndmask_b32_e64 v100, v97, v98, s[0:1]
	v_cndmask_b32_e64 v111, v109, v110, s[0:1]
	v_mov_b32_e32 v109, s12
	v_mov_b32_e32 v110, s14
	v_cndmask_b32_e64 v110, v109, v110, s[0:1]
	v_lshlrev_b64 v[100:101], 11, v[100:101]
	v_lshl_add_u64 v[100:101], v[110:111], 0, v[100:101]
	v_mul_f32_e32 v110, v62, v103
	v_lshl_add_u64 v[100:101], v[132:133], 2, v[100:101]
	v_mul_f32_e32 v109, v46, v102
	v_cmp_lt_i32_e32 vcc, s41, v98
	global_store_dword v[100:101], v110, off
	global_store_dword v[100:101], v109, off offset:128
	v_mov_b64_e32 v[100:101], v[98:99]
	s_and_saveexec_b64 s[0:1], vcc
	v_lshrrev_b32_e32 v97, 6, v97
	v_mul_lo_u32 v97, v97, s54
	v_and_or_b32 v97, v98, 62, v97
	v_add_u32_e32 v100, 0x4400, v97
	v_mov_b32_e32 v101, v133
	s_or_b64 exec, exec, s[0:1]
	v_lshlrev_b64 v[100:101], 10, v[100:101]
	v_lshl_add_u64 v[100:101], s[8:9], 0, v[100:101]
	v_cvt_pk_bf16_f32 v97, v110, v110
	v_lshl_add_u64 v[100:101], v[132:133], 1, v[100:101]
	global_store_short v[100:101], v97, off
	v_cvt_pk_bf16_f32 v97, v109, v109
	global_store_short v[100:101], v97, off offset:64
	v_mul_f32_e32 v97, v46, v46
	v_fmac_f32_e32 v97, v62, v62
	s_nop 1
	v_add_f32_dpp v97, v97, v97 quad_perm:[1,0,3,2] row_mask:0xf bank_mask:0xf
	s_nop 1
	v_add_f32_dpp v97, v97, v97 quad_perm:[2,3,0,1] row_mask:0xf bank_mask:0xf
	s_nop 1
	v_add_f32_dpp v97, v97, v97 row_half_mirror row_mask:0xf bank_mask:0xf
	s_nop 1
	v_add_f32_dpp v97, v97, v97 row_mirror row_mask:0xf bank_mask:0xf
	ds_bpermute_b32 v100, v108, v97
	s_and_saveexec_b64 s[0:1], s[4:5]
	s_cbranch_execz .LBB0_817
	v_lshl_add_u64 v[98:99], v[98:99], 2, s[10:11]
	s_waitcnt lgkmcnt(0)
	v_add_f32_e32 v97, v97, v100
	global_atomic_add_f32 v[98:99], v97, off
; __device__ __forceinline__ bf16_t f2bf(float f) { return (bf16_t)(pk_bf16(f, f) & 0xffffu); }
; __device__ __forceinline__ float halfsum32(float s) {
;     s += __shfl_xor(s, 1); s += __shfl_xor(s, 2); s += __shfl_xor(s, 4); s += __shfl_xor(s, 8); s += __shfl_xor(s, 16); return s;
;     template <int MT> __device__ __forceinline__ void run(const Params& P, f32x16 (&acc)[MT][2], int rbase, int pn, int wc, int lane) const {
;     ...
;             bf16_t* CK = (bf16_t*)(ws + OFF_CKVA); float* SSQ = (float*)(ws + OFF_SSQK);
;             const int c0 = (pn - 4) * 128 + wc * 64 + n, c1 = c0 + 32; const float g0 = P.gkv[c0], g1 = P.gkv[c1];
; #pragma unroll
;             for (int mt = 0; mt < MT; ++mt)
; #pragma unroll
;                 for (int rg = 0; rg < 16; ++rg) { const int r = ROWOF(rb, mt, rg); const float v0 = acc[mt][0][rg], v1 = acc[mt][1][rg];
;                     float* o = (r < NPR) ? out + O_PCKV + (size_t)r * 512 : out + O_SCKV + (size_t)(r - NPR) * 512;
;                     o[c0] = v0 * g0; o[c1] = v1 * g1;
;                     const size_t kr = tok_keyrow(r);
;                     CK[kr * 512 + c0] = f2bf(v0 * g0); CK[kr * 512 + c1] = f2bf(v1 * g1);
;                     const float s = halfsum32(v0 * v0 + v1 * v1); if (n == 0) atomicAdd(SSQ + r, s); }
.LBB0_817:
	s_or_b64 exec, exec, s[0:1]
	v_add_u32_e32 v98, 59, v96
	v_ashrrev_i32_e32 v99, 31, v98
	v_add_u32_e32 v97, 0xffffc03b, v96
	v_cmp_gt_i32_e64 s[0:1], s40, v98
	v_mov_b32_e32 v109, s13
	v_mov_b32_e32 v110, s15
	v_cndmask_b32_e64 v101, 0, v99, s[0:1]
	s_waitcnt lgkmcnt(0)
	v_cndmask_b32_e64 v100, v97, v98, s[0:1]
	v_cndmask_b32_e64 v111, v109, v110, s[0:1]
	v_mov_b32_e32 v109, s12
	v_mov_b32_e32 v110, s14
	v_cndmask_b32_e64 v110, v109, v110, s[0:1]
	v_lshlrev_b64 v[100:101], 11, v[100:101]
	v_lshl_add_u64 v[100:101], v[110:111], 0, v[100:101]
	v_mul_f32_e32 v110, v63, v103
	v_lshl_add_u64 v[100:101], v[132:133], 2, v[100:101]
	v_mul_f32_e32 v109, v47, v102
	v_cmp_lt_i32_e32 vcc, s41, v98
	global_store_dword v[100:101], v110, off
	global_store_dword v[100:101], v109, off offset:128
	v_mov_b64_e32 v[100:101], v[98:99]
	s_and_saveexec_b64 s[0:1], vcc
	v_lshrrev_b32_e32 v97, 6, v97
	v_mul_lo_u32 v97, v97, s54
	v_and_or_b32 v97, v98, 63, v97
	v_add_u32_e32 v100, 0x4400, v97
	v_mov_b32_e32 v101, v133
	s_or_b64 exec, exec, s[0:1]
	v_lshlrev_b64 v[100:101], 10, v[100:101]
	v_lshl_add_u64 v[100:101], s[8:9], 0, v[100:101]
	v_cvt_pk_bf16_f32 v97, v110, v110
	v_lshl_add_u64 v[100:101], v[132:133], 1, v[100:101]
	global_store_short v[100:101], v97, off
	v_cvt_pk_bf16_f32 v97, v109, v109
	global_store_short v[100:101], v97, off offset:64
	v_mul_f32_e32 v97, v47, v47
	v_fmac_f32_e32 v97, v63, v63
	s_nop 1
	v_add_f32_dpp v97, v97, v97 quad_perm:[1,0,3,2] row_mask:0xf bank_mask:0xf
	s_nop 1
	v_add_f32_dpp v97, v97, v97 quad_perm:[2,3,0,1] row_mask:0xf bank_mask:0xf
	s_nop 1
	v_add_f32_dpp v97, v97, v97 row_half_mirror row_mask:0xf bank_mask:0xf
	s_nop 1
	v_add_f32_dpp v97, v97, v97 row_mirror row_mask:0xf bank_mask:0xf
	ds_bpermute_b32 v100, v108, v97
	s_and_saveexec_b64 s[0:1], s[4:5]
	s_cbranch_execz .LBB0_821
	v_lshl_add_u64 v[98:99], v[98:99], 2, s[10:11]
	s_waitcnt lgkmcnt(0)
	v_add_f32_e32 v97, v97, v100
	global_atomic_add_f32 v[98:99], v97, off
.LBB0_821:
	s_or_b64 exec, exec, s[0:1]
	s_movk_i32 s0, 0x3fbf
	v_add_u32_e32 v98, 64, v96
	v_cmp_lt_i32_e32 vcc, s0, v96
	s_movk_i32 s0, 0x3fc0
	v_ashrrev_i32_e32 v99, 31, v98
	v_add_u32_e32 v97, 0xffffc040, v96
	v_cmp_gt_i32_e64 s[0:1], s0, v96
	v_mov_b32_e32 v109, s13
	v_mov_b32_e32 v110, s15
	v_cndmask_b32_e64 v101, 0, v99, s[0:1]
	s_waitcnt lgkmcnt(0)
	v_cndmask_b32_e64 v100, v97, v98, s[0:1]
	v_cndmask_b32_e64 v111, v109, v110, s[0:1]
	v_mov_b32_e32 v109, s12
	v_mov_b32_e32 v110, s14
	v_cndmask_b32_e64 v110, v109, v110, s[0:1]
	v_lshlrev_b64 v[100:101], 11, v[100:101]
	v_lshl_add_u64 v[100:101], v[110:111], 0, v[100:101]
	v_mul_f32_e32 v110, v16, v103
	v_lshl_add_u64 v[100:101], v[132:133], 2, v[100:101]
	v_mul_f32_e32 v109, v0, v102
	global_store_dword v[100:101], v110, off
	global_store_dword v[100:101], v109, off offset:128
	v_mov_b64_e32 v[100:101], v[98:99]
	s_and_saveexec_b64 s[0:1], vcc
	v_lshrrev_b32_e32 v97, 6, v97
	v_mul_lo_u32 v97, v97, s54
	v_and_or_b32 v97, v96, 36, v97
	v_add_u32_e32 v100, 0x4400, v97
	v_mov_b32_e32 v101, v133
	s_or_b64 exec, exec, s[0:1]
	v_lshlrev_b64 v[100:101], 10, v[100:101]
	v_lshl_add_u64 v[100:101], s[8:9], 0, v[100:101]
	v_cvt_pk_bf16_f32 v97, v110, v110
	v_lshl_add_u64 v[100:101], v[132:133], 1, v[100:101]
	global_store_short v[100:101], v97, off
	v_cvt_pk_bf16_f32 v97, v109, v109
	global_store_short v[100:101], v97, off offset:64
	v_mul_f32_e32 v97, v0, v0
	v_fmac_f32_e32 v97, v16, v16
	s_nop 1
	v_add_f32_dpp v97, v97, v97 quad_perm:[1,0,3,2] row_mask:0xf bank_mask:0xf
	s_nop 1
	v_add_f32_dpp v97, v97, v97 quad_perm:[2,3,0,1] row_mask:0xf bank_mask:0xf
	s_nop 1
	v_add_f32_dpp v97, v97, v97 row_half_mirror row_mask:0xf bank_mask:0xf
	s_nop 1
	v_add_f32_dpp v97, v97, v97 row_mirror row_mask:0xf bank_mask:0xf
	ds_bpermute_b32 v100, v108, v97
	s_and_saveexec_b64 s[0:1], s[4:5]
	s_cbranch_execz .LBB0_825
	v_lshl_add_u64 v[98:99], v[98:99], 2, s[10:11]
	s_waitcnt lgkmcnt(0)
	v_add_f32_e32 v97, v97, v100
	global_atomic_add_f32 v[98:99], v97, off
.LBB0_825:
	s_or_b64 exec, exec, s[0:1]
	v_add_u32_e32 v98, 0x41, v96
	v_ashrrev_i32_e32 v99, 31, v98
	v_add_u32_e32 v97, 0xffffc041, v96
	v_cmp_gt_i32_e64 s[0:1], s40, v98
	v_mov_b32_e32 v109, s13
	v_mov_b32_e32 v110, s15
	v_cndmask_b32_e64 v101, 0, v99, s[0:1]
	s_waitcnt lgkmcnt(0)
	v_cndmask_b32_e64 v100, v97, v98, s[0:1]
	v_cndmask_b32_e64 v111, v109, v110, s[0:1]
	v_mov_b32_e32 v109, s12
	v_mov_b32_e32 v110, s14
	v_cndmask_b32_e64 v110, v109, v110, s[0:1]
	v_lshlrev_b64 v[100:101], 11, v[100:101]
	v_lshl_add_u64 v[100:101], v[110:111], 0, v[100:101]
	v_mul_f32_e32 v110, v17, v103
	v_lshl_add_u64 v[100:101], v[132:133], 2, v[100:101]
	v_mul_f32_e32 v109, v1, v102
	v_cmp_lt_i32_e32 vcc, s41, v98
	global_store_dword v[100:101], v110, off
	global_store_dword v[100:101], v109, off offset:128
	v_mov_b64_e32 v[100:101], v[98:99]
	s_and_saveexec_b64 s[0:1], vcc
	v_lshrrev_b32_e32 v97, 6, v97
	v_mul_lo_u32 v97, v97, s54
	v_and_or_b32 v97, v98, 37, v97
	v_add_u32_e32 v100, 0x4400, v97
	v_mov_b32_e32 v101, v133
	s_or_b64 exec, exec, s[0:1]
	v_lshlrev_b64 v[100:101], 10, v[100:101]
	v_lshl_add_u64 v[100:101], s[8:9], 0, v[100:101]
	v_cvt_pk_bf16_f32 v97, v110, v110
	v_lshl_add_u64 v[100:101], v[132:133], 1, v[100:101]
	global_store_short v[100:101], v97, off
	v_cvt_pk_bf16_f32 v97, v109, v109
	global_store_short v[100:101], v97, off offset:64
	v_mul_f32_e32 v97, v1, v1
	v_fmac_f32_e32 v97, v17, v17
	s_nop 1
	v_add_f32_dpp v97, v97, v97 quad_perm:[1,0,3,2] row_mask:0xf bank_mask:0xf
	s_nop 1
	v_add_f32_dpp v97, v97, v97 quad_perm:[2,3,0,1] row_mask:0xf bank_mask:0xf
	s_nop 1
	v_add_f32_dpp v97, v97, v97 row_half_mirror row_mask:0xf bank_mask:0xf
	s_nop 1
	v_add_f32_dpp v97, v97, v97 row_mirror row_mask:0xf bank_mask:0xf
	ds_bpermute_b32 v100, v108, v97
	s_and_saveexec_b64 s[0:1], s[4:5]
	s_cbranch_execz .LBB0_829
	v_lshl_add_u64 v[98:99], v[98:99], 2, s[10:11]
	s_waitcnt lgkmcnt(0)
	v_add_f32_e32 v97, v97, v100
	global_atomic_add_f32 v[98:99], v97, off
; __device__ __forceinline__ bf16_t f2bf(float f) { return (bf16_t)(pk_bf16(f, f) & 0xffffu); }
; __device__ __forceinline__ float halfsum32(float s) {
;     s += __shfl_xor(s, 1); s += __shfl_xor(s, 2); s += __shfl_xor(s, 4); s += __shfl_xor(s, 8); s += __shfl_xor(s, 16); return s;
;     template <int MT> __device__ __forceinline__ void run(const Params& P, f32x16 (&acc)[MT][2], int rbase, int pn, int wc, int lane) const {
;     ...
;             bf16_t* CK = (bf16_t*)(ws + OFF_CKVA); float* SSQ = (float*)(ws + OFF_SSQK);
;             const int c0 = (pn - 4) * 128 + wc * 64 + n, c1 = c0 + 32; const float g0 = P.gkv[c0], g1 = P.gkv[c1];
; #pragma unroll
;             for (int mt = 0; mt < MT; ++mt)
; #pragma unroll
;                 for (int rg = 0; rg < 16; ++rg) { const int r = ROWOF(rb, mt, rg); const float v0 = acc[mt][0][rg], v1 = acc[mt][1][rg];
;                     float* o = (r < NPR) ? out + O_PCKV + (size_t)r * 512 : out + O_SCKV + (size_t)(r - NPR) * 512;
;                     o[c0] = v0 * g0; o[c1] = v1 * g1;
;                     const size_t kr = tok_keyrow(r);
;                     CK[kr * 512 + c0] = f2bf(v0 * g0); CK[kr * 512 + c1] = f2bf(v1 * g1);
;                     const float s = halfsum32(v0 * v0 + v1 * v1); if (n == 0) atomicAdd(SSQ + r, s); }
.LBB0_829:
	s_or_b64 exec, exec, s[0:1]
	v_add_u32_e32 v98, 0x42, v96
	v_ashrrev_i32_e32 v99, 31, v98
	v_add_u32_e32 v97, 0xffffc042, v96
	v_cmp_gt_i32_e64 s[0:1], s40, v98
	v_mov_b32_e32 v109, s13
	v_mov_b32_e32 v110, s15
	v_cndmask_b32_e64 v101, 0, v99, s[0:1]
	s_waitcnt lgkmcnt(0)
	v_cndmask_b32_e64 v100, v97, v98, s[0:1]
	v_cndmask_b32_e64 v111, v109, v110, s[0:1]
	v_mov_b32_e32 v109, s12
	v_mov_b32_e32 v110, s14
	v_cndmask_b32_e64 v110, v109, v110, s[0:1]
	v_lshlrev_b64 v[100:101], 11, v[100:101]
	v_lshl_add_u64 v[100:101], v[110:111], 0, v[100:101]
	v_mul_f32_e32 v110, v18, v103
	v_lshl_add_u64 v[100:101], v[132:133], 2, v[100:101]
	v_mul_f32_e32 v109, v2, v102
	v_cmp_lt_i32_e32 vcc, s41, v98
	global_store_dword v[100:101], v110, off
	global_store_dword v[100:101], v109, off offset:128
	v_mov_b64_e32 v[100:101], v[98:99]
	s_and_saveexec_b64 s[0:1], vcc
	v_lshrrev_b32_e32 v97, 6, v97
	v_mul_lo_u32 v97, v97, s54
	v_and_or_b32 v97, v98, 38, v97
	v_add_u32_e32 v100, 0x4400, v97
	v_mov_b32_e32 v101, v133
	s_or_b64 exec, exec, s[0:1]
	v_lshlrev_b64 v[100:101], 10, v[100:101]
	v_lshl_add_u64 v[100:101], s[8:9], 0, v[100:101]
	v_cvt_pk_bf16_f32 v97, v110, v110
	v_lshl_add_u64 v[100:101], v[132:133], 1, v[100:101]
	global_store_short v[100:101], v97, off
	v_cvt_pk_bf16_f32 v97, v109, v109
	global_store_short v[100:101], v97, off offset:64
	v_mul_f32_e32 v97, v2, v2
	v_fmac_f32_e32 v97, v18, v18
	s_nop 1
	v_add_f32_dpp v97, v97, v97 quad_perm:[1,0,3,2] row_mask:0xf bank_mask:0xf
	s_nop 1
	v_add_f32_dpp v97, v97, v97 quad_perm:[2,3,0,1] row_mask:0xf bank_mask:0xf
	s_nop 1
	v_add_f32_dpp v97, v97, v97 row_half_mirror row_mask:0xf bank_mask:0xf
	s_nop 1
	v_add_f32_dpp v97, v97, v97 row_mirror row_mask:0xf bank_mask:0xf
	ds_bpermute_b32 v100, v108, v97
	s_and_saveexec_b64 s[0:1], s[4:5]
	s_cbranch_execz .LBB0_833
	v_lshl_add_u64 v[98:99], v[98:99], 2, s[10:11]
	s_waitcnt lgkmcnt(0)
	v_add_f32_e32 v97, v97, v100
	global_atomic_add_f32 v[98:99], v97, off
.LBB0_833:
	s_or_b64 exec, exec, s[0:1]
	v_add_u32_e32 v98, 0x43, v96
	v_ashrrev_i32_e32 v99, 31, v98
	v_add_u32_e32 v97, 0xffffc043, v96
	v_cmp_gt_i32_e64 s[0:1], s40, v98
	v_mov_b32_e32 v109, s13
	v_mov_b32_e32 v110, s15
	v_cndmask_b32_e64 v101, 0, v99, s[0:1]
	s_waitcnt lgkmcnt(0)
	v_cndmask_b32_e64 v100, v97, v98, s[0:1]
	v_cndmask_b32_e64 v111, v109, v110, s[0:1]
	v_mov_b32_e32 v109, s12
	v_mov_b32_e32 v110, s14
	v_cndmask_b32_e64 v110, v109, v110, s[0:1]
	v_lshlrev_b64 v[100:101], 11, v[100:101]
	v_lshl_add_u64 v[100:101], v[110:111], 0, v[100:101]
	v_mul_f32_e32 v110, v19, v103
	v_lshl_add_u64 v[100:101], v[132:133], 2, v[100:101]
	v_mul_f32_e32 v109, v3, v102
	v_cmp_lt_i32_e32 vcc, s41, v98
	global_store_dword v[100:101], v110, off
	global_store_dword v[100:101], v109, off offset:128
	v_mov_b64_e32 v[100:101], v[98:99]
	s_and_saveexec_b64 s[0:1], vcc
	v_lshrrev_b32_e32 v97, 6, v97
	v_mul_lo_u32 v97, v97, s54
	v_and_or_b32 v97, v98, 39, v97
	v_add_u32_e32 v100, 0x4400, v97
	v_mov_b32_e32 v101, v133
	s_or_b64 exec, exec, s[0:1]
	v_lshlrev_b64 v[100:101], 10, v[100:101]
	v_lshl_add_u64 v[100:101], s[8:9], 0, v[100:101]
	v_cvt_pk_bf16_f32 v97, v110, v110
	v_lshl_add_u64 v[100:101], v[132:133], 1, v[100:101]
	global_store_short v[100:101], v97, off
	v_cvt_pk_bf16_f32 v97, v109, v109
	global_store_short v[100:101], v97, off offset:64
	v_mul_f32_e32 v97, v3, v3
	v_fmac_f32_e32 v97, v19, v19
	s_nop 1
	v_add_f32_dpp v97, v97, v97 quad_perm:[1,0,3,2] row_mask:0xf bank_mask:0xf
	s_nop 1
	v_add_f32_dpp v97, v97, v97 quad_perm:[2,3,0,1] row_mask:0xf bank_mask:0xf
	s_nop 1
	v_add_f32_dpp v97, v97, v97 row_half_mirror row_mask:0xf bank_mask:0xf
	s_nop 1
	v_add_f32_dpp v97, v97, v97 row_mirror row_mask:0xf bank_mask:0xf
	ds_bpermute_b32 v100, v108, v97
	s_and_saveexec_b64 s[0:1], s[4:5]
	s_cbranch_execz .LBB0_837
	v_lshl_add_u64 v[98:99], v[98:99], 2, s[10:11]
	s_waitcnt lgkmcnt(0)
	v_add_f32_e32 v97, v97, v100
	global_atomic_add_f32 v[98:99], v97, off
.LBB0_837:
	s_or_b64 exec, exec, s[0:1]
	v_add_u32_e32 v98, 0x48, v96
	v_ashrrev_i32_e32 v99, 31, v98
	v_add_u32_e32 v97, 0xffffc048, v96
	v_cmp_gt_i32_e64 s[0:1], s40, v98
	v_mov_b32_e32 v109, s13
	v_mov_b32_e32 v110, s15
	v_cndmask_b32_e64 v101, 0, v99, s[0:1]
	s_waitcnt lgkmcnt(0)
	v_cndmask_b32_e64 v100, v97, v98, s[0:1]
	v_cndmask_b32_e64 v111, v109, v110, s[0:1]
	v_mov_b32_e32 v109, s12
	v_mov_b32_e32 v110, s14
	v_cndmask_b32_e64 v110, v109, v110, s[0:1]
	v_lshlrev_b64 v[100:101], 11, v[100:101]
	v_lshl_add_u64 v[100:101], v[110:111], 0, v[100:101]
	v_mul_f32_e32 v110, v20, v103
	v_lshl_add_u64 v[100:101], v[132:133], 2, v[100:101]
	v_mul_f32_e32 v109, v4, v102
	v_cmp_lt_i32_e32 vcc, s41, v98
	global_store_dword v[100:101], v110, off
	global_store_dword v[100:101], v109, off offset:128
	v_mov_b64_e32 v[100:101], v[98:99]
	s_and_saveexec_b64 s[0:1], vcc
	v_lshrrev_b32_e32 v97, 6, v97
	v_mul_lo_u32 v97, v97, s54
	v_and_or_b32 v97, v98, 44, v97
	v_add_u32_e32 v100, 0x4400, v97
	v_mov_b32_e32 v101, v133
	s_or_b64 exec, exec, s[0:1]
	v_lshlrev_b64 v[100:101], 10, v[100:101]
	v_lshl_add_u64 v[100:101], s[8:9], 0, v[100:101]
	v_cvt_pk_bf16_f32 v97, v110, v110
	v_lshl_add_u64 v[100:101], v[132:133], 1, v[100:101]
	global_store_short v[100:101], v97, off
	v_cvt_pk_bf16_f32 v97, v109, v109
	global_store_short v[100:101], v97, off offset:64
	v_mul_f32_e32 v97, v4, v4
	v_fmac_f32_e32 v97, v20, v20
	s_nop 1
	v_add_f32_dpp v97, v97, v97 quad_perm:[1,0,3,2] row_mask:0xf bank_mask:0xf
	s_nop 1
	v_add_f32_dpp v97, v97, v97 quad_perm:[2,3,0,1] row_mask:0xf bank_mask:0xf
	s_nop 1
	v_add_f32_dpp v97, v97, v97 row_half_mirror row_mask:0xf bank_mask:0xf
	s_nop 1
	v_add_f32_dpp v97, v97, v97 row_mirror row_mask:0xf bank_mask:0xf
	ds_bpermute_b32 v100, v108, v97
	s_and_saveexec_b64 s[0:1], s[4:5]
	s_cbranch_execz .LBB0_841
	v_lshl_add_u64 v[98:99], v[98:99], 2, s[10:11]
	s_waitcnt lgkmcnt(0)
	v_add_f32_e32 v97, v97, v100
	global_atomic_add_f32 v[98:99], v97, off
; __device__ __forceinline__ bf16_t f2bf(float f) { return (bf16_t)(pk_bf16(f, f) & 0xffffu); }
; __device__ __forceinline__ float halfsum32(float s) {
;     s += __shfl_xor(s, 1); s += __shfl_xor(s, 2); s += __shfl_xor(s, 4); s += __shfl_xor(s, 8); s += __shfl_xor(s, 16); return s;
;     template <int MT> __device__ __forceinline__ void run(const Params& P, f32x16 (&acc)[MT][2], int rbase, int pn, int wc, int lane) const {
;     ...
;             bf16_t* CK = (bf16_t*)(ws + OFF_CKVA); float* SSQ = (float*)(ws + OFF_SSQK);
;             const int c0 = (pn - 4) * 128 + wc * 64 + n, c1 = c0 + 32; const float g0 = P.gkv[c0], g1 = P.gkv[c1];
; #pragma unroll
;             for (int mt = 0; mt < MT; ++mt)
; #pragma unroll
;                 for (int rg = 0; rg < 16; ++rg) { const int r = ROWOF(rb, mt, rg); const float v0 = acc[mt][0][rg], v1 = acc[mt][1][rg];
;                     float* o = (r < NPR) ? out + O_PCKV + (size_t)r * 512 : out + O_SCKV + (size_t)(r - NPR) * 512;
;                     o[c0] = v0 * g0; o[c1] = v1 * g1;
;                     const size_t kr = tok_keyrow(r);
;                     CK[kr * 512 + c0] = f2bf(v0 * g0); CK[kr * 512 + c1] = f2bf(v1 * g1);
;                     const float s = halfsum32(v0 * v0 + v1 * v1); if (n == 0) atomicAdd(SSQ + r, s); }
.LBB0_841:
	s_or_b64 exec, exec, s[0:1]
	v_add_u32_e32 v98, 0x49, v96
	v_ashrrev_i32_e32 v99, 31, v98
	v_add_u32_e32 v97, 0xffffc049, v96
	v_cmp_gt_i32_e64 s[0:1], s40, v98
	v_mov_b32_e32 v109, s13
	v_mov_b32_e32 v110, s15
	v_cndmask_b32_e64 v101, 0, v99, s[0:1]
	s_waitcnt lgkmcnt(0)
	v_cndmask_b32_e64 v100, v97, v98, s[0:1]
	v_cndmask_b32_e64 v111, v109, v110, s[0:1]
	v_mov_b32_e32 v109, s12
	v_mov_b32_e32 v110, s14
	v_cndmask_b32_e64 v110, v109, v110, s[0:1]
	v_lshlrev_b64 v[100:101], 11, v[100:101]
	v_lshl_add_u64 v[100:101], v[110:111], 0, v[100:101]
	v_mul_f32_e32 v110, v21, v103
	v_lshl_add_u64 v[100:101], v[132:133], 2, v[100:101]
	v_mul_f32_e32 v109, v5, v102
	v_cmp_lt_i32_e32 vcc, s41, v98
	global_store_dword v[100:101], v110, off
	global_store_dword v[100:101], v109, off offset:128
	v_mov_b64_e32 v[100:101], v[98:99]
	s_and_saveexec_b64 s[0:1], vcc
	v_lshrrev_b32_e32 v97, 6, v97
	v_mul_lo_u32 v97, v97, s54
	v_and_or_b32 v97, v98, 45, v97
	v_add_u32_e32 v100, 0x4400, v97
	v_mov_b32_e32 v101, v133
	s_or_b64 exec, exec, s[0:1]
	v_lshlrev_b64 v[100:101], 10, v[100:101]
	v_lshl_add_u64 v[100:101], s[8:9], 0, v[100:101]
	v_cvt_pk_bf16_f32 v97, v110, v110
	v_lshl_add_u64 v[100:101], v[132:133], 1, v[100:101]
	global_store_short v[100:101], v97, off
	v_cvt_pk_bf16_f32 v97, v109, v109
	global_store_short v[100:101], v97, off offset:64
	v_mul_f32_e32 v97, v5, v5
	v_fmac_f32_e32 v97, v21, v21
	s_nop 1
	v_add_f32_dpp v97, v97, v97 quad_perm:[1,0,3,2] row_mask:0xf bank_mask:0xf
	s_nop 1
	v_add_f32_dpp v97, v97, v97 quad_perm:[2,3,0,1] row_mask:0xf bank_mask:0xf
	s_nop 1
	v_add_f32_dpp v97, v97, v97 row_half_mirror row_mask:0xf bank_mask:0xf
	s_nop 1
	v_add_f32_dpp v97, v97, v97 row_mirror row_mask:0xf bank_mask:0xf
	ds_bpermute_b32 v100, v108, v97
	s_and_saveexec_b64 s[0:1], s[4:5]
	s_cbranch_execz .LBB0_845
	v_lshl_add_u64 v[98:99], v[98:99], 2, s[10:11]
	s_waitcnt lgkmcnt(0)
	v_add_f32_e32 v97, v97, v100
	global_atomic_add_f32 v[98:99], v97, off
.LBB0_845:
	s_or_b64 exec, exec, s[0:1]
	v_add_u32_e32 v98, 0x4a, v96
	v_ashrrev_i32_e32 v99, 31, v98
	v_add_u32_e32 v97, 0xffffc04a, v96
	v_cmp_gt_i32_e64 s[0:1], s40, v98
	v_mov_b32_e32 v109, s13
	v_mov_b32_e32 v110, s15
	v_cndmask_b32_e64 v101, 0, v99, s[0:1]
	s_waitcnt lgkmcnt(0)
	v_cndmask_b32_e64 v100, v97, v98, s[0:1]
	v_cndmask_b32_e64 v111, v109, v110, s[0:1]
	v_mov_b32_e32 v109, s12
	v_mov_b32_e32 v110, s14
	v_cndmask_b32_e64 v110, v109, v110, s[0:1]
	v_lshlrev_b64 v[100:101], 11, v[100:101]
	v_lshl_add_u64 v[100:101], v[110:111], 0, v[100:101]
	v_mul_f32_e32 v110, v22, v103
	v_lshl_add_u64 v[100:101], v[132:133], 2, v[100:101]
	v_mul_f32_e32 v109, v6, v102
	v_cmp_lt_i32_e32 vcc, s41, v98
	global_store_dword v[100:101], v110, off
	global_store_dword v[100:101], v109, off offset:128
	v_mov_b64_e32 v[100:101], v[98:99]
	s_and_saveexec_b64 s[0:1], vcc
	v_lshrrev_b32_e32 v97, 6, v97
	v_mul_lo_u32 v97, v97, s54
	v_and_or_b32 v97, v98, 46, v97
	v_add_u32_e32 v100, 0x4400, v97
	v_mov_b32_e32 v101, v133
	s_or_b64 exec, exec, s[0:1]
	v_lshlrev_b64 v[100:101], 10, v[100:101]
	v_lshl_add_u64 v[100:101], s[8:9], 0, v[100:101]
	v_cvt_pk_bf16_f32 v97, v110, v110
	v_lshl_add_u64 v[100:101], v[132:133], 1, v[100:101]
	global_store_short v[100:101], v97, off
	v_cvt_pk_bf16_f32 v97, v109, v109
	global_store_short v[100:101], v97, off offset:64
	v_mul_f32_e32 v97, v6, v6
	v_fmac_f32_e32 v97, v22, v22
	s_nop 1
	v_add_f32_dpp v97, v97, v97 quad_perm:[1,0,3,2] row_mask:0xf bank_mask:0xf
	s_nop 1
	v_add_f32_dpp v97, v97, v97 quad_perm:[2,3,0,1] row_mask:0xf bank_mask:0xf
	s_nop 1
	v_add_f32_dpp v97, v97, v97 row_half_mirror row_mask:0xf bank_mask:0xf
	s_nop 1
	v_add_f32_dpp v97, v97, v97 row_mirror row_mask:0xf bank_mask:0xf
	ds_bpermute_b32 v100, v108, v97
	s_and_saveexec_b64 s[0:1], s[4:5]
	s_cbranch_execz .LBB0_849
	v_lshl_add_u64 v[98:99], v[98:99], 2, s[10:11]
	s_waitcnt lgkmcnt(0)
	v_add_f32_e32 v97, v97, v100
	global_atomic_add_f32 v[98:99], v97, off
.LBB0_849:
	s_or_b64 exec, exec, s[0:1]
	v_add_u32_e32 v98, 0x4b, v96
	v_ashrrev_i32_e32 v99, 31, v98
	v_add_u32_e32 v97, 0xffffc04b, v96
	v_cmp_gt_i32_e64 s[0:1], s40, v98
	v_mov_b32_e32 v109, s13
	v_mov_b32_e32 v110, s15
	v_cndmask_b32_e64 v101, 0, v99, s[0:1]
	s_waitcnt lgkmcnt(0)
	v_cndmask_b32_e64 v100, v97, v98, s[0:1]
	v_cndmask_b32_e64 v111, v109, v110, s[0:1]
	v_mov_b32_e32 v109, s12
	v_mov_b32_e32 v110, s14
	v_cndmask_b32_e64 v110, v109, v110, s[0:1]
	v_lshlrev_b64 v[100:101], 11, v[100:101]
	v_lshl_add_u64 v[100:101], v[110:111], 0, v[100:101]
	v_mul_f32_e32 v110, v23, v103
	v_lshl_add_u64 v[100:101], v[132:133], 2, v[100:101]
	v_mul_f32_e32 v109, v7, v102
	v_cmp_lt_i32_e32 vcc, s41, v98
	global_store_dword v[100:101], v110, off
	global_store_dword v[100:101], v109, off offset:128
	v_mov_b64_e32 v[100:101], v[98:99]
	s_and_saveexec_b64 s[0:1], vcc
	v_lshrrev_b32_e32 v97, 6, v97
	v_mul_lo_u32 v97, v97, s54
	v_and_or_b32 v97, v98, 47, v97
	v_add_u32_e32 v100, 0x4400, v97
	v_mov_b32_e32 v101, v133
	s_or_b64 exec, exec, s[0:1]
	v_lshlrev_b64 v[100:101], 10, v[100:101]
	v_lshl_add_u64 v[100:101], s[8:9], 0, v[100:101]
	v_cvt_pk_bf16_f32 v97, v110, v110
	v_lshl_add_u64 v[100:101], v[132:133], 1, v[100:101]
	global_store_short v[100:101], v97, off
	v_cvt_pk_bf16_f32 v97, v109, v109
	global_store_short v[100:101], v97, off offset:64
	v_mul_f32_e32 v97, v7, v7
	v_fmac_f32_e32 v97, v23, v23
	s_nop 1
	v_add_f32_dpp v97, v97, v97 quad_perm:[1,0,3,2] row_mask:0xf bank_mask:0xf
	s_nop 1
	v_add_f32_dpp v97, v97, v97 quad_perm:[2,3,0,1] row_mask:0xf bank_mask:0xf
	s_nop 1
	v_add_f32_dpp v97, v97, v97 row_half_mirror row_mask:0xf bank_mask:0xf
	s_nop 1
	v_add_f32_dpp v97, v97, v97 row_mirror row_mask:0xf bank_mask:0xf
	ds_bpermute_b32 v100, v108, v97
	s_and_saveexec_b64 s[0:1], s[4:5]
	s_cbranch_execz .LBB0_853
	v_lshl_add_u64 v[98:99], v[98:99], 2, s[10:11]
	s_waitcnt lgkmcnt(0)
	v_add_f32_e32 v97, v97, v100
	global_atomic_add_f32 v[98:99], v97, off
; __device__ __forceinline__ bf16_t f2bf(float f) { return (bf16_t)(pk_bf16(f, f) & 0xffffu); }
; __device__ __forceinline__ float halfsum32(float s) {
;     s += __shfl_xor(s, 1); s += __shfl_xor(s, 2); s += __shfl_xor(s, 4); s += __shfl_xor(s, 8); s += __shfl_xor(s, 16); return s;
;     template <int MT> __device__ __forceinline__ void run(const Params& P, f32x16 (&acc)[MT][2], int rbase, int pn, int wc, int lane) const {
;     ...
;             bf16_t* CK = (bf16_t*)(ws + OFF_CKVA); float* SSQ = (float*)(ws + OFF_SSQK);
;             const int c0 = (pn - 4) * 128 + wc * 64 + n, c1 = c0 + 32; const float g0 = P.gkv[c0], g1 = P.gkv[c1];
; #pragma unroll
;             for (int mt = 0; mt < MT; ++mt)
; #pragma unroll
;                 for (int rg = 0; rg < 16; ++rg) { const int r = ROWOF(rb, mt, rg); const float v0 = acc[mt][0][rg], v1 = acc[mt][1][rg];
;                     float* o = (r < NPR) ? out + O_PCKV + (size_t)r * 512 : out + O_SCKV + (size_t)(r - NPR) * 512;
;                     o[c0] = v0 * g0; o[c1] = v1 * g1;
;                     const size_t kr = tok_keyrow(r);
;                     CK[kr * 512 + c0] = f2bf(v0 * g0); CK[kr * 512 + c1] = f2bf(v1 * g1);
;                     const float s = halfsum32(v0 * v0 + v1 * v1); if (n == 0) atomicAdd(SSQ + r, s); }
.LBB0_853:
	s_or_b64 exec, exec, s[0:1]
	v_add_u32_e32 v98, 0x50, v96
	v_ashrrev_i32_e32 v99, 31, v98
	v_add_u32_e32 v97, 0xffffc050, v96
	v_cmp_gt_i32_e64 s[0:1], s40, v98
	v_mov_b32_e32 v109, s13
	v_mov_b32_e32 v110, s15
	v_cndmask_b32_e64 v101, 0, v99, s[0:1]
	s_waitcnt lgkmcnt(0)
	v_cndmask_b32_e64 v100, v97, v98, s[0:1]
	v_cndmask_b32_e64 v111, v109, v110, s[0:1]
	v_mov_b32_e32 v109, s12
	v_mov_b32_e32 v110, s14
	v_cndmask_b32_e64 v110, v109, v110, s[0:1]
	v_lshlrev_b64 v[100:101], 11, v[100:101]
	v_lshl_add_u64 v[100:101], v[110:111], 0, v[100:101]
	v_mul_f32_e32 v110, v24, v103
	v_lshl_add_u64 v[100:101], v[132:133], 2, v[100:101]
	v_mul_f32_e32 v109, v8, v102
	v_cmp_lt_i32_e32 vcc, s41, v98
	global_store_dword v[100:101], v110, off
	global_store_dword v[100:101], v109, off offset:128
	v_mov_b64_e32 v[100:101], v[98:99]
	s_and_saveexec_b64 s[0:1], vcc
	v_lshrrev_b32_e32 v97, 6, v97
	v_mul_lo_u32 v97, v97, s54
	v_and_or_b32 v97, v98, 52, v97
	v_add_u32_e32 v100, 0x4400, v97
	v_mov_b32_e32 v101, v133
	s_or_b64 exec, exec, s[0:1]
	v_lshlrev_b64 v[100:101], 10, v[100:101]
	v_lshl_add_u64 v[100:101], s[8:9], 0, v[100:101]
	v_cvt_pk_bf16_f32 v97, v110, v110
	v_lshl_add_u64 v[100:101], v[132:133], 1, v[100:101]
	global_store_short v[100:101], v97, off
	v_cvt_pk_bf16_f32 v97, v109, v109
	global_store_short v[100:101], v97, off offset:64
	v_mul_f32_e32 v97, v8, v8
	v_fmac_f32_e32 v97, v24, v24
	s_nop 1
	v_add_f32_dpp v97, v97, v97 quad_perm:[1,0,3,2] row_mask:0xf bank_mask:0xf
	s_nop 1
	v_add_f32_dpp v97, v97, v97 quad_perm:[2,3,0,1] row_mask:0xf bank_mask:0xf
	s_nop 1
	v_add_f32_dpp v97, v97, v97 row_half_mirror row_mask:0xf bank_mask:0xf
	s_nop 1
	v_add_f32_dpp v97, v97, v97 row_mirror row_mask:0xf bank_mask:0xf
	ds_bpermute_b32 v100, v108, v97
	s_and_saveexec_b64 s[0:1], s[4:5]
	s_cbranch_execz .LBB0_857
	v_lshl_add_u64 v[98:99], v[98:99], 2, s[10:11]
	s_waitcnt lgkmcnt(0)
	v_add_f32_e32 v97, v97, v100
	global_atomic_add_f32 v[98:99], v97, off
.LBB0_857:
	s_or_b64 exec, exec, s[0:1]
	v_add_u32_e32 v98, 0x51, v96
	v_ashrrev_i32_e32 v99, 31, v98
	v_add_u32_e32 v97, 0xffffc051, v96
	v_cmp_gt_i32_e64 s[0:1], s40, v98
	v_mov_b32_e32 v109, s13
	v_mov_b32_e32 v110, s15
	v_cndmask_b32_e64 v101, 0, v99, s[0:1]
	s_waitcnt lgkmcnt(0)
	v_cndmask_b32_e64 v100, v97, v98, s[0:1]
	v_cndmask_b32_e64 v111, v109, v110, s[0:1]
	v_mov_b32_e32 v109, s12
	v_mov_b32_e32 v110, s14
	v_cndmask_b32_e64 v110, v109, v110, s[0:1]
	v_lshlrev_b64 v[100:101], 11, v[100:101]
	v_lshl_add_u64 v[100:101], v[110:111], 0, v[100:101]
	v_mul_f32_e32 v110, v25, v103
	v_lshl_add_u64 v[100:101], v[132:133], 2, v[100:101]
	v_mul_f32_e32 v109, v9, v102
	v_cmp_lt_i32_e32 vcc, s41, v98
	global_store_dword v[100:101], v110, off
	global_store_dword v[100:101], v109, off offset:128
	v_mov_b64_e32 v[100:101], v[98:99]
	s_and_saveexec_b64 s[0:1], vcc
	v_lshrrev_b32_e32 v97, 6, v97
	v_mul_lo_u32 v97, v97, s54
	v_and_or_b32 v97, v98, 53, v97
	v_add_u32_e32 v100, 0x4400, v97
	v_mov_b32_e32 v101, v133
	s_or_b64 exec, exec, s[0:1]
	v_lshlrev_b64 v[100:101], 10, v[100:101]
	v_lshl_add_u64 v[100:101], s[8:9], 0, v[100:101]
	v_cvt_pk_bf16_f32 v97, v110, v110
	v_lshl_add_u64 v[100:101], v[132:133], 1, v[100:101]
	global_store_short v[100:101], v97, off
	v_cvt_pk_bf16_f32 v97, v109, v109
	global_store_short v[100:101], v97, off offset:64
	v_mul_f32_e32 v97, v9, v9
	v_fmac_f32_e32 v97, v25, v25
	s_nop 1
	v_add_f32_dpp v97, v97, v97 quad_perm:[1,0,3,2] row_mask:0xf bank_mask:0xf
	s_nop 1
	v_add_f32_dpp v97, v97, v97 quad_perm:[2,3,0,1] row_mask:0xf bank_mask:0xf
	s_nop 1
	v_add_f32_dpp v97, v97, v97 row_half_mirror row_mask:0xf bank_mask:0xf
	s_nop 1
	v_add_f32_dpp v97, v97, v97 row_mirror row_mask:0xf bank_mask:0xf
	ds_bpermute_b32 v100, v108, v97
	s_and_saveexec_b64 s[0:1], s[4:5]
	s_cbranch_execz .LBB0_861
	v_lshl_add_u64 v[98:99], v[98:99], 2, s[10:11]
	s_waitcnt lgkmcnt(0)
	v_add_f32_e32 v97, v97, v100
	global_atomic_add_f32 v[98:99], v97, off
.LBB0_861:
	s_or_b64 exec, exec, s[0:1]
	v_add_u32_e32 v98, 0x52, v96
	v_ashrrev_i32_e32 v99, 31, v98
	v_add_u32_e32 v97, 0xffffc052, v96
	v_cmp_gt_i32_e64 s[0:1], s40, v98
	v_mov_b32_e32 v109, s13
	v_mov_b32_e32 v110, s15
	v_cndmask_b32_e64 v101, 0, v99, s[0:1]
	s_waitcnt lgkmcnt(0)
	v_cndmask_b32_e64 v100, v97, v98, s[0:1]
	v_cndmask_b32_e64 v111, v109, v110, s[0:1]
	v_mov_b32_e32 v109, s12
	v_mov_b32_e32 v110, s14
	v_cndmask_b32_e64 v110, v109, v110, s[0:1]
	v_lshlrev_b64 v[100:101], 11, v[100:101]
	v_lshl_add_u64 v[100:101], v[110:111], 0, v[100:101]
	v_mul_f32_e32 v110, v26, v103
	v_lshl_add_u64 v[100:101], v[132:133], 2, v[100:101]
	v_mul_f32_e32 v109, v10, v102
	v_cmp_lt_i32_e32 vcc, s41, v98
	global_store_dword v[100:101], v110, off
	global_store_dword v[100:101], v109, off offset:128
	v_mov_b64_e32 v[100:101], v[98:99]
	s_and_saveexec_b64 s[0:1], vcc
	v_lshrrev_b32_e32 v97, 6, v97
	v_mul_lo_u32 v97, v97, s54
	v_and_or_b32 v97, v98, 54, v97
	v_add_u32_e32 v100, 0x4400, v97
	v_mov_b32_e32 v101, v133
	s_or_b64 exec, exec, s[0:1]
	v_lshlrev_b64 v[100:101], 10, v[100:101]
	v_lshl_add_u64 v[100:101], s[8:9], 0, v[100:101]
	v_cvt_pk_bf16_f32 v97, v110, v110
	v_lshl_add_u64 v[100:101], v[132:133], 1, v[100:101]
	global_store_short v[100:101], v97, off
	v_cvt_pk_bf16_f32 v97, v109, v109
	global_store_short v[100:101], v97, off offset:64
	v_mul_f32_e32 v97, v10, v10
	v_fmac_f32_e32 v97, v26, v26
	s_nop 1
	v_add_f32_dpp v97, v97, v97 quad_perm:[1,0,3,2] row_mask:0xf bank_mask:0xf
	s_nop 1
	v_add_f32_dpp v97, v97, v97 quad_perm:[2,3,0,1] row_mask:0xf bank_mask:0xf
	s_nop 1
	v_add_f32_dpp v97, v97, v97 row_half_mirror row_mask:0xf bank_mask:0xf
	s_nop 1
	v_add_f32_dpp v97, v97, v97 row_mirror row_mask:0xf bank_mask:0xf
	ds_bpermute_b32 v100, v108, v97
	s_and_saveexec_b64 s[0:1], s[4:5]
	s_cbranch_execz .LBB0_865
	v_lshl_add_u64 v[98:99], v[98:99], 2, s[10:11]
	s_waitcnt lgkmcnt(0)
	v_add_f32_e32 v97, v97, v100
	global_atomic_add_f32 v[98:99], v97, off
; __device__ __forceinline__ bf16_t f2bf(float f) { return (bf16_t)(pk_bf16(f, f) & 0xffffu); }
; __device__ __forceinline__ float halfsum32(float s) {
;     s += __shfl_xor(s, 1); s += __shfl_xor(s, 2); s += __shfl_xor(s, 4); s += __shfl_xor(s, 8); s += __shfl_xor(s, 16); return s;
;     template <int MT> __device__ __forceinline__ void run(const Params& P, f32x16 (&acc)[MT][2], int rbase, int pn, int wc, int lane) const {
;     ...
;             bf16_t* CK = (bf16_t*)(ws + OFF_CKVA); float* SSQ = (float*)(ws + OFF_SSQK);
;             const int c0 = (pn - 4) * 128 + wc * 64 + n, c1 = c0 + 32; const float g0 = P.gkv[c0], g1 = P.gkv[c1];
; #pragma unroll
;             for (int mt = 0; mt < MT; ++mt)
; #pragma unroll
;                 for (int rg = 0; rg < 16; ++rg) { const int r = ROWOF(rb, mt, rg); const float v0 = acc[mt][0][rg], v1 = acc[mt][1][rg];
;                     float* o = (r < NPR) ? out + O_PCKV + (size_t)r * 512 : out + O_SCKV + (size_t)(r - NPR) * 512;
;                     o[c0] = v0 * g0; o[c1] = v1 * g1;
;                     const size_t kr = tok_keyrow(r);
;                     CK[kr * 512 + c0] = f2bf(v0 * g0); CK[kr * 512 + c1] = f2bf(v1 * g1);
;                     const float s = halfsum32(v0 * v0 + v1 * v1); if (n == 0) atomicAdd(SSQ + r, s); }
.LBB0_865:
	s_or_b64 exec, exec, s[0:1]
	v_add_u32_e32 v98, 0x53, v96
	v_ashrrev_i32_e32 v99, 31, v98
	v_add_u32_e32 v97, 0xffffc053, v96
	v_cmp_gt_i32_e64 s[0:1], s40, v98
	v_mov_b32_e32 v109, s13
	v_mov_b32_e32 v110, s15
	v_cndmask_b32_e64 v101, 0, v99, s[0:1]
	s_waitcnt lgkmcnt(0)
	v_cndmask_b32_e64 v100, v97, v98, s[0:1]
	v_cndmask_b32_e64 v111, v109, v110, s[0:1]
	v_mov_b32_e32 v109, s12
	v_mov_b32_e32 v110, s14
	v_cndmask_b32_e64 v110, v109, v110, s[0:1]
	v_lshlrev_b64 v[100:101], 11, v[100:101]
	v_lshl_add_u64 v[100:101], v[110:111], 0, v[100:101]
	v_mul_f32_e32 v110, v27, v103
	v_lshl_add_u64 v[100:101], v[132:133], 2, v[100:101]
	v_mul_f32_e32 v109, v11, v102
	v_cmp_lt_i32_e32 vcc, s41, v98
	global_store_dword v[100:101], v110, off
	global_store_dword v[100:101], v109, off offset:128
	v_mov_b64_e32 v[100:101], v[98:99]
	s_and_saveexec_b64 s[0:1], vcc
	v_lshrrev_b32_e32 v97, 6, v97
	v_mul_lo_u32 v97, v97, s54
	v_and_or_b32 v97, v98, 55, v97
	v_add_u32_e32 v100, 0x4400, v97
	v_mov_b32_e32 v101, v133
	s_or_b64 exec, exec, s[0:1]
	v_lshlrev_b64 v[100:101], 10, v[100:101]
	v_lshl_add_u64 v[100:101], s[8:9], 0, v[100:101]
	v_cvt_pk_bf16_f32 v97, v110, v110
	v_lshl_add_u64 v[100:101], v[132:133], 1, v[100:101]
	global_store_short v[100:101], v97, off
	v_cvt_pk_bf16_f32 v97, v109, v109
	global_store_short v[100:101], v97, off offset:64
	v_mul_f32_e32 v97, v11, v11
	v_fmac_f32_e32 v97, v27, v27
	s_nop 1
	v_add_f32_dpp v97, v97, v97 quad_perm:[1,0,3,2] row_mask:0xf bank_mask:0xf
	s_nop 1
	v_add_f32_dpp v97, v97, v97 quad_perm:[2,3,0,1] row_mask:0xf bank_mask:0xf
	s_nop 1
	v_add_f32_dpp v97, v97, v97 row_half_mirror row_mask:0xf bank_mask:0xf
	s_nop 1
	v_add_f32_dpp v97, v97, v97 row_mirror row_mask:0xf bank_mask:0xf
	ds_bpermute_b32 v100, v108, v97
	s_and_saveexec_b64 s[0:1], s[4:5]
	s_cbranch_execz .LBB0_869
	v_lshl_add_u64 v[98:99], v[98:99], 2, s[10:11]
	s_waitcnt lgkmcnt(0)
	v_add_f32_e32 v97, v97, v100
	global_atomic_add_f32 v[98:99], v97, off
.LBB0_869:
	s_or_b64 exec, exec, s[0:1]
	v_add_u32_e32 v98, 0x58, v96
	v_ashrrev_i32_e32 v99, 31, v98
	v_add_u32_e32 v97, 0xffffc058, v96
	v_cmp_gt_i32_e64 s[0:1], s40, v98
	v_mov_b32_e32 v109, s13
	v_mov_b32_e32 v110, s15
	v_cndmask_b32_e64 v101, 0, v99, s[0:1]
	s_waitcnt lgkmcnt(0)
	v_cndmask_b32_e64 v100, v97, v98, s[0:1]
	v_cndmask_b32_e64 v111, v109, v110, s[0:1]
	v_mov_b32_e32 v109, s12
	v_mov_b32_e32 v110, s14
	v_cndmask_b32_e64 v110, v109, v110, s[0:1]
	v_lshlrev_b64 v[100:101], 11, v[100:101]
	v_lshl_add_u64 v[100:101], v[110:111], 0, v[100:101]
	v_mul_f32_e32 v110, v28, v103
	v_lshl_add_u64 v[100:101], v[132:133], 2, v[100:101]
	v_mul_f32_e32 v109, v12, v102
	v_cmp_lt_i32_e32 vcc, s41, v98
	global_store_dword v[100:101], v110, off
	global_store_dword v[100:101], v109, off offset:128
	v_mov_b64_e32 v[100:101], v[98:99]
	s_and_saveexec_b64 s[0:1], vcc
	v_lshrrev_b32_e32 v97, 6, v97
	v_mul_lo_u32 v97, v97, s54
	v_and_or_b32 v97, v98, 60, v97
	v_add_u32_e32 v100, 0x4400, v97
	v_mov_b32_e32 v101, v133
	s_or_b64 exec, exec, s[0:1]
	v_lshlrev_b64 v[100:101], 10, v[100:101]
	v_lshl_add_u64 v[100:101], s[8:9], 0, v[100:101]
	v_cvt_pk_bf16_f32 v97, v110, v110
	v_lshl_add_u64 v[100:101], v[132:133], 1, v[100:101]
	global_store_short v[100:101], v97, off
	v_cvt_pk_bf16_f32 v97, v109, v109
	global_store_short v[100:101], v97, off offset:64
	v_mul_f32_e32 v97, v12, v12
	v_fmac_f32_e32 v97, v28, v28
	s_nop 1
	v_add_f32_dpp v97, v97, v97 quad_perm:[1,0,3,2] row_mask:0xf bank_mask:0xf
	s_nop 1
	v_add_f32_dpp v97, v97, v97 quad_perm:[2,3,0,1] row_mask:0xf bank_mask:0xf
	s_nop 1
	v_add_f32_dpp v97, v97, v97 row_half_mirror row_mask:0xf bank_mask:0xf
	s_nop 1
	v_add_f32_dpp v97, v97, v97 row_mirror row_mask:0xf bank_mask:0xf
	ds_bpermute_b32 v100, v108, v97
	s_and_saveexec_b64 s[0:1], s[4:5]
	s_cbranch_execz .LBB0_873
	v_lshl_add_u64 v[98:99], v[98:99], 2, s[10:11]
	s_waitcnt lgkmcnt(0)
	v_add_f32_e32 v97, v97, v100
	global_atomic_add_f32 v[98:99], v97, off
; __device__ __forceinline__ bf16_t f2bf(float f) { return (bf16_t)(pk_bf16(f, f) & 0xffffu); }
; __device__ __forceinline__ float halfsum32(float s) {
;     s += __shfl_xor(s, 1); s += __shfl_xor(s, 2); s += __shfl_xor(s, 4); s += __shfl_xor(s, 8); s += __shfl_xor(s, 16); return s;
;     template <int MT> __device__ __forceinline__ void run(const Params& P, f32x16 (&acc)[MT][2], int rbase, int pn, int wc, int lane) const {
;     ...
;             bf16_t* CK = (bf16_t*)(ws + OFF_CKVA); float* SSQ = (float*)(ws + OFF_SSQK);
;             const int c0 = (pn - 4) * 128 + wc * 64 + n, c1 = c0 + 32; const float g0 = P.gkv[c0], g1 = P.gkv[c1];
; #pragma unroll
;             for (int mt = 0; mt < MT; ++mt)
; #pragma unroll
;                 for (int rg = 0; rg < 16; ++rg) { const int r = ROWOF(rb, mt, rg); const float v0 = acc[mt][0][rg], v1 = acc[mt][1][rg];
;                     float* o = (r < NPR) ? out + O_PCKV + (size_t)r * 512 : out + O_SCKV + (size_t)(r - NPR) * 512;
;                     o[c0] = v0 * g0; o[c1] = v1 * g1;
;                     const size_t kr = tok_keyrow(r);
;                     CK[kr * 512 + c0] = f2bf(v0 * g0); CK[kr * 512 + c1] = f2bf(v1 * g1);
;                     const float s = halfsum32(v0 * v0 + v1 * v1); if (n == 0) atomicAdd(SSQ + r, s); }
.LBB0_873:
	s_or_b64 exec, exec, s[0:1]
	v_add_u32_e32 v98, 0x59, v96
	v_ashrrev_i32_e32 v99, 31, v98
	v_add_u32_e32 v97, 0xffffc059, v96
	v_cmp_gt_i32_e64 s[0:1], s40, v98
	v_mov_b32_e32 v109, s13
	v_mov_b32_e32 v110, s15
	v_cndmask_b32_e64 v101, 0, v99, s[0:1]
	s_waitcnt lgkmcnt(0)
	v_cndmask_b32_e64 v100, v97, v98, s[0:1]
	v_cndmask_b32_e64 v111, v109, v110, s[0:1]
	v_mov_b32_e32 v109, s12
	v_mov_b32_e32 v110, s14
	v_cndmask_b32_e64 v110, v109, v110, s[0:1]
	v_lshlrev_b64 v[100:101], 11, v[100:101]
	v_lshl_add_u64 v[100:101], v[110:111], 0, v[100:101]
	v_mul_f32_e32 v110, v29, v103
	v_lshl_add_u64 v[100:101], v[132:133], 2, v[100:101]
	v_mul_f32_e32 v109, v13, v102
	v_cmp_lt_i32_e32 vcc, s41, v98
	global_store_dword v[100:101], v110, off
	global_store_dword v[100:101], v109, off offset:128
	v_mov_b64_e32 v[100:101], v[98:99]
	s_and_saveexec_b64 s[0:1], vcc
	v_lshrrev_b32_e32 v97, 6, v97
	v_mul_lo_u32 v97, v97, s54
	v_and_or_b32 v97, v98, 61, v97
	v_add_u32_e32 v100, 0x4400, v97
	v_mov_b32_e32 v101, v133
	s_or_b64 exec, exec, s[0:1]
	v_lshlrev_b64 v[100:101], 10, v[100:101]
	v_lshl_add_u64 v[100:101], s[8:9], 0, v[100:101]
	v_cvt_pk_bf16_f32 v97, v110, v110
	v_lshl_add_u64 v[100:101], v[132:133], 1, v[100:101]
	global_store_short v[100:101], v97, off
	v_cvt_pk_bf16_f32 v97, v109, v109
	global_store_short v[100:101], v97, off offset:64
	v_mul_f32_e32 v97, v13, v13
	v_fmac_f32_e32 v97, v29, v29
	s_nop 1
	v_add_f32_dpp v97, v97, v97 quad_perm:[1,0,3,2] row_mask:0xf bank_mask:0xf
	s_nop 1
	v_add_f32_dpp v97, v97, v97 quad_perm:[2,3,0,1] row_mask:0xf bank_mask:0xf
	s_nop 1
	v_add_f32_dpp v97, v97, v97 row_half_mirror row_mask:0xf bank_mask:0xf
	s_nop 1
	v_add_f32_dpp v97, v97, v97 row_mirror row_mask:0xf bank_mask:0xf
	ds_bpermute_b32 v100, v108, v97
	s_and_saveexec_b64 s[0:1], s[4:5]
	s_cbranch_execz .LBB0_877
	v_lshl_add_u64 v[98:99], v[98:99], 2, s[10:11]
	s_waitcnt lgkmcnt(0)
	v_add_f32_e32 v97, v97, v100
	global_atomic_add_f32 v[98:99], v97, off
.LBB0_877:
	s_or_b64 exec, exec, s[0:1]
	v_add_u32_e32 v98, 0x5a, v96
	v_ashrrev_i32_e32 v99, 31, v98
	v_add_u32_e32 v97, 0xffffc05a, v96
	v_cmp_gt_i32_e64 s[0:1], s40, v98
	v_mov_b32_e32 v109, s13
	v_mov_b32_e32 v110, s15
	v_cndmask_b32_e64 v101, 0, v99, s[0:1]
	s_waitcnt lgkmcnt(0)
	v_cndmask_b32_e64 v100, v97, v98, s[0:1]
	v_cndmask_b32_e64 v111, v109, v110, s[0:1]
	v_mov_b32_e32 v109, s12
	v_mov_b32_e32 v110, s14
	v_cndmask_b32_e64 v110, v109, v110, s[0:1]
	v_lshlrev_b64 v[100:101], 11, v[100:101]
	v_lshl_add_u64 v[100:101], v[110:111], 0, v[100:101]
	v_mul_f32_e32 v110, v30, v103
	v_lshl_add_u64 v[100:101], v[132:133], 2, v[100:101]
	v_mul_f32_e32 v109, v14, v102
	v_cmp_lt_i32_e32 vcc, s41, v98
	global_store_dword v[100:101], v110, off
	global_store_dword v[100:101], v109, off offset:128
	v_mov_b64_e32 v[100:101], v[98:99]
	s_and_saveexec_b64 s[0:1], vcc
	v_lshrrev_b32_e32 v97, 6, v97
	v_mul_lo_u32 v97, v97, s54
	v_and_or_b32 v97, v98, 62, v97
	v_add_u32_e32 v100, 0x4400, v97
	v_mov_b32_e32 v101, v133
	s_or_b64 exec, exec, s[0:1]
	v_lshlrev_b64 v[100:101], 10, v[100:101]
	v_lshl_add_u64 v[100:101], s[8:9], 0, v[100:101]
	v_cvt_pk_bf16_f32 v97, v110, v110
	v_lshl_add_u64 v[100:101], v[132:133], 1, v[100:101]
	global_store_short v[100:101], v97, off
	v_cvt_pk_bf16_f32 v97, v109, v109
	global_store_short v[100:101], v97, off offset:64
	v_mul_f32_e32 v97, v14, v14
	v_fmac_f32_e32 v97, v30, v30
	s_nop 1
	v_add_f32_dpp v97, v97, v97 quad_perm:[1,0,3,2] row_mask:0xf bank_mask:0xf
	s_nop 1
	v_add_f32_dpp v97, v97, v97 quad_perm:[2,3,0,1] row_mask:0xf bank_mask:0xf
	s_nop 1
	v_add_f32_dpp v97, v97, v97 row_half_mirror row_mask:0xf bank_mask:0xf
	s_nop 1
	v_add_f32_dpp v97, v97, v97 row_mirror row_mask:0xf bank_mask:0xf
	ds_bpermute_b32 v100, v108, v97
	s_and_saveexec_b64 s[0:1], s[4:5]
	s_cbranch_execz .LBB0_881
	v_lshl_add_u64 v[98:99], v[98:99], 2, s[10:11]
	s_waitcnt lgkmcnt(0)
	v_add_f32_e32 v97, v97, v100
	global_atomic_add_f32 v[98:99], v97, off

; __device__ __forceinline__ bf16_t f2bf(float f) { return (bf16_t)(pk_bf16(f, f) & 0xffffu); }
; __device__ __forceinline__ float halfsum32(float s) {
;     s += __shfl_xor(s, 1); s += __shfl_xor(s, 2); s += __shfl_xor(s, 4); s += __shfl_xor(s, 8); s += __shfl_xor(s, 16); return s;
;     template <int MT> __device__ __forceinline__ void run(const Params& P, f32x16 (&acc)[MT][2], int rbase, int pn, int wc, int lane) const {
;     ...
;             bf16_t* CQ = (bf16_t*)(ws + OFF_CQ); float* SSQ = (float*)(ws + OFF_SSQQ);
;             const int c0 = pn * 128 + wc * 64 + n, c1 = c0 + 32; const float g0 = P.gq[c0], g1 = P.gq[c1];
; #pragma unroll
;             for (int mt = 0; mt < MT; ++mt)
; #pragma unroll
;                 for (int rg = 0; rg < 16; ++rg) { const int r = ROWOF(rb, mt, rg); const float v0 = acc[mt][0][rg], v1 = acc[mt][1][rg];
;                     CQ[(size_t)r * 512 + c0] = f2bf(v0 * g0); CQ[(size_t)r * 512 + c1] = f2bf(v1 * g1);
;                     const float s = halfsum32(v0 * v0 + v1 * v1); if (n == 0) atomicAdd(SSQ + r, s); }
.LBB0_890:
	s_or_b64 exec, exec, s[0:1]
	s_waitcnt lgkmcnt(0)
	v_or_b32_e32 v100, 1, v96
	v_ashrrev_i32_e32 v101, 31, v100
	v_lshlrev_b64 v[108:109], 10, v[100:101]
	v_mul_f32_e32 v64, v81, v103
	v_lshl_add_u64 v[108:109], s[20:21], 0, v[108:109]
	v_cvt_pk_bf16_f32 v64, v64, v64
	v_lshl_add_u64 v[108:109], v[98:99], 1, v[108:109]
	global_store_short v[108:109], v64, off
	v_mul_f32_e32 v64, v65, v102
	v_cvt_pk_bf16_f32 v64, v64, v64
	global_store_short v[108:109], v64, off offset:64
	v_mul_f32_e32 v64, v65, v65
	v_fmac_f32_e32 v64, v81, v81
	s_nop 1
	v_add_f32_dpp v64, v64, v64 quad_perm:[1,0,3,2] row_mask:0xf bank_mask:0xf
	s_nop 1
	v_add_f32_dpp v64, v64, v64 quad_perm:[2,3,0,1] row_mask:0xf bank_mask:0xf
	s_nop 1
	v_add_f32_dpp v64, v64, v64 row_half_mirror row_mask:0xf bank_mask:0xf
	s_nop 1
	v_add_f32_dpp v64, v64, v64 row_mirror row_mask:0xf bank_mask:0xf
	ds_bpermute_b32 v65, v107, v64
	s_and_saveexec_b64 s[0:1], s[4:5]
	s_cbranch_execz .LBB0_892
	v_lshl_add_u64 v[100:101], v[100:101], 2, s[18:19]
	s_waitcnt lgkmcnt(0)
	v_add_f32_e32 v64, v64, v65
	global_atomic_add_f32 v[100:101], v64, off
.LBB0_892:
	s_or_b64 exec, exec, s[0:1]
	v_or_b32_e32 v64, 2, v96
	s_waitcnt lgkmcnt(0)
	v_mul_f32_e32 v65, v82, v103
	v_cvt_pk_bf16_f32 v81, v65, v65
	v_ashrrev_i32_e32 v65, 31, v64
	v_lshlrev_b64 v[100:101], 10, v[64:65]
	v_lshl_add_u64 v[100:101], s[20:21], 0, v[100:101]
	v_lshl_add_u64 v[100:101], v[98:99], 1, v[100:101]
	global_store_short v[100:101], v81, off
	v_mul_f32_e32 v81, v66, v102
	v_mul_f32_e32 v66, v66, v66
	v_cvt_pk_bf16_f32 v81, v81, v81
	v_fmac_f32_e32 v66, v82, v82
	global_store_short v[100:101], v81, off offset:64
	s_nop 1
	v_add_f32_dpp v66, v66, v66 quad_perm:[1,0,3,2] row_mask:0xf bank_mask:0xf
	s_nop 1
	v_add_f32_dpp v66, v66, v66 quad_perm:[2,3,0,1] row_mask:0xf bank_mask:0xf
	s_nop 1
	v_add_f32_dpp v66, v66, v66 row_half_mirror row_mask:0xf bank_mask:0xf
	s_nop 1
	v_add_f32_dpp v66, v66, v66 row_mirror row_mask:0xf bank_mask:0xf
	ds_bpermute_b32 v81, v107, v66
	s_and_saveexec_b64 s[0:1], s[4:5]
	s_mov_b64 s[68:69], 0x156a0c80
	s_cbranch_execz .LBB0_894
	v_lshl_add_u64 v[64:65], v[64:65], 2, s[18:19]
	s_waitcnt lgkmcnt(0)
	v_add_f32_e32 v66, v66, v81
	global_atomic_add_f32 v[64:65], v66, off
.LBB0_894:
	s_or_b64 exec, exec, s[0:1]
	v_or_b32_e32 v64, 3, v96
	v_mul_f32_e32 v65, v83, v103
	v_cvt_pk_bf16_f32 v66, v65, v65
	v_ashrrev_i32_e32 v65, 31, v64
	v_lshlrev_b64 v[100:101], 10, v[64:65]
	v_lshl_add_u64 v[100:101], s[20:21], 0, v[100:101]
	v_lshl_add_u64 v[100:101], v[98:99], 1, v[100:101]
	global_store_short v[100:101], v66, off
	v_mul_f32_e32 v66, v67, v102
	v_cvt_pk_bf16_f32 v66, v66, v66
	global_store_short v[100:101], v66, off offset:64
	v_mul_f32_e32 v66, v67, v67
	v_fmac_f32_e32 v66, v83, v83
	s_nop 1
	v_add_f32_dpp v66, v66, v66 quad_perm:[1,0,3,2] row_mask:0xf bank_mask:0xf
	s_nop 1
	v_add_f32_dpp v66, v66, v66 quad_perm:[2,3,0,1] row_mask:0xf bank_mask:0xf
	s_nop 1
	v_add_f32_dpp v66, v66, v66 row_half_mirror row_mask:0xf bank_mask:0xf
	s_nop 1
	v_add_f32_dpp v66, v66, v66 row_mirror row_mask:0xf bank_mask:0xf
	ds_bpermute_b32 v67, v107, v66
	s_and_saveexec_b64 s[0:1], s[4:5]
	s_cbranch_execz .LBB0_896
	v_lshl_add_u64 v[64:65], v[64:65], 2, s[18:19]
	s_waitcnt lgkmcnt(0)
	v_add_f32_e32 v66, v66, v67
	global_atomic_add_f32 v[64:65], v66, off
.LBB0_896:
	s_or_b64 exec, exec, s[0:1]
	v_or_b32_e32 v64, 8, v96
	v_mul_f32_e32 v65, v84, v103
	v_cvt_pk_bf16_f32 v81, v65, v65
	v_ashrrev_i32_e32 v65, 31, v64
	s_waitcnt lgkmcnt(0)
	v_lshlrev_b64 v[66:67], 10, v[64:65]
	v_lshl_add_u64 v[66:67], s[20:21], 0, v[66:67]
	v_lshl_add_u64 v[66:67], v[98:99], 1, v[66:67]
	global_store_short v[66:67], v81, off
	v_mul_f32_e32 v81, v68, v102
	v_cvt_pk_bf16_f32 v81, v81, v81
	global_store_short v[66:67], v81, off offset:64
	v_mul_f32_e32 v66, v68, v68
	v_fmac_f32_e32 v66, v84, v84
	s_nop 1
	v_add_f32_dpp v66, v66, v66 quad_perm:[1,0,3,2] row_mask:0xf bank_mask:0xf
	s_nop 1
	v_add_f32_dpp v66, v66, v66 quad_perm:[2,3,0,1] row_mask:0xf bank_mask:0xf
	s_nop 1
	v_add_f32_dpp v66, v66, v66 row_half_mirror row_mask:0xf bank_mask:0xf
	s_nop 1
	v_add_f32_dpp v66, v66, v66 row_mirror row_mask:0xf bank_mask:0xf
	ds_bpermute_b32 v67, v107, v66
	s_and_saveexec_b64 s[0:1], s[4:5]
	s_cbranch_execz .LBB0_898
	v_lshl_add_u64 v[64:65], v[64:65], 2, s[18:19]
	s_waitcnt lgkmcnt(0)
	v_add_f32_e32 v66, v66, v67
	global_atomic_add_f32 v[64:65], v66, off
.LBB0_898:
	s_or_b64 exec, exec, s[0:1]
	v_or_b32_e32 v64, 9, v96
	v_mul_f32_e32 v65, v85, v103
	v_cvt_pk_bf16_f32 v68, v65, v65
	v_ashrrev_i32_e32 v65, 31, v64
	s_waitcnt lgkmcnt(0)
	v_lshlrev_b64 v[66:67], 10, v[64:65]
	v_lshl_add_u64 v[66:67], s[20:21], 0, v[66:67]
	v_lshl_add_u64 v[66:67], v[98:99], 1, v[66:67]
	global_store_short v[66:67], v68, off
	v_mul_f32_e32 v68, v69, v102
	v_cvt_pk_bf16_f32 v68, v68, v68
	global_store_short v[66:67], v68, off offset:64
	v_mul_f32_e32 v66, v69, v69
	v_fmac_f32_e32 v66, v85, v85
	s_nop 1
	v_add_f32_dpp v66, v66, v66 quad_perm:[1,0,3,2] row_mask:0xf bank_mask:0xf
	s_nop 1
	v_add_f32_dpp v66, v66, v66 quad_perm:[2,3,0,1] row_mask:0xf bank_mask:0xf
	s_nop 1
	v_add_f32_dpp v66, v66, v66 row_half_mirror row_mask:0xf bank_mask:0xf
	s_nop 1
	v_add_f32_dpp v66, v66, v66 row_mirror row_mask:0xf bank_mask:0xf
	ds_bpermute_b32 v67, v107, v66
	s_and_saveexec_b64 s[0:1], s[4:5]
	s_cbranch_execz .LBB0_900
	v_lshl_add_u64 v[64:65], v[64:65], 2, s[18:19]
	s_waitcnt lgkmcnt(0)
	v_add_f32_e32 v66, v66, v67
	global_atomic_add_f32 v[64:65], v66, off
; __device__ __forceinline__ bf16_t f2bf(float f) { return (bf16_t)(pk_bf16(f, f) & 0xffffu); }
; __device__ __forceinline__ float halfsum32(float s) {
;     s += __shfl_xor(s, 1); s += __shfl_xor(s, 2); s += __shfl_xor(s, 4); s += __shfl_xor(s, 8); s += __shfl_xor(s, 16); return s;
; }
;     template <int MT> __device__ __forceinline__ void run(const Params& P, f32x16 (&acc)[MT][2], int rbase, int pn, int wc, int lane) const {
;     ...
;             bf16_t* CQ = (bf16_t*)(ws + OFF_CQ); float* SSQ = (float*)(ws + OFF_SSQQ);
;             const int c0 = pn * 128 + wc * 64 + n, c1 = c0 + 32; const float g0 = P.gq[c0], g1 = P.gq[c1];
; #pragma unroll
;             for (int mt = 0; mt < MT; ++mt)
; #pragma unroll
;                 for (int rg = 0; rg < 16; ++rg) { const int r = ROWOF(rb, mt, rg); const float v0 = acc[mt][0][rg], v1 = acc[mt][1][rg];
;                     CQ[(size_t)r * 512 + c0] = f2bf(v0 * g0); CQ[(size_t)r * 512 + c1] = f2bf(v1 * g1);
;                     const float s = halfsum32(v0 * v0 + v1 * v1); if (n == 0) atomicAdd(SSQ + r, s); }
.LBB0_900:
	s_or_b64 exec, exec, s[0:1]
	v_or_b32_e32 v64, 10, v96
	v_mul_f32_e32 v65, v86, v103
	v_cvt_pk_bf16_f32 v68, v65, v65
	v_ashrrev_i32_e32 v65, 31, v64
	s_waitcnt lgkmcnt(0)
	v_lshlrev_b64 v[66:67], 10, v[64:65]
	v_lshl_add_u64 v[66:67], s[20:21], 0, v[66:67]
	v_lshl_add_u64 v[66:67], v[98:99], 1, v[66:67]
	global_store_short v[66:67], v68, off
	v_mul_f32_e32 v68, v70, v102
	v_cvt_pk_bf16_f32 v68, v68, v68
	global_store_short v[66:67], v68, off offset:64
	v_mul_f32_e32 v66, v70, v70
	v_fmac_f32_e32 v66, v86, v86
	s_nop 1
	v_add_f32_dpp v66, v66, v66 quad_perm:[1,0,3,2] row_mask:0xf bank_mask:0xf
	s_nop 1
	v_add_f32_dpp v66, v66, v66 quad_perm:[2,3,0,1] row_mask:0xf bank_mask:0xf
	s_nop 1
	v_add_f32_dpp v66, v66, v66 row_half_mirror row_mask:0xf bank_mask:0xf
	s_nop 1
	v_add_f32_dpp v66, v66, v66 row_mirror row_mask:0xf bank_mask:0xf
	ds_bpermute_b32 v67, v107, v66
	s_and_saveexec_b64 s[0:1], s[4:5]
	s_cbranch_execz .LBB0_902
	v_lshl_add_u64 v[64:65], v[64:65], 2, s[18:19]
	s_waitcnt lgkmcnt(0)
	v_add_f32_e32 v66, v66, v67
	global_atomic_add_f32 v[64:65], v66, off
.LBB0_902:
	s_or_b64 exec, exec, s[0:1]
	v_or_b32_e32 v64, 11, v96
	v_mul_f32_e32 v65, v87, v103
	v_cvt_pk_bf16_f32 v68, v65, v65
	v_ashrrev_i32_e32 v65, 31, v64
	s_waitcnt lgkmcnt(0)
	v_lshlrev_b64 v[66:67], 10, v[64:65]
	v_lshl_add_u64 v[66:67], s[20:21], 0, v[66:67]
	v_lshl_add_u64 v[66:67], v[98:99], 1, v[66:67]
	global_store_short v[66:67], v68, off
	v_mul_f32_e32 v68, v71, v102
	v_cvt_pk_bf16_f32 v68, v68, v68
	global_store_short v[66:67], v68, off offset:64
	v_mul_f32_e32 v66, v71, v71
	v_fmac_f32_e32 v66, v87, v87
	s_nop 1
	v_add_f32_dpp v66, v66, v66 quad_perm:[1,0,3,2] row_mask:0xf bank_mask:0xf
	s_nop 1
	v_add_f32_dpp v66, v66, v66 quad_perm:[2,3,0,1] row_mask:0xf bank_mask:0xf
	s_nop 1
	v_add_f32_dpp v66, v66, v66 row_half_mirror row_mask:0xf bank_mask:0xf
	s_nop 1
	v_add_f32_dpp v66, v66, v66 row_mirror row_mask:0xf bank_mask:0xf
	ds_bpermute_b32 v67, v107, v66
	s_and_saveexec_b64 s[0:1], s[4:5]
	s_cbranch_execz .LBB0_904
	v_lshl_add_u64 v[64:65], v[64:65], 2, s[18:19]
	s_waitcnt lgkmcnt(0)
	v_add_f32_e32 v66, v66, v67
	global_atomic_add_f32 v[64:65], v66, off
.LBB0_904:
	s_or_b64 exec, exec, s[0:1]
	v_or_b32_e32 v64, 16, v96
	v_mul_f32_e32 v65, v88, v103
	v_cvt_pk_bf16_f32 v68, v65, v65
	v_ashrrev_i32_e32 v65, 31, v64
	s_waitcnt lgkmcnt(0)
	v_lshlrev_b64 v[66:67], 10, v[64:65]
	v_lshl_add_u64 v[66:67], s[20:21], 0, v[66:67]
	v_lshl_add_u64 v[66:67], v[98:99], 1, v[66:67]
	global_store_short v[66:67], v68, off
	v_mul_f32_e32 v68, v72, v102
	v_cvt_pk_bf16_f32 v68, v68, v68
	global_store_short v[66:67], v68, off offset:64
	v_mul_f32_e32 v66, v72, v72
	v_fmac_f32_e32 v66, v88, v88
	s_nop 1
	v_add_f32_dpp v66, v66, v66 quad_perm:[1,0,3,2] row_mask:0xf bank_mask:0xf
	s_nop 1
	v_add_f32_dpp v66, v66, v66 quad_perm:[2,3,0,1] row_mask:0xf bank_mask:0xf
	s_nop 1
	v_add_f32_dpp v66, v66, v66 row_half_mirror row_mask:0xf bank_mask:0xf
	s_nop 1
	v_add_f32_dpp v66, v66, v66 row_mirror row_mask:0xf bank_mask:0xf
	ds_bpermute_b32 v67, v107, v66
	s_and_saveexec_b64 s[0:1], s[4:5]
	s_cbranch_execz .LBB0_906
	v_lshl_add_u64 v[64:65], v[64:65], 2, s[18:19]
	s_waitcnt lgkmcnt(0)
	v_add_f32_e32 v66, v66, v67
	global_atomic_add_f32 v[64:65], v66, off
.LBB0_906:
	s_or_b64 exec, exec, s[0:1]
	v_or_b32_e32 v64, 17, v96
	v_mul_f32_e32 v65, v89, v103
	v_cvt_pk_bf16_f32 v68, v65, v65
	v_ashrrev_i32_e32 v65, 31, v64
	s_waitcnt lgkmcnt(0)
	v_lshlrev_b64 v[66:67], 10, v[64:65]
	v_lshl_add_u64 v[66:67], s[20:21], 0, v[66:67]
	v_lshl_add_u64 v[66:67], v[98:99], 1, v[66:67]
	global_store_short v[66:67], v68, off
	v_mul_f32_e32 v68, v73, v102
	v_cvt_pk_bf16_f32 v68, v68, v68
	global_store_short v[66:67], v68, off offset:64
	v_mul_f32_e32 v66, v73, v73
	v_fmac_f32_e32 v66, v89, v89
	s_nop 1
	v_add_f32_dpp v66, v66, v66 quad_perm:[1,0,3,2] row_mask:0xf bank_mask:0xf
	s_nop 1
	v_add_f32_dpp v66, v66, v66 quad_perm:[2,3,0,1] row_mask:0xf bank_mask:0xf
	s_nop 1
	v_add_f32_dpp v66, v66, v66 row_half_mirror row_mask:0xf bank_mask:0xf
	s_nop 1
	v_add_f32_dpp v66, v66, v66 row_mirror row_mask:0xf bank_mask:0xf
	ds_bpermute_b32 v67, v107, v66
	s_and_saveexec_b64 s[0:1], s[4:5]
	s_cbranch_execz .LBB0_908
	v_lshl_add_u64 v[64:65], v[64:65], 2, s[18:19]
	s_waitcnt lgkmcnt(0)
	v_add_f32_e32 v66, v66, v67
	global_atomic_add_f32 v[64:65], v66, off
; __device__ __forceinline__ bf16_t f2bf(float f) { return (bf16_t)(pk_bf16(f, f) & 0xffffu); }
; __device__ __forceinline__ float halfsum32(float s) {
;     s += __shfl_xor(s, 1); s += __shfl_xor(s, 2); s += __shfl_xor(s, 4); s += __shfl_xor(s, 8); s += __shfl_xor(s, 16); return s;
; }
;     template <int MT> __device__ __forceinline__ void run(const Params& P, f32x16 (&acc)[MT][2], int rbase, int pn, int wc, int lane) const {
;     ...
;             bf16_t* CQ = (bf16_t*)(ws + OFF_CQ); float* SSQ = (float*)(ws + OFF_SSQQ);
;             const int c0 = pn * 128 + wc * 64 + n, c1 = c0 + 32; const float g0 = P.gq[c0], g1 = P.gq[c1];
; #pragma unroll
;             for (int mt = 0; mt < MT; ++mt)
; #pragma unroll
;                 for (int rg = 0; rg < 16; ++rg) { const int r = ROWOF(rb, mt, rg); const float v0 = acc[mt][0][rg], v1 = acc[mt][1][rg];
;                     CQ[(size_t)r * 512 + c0] = f2bf(v0 * g0); CQ[(size_t)r * 512 + c1] = f2bf(v1 * g1);
;                     const float s = halfsum32(v0 * v0 + v1 * v1); if (n == 0) atomicAdd(SSQ + r, s); }
.LBB0_908:
	s_or_b64 exec, exec, s[0:1]
	v_or_b32_e32 v64, 18, v96
	v_mul_f32_e32 v65, v90, v103
	v_cvt_pk_bf16_f32 v68, v65, v65
	v_ashrrev_i32_e32 v65, 31, v64
	s_waitcnt lgkmcnt(0)
	v_lshlrev_b64 v[66:67], 10, v[64:65]
	v_lshl_add_u64 v[66:67], s[20:21], 0, v[66:67]
	v_lshl_add_u64 v[66:67], v[98:99], 1, v[66:67]
	global_store_short v[66:67], v68, off
	v_mul_f32_e32 v68, v74, v102
	v_cvt_pk_bf16_f32 v68, v68, v68
	global_store_short v[66:67], v68, off offset:64
	v_mul_f32_e32 v66, v74, v74
	v_fmac_f32_e32 v66, v90, v90
	s_nop 1
	v_add_f32_dpp v66, v66, v66 quad_perm:[1,0,3,2] row_mask:0xf bank_mask:0xf
	s_nop 1
	v_add_f32_dpp v66, v66, v66 quad_perm:[2,3,0,1] row_mask:0xf bank_mask:0xf
	s_nop 1
	v_add_f32_dpp v66, v66, v66 row_half_mirror row_mask:0xf bank_mask:0xf
	s_nop 1
	v_add_f32_dpp v66, v66, v66 row_mirror row_mask:0xf bank_mask:0xf
	ds_bpermute_b32 v67, v107, v66
	s_and_saveexec_b64 s[0:1], s[4:5]
	s_cbranch_execz .LBB0_910
	v_lshl_add_u64 v[64:65], v[64:65], 2, s[18:19]
	s_waitcnt lgkmcnt(0)
	v_add_f32_e32 v66, v66, v67
	global_atomic_add_f32 v[64:65], v66, off
.LBB0_910:
	s_or_b64 exec, exec, s[0:1]
	v_or_b32_e32 v64, 19, v96
	v_mul_f32_e32 v65, v91, v103
	v_cvt_pk_bf16_f32 v68, v65, v65
	v_ashrrev_i32_e32 v65, 31, v64
	s_waitcnt lgkmcnt(0)
	v_lshlrev_b64 v[66:67], 10, v[64:65]
	v_lshl_add_u64 v[66:67], s[20:21], 0, v[66:67]
	v_lshl_add_u64 v[66:67], v[98:99], 1, v[66:67]
	global_store_short v[66:67], v68, off
	v_mul_f32_e32 v68, v75, v102
	v_cvt_pk_bf16_f32 v68, v68, v68
	global_store_short v[66:67], v68, off offset:64
	v_mul_f32_e32 v66, v75, v75
	v_fmac_f32_e32 v66, v91, v91
	s_nop 1
	v_add_f32_dpp v66, v66, v66 quad_perm:[1,0,3,2] row_mask:0xf bank_mask:0xf
	s_nop 1
	v_add_f32_dpp v66, v66, v66 quad_perm:[2,3,0,1] row_mask:0xf bank_mask:0xf
	s_nop 1
	v_add_f32_dpp v66, v66, v66 row_half_mirror row_mask:0xf bank_mask:0xf
	s_nop 1
	v_add_f32_dpp v66, v66, v66 row_mirror row_mask:0xf bank_mask:0xf
	ds_bpermute_b32 v67, v107, v66
	s_and_saveexec_b64 s[0:1], s[4:5]
	s_cbranch_execz .LBB0_912
	v_lshl_add_u64 v[64:65], v[64:65], 2, s[18:19]
	s_waitcnt lgkmcnt(0)
	v_add_f32_e32 v66, v66, v67
	global_atomic_add_f32 v[64:65], v66, off
.LBB0_912:
	s_or_b64 exec, exec, s[0:1]
	v_or_b32_e32 v64, 24, v96
	v_mul_f32_e32 v65, v92, v103
	v_cvt_pk_bf16_f32 v68, v65, v65
	v_ashrrev_i32_e32 v65, 31, v64
	s_waitcnt lgkmcnt(0)
	v_lshlrev_b64 v[66:67], 10, v[64:65]
	v_lshl_add_u64 v[66:67], s[20:21], 0, v[66:67]
	v_lshl_add_u64 v[66:67], v[98:99], 1, v[66:67]
	global_store_short v[66:67], v68, off
	v_mul_f32_e32 v68, v76, v102
	v_cvt_pk_bf16_f32 v68, v68, v68
	global_store_short v[66:67], v68, off offset:64
	v_mul_f32_e32 v66, v76, v76
	v_fmac_f32_e32 v66, v92, v92
	s_nop 1
	v_add_f32_dpp v66, v66, v66 quad_perm:[1,0,3,2] row_mask:0xf bank_mask:0xf
	s_nop 1
	v_add_f32_dpp v66, v66, v66 quad_perm:[2,3,0,1] row_mask:0xf bank_mask:0xf
	s_nop 1
	v_add_f32_dpp v66, v66, v66 row_half_mirror row_mask:0xf bank_mask:0xf
	s_nop 1
	v_add_f32_dpp v66, v66, v66 row_mirror row_mask:0xf bank_mask:0xf
	ds_bpermute_b32 v67, v107, v66
	s_and_saveexec_b64 s[0:1], s[4:5]
	s_cbranch_execz .LBB0_914
	v_lshl_add_u64 v[64:65], v[64:65], 2, s[18:19]
	s_waitcnt lgkmcnt(0)
	v_add_f32_e32 v66, v66, v67
	global_atomic_add_f32 v[64:65], v66, off
.LBB0_914:
	s_or_b64 exec, exec, s[0:1]
	v_or_b32_e32 v64, 25, v96
	v_mul_f32_e32 v65, v93, v103
	v_cvt_pk_bf16_f32 v68, v65, v65
	v_ashrrev_i32_e32 v65, 31, v64
	s_waitcnt lgkmcnt(0)
	v_lshlrev_b64 v[66:67], 10, v[64:65]
	v_lshl_add_u64 v[66:67], s[20:21], 0, v[66:67]
	v_lshl_add_u64 v[66:67], v[98:99], 1, v[66:67]
	global_store_short v[66:67], v68, off
	v_mul_f32_e32 v68, v77, v102
	v_cvt_pk_bf16_f32 v68, v68, v68
	global_store_short v[66:67], v68, off offset:64
	v_mul_f32_e32 v66, v77, v77
	v_fmac_f32_e32 v66, v93, v93
	s_nop 1
	v_add_f32_dpp v66, v66, v66 quad_perm:[1,0,3,2] row_mask:0xf bank_mask:0xf
	s_nop 1
	v_add_f32_dpp v66, v66, v66 quad_perm:[2,3,0,1] row_mask:0xf bank_mask:0xf
	s_nop 1
	v_add_f32_dpp v66, v66, v66 row_half_mirror row_mask:0xf bank_mask:0xf
	s_nop 1
	v_add_f32_dpp v66, v66, v66 row_mirror row_mask:0xf bank_mask:0xf
	ds_bpermute_b32 v67, v107, v66
	s_and_saveexec_b64 s[0:1], s[4:5]
	s_cbranch_execz .LBB0_916
	v_lshl_add_u64 v[64:65], v[64:65], 2, s[18:19]
	s_waitcnt lgkmcnt(0)
	v_add_f32_e32 v66, v66, v67
	global_atomic_add_f32 v[64:65], v66, off
.LBB0_916:
	s_or_b64 exec, exec, s[0:1]
	v_or_b32_e32 v64, 26, v96
	v_mul_f32_e32 v65, v94, v103
	v_cvt_pk_bf16_f32 v68, v65, v65
	v_ashrrev_i32_e32 v65, 31, v64
	s_waitcnt lgkmcnt(0)
	v_lshlrev_b64 v[66:67], 10, v[64:65]
	v_lshl_add_u64 v[66:67], s[20:21], 0, v[66:67]
	v_lshl_add_u64 v[66:67], v[98:99], 1, v[66:67]
	global_store_short v[66:67], v68, off
	v_mul_f32_e32 v68, v78, v102
	v_cvt_pk_bf16_f32 v68, v68, v68
	global_store_short v[66:67], v68, off offset:64
	v_mul_f32_e32 v66, v78, v78
	v_fmac_f32_e32 v66, v94, v94
	s_nop 1
	v_add_f32_dpp v66, v66, v66 quad_perm:[1,0,3,2] row_mask:0xf bank_mask:0xf
	s_nop 1
	v_add_f32_dpp v66, v66, v66 quad_perm:[2,3,0,1] row_mask:0xf bank_mask:0xf
	s_nop 1
	v_add_f32_dpp v66, v66, v66 row_half_mirror row_mask:0xf bank_mask:0xf
	s_nop 1
	v_add_f32_dpp v66, v66, v66 row_mirror row_mask:0xf bank_mask:0xf
	ds_bpermute_b32 v67, v107, v66
	s_and_saveexec_b64 s[0:1], s[4:5]
	s_cbranch_execz .LBB0_918
	v_lshl_add_u64 v[64:65], v[64:65], 2, s[18:19]
	s_waitcnt lgkmcnt(0)
	v_add_f32_e32 v66, v66, v67
	global_atomic_add_f32 v[64:65], v66, off

; __device__ __forceinline__ bf16_t f2bf(float f) { return (bf16_t)(pk_bf16(f, f) & 0xffffu); }
; __device__ __forceinline__ float halfsum32(float s) {
;     s += __shfl_xor(s, 1); s += __shfl_xor(s, 2); s += __shfl_xor(s, 4); s += __shfl_xor(s, 8); s += __shfl_xor(s, 16); return s;
; }
;     template <int MT> __device__ __forceinline__ void run(const Params& P, f32x16 (&acc)[MT][2], int rbase, int pn, int wc, int lane) const {
;     ...
;             bf16_t* CQ = (bf16_t*)(ws + OFF_CQ); float* SSQ = (float*)(ws + OFF_SSQQ);
;             const int c0 = pn * 128 + wc * 64 + n, c1 = c0 + 32; const float g0 = P.gq[c0], g1 = P.gq[c1];
; #pragma unroll
;             for (int mt = 0; mt < MT; ++mt)
; #pragma unroll
;                 for (int rg = 0; rg < 16; ++rg) { const int r = ROWOF(rb, mt, rg); const float v0 = acc[mt][0][rg], v1 = acc[mt][1][rg];
;                     CQ[(size_t)r * 512 + c0] = f2bf(v0 * g0); CQ[(size_t)r * 512 + c1] = f2bf(v1 * g1);
;                     const float s = halfsum32(v0 * v0 + v1 * v1); if (n == 0) atomicAdd(SSQ + r, s); }
.LBB0_922:
	s_or_b64 exec, exec, s[0:1]
	v_add_u32_e32 v64, 33, v96
	v_ashrrev_i32_e32 v65, 31, v64
	v_lshlrev_b64 v[66:67], 10, v[64:65]
	v_mul_f32_e32 v32, v49, v103
	v_lshl_add_u64 v[66:67], s[20:21], 0, v[66:67]
	v_cvt_pk_bf16_f32 v32, v32, v32
	v_lshl_add_u64 v[66:67], v[98:99], 1, v[66:67]
	global_store_short v[66:67], v32, off
	v_mul_f32_e32 v32, v33, v102
	v_cvt_pk_bf16_f32 v32, v32, v32
	global_store_short v[66:67], v32, off offset:64
	v_mul_f32_e32 v32, v33, v33
	v_fmac_f32_e32 v32, v49, v49
	s_nop 1
	v_add_f32_dpp v32, v32, v32 quad_perm:[1,0,3,2] row_mask:0xf bank_mask:0xf
	s_nop 1
	v_add_f32_dpp v32, v32, v32 quad_perm:[2,3,0,1] row_mask:0xf bank_mask:0xf
	s_nop 1
	v_add_f32_dpp v32, v32, v32 row_half_mirror row_mask:0xf bank_mask:0xf
	s_nop 1
	v_add_f32_dpp v32, v32, v32 row_mirror row_mask:0xf bank_mask:0xf
	ds_bpermute_b32 v33, v107, v32
	s_and_saveexec_b64 s[0:1], s[4:5]
	s_cbranch_execz .LBB0_924
	v_lshl_add_u64 v[48:49], v[64:65], 2, s[18:19]
	s_waitcnt lgkmcnt(0)
	v_add_f32_e32 v32, v32, v33
	global_atomic_add_f32 v[48:49], v32, off
.LBB0_924:
	s_or_b64 exec, exec, s[0:1]
	v_add_u32_e32 v32, 34, v96
	s_waitcnt lgkmcnt(0)
	v_mul_f32_e32 v33, v50, v103
	v_cvt_pk_bf16_f32 v64, v33, v33
	v_ashrrev_i32_e32 v33, 31, v32
	v_lshlrev_b64 v[48:49], 10, v[32:33]
	v_lshl_add_u64 v[48:49], s[20:21], 0, v[48:49]
	v_lshl_add_u64 v[48:49], v[98:99], 1, v[48:49]
	global_store_short v[48:49], v64, off
	v_mul_f32_e32 v64, v34, v102
	v_mul_f32_e32 v34, v34, v34
	v_fmac_f32_e32 v34, v50, v50
	v_cvt_pk_bf16_f32 v64, v64, v64
	global_store_short v[48:49], v64, off offset:64
	s_nop 1
	v_add_f32_dpp v34, v34, v34 quad_perm:[1,0,3,2] row_mask:0xf bank_mask:0xf
	s_nop 1
	v_add_f32_dpp v34, v34, v34 quad_perm:[2,3,0,1] row_mask:0xf bank_mask:0xf
	s_nop 1
	v_add_f32_dpp v34, v34, v34 row_half_mirror row_mask:0xf bank_mask:0xf
	s_nop 1
	v_add_f32_dpp v34, v34, v34 row_mirror row_mask:0xf bank_mask:0xf
	ds_bpermute_b32 v48, v107, v34
	s_and_saveexec_b64 s[0:1], s[4:5]
	s_cbranch_execz .LBB0_926
	v_lshl_add_u64 v[32:33], v[32:33], 2, s[18:19]
	s_waitcnt lgkmcnt(0)
	v_add_f32_e32 v34, v34, v48
	global_atomic_add_f32 v[32:33], v34, off
.LBB0_926:
	s_or_b64 exec, exec, s[0:1]
	v_add_u32_e32 v32, 35, v96
	v_mul_f32_e32 v33, v51, v103
	v_cvt_pk_bf16_f32 v34, v33, v33
	v_ashrrev_i32_e32 v33, 31, v32
	s_waitcnt lgkmcnt(0)
	v_lshlrev_b64 v[48:49], 10, v[32:33]
	v_lshl_add_u64 v[48:49], s[20:21], 0, v[48:49]
	v_lshl_add_u64 v[48:49], v[98:99], 1, v[48:49]
	global_store_short v[48:49], v34, off
	v_mul_f32_e32 v34, v35, v102
	v_cvt_pk_bf16_f32 v34, v34, v34
	global_store_short v[48:49], v34, off offset:64
	v_mul_f32_e32 v34, v35, v35
	v_fmac_f32_e32 v34, v51, v51
	s_nop 1
	v_add_f32_dpp v34, v34, v34 quad_perm:[1,0,3,2] row_mask:0xf bank_mask:0xf
	s_nop 1
	v_add_f32_dpp v34, v34, v34 quad_perm:[2,3,0,1] row_mask:0xf bank_mask:0xf
	s_nop 1
	v_add_f32_dpp v34, v34, v34 row_half_mirror row_mask:0xf bank_mask:0xf
	s_nop 1
	v_add_f32_dpp v34, v34, v34 row_mirror row_mask:0xf bank_mask:0xf
	ds_bpermute_b32 v35, v107, v34
	s_and_saveexec_b64 s[0:1], s[4:5]
	s_cbranch_execz .LBB0_928
	v_lshl_add_u64 v[32:33], v[32:33], 2, s[18:19]
	s_waitcnt lgkmcnt(0)
	v_add_f32_e32 v34, v34, v35
	global_atomic_add_f32 v[32:33], v34, off
.LBB0_928:
	s_or_b64 exec, exec, s[0:1]
	v_add_u32_e32 v32, 40, v96
	v_mul_f32_e32 v33, v52, v103
	v_cvt_pk_bf16_f32 v48, v33, v33
	v_ashrrev_i32_e32 v33, 31, v32
	s_waitcnt lgkmcnt(0)
	v_lshlrev_b64 v[34:35], 10, v[32:33]
	v_lshl_add_u64 v[34:35], s[20:21], 0, v[34:35]
	v_lshl_add_u64 v[34:35], v[98:99], 1, v[34:35]
	global_store_short v[34:35], v48, off
	v_mul_f32_e32 v48, v36, v102
	v_cvt_pk_bf16_f32 v48, v48, v48
	global_store_short v[34:35], v48, off offset:64
	v_mul_f32_e32 v34, v36, v36
	v_fmac_f32_e32 v34, v52, v52
	s_nop 1
	v_add_f32_dpp v34, v34, v34 quad_perm:[1,0,3,2] row_mask:0xf bank_mask:0xf
	s_nop 1
	v_add_f32_dpp v34, v34, v34 quad_perm:[2,3,0,1] row_mask:0xf bank_mask:0xf
	s_nop 1
	v_add_f32_dpp v34, v34, v34 row_half_mirror row_mask:0xf bank_mask:0xf
	s_nop 1
	v_add_f32_dpp v34, v34, v34 row_mirror row_mask:0xf bank_mask:0xf
	ds_bpermute_b32 v35, v107, v34
	s_and_saveexec_b64 s[0:1], s[4:5]
	s_cbranch_execz .LBB0_930
	v_lshl_add_u64 v[32:33], v[32:33], 2, s[18:19]
	s_waitcnt lgkmcnt(0)
	v_add_f32_e32 v34, v34, v35
	global_atomic_add_f32 v[32:33], v34, off
.LBB0_930:
	s_or_b64 exec, exec, s[0:1]
	v_add_u32_e32 v32, 41, v96
	v_mul_f32_e32 v33, v53, v103
	v_cvt_pk_bf16_f32 v36, v33, v33
	v_ashrrev_i32_e32 v33, 31, v32
	s_waitcnt lgkmcnt(0)
	v_lshlrev_b64 v[34:35], 10, v[32:33]
	v_lshl_add_u64 v[34:35], s[20:21], 0, v[34:35]
	v_lshl_add_u64 v[34:35], v[98:99], 1, v[34:35]
	global_store_short v[34:35], v36, off
	v_mul_f32_e32 v36, v37, v102
	v_cvt_pk_bf16_f32 v36, v36, v36
	global_store_short v[34:35], v36, off offset:64
	v_mul_f32_e32 v34, v37, v37
	v_fmac_f32_e32 v34, v53, v53
	s_nop 1
	v_add_f32_dpp v34, v34, v34 quad_perm:[1,0,3,2] row_mask:0xf bank_mask:0xf
	s_nop 1
	v_add_f32_dpp v34, v34, v34 quad_perm:[2,3,0,1] row_mask:0xf bank_mask:0xf
	s_nop 1
	v_add_f32_dpp v34, v34, v34 row_half_mirror row_mask:0xf bank_mask:0xf
	s_nop 1
	v_add_f32_dpp v34, v34, v34 row_mirror row_mask:0xf bank_mask:0xf
	ds_bpermute_b32 v35, v107, v34
	s_and_saveexec_b64 s[0:1], s[4:5]
	s_cbranch_execz .LBB0_932
	v_lshl_add_u64 v[32:33], v[32:33], 2, s[18:19]
	s_waitcnt lgkmcnt(0)
	v_add_f32_e32 v34, v34, v35
	global_atomic_add_f32 v[32:33], v34, off
; __device__ __forceinline__ bf16_t f2bf(float f) { return (bf16_t)(pk_bf16(f, f) & 0xffffu); }
; __device__ __forceinline__ float halfsum32(float s) {
;     s += __shfl_xor(s, 1); s += __shfl_xor(s, 2); s += __shfl_xor(s, 4); s += __shfl_xor(s, 8); s += __shfl_xor(s, 16); return s;
; }
;     template <int MT> __device__ __forceinline__ void run(const Params& P, f32x16 (&acc)[MT][2], int rbase, int pn, int wc, int lane) const {
;     ...
;             bf16_t* CQ = (bf16_t*)(ws + OFF_CQ); float* SSQ = (float*)(ws + OFF_SSQQ);
;             const int c0 = pn * 128 + wc * 64 + n, c1 = c0 + 32; const float g0 = P.gq[c0], g1 = P.gq[c1];
; #pragma unroll
;             for (int mt = 0; mt < MT; ++mt)
; #pragma unroll
;                 for (int rg = 0; rg < 16; ++rg) { const int r = ROWOF(rb, mt, rg); const float v0 = acc[mt][0][rg], v1 = acc[mt][1][rg];
;                     CQ[(size_t)r * 512 + c0] = f2bf(v0 * g0); CQ[(size_t)r * 512 + c1] = f2bf(v1 * g1);
;                     const float s = halfsum32(v0 * v0 + v1 * v1); if (n == 0) atomicAdd(SSQ + r, s); }
.LBB0_932:
	s_or_b64 exec, exec, s[0:1]
	v_add_u32_e32 v32, 42, v96
	v_mul_f32_e32 v33, v54, v103
	v_cvt_pk_bf16_f32 v36, v33, v33
	v_ashrrev_i32_e32 v33, 31, v32
	s_waitcnt lgkmcnt(0)
	v_lshlrev_b64 v[34:35], 10, v[32:33]
	v_lshl_add_u64 v[34:35], s[20:21], 0, v[34:35]
	v_lshl_add_u64 v[34:35], v[98:99], 1, v[34:35]
	global_store_short v[34:35], v36, off
	v_mul_f32_e32 v36, v38, v102
	v_cvt_pk_bf16_f32 v36, v36, v36
	global_store_short v[34:35], v36, off offset:64
	v_mul_f32_e32 v34, v38, v38
	v_fmac_f32_e32 v34, v54, v54
	s_nop 1
	v_add_f32_dpp v34, v34, v34 quad_perm:[1,0,3,2] row_mask:0xf bank_mask:0xf
	s_nop 1
	v_add_f32_dpp v34, v34, v34 quad_perm:[2,3,0,1] row_mask:0xf bank_mask:0xf
	s_nop 1
	v_add_f32_dpp v34, v34, v34 row_half_mirror row_mask:0xf bank_mask:0xf
	s_nop 1
	v_add_f32_dpp v34, v34, v34 row_mirror row_mask:0xf bank_mask:0xf
	ds_bpermute_b32 v35, v107, v34
	s_and_saveexec_b64 s[0:1], s[4:5]
	s_cbranch_execz .LBB0_934
	v_lshl_add_u64 v[32:33], v[32:33], 2, s[18:19]
	s_waitcnt lgkmcnt(0)
	v_add_f32_e32 v34, v34, v35
	global_atomic_add_f32 v[32:33], v34, off
.LBB0_934:
	s_or_b64 exec, exec, s[0:1]
	v_add_u32_e32 v32, 43, v96
	v_mul_f32_e32 v33, v55, v103
	v_cvt_pk_bf16_f32 v36, v33, v33
	v_ashrrev_i32_e32 v33, 31, v32
	s_waitcnt lgkmcnt(0)
	v_lshlrev_b64 v[34:35], 10, v[32:33]
	v_lshl_add_u64 v[34:35], s[20:21], 0, v[34:35]
	v_lshl_add_u64 v[34:35], v[98:99], 1, v[34:35]
	global_store_short v[34:35], v36, off
	v_mul_f32_e32 v36, v39, v102
	v_cvt_pk_bf16_f32 v36, v36, v36
	global_store_short v[34:35], v36, off offset:64
	v_mul_f32_e32 v34, v39, v39
	v_fmac_f32_e32 v34, v55, v55
	s_nop 1
	v_add_f32_dpp v34, v34, v34 quad_perm:[1,0,3,2] row_mask:0xf bank_mask:0xf
	s_nop 1
	v_add_f32_dpp v34, v34, v34 quad_perm:[2,3,0,1] row_mask:0xf bank_mask:0xf
	s_nop 1
	v_add_f32_dpp v34, v34, v34 row_half_mirror row_mask:0xf bank_mask:0xf
	s_nop 1
	v_add_f32_dpp v34, v34, v34 row_mirror row_mask:0xf bank_mask:0xf
	ds_bpermute_b32 v35, v107, v34
	s_and_saveexec_b64 s[0:1], s[4:5]
	s_cbranch_execz .LBB0_936
	v_lshl_add_u64 v[32:33], v[32:33], 2, s[18:19]
	s_waitcnt lgkmcnt(0)
	v_add_f32_e32 v34, v34, v35
	global_atomic_add_f32 v[32:33], v34, off
.LBB0_936:
	s_or_b64 exec, exec, s[0:1]
	v_add_u32_e32 v32, 48, v96
	v_mul_f32_e32 v33, v56, v103
	v_cvt_pk_bf16_f32 v36, v33, v33
	v_ashrrev_i32_e32 v33, 31, v32
	s_waitcnt lgkmcnt(0)
	v_lshlrev_b64 v[34:35], 10, v[32:33]
	v_lshl_add_u64 v[34:35], s[20:21], 0, v[34:35]
	v_lshl_add_u64 v[34:35], v[98:99], 1, v[34:35]
	global_store_short v[34:35], v36, off
	v_mul_f32_e32 v36, v40, v102
	v_cvt_pk_bf16_f32 v36, v36, v36
	global_store_short v[34:35], v36, off offset:64
	v_mul_f32_e32 v34, v40, v40
	v_fmac_f32_e32 v34, v56, v56
	s_nop 1
	v_add_f32_dpp v34, v34, v34 quad_perm:[1,0,3,2] row_mask:0xf bank_mask:0xf
	s_nop 1
	v_add_f32_dpp v34, v34, v34 quad_perm:[2,3,0,1] row_mask:0xf bank_mask:0xf
	s_nop 1
	v_add_f32_dpp v34, v34, v34 row_half_mirror row_mask:0xf bank_mask:0xf
	s_nop 1
	v_add_f32_dpp v34, v34, v34 row_mirror row_mask:0xf bank_mask:0xf
	ds_bpermute_b32 v35, v107, v34
	s_and_saveexec_b64 s[0:1], s[4:5]
	s_cbranch_execz .LBB0_938
	v_lshl_add_u64 v[32:33], v[32:33], 2, s[18:19]
	s_waitcnt lgkmcnt(0)
	v_add_f32_e32 v34, v34, v35
	global_atomic_add_f32 v[32:33], v34, off
.LBB0_938:
	s_or_b64 exec, exec, s[0:1]
	v_add_u32_e32 v32, 49, v96
	v_mul_f32_e32 v33, v57, v103
	v_cvt_pk_bf16_f32 v36, v33, v33
	v_ashrrev_i32_e32 v33, 31, v32
	s_waitcnt lgkmcnt(0)
	v_lshlrev_b64 v[34:35], 10, v[32:33]
	v_lshl_add_u64 v[34:35], s[20:21], 0, v[34:35]
	v_lshl_add_u64 v[34:35], v[98:99], 1, v[34:35]
	global_store_short v[34:35], v36, off
	v_mul_f32_e32 v36, v41, v102
	v_cvt_pk_bf16_f32 v36, v36, v36
	global_store_short v[34:35], v36, off offset:64
	v_mul_f32_e32 v34, v41, v41
	v_fmac_f32_e32 v34, v57, v57
	s_nop 1
	v_add_f32_dpp v34, v34, v34 quad_perm:[1,0,3,2] row_mask:0xf bank_mask:0xf
	s_nop 1
	v_add_f32_dpp v34, v34, v34 quad_perm:[2,3,0,1] row_mask:0xf bank_mask:0xf
	s_nop 1
	v_add_f32_dpp v34, v34, v34 row_half_mirror row_mask:0xf bank_mask:0xf
	s_nop 1
	v_add_f32_dpp v34, v34, v34 row_mirror row_mask:0xf bank_mask:0xf
	ds_bpermute_b32 v35, v107, v34
	s_and_saveexec_b64 s[0:1], s[4:5]
	s_cbranch_execz .LBB0_940
	v_lshl_add_u64 v[32:33], v[32:33], 2, s[18:19]
	s_waitcnt lgkmcnt(0)
	v_add_f32_e32 v34, v34, v35
	global_atomic_add_f32 v[32:33], v34, off
; __device__ __forceinline__ bf16_t f2bf(float f) { return (bf16_t)(pk_bf16(f, f) & 0xffffu); }
; __device__ __forceinline__ float halfsum32(float s) {
;     s += __shfl_xor(s, 1); s += __shfl_xor(s, 2); s += __shfl_xor(s, 4); s += __shfl_xor(s, 8); s += __shfl_xor(s, 16); return s;
; }
;     template <int MT> __device__ __forceinline__ void run(const Params& P, f32x16 (&acc)[MT][2], int rbase, int pn, int wc, int lane) const {
;     ...
;             bf16_t* CQ = (bf16_t*)(ws + OFF_CQ); float* SSQ = (float*)(ws + OFF_SSQQ);
;             const int c0 = pn * 128 + wc * 64 + n, c1 = c0 + 32; const float g0 = P.gq[c0], g1 = P.gq[c1];
; #pragma unroll
;             for (int mt = 0; mt < MT; ++mt)
; #pragma unroll
;                 for (int rg = 0; rg < 16; ++rg) { const int r = ROWOF(rb, mt, rg); const float v0 = acc[mt][0][rg], v1 = acc[mt][1][rg];
;                     CQ[(size_t)r * 512 + c0] = f2bf(v0 * g0); CQ[(size_t)r * 512 + c1] = f2bf(v1 * g1);
;                     const float s = halfsum32(v0 * v0 + v1 * v1); if (n == 0) atomicAdd(SSQ + r, s); }
.LBB0_940:
	s_or_b64 exec, exec, s[0:1]
	v_add_u32_e32 v32, 50, v96
	v_mul_f32_e32 v33, v58, v103
	v_cvt_pk_bf16_f32 v36, v33, v33
	v_ashrrev_i32_e32 v33, 31, v32
	s_waitcnt lgkmcnt(0)
	v_lshlrev_b64 v[34:35], 10, v[32:33]
	v_lshl_add_u64 v[34:35], s[20:21], 0, v[34:35]
	v_lshl_add_u64 v[34:35], v[98:99], 1, v[34:35]
	global_store_short v[34:35], v36, off
	v_mul_f32_e32 v36, v42, v102
	v_cvt_pk_bf16_f32 v36, v36, v36
	global_store_short v[34:35], v36, off offset:64
	v_mul_f32_e32 v34, v42, v42
	v_fmac_f32_e32 v34, v58, v58
	s_nop 1
	v_add_f32_dpp v34, v34, v34 quad_perm:[1,0,3,2] row_mask:0xf bank_mask:0xf
	s_nop 1
	v_add_f32_dpp v34, v34, v34 quad_perm:[2,3,0,1] row_mask:0xf bank_mask:0xf
	s_nop 1
	v_add_f32_dpp v34, v34, v34 row_half_mirror row_mask:0xf bank_mask:0xf
	s_nop 1
	v_add_f32_dpp v34, v34, v34 row_mirror row_mask:0xf bank_mask:0xf
	ds_bpermute_b32 v35, v107, v34
	s_and_saveexec_b64 s[0:1], s[4:5]
	s_cbranch_execz .LBB0_942
	v_lshl_add_u64 v[32:33], v[32:33], 2, s[18:19]
	s_waitcnt lgkmcnt(0)
	v_add_f32_e32 v34, v34, v35
	global_atomic_add_f32 v[32:33], v34, off
.LBB0_942:
	s_or_b64 exec, exec, s[0:1]
	v_add_u32_e32 v32, 51, v96
	v_mul_f32_e32 v33, v59, v103
	v_cvt_pk_bf16_f32 v36, v33, v33
	v_ashrrev_i32_e32 v33, 31, v32
	s_waitcnt lgkmcnt(0)
	v_lshlrev_b64 v[34:35], 10, v[32:33]
	v_lshl_add_u64 v[34:35], s[20:21], 0, v[34:35]
	v_lshl_add_u64 v[34:35], v[98:99], 1, v[34:35]
	global_store_short v[34:35], v36, off
	v_mul_f32_e32 v36, v43, v102
	v_cvt_pk_bf16_f32 v36, v36, v36
	global_store_short v[34:35], v36, off offset:64
	v_mul_f32_e32 v34, v43, v43
	v_fmac_f32_e32 v34, v59, v59
	s_nop 1
	v_add_f32_dpp v34, v34, v34 quad_perm:[1,0,3,2] row_mask:0xf bank_mask:0xf
	s_nop 1
	v_add_f32_dpp v34, v34, v34 quad_perm:[2,3,0,1] row_mask:0xf bank_mask:0xf
	s_nop 1
	v_add_f32_dpp v34, v34, v34 row_half_mirror row_mask:0xf bank_mask:0xf
	s_nop 1
	v_add_f32_dpp v34, v34, v34 row_mirror row_mask:0xf bank_mask:0xf
	ds_bpermute_b32 v35, v107, v34
	s_and_saveexec_b64 s[0:1], s[4:5]
	s_cbranch_execz .LBB0_944
	v_lshl_add_u64 v[32:33], v[32:33], 2, s[18:19]
	s_waitcnt lgkmcnt(0)
	v_add_f32_e32 v34, v34, v35
	global_atomic_add_f32 v[32:33], v34, off
.LBB0_944:
	s_or_b64 exec, exec, s[0:1]
	v_add_u32_e32 v32, 56, v96
	v_mul_f32_e32 v33, v60, v103
	v_cvt_pk_bf16_f32 v36, v33, v33
	v_ashrrev_i32_e32 v33, 31, v32
	s_waitcnt lgkmcnt(0)
	v_lshlrev_b64 v[34:35], 10, v[32:33]
	v_lshl_add_u64 v[34:35], s[20:21], 0, v[34:35]
	v_lshl_add_u64 v[34:35], v[98:99], 1, v[34:35]
	global_store_short v[34:35], v36, off
	v_mul_f32_e32 v36, v44, v102
	v_cvt_pk_bf16_f32 v36, v36, v36
	global_store_short v[34:35], v36, off offset:64
	v_mul_f32_e32 v34, v44, v44
	v_fmac_f32_e32 v34, v60, v60
	s_nop 1
	v_add_f32_dpp v34, v34, v34 quad_perm:[1,0,3,2] row_mask:0xf bank_mask:0xf
	s_nop 1
	v_add_f32_dpp v34, v34, v34 quad_perm:[2,3,0,1] row_mask:0xf bank_mask:0xf
	s_nop 1
	v_add_f32_dpp v34, v34, v34 row_half_mirror row_mask:0xf bank_mask:0xf
	s_nop 1
	v_add_f32_dpp v34, v34, v34 row_mirror row_mask:0xf bank_mask:0xf
	ds_bpermute_b32 v35, v107, v34
	s_and_saveexec_b64 s[0:1], s[4:5]
	s_cbranch_execz .LBB0_946
	v_lshl_add_u64 v[32:33], v[32:33], 2, s[18:19]
	s_waitcnt lgkmcnt(0)
	v_add_f32_e32 v34, v34, v35
	global_atomic_add_f32 v[32:33], v34, off
.LBB0_946:
	s_or_b64 exec, exec, s[0:1]
	v_add_u32_e32 v32, 57, v96
	v_mul_f32_e32 v33, v61, v103
	v_cvt_pk_bf16_f32 v36, v33, v33
	v_ashrrev_i32_e32 v33, 31, v32
	s_waitcnt lgkmcnt(0)
	v_lshlrev_b64 v[34:35], 10, v[32:33]
	v_lshl_add_u64 v[34:35], s[20:21], 0, v[34:35]
	v_lshl_add_u64 v[34:35], v[98:99], 1, v[34:35]
	global_store_short v[34:35], v36, off
	v_mul_f32_e32 v36, v45, v102
	v_cvt_pk_bf16_f32 v36, v36, v36
	global_store_short v[34:35], v36, off offset:64
	v_mul_f32_e32 v34, v45, v45
	v_fmac_f32_e32 v34, v61, v61
	s_nop 1
	v_add_f32_dpp v34, v34, v34 quad_perm:[1,0,3,2] row_mask:0xf bank_mask:0xf
	s_nop 1
	v_add_f32_dpp v34, v34, v34 quad_perm:[2,3,0,1] row_mask:0xf bank_mask:0xf
	s_nop 1
	v_add_f32_dpp v34, v34, v34 row_half_mirror row_mask:0xf bank_mask:0xf
	s_nop 1
	v_add_f32_dpp v34, v34, v34 row_mirror row_mask:0xf bank_mask:0xf
	ds_bpermute_b32 v35, v107, v34
	s_and_saveexec_b64 s[0:1], s[4:5]
	s_cbranch_execz .LBB0_948
	v_lshl_add_u64 v[32:33], v[32:33], 2, s[18:19]
	s_waitcnt lgkmcnt(0)
	v_add_f32_e32 v34, v34, v35
	global_atomic_add_f32 v[32:33], v34, off
.LBB0_948:
	s_or_b64 exec, exec, s[0:1]
	v_add_u32_e32 v32, 58, v96
	v_mul_f32_e32 v33, v62, v103
	v_cvt_pk_bf16_f32 v36, v33, v33
	v_ashrrev_i32_e32 v33, 31, v32
	s_waitcnt lgkmcnt(0)
	v_lshlrev_b64 v[34:35], 10, v[32:33]
	v_lshl_add_u64 v[34:35], s[20:21], 0, v[34:35]
	v_lshl_add_u64 v[34:35], v[98:99], 1, v[34:35]
	global_store_short v[34:35], v36, off
	v_mul_f32_e32 v36, v46, v102
	v_cvt_pk_bf16_f32 v36, v36, v36
	global_store_short v[34:35], v36, off offset:64
	v_mul_f32_e32 v34, v46, v46
	v_fmac_f32_e32 v34, v62, v62
	s_nop 1
	v_add_f32_dpp v34, v34, v34 quad_perm:[1,0,3,2] row_mask:0xf bank_mask:0xf
	s_nop 1
	v_add_f32_dpp v34, v34, v34 quad_perm:[2,3,0,1] row_mask:0xf bank_mask:0xf
	s_nop 1
	v_add_f32_dpp v34, v34, v34 row_half_mirror row_mask:0xf bank_mask:0xf
	s_nop 1
	v_add_f32_dpp v34, v34, v34 row_mirror row_mask:0xf bank_mask:0xf
	ds_bpermute_b32 v35, v107, v34
	s_and_saveexec_b64 s[0:1], s[4:5]
	s_cbranch_execz .LBB0_950
	v_lshl_add_u64 v[32:33], v[32:33], 2, s[18:19]
	s_waitcnt lgkmcnt(0)
	v_add_f32_e32 v34, v34, v35
	global_atomic_add_f32 v[32:33], v34, off

; __device__ __forceinline__ bf16_t f2bf(float f) { return (bf16_t)(pk_bf16(f, f) & 0xffffu); }
; __device__ __forceinline__ float halfsum32(float s) {
;     s += __shfl_xor(s, 1); s += __shfl_xor(s, 2); s += __shfl_xor(s, 4); s += __shfl_xor(s, 8); s += __shfl_xor(s, 16); return s;
; }
;     template <int MT> __device__ __forceinline__ void run(const Params& P, f32x16 (&acc)[MT][2], int rbase, int pn, int wc, int lane) const {
;     ...
;             bf16_t* CQ = (bf16_t*)(ws + OFF_CQ); float* SSQ = (float*)(ws + OFF_SSQQ);
;             const int c0 = pn * 128 + wc * 64 + n, c1 = c0 + 32; const float g0 = P.gq[c0], g1 = P.gq[c1];
; #pragma unroll
;             for (int mt = 0; mt < MT; ++mt)
; #pragma unroll
;                 for (int rg = 0; rg < 16; ++rg) { const int r = ROWOF(rb, mt, rg); const float v0 = acc[mt][0][rg], v1 = acc[mt][1][rg];
;                     CQ[(size_t)r * 512 + c0] = f2bf(v0 * g0); CQ[(size_t)r * 512 + c1] = f2bf(v1 * g1);
;                     const float s = halfsum32(v0 * v0 + v1 * v1); if (n == 0) atomicAdd(SSQ + r, s); }
.LBB0_954:
	s_or_b64 exec, exec, s[0:1]
	v_add_u32_e32 v32, 0x41, v96
	v_ashrrev_i32_e32 v33, 31, v32
	v_lshlrev_b64 v[34:35], 10, v[32:33]
	v_mul_f32_e32 v0, v17, v103
	v_lshl_add_u64 v[34:35], s[20:21], 0, v[34:35]
	v_cvt_pk_bf16_f32 v0, v0, v0
	v_lshl_add_u64 v[34:35], v[98:99], 1, v[34:35]
	global_store_short v[34:35], v0, off
	v_mul_f32_e32 v0, v1, v102
	v_cvt_pk_bf16_f32 v0, v0, v0
	global_store_short v[34:35], v0, off offset:64
	v_mul_f32_e32 v0, v1, v1
	v_fmac_f32_e32 v0, v17, v17
	s_nop 1
	v_add_f32_dpp v0, v0, v0 quad_perm:[1,0,3,2] row_mask:0xf bank_mask:0xf
	s_nop 1
	v_add_f32_dpp v0, v0, v0 quad_perm:[2,3,0,1] row_mask:0xf bank_mask:0xf
	s_nop 1
	v_add_f32_dpp v0, v0, v0 row_half_mirror row_mask:0xf bank_mask:0xf
	s_nop 1
	v_add_f32_dpp v0, v0, v0 row_mirror row_mask:0xf bank_mask:0xf
	ds_bpermute_b32 v1, v107, v0
	s_and_saveexec_b64 s[0:1], s[4:5]
	s_cbranch_execz .LBB0_956
	v_lshl_add_u64 v[16:17], v[32:33], 2, s[18:19]
	s_waitcnt lgkmcnt(0)
	v_add_f32_e32 v0, v0, v1
	global_atomic_add_f32 v[16:17], v0, off
.LBB0_956:
	s_or_b64 exec, exec, s[0:1]
	v_add_u32_e32 v0, 0x42, v96
	s_waitcnt lgkmcnt(0)
	v_mul_f32_e32 v1, v18, v103
	v_cvt_pk_bf16_f32 v32, v1, v1
	v_ashrrev_i32_e32 v1, 31, v0
	v_lshlrev_b64 v[16:17], 10, v[0:1]
	v_lshl_add_u64 v[16:17], s[20:21], 0, v[16:17]
	v_lshl_add_u64 v[16:17], v[98:99], 1, v[16:17]
	global_store_short v[16:17], v32, off
	v_mul_f32_e32 v32, v2, v102
	v_mul_f32_e32 v2, v2, v2
	v_fmac_f32_e32 v2, v18, v18
	v_cvt_pk_bf16_f32 v32, v32, v32
	global_store_short v[16:17], v32, off offset:64
	s_nop 1
	v_add_f32_dpp v2, v2, v2 quad_perm:[1,0,3,2] row_mask:0xf bank_mask:0xf
	s_nop 1
	v_add_f32_dpp v2, v2, v2 quad_perm:[2,3,0,1] row_mask:0xf bank_mask:0xf
	s_nop 1
	v_add_f32_dpp v2, v2, v2 row_half_mirror row_mask:0xf bank_mask:0xf
	s_nop 1
	v_add_f32_dpp v2, v2, v2 row_mirror row_mask:0xf bank_mask:0xf
	ds_bpermute_b32 v16, v107, v2
	s_and_saveexec_b64 s[0:1], s[4:5]
	s_cbranch_execz .LBB0_958
	v_lshl_add_u64 v[0:1], v[0:1], 2, s[18:19]
	s_waitcnt lgkmcnt(0)
	v_add_f32_e32 v2, v2, v16
	global_atomic_add_f32 v[0:1], v2, off
.LBB0_958:
	s_or_b64 exec, exec, s[0:1]
	v_add_u32_e32 v0, 0x43, v96
	v_mul_f32_e32 v1, v19, v103
	v_cvt_pk_bf16_f32 v2, v1, v1
	v_ashrrev_i32_e32 v1, 31, v0
	s_waitcnt lgkmcnt(0)
	v_lshlrev_b64 v[16:17], 10, v[0:1]
	v_lshl_add_u64 v[16:17], s[20:21], 0, v[16:17]
	v_lshl_add_u64 v[16:17], v[98:99], 1, v[16:17]
	global_store_short v[16:17], v2, off
	v_mul_f32_e32 v2, v3, v102
	v_cvt_pk_bf16_f32 v2, v2, v2
	global_store_short v[16:17], v2, off offset:64
	v_mul_f32_e32 v2, v3, v3
	v_fmac_f32_e32 v2, v19, v19
	s_nop 1
	v_add_f32_dpp v2, v2, v2 quad_perm:[1,0,3,2] row_mask:0xf bank_mask:0xf
	s_nop 1
	v_add_f32_dpp v2, v2, v2 quad_perm:[2,3,0,1] row_mask:0xf bank_mask:0xf
	s_nop 1
	v_add_f32_dpp v2, v2, v2 row_half_mirror row_mask:0xf bank_mask:0xf
	s_nop 1
	v_add_f32_dpp v2, v2, v2 row_mirror row_mask:0xf bank_mask:0xf
	ds_bpermute_b32 v3, v107, v2
	s_and_saveexec_b64 s[0:1], s[4:5]
	s_cbranch_execz .LBB0_960
	v_lshl_add_u64 v[0:1], v[0:1], 2, s[18:19]
	s_waitcnt lgkmcnt(0)
	v_add_f32_e32 v2, v2, v3
	global_atomic_add_f32 v[0:1], v2, off
.LBB0_960:
	s_or_b64 exec, exec, s[0:1]
	v_add_u32_e32 v0, 0x48, v96
	v_mul_f32_e32 v1, v20, v103
	v_cvt_pk_bf16_f32 v16, v1, v1
	v_ashrrev_i32_e32 v1, 31, v0
	s_waitcnt lgkmcnt(0)
	v_lshlrev_b64 v[2:3], 10, v[0:1]
	v_lshl_add_u64 v[2:3], s[20:21], 0, v[2:3]
	v_lshl_add_u64 v[2:3], v[98:99], 1, v[2:3]
	global_store_short v[2:3], v16, off
	v_mul_f32_e32 v16, v4, v102
	v_cvt_pk_bf16_f32 v16, v16, v16
	global_store_short v[2:3], v16, off offset:64
	v_mul_f32_e32 v2, v4, v4
	v_fmac_f32_e32 v2, v20, v20
	s_nop 1
	v_add_f32_dpp v2, v2, v2 quad_perm:[1,0,3,2] row_mask:0xf bank_mask:0xf
	s_nop 1
	v_add_f32_dpp v2, v2, v2 quad_perm:[2,3,0,1] row_mask:0xf bank_mask:0xf
	s_nop 1
	v_add_f32_dpp v2, v2, v2 row_half_mirror row_mask:0xf bank_mask:0xf
	s_nop 1
	v_add_f32_dpp v2, v2, v2 row_mirror row_mask:0xf bank_mask:0xf
	ds_bpermute_b32 v3, v107, v2
	s_and_saveexec_b64 s[0:1], s[4:5]
	s_cbranch_execz .LBB0_962
	v_lshl_add_u64 v[0:1], v[0:1], 2, s[18:19]
	s_waitcnt lgkmcnt(0)
	v_add_f32_e32 v2, v2, v3
	global_atomic_add_f32 v[0:1], v2, off
.LBB0_962:
	s_or_b64 exec, exec, s[0:1]
	v_add_u32_e32 v0, 0x49, v96
	v_mul_f32_e32 v1, v21, v103
	v_cvt_pk_bf16_f32 v4, v1, v1
	v_ashrrev_i32_e32 v1, 31, v0
	s_waitcnt lgkmcnt(0)
	v_lshlrev_b64 v[2:3], 10, v[0:1]
	v_lshl_add_u64 v[2:3], s[20:21], 0, v[2:3]
	v_lshl_add_u64 v[2:3], v[98:99], 1, v[2:3]
	global_store_short v[2:3], v4, off
	v_mul_f32_e32 v4, v5, v102
	v_cvt_pk_bf16_f32 v4, v4, v4
	global_store_short v[2:3], v4, off offset:64
	v_mul_f32_e32 v2, v5, v5
	v_fmac_f32_e32 v2, v21, v21
	s_nop 1
	v_add_f32_dpp v2, v2, v2 quad_perm:[1,0,3,2] row_mask:0xf bank_mask:0xf
	s_nop 1
	v_add_f32_dpp v2, v2, v2 quad_perm:[2,3,0,1] row_mask:0xf bank_mask:0xf
	s_nop 1
	v_add_f32_dpp v2, v2, v2 row_half_mirror row_mask:0xf bank_mask:0xf
	s_nop 1
	v_add_f32_dpp v2, v2, v2 row_mirror row_mask:0xf bank_mask:0xf
	ds_bpermute_b32 v3, v107, v2
	s_and_saveexec_b64 s[0:1], s[4:5]
	s_cbranch_execz .LBB0_964
	v_lshl_add_u64 v[0:1], v[0:1], 2, s[18:19]
	s_waitcnt lgkmcnt(0)
	v_add_f32_e32 v2, v2, v3
	global_atomic_add_f32 v[0:1], v2, off
; __device__ __forceinline__ bf16_t f2bf(float f) { return (bf16_t)(pk_bf16(f, f) & 0xffffu); }
; __device__ __forceinline__ float halfsum32(float s) {
;     s += __shfl_xor(s, 1); s += __shfl_xor(s, 2); s += __shfl_xor(s, 4); s += __shfl_xor(s, 8); s += __shfl_xor(s, 16); return s;
; }
;     template <int MT> __device__ __forceinline__ void run(const Params& P, f32x16 (&acc)[MT][2], int rbase, int pn, int wc, int lane) const {
;     ...
;             bf16_t* CQ = (bf16_t*)(ws + OFF_CQ); float* SSQ = (float*)(ws + OFF_SSQQ);
;             const int c0 = pn * 128 + wc * 64 + n, c1 = c0 + 32; const float g0 = P.gq[c0], g1 = P.gq[c1];
; #pragma unroll
;             for (int mt = 0; mt < MT; ++mt)
; #pragma unroll
;                 for (int rg = 0; rg < 16; ++rg) { const int r = ROWOF(rb, mt, rg); const float v0 = acc[mt][0][rg], v1 = acc[mt][1][rg];
;                     CQ[(size_t)r * 512 + c0] = f2bf(v0 * g0); CQ[(size_t)r * 512 + c1] = f2bf(v1 * g1);
;                     const float s = halfsum32(v0 * v0 + v1 * v1); if (n == 0) atomicAdd(SSQ + r, s); }
.LBB0_964:
	s_or_b64 exec, exec, s[0:1]
	v_add_u32_e32 v0, 0x4a, v96
	v_mul_f32_e32 v1, v22, v103
	v_cvt_pk_bf16_f32 v4, v1, v1
	v_ashrrev_i32_e32 v1, 31, v0
	s_waitcnt lgkmcnt(0)
	v_lshlrev_b64 v[2:3], 10, v[0:1]
	v_lshl_add_u64 v[2:3], s[20:21], 0, v[2:3]
	v_lshl_add_u64 v[2:3], v[98:99], 1, v[2:3]
	global_store_short v[2:3], v4, off
	v_mul_f32_e32 v4, v6, v102
	v_cvt_pk_bf16_f32 v4, v4, v4
	global_store_short v[2:3], v4, off offset:64
	v_mul_f32_e32 v2, v6, v6
	v_fmac_f32_e32 v2, v22, v22
	s_nop 1
	v_add_f32_dpp v2, v2, v2 quad_perm:[1,0,3,2] row_mask:0xf bank_mask:0xf
	s_nop 1
	v_add_f32_dpp v2, v2, v2 quad_perm:[2,3,0,1] row_mask:0xf bank_mask:0xf
	s_nop 1
	v_add_f32_dpp v2, v2, v2 row_half_mirror row_mask:0xf bank_mask:0xf
	s_nop 1
	v_add_f32_dpp v2, v2, v2 row_mirror row_mask:0xf bank_mask:0xf
	ds_bpermute_b32 v3, v107, v2
	s_and_saveexec_b64 s[0:1], s[4:5]
	s_cbranch_execz .LBB0_966
	v_lshl_add_u64 v[0:1], v[0:1], 2, s[18:19]
	s_waitcnt lgkmcnt(0)
	v_add_f32_e32 v2, v2, v3
	global_atomic_add_f32 v[0:1], v2, off
.LBB0_966:
	s_or_b64 exec, exec, s[0:1]
	v_add_u32_e32 v0, 0x4b, v96
	v_mul_f32_e32 v1, v23, v103
	v_cvt_pk_bf16_f32 v4, v1, v1
	v_ashrrev_i32_e32 v1, 31, v0
	s_waitcnt lgkmcnt(0)
	v_lshlrev_b64 v[2:3], 10, v[0:1]
	v_lshl_add_u64 v[2:3], s[20:21], 0, v[2:3]
	v_lshl_add_u64 v[2:3], v[98:99], 1, v[2:3]
	global_store_short v[2:3], v4, off
	v_mul_f32_e32 v4, v7, v102
	v_cvt_pk_bf16_f32 v4, v4, v4
	global_store_short v[2:3], v4, off offset:64
	v_mul_f32_e32 v2, v7, v7
	v_fmac_f32_e32 v2, v23, v23
	s_nop 1
	v_add_f32_dpp v2, v2, v2 quad_perm:[1,0,3,2] row_mask:0xf bank_mask:0xf
	s_nop 1
	v_add_f32_dpp v2, v2, v2 quad_perm:[2,3,0,1] row_mask:0xf bank_mask:0xf
	s_nop 1
	v_add_f32_dpp v2, v2, v2 row_half_mirror row_mask:0xf bank_mask:0xf
	s_nop 1
	v_add_f32_dpp v2, v2, v2 row_mirror row_mask:0xf bank_mask:0xf
	ds_bpermute_b32 v3, v107, v2
	s_and_saveexec_b64 s[0:1], s[4:5]
	s_cbranch_execz .LBB0_968
	v_lshl_add_u64 v[0:1], v[0:1], 2, s[18:19]
	s_waitcnt lgkmcnt(0)
	v_add_f32_e32 v2, v2, v3
	global_atomic_add_f32 v[0:1], v2, off
.LBB0_968:
	s_or_b64 exec, exec, s[0:1]
	v_add_u32_e32 v0, 0x50, v96
	v_mul_f32_e32 v1, v24, v103
	v_cvt_pk_bf16_f32 v4, v1, v1
	v_ashrrev_i32_e32 v1, 31, v0
	s_waitcnt lgkmcnt(0)
	v_lshlrev_b64 v[2:3], 10, v[0:1]
	v_lshl_add_u64 v[2:3], s[20:21], 0, v[2:3]
	v_lshl_add_u64 v[2:3], v[98:99], 1, v[2:3]
	global_store_short v[2:3], v4, off
	v_mul_f32_e32 v4, v8, v102
	v_cvt_pk_bf16_f32 v4, v4, v4
	global_store_short v[2:3], v4, off offset:64
	v_mul_f32_e32 v2, v8, v8
	v_fmac_f32_e32 v2, v24, v24
	s_nop 1
	v_add_f32_dpp v2, v2, v2 quad_perm:[1,0,3,2] row_mask:0xf bank_mask:0xf
	s_nop 1
	v_add_f32_dpp v2, v2, v2 quad_perm:[2,3,0,1] row_mask:0xf bank_mask:0xf
	s_nop 1
	v_add_f32_dpp v2, v2, v2 row_half_mirror row_mask:0xf bank_mask:0xf
	s_nop 1
	v_add_f32_dpp v2, v2, v2 row_mirror row_mask:0xf bank_mask:0xf
	ds_bpermute_b32 v3, v107, v2
	s_and_saveexec_b64 s[0:1], s[4:5]
	s_cbranch_execz .LBB0_970
	v_lshl_add_u64 v[0:1], v[0:1], 2, s[18:19]
	s_waitcnt lgkmcnt(0)
	v_add_f32_e32 v2, v2, v3
	global_atomic_add_f32 v[0:1], v2, off
.LBB0_970:
	s_or_b64 exec, exec, s[0:1]
	v_add_u32_e32 v0, 0x51, v96
	v_mul_f32_e32 v1, v25, v103
	v_cvt_pk_bf16_f32 v4, v1, v1
	v_ashrrev_i32_e32 v1, 31, v0
	s_waitcnt lgkmcnt(0)
	v_lshlrev_b64 v[2:3], 10, v[0:1]
	v_lshl_add_u64 v[2:3], s[20:21], 0, v[2:3]
	v_lshl_add_u64 v[2:3], v[98:99], 1, v[2:3]
	global_store_short v[2:3], v4, off
	v_mul_f32_e32 v4, v9, v102
	v_cvt_pk_bf16_f32 v4, v4, v4
	global_store_short v[2:3], v4, off offset:64
	v_mul_f32_e32 v2, v9, v9
	v_fmac_f32_e32 v2, v25, v25
	s_nop 1
	v_add_f32_dpp v2, v2, v2 quad_perm:[1,0,3,2] row_mask:0xf bank_mask:0xf
	s_nop 1
	v_add_f32_dpp v2, v2, v2 quad_perm:[2,3,0,1] row_mask:0xf bank_mask:0xf
	s_nop 1
	v_add_f32_dpp v2, v2, v2 row_half_mirror row_mask:0xf bank_mask:0xf
	s_nop 1
	v_add_f32_dpp v2, v2, v2 row_mirror row_mask:0xf bank_mask:0xf
	ds_bpermute_b32 v3, v107, v2
	s_and_saveexec_b64 s[0:1], s[4:5]
	s_cbranch_execz .LBB0_972
	v_lshl_add_u64 v[0:1], v[0:1], 2, s[18:19]
	s_waitcnt lgkmcnt(0)
	v_add_f32_e32 v2, v2, v3
	global_atomic_add_f32 v[0:1], v2, off
.LBB0_972:
	s_or_b64 exec, exec, s[0:1]
	v_add_u32_e32 v0, 0x52, v96
	v_mul_f32_e32 v1, v26, v103
	v_cvt_pk_bf16_f32 v4, v1, v1
	v_ashrrev_i32_e32 v1, 31, v0
	s_waitcnt lgkmcnt(0)
	v_lshlrev_b64 v[2:3], 10, v[0:1]
	v_lshl_add_u64 v[2:3], s[20:21], 0, v[2:3]
	v_lshl_add_u64 v[2:3], v[98:99], 1, v[2:3]
	global_store_short v[2:3], v4, off
	v_mul_f32_e32 v4, v10, v102
	v_cvt_pk_bf16_f32 v4, v4, v4
	global_store_short v[2:3], v4, off offset:64
	v_mul_f32_e32 v2, v10, v10
	v_fmac_f32_e32 v2, v26, v26
	s_nop 1
	v_add_f32_dpp v2, v2, v2 quad_perm:[1,0,3,2] row_mask:0xf bank_mask:0xf
	s_nop 1
	v_add_f32_dpp v2, v2, v2 quad_perm:[2,3,0,1] row_mask:0xf bank_mask:0xf
	s_nop 1
	v_add_f32_dpp v2, v2, v2 row_half_mirror row_mask:0xf bank_mask:0xf
	s_nop 1
	v_add_f32_dpp v2, v2, v2 row_mirror row_mask:0xf bank_mask:0xf
	ds_bpermute_b32 v3, v107, v2
	s_and_saveexec_b64 s[0:1], s[4:5]
	s_cbranch_execz .LBB0_974
	v_lshl_add_u64 v[0:1], v[0:1], 2, s[18:19]
	s_waitcnt lgkmcnt(0)
	v_add_f32_e32 v2, v2, v3
	global_atomic_add_f32 v[0:1], v2, off
; __device__ __forceinline__ bf16_t f2bf(float f) { return (bf16_t)(pk_bf16(f, f) & 0xffffu); }
; __device__ __forceinline__ float halfsum32(float s) {
;     s += __shfl_xor(s, 1); s += __shfl_xor(s, 2); s += __shfl_xor(s, 4); s += __shfl_xor(s, 8); s += __shfl_xor(s, 16); return s;
; }
;     template <int MT> __device__ __forceinline__ void run(const Params& P, f32x16 (&acc)[MT][2], int rbase, int pn, int wc, int lane) const {
;     ...
;             bf16_t* CQ = (bf16_t*)(ws + OFF_CQ); float* SSQ = (float*)(ws + OFF_SSQQ);
;             const int c0 = pn * 128 + wc * 64 + n, c1 = c0 + 32; const float g0 = P.gq[c0], g1 = P.gq[c1];
; #pragma unroll
;             for (int mt = 0; mt < MT; ++mt)
; #pragma unroll
;                 for (int rg = 0; rg < 16; ++rg) { const int r = ROWOF(rb, mt, rg); const float v0 = acc[mt][0][rg], v1 = acc[mt][1][rg];
;                     CQ[(size_t)r * 512 + c0] = f2bf(v0 * g0); CQ[(size_t)r * 512 + c1] = f2bf(v1 * g1);
;                     const float s = halfsum32(v0 * v0 + v1 * v1); if (n == 0) atomicAdd(SSQ + r, s); }
.LBB0_974:
	s_or_b64 exec, exec, s[0:1]
	v_add_u32_e32 v0, 0x53, v96
	v_mul_f32_e32 v1, v27, v103
	v_cvt_pk_bf16_f32 v4, v1, v1
	v_ashrrev_i32_e32 v1, 31, v0
	s_waitcnt lgkmcnt(0)
	v_lshlrev_b64 v[2:3], 10, v[0:1]
	v_lshl_add_u64 v[2:3], s[20:21], 0, v[2:3]
	v_lshl_add_u64 v[2:3], v[98:99], 1, v[2:3]
	global_store_short v[2:3], v4, off
	v_mul_f32_e32 v4, v11, v102
	v_cvt_pk_bf16_f32 v4, v4, v4
	global_store_short v[2:3], v4, off offset:64
	v_mul_f32_e32 v2, v11, v11
	v_fmac_f32_e32 v2, v27, v27
	s_nop 1
	v_add_f32_dpp v2, v2, v2 quad_perm:[1,0,3,2] row_mask:0xf bank_mask:0xf
	s_nop 1
	v_add_f32_dpp v2, v2, v2 quad_perm:[2,3,0,1] row_mask:0xf bank_mask:0xf
	s_nop 1
	v_add_f32_dpp v2, v2, v2 row_half_mirror row_mask:0xf bank_mask:0xf
	s_nop 1
	v_add_f32_dpp v2, v2, v2 row_mirror row_mask:0xf bank_mask:0xf
	ds_bpermute_b32 v3, v107, v2
	s_and_saveexec_b64 s[0:1], s[4:5]
	s_cbranch_execz .LBB0_976
	v_lshl_add_u64 v[0:1], v[0:1], 2, s[18:19]
	s_waitcnt lgkmcnt(0)
	v_add_f32_e32 v2, v2, v3
	global_atomic_add_f32 v[0:1], v2, off
.LBB0_976:
	s_or_b64 exec, exec, s[0:1]
	v_add_u32_e32 v0, 0x58, v96
	v_mul_f32_e32 v1, v28, v103
	v_cvt_pk_bf16_f32 v4, v1, v1
	v_ashrrev_i32_e32 v1, 31, v0
	s_waitcnt lgkmcnt(0)
	v_lshlrev_b64 v[2:3], 10, v[0:1]
	v_lshl_add_u64 v[2:3], s[20:21], 0, v[2:3]
	v_lshl_add_u64 v[2:3], v[98:99], 1, v[2:3]
	global_store_short v[2:3], v4, off
	v_mul_f32_e32 v4, v12, v102
	v_cvt_pk_bf16_f32 v4, v4, v4
	global_store_short v[2:3], v4, off offset:64
	v_mul_f32_e32 v2, v12, v12
	v_fmac_f32_e32 v2, v28, v28
	s_nop 1
	v_add_f32_dpp v2, v2, v2 quad_perm:[1,0,3,2] row_mask:0xf bank_mask:0xf
	s_nop 1
	v_add_f32_dpp v2, v2, v2 quad_perm:[2,3,0,1] row_mask:0xf bank_mask:0xf
	s_nop 1
	v_add_f32_dpp v2, v2, v2 row_half_mirror row_mask:0xf bank_mask:0xf
	s_nop 1
	v_add_f32_dpp v2, v2, v2 row_mirror row_mask:0xf bank_mask:0xf
	ds_bpermute_b32 v3, v107, v2
	s_and_saveexec_b64 s[0:1], s[4:5]
	s_cbranch_execz .LBB0_978
	v_lshl_add_u64 v[0:1], v[0:1], 2, s[18:19]
	s_waitcnt lgkmcnt(0)
	v_add_f32_e32 v2, v2, v3
	global_atomic_add_f32 v[0:1], v2, off
.LBB0_978:
	s_or_b64 exec, exec, s[0:1]
	v_add_u32_e32 v0, 0x59, v96
	v_mul_f32_e32 v1, v29, v103
	v_cvt_pk_bf16_f32 v4, v1, v1
	v_ashrrev_i32_e32 v1, 31, v0
	s_waitcnt lgkmcnt(0)
	v_lshlrev_b64 v[2:3], 10, v[0:1]
	v_lshl_add_u64 v[2:3], s[20:21], 0, v[2:3]
	v_lshl_add_u64 v[2:3], v[98:99], 1, v[2:3]
	global_store_short v[2:3], v4, off
	v_mul_f32_e32 v4, v13, v102
	v_cvt_pk_bf16_f32 v4, v4, v4
	global_store_short v[2:3], v4, off offset:64
	v_mul_f32_e32 v2, v13, v13
	v_fmac_f32_e32 v2, v29, v29
	s_nop 1
	v_add_f32_dpp v2, v2, v2 quad_perm:[1,0,3,2] row_mask:0xf bank_mask:0xf
	s_nop 1
	v_add_f32_dpp v2, v2, v2 quad_perm:[2,3,0,1] row_mask:0xf bank_mask:0xf
	s_nop 1
	v_add_f32_dpp v2, v2, v2 row_half_mirror row_mask:0xf bank_mask:0xf
	s_nop 1
	v_add_f32_dpp v2, v2, v2 row_mirror row_mask:0xf bank_mask:0xf
	ds_bpermute_b32 v3, v107, v2
	s_and_saveexec_b64 s[0:1], s[4:5]
	s_cbranch_execz .LBB0_980
	v_lshl_add_u64 v[0:1], v[0:1], 2, s[18:19]
	s_waitcnt lgkmcnt(0)
	v_add_f32_e32 v2, v2, v3
	global_atomic_add_f32 v[0:1], v2, off
.LBB0_980:
	s_or_b64 exec, exec, s[0:1]
	v_add_u32_e32 v0, 0x5a, v96
	v_mul_f32_e32 v1, v30, v103
	v_cvt_pk_bf16_f32 v4, v1, v1
	v_ashrrev_i32_e32 v1, 31, v0
	s_waitcnt lgkmcnt(0)
	v_lshlrev_b64 v[2:3], 10, v[0:1]
	v_lshl_add_u64 v[2:3], s[20:21], 0, v[2:3]
	v_lshl_add_u64 v[2:3], v[98:99], 1, v[2:3]
	global_store_short v[2:3], v4, off
	v_mul_f32_e32 v4, v14, v102
	v_cvt_pk_bf16_f32 v4, v4, v4
	global_store_short v[2:3], v4, off offset:64
	v_mul_f32_e32 v2, v14, v14
	v_fmac_f32_e32 v2, v30, v30
	s_nop 1
	v_add_f32_dpp v2, v2, v2 quad_perm:[1,0,3,2] row_mask:0xf bank_mask:0xf
	s_nop 1
	v_add_f32_dpp v2, v2, v2 quad_perm:[2,3,0,1] row_mask:0xf bank_mask:0xf
	s_nop 1
	v_add_f32_dpp v2, v2, v2 row_half_mirror row_mask:0xf bank_mask:0xf
	s_nop 1
	v_add_f32_dpp v2, v2, v2 row_mirror row_mask:0xf bank_mask:0xf
	ds_bpermute_b32 v3, v107, v2
	s_and_saveexec_b64 s[0:1], s[4:5]
	s_cbranch_execz .LBB0_982
	v_lshl_add_u64 v[0:1], v[0:1], 2, s[18:19]
	s_waitcnt lgkmcnt(0)
	v_add_f32_e32 v2, v2, v3
	global_atomic_add_f32 v[0:1], v2, off

; #define G_STORE(BUF) do { char* l_ = lds + (BUF) * STAGE + wofs; \
;         *(uint4*)(l_) = ra0; *(uint4*)(l_ + 8192) = ra1; *(uint4*)(l_ + 16384) = ra2; if (MT == 4) *(uint4*)(l_ + 24576) = ra3; \
;         *(uint4*)(l_ + ABYTES) = rb0; *(uint4*)(l_ + ABYTES + 8192) = rb1; *(uint4*)(l_ + ABYTES + 16384) = rb2; *(uint4*)(l_ + ABYTES + 24576) = rb3; } while (0)
; template <int MT, bool PIN, class Epi>
; __device__ __forceinline__ void gemm_phase(const Params& P, const bf16_t* __restrict__ A, const bf16_t* __restrict__ Bt, int nM, int nN, int K, const Epi epi, char* lds) {
;     ...
;         G_LOAD(0);
;         f32x16 acc[MT][2];
; #pragma unroll
;         for (int a = 0; a < MT; ++a)
; #pragma unroll
;             for (int b = 0; b < 2; ++b)
; #pragma unroll
;                 for (int e = 0; e < 16; ++e) acc[a][b][e] = 0.f;
;         bf16x8 fa[2][MT], fb[2][2];
;         __syncthreads();
;         G_STORE(0);
;         G_LOAD(1);
;         __syncthreads();
;         for (int kt = 0; kt < nk; kt += 2) { G_STEP(0, kt); G_STEP(1, kt + 1); }
.LBB0_2403:
	v_add_u32_e32 v180, v145, v143
	ds_read_b128 v[164:167], v144
	ds_read_b128 v[168:171], v144 offset:4096
	ds_read_b128 v[172:175], v144 offset:8192
	ds_read_b128 v[176:179], v180 offset:24576
	ds_read_b128 v[180:183], v180 offset:28672
	s_add_i32 s16, s15, 2
	s_min_u32 s17, s1, 0xf80
	s_add_i32 s98, s1, 0x80
	s_min_u32 s98, s98, 0xf80
	s_addk_i32 s1, 0x100
	v_add_u32_e32 v240, s17, v124
	v_add_u32_e32 v241, 0x40000, v240
	v_add_u32_e32 v242, 0x80000, v240
	v_add_u32_e32 v243, 0xc0000, v240
	s_waitcnt lgkmcnt(1)
	v_mfma_f32_32x32x16_bf16 v[80:95], v[164:167], v[176:179], v[80:95]
	v_add_u32_e32 v188, v145, v149
	v_add_u32_e32 v126, v154, v143
	s_waitcnt lgkmcnt(0)
	v_mfma_f32_32x32x16_bf16 v[64:79], v[164:167], v[180:183], v[64:79]
	ds_read_b128 v[164:167], v148
	s_waitcnt vmcnt(13)
	ds_write_b128 v142, v[96:99] offset:57344
	global_load_dwordx4 v[96:99], v240, s[4:5]
	v_mfma_f32_32x32x16_bf16 v[48:63], v[168:171], v[176:179], v[48:63]
	v_mfma_f32_32x32x16_bf16 v[32:47], v[168:171], v[180:183], v[32:47]
	s_waitcnt vmcnt(13)
	ds_write_b128 v146, v[100:103] offset:8192
	global_load_dwordx4 v[100:103], v241, s[4:5]
	v_mfma_f32_32x32x16_bf16 v[0:15], v[172:175], v[180:183], v[0:15]
	v_add_u32_e32 v180, v145, v147
	v_mfma_f32_32x32x16_bf16 v[16:31], v[172:175], v[176:179], v[16:31]
	ds_read_b128 v[168:171], v180 offset:24576
	ds_read_b128 v[172:175], v148 offset:4096
	ds_read_b128 v[176:179], v152 offset:8192
	ds_read_b128 v[180:183], v180 offset:28672
	ds_read_b128 v[184:187], v188 offset:24576
	s_waitcnt vmcnt(13)
	ds_write_b128 v146, v[108:111] offset:16384
	global_load_dwordx4 v[108:111], v242, s[4:5]
	s_waitcnt lgkmcnt(5)
	v_mfma_f32_32x32x16_bf16 v[80:95], v[164:167], v[168:171], v[80:95]
	s_waitcnt lgkmcnt(2)
	v_mfma_f32_32x32x16_bf16 v[64:79], v[164:167], v[180:183], v[64:79]
	s_waitcnt vmcnt(13)
	ds_write_b128 v146, v[104:107] offset:24576
	global_load_dwordx4 v[104:107], v240, s[6:7]
	v_mfma_f32_32x32x16_bf16 v[48:63], v[172:175], v[168:171], v[48:63]
	v_mfma_f32_32x32x16_bf16 v[32:47], v[172:175], v[180:183], v[32:47]
	ds_read_b128 v[164:167], v148 offset:8192
	ds_read_b128 v[172:175], v150
	s_waitcnt vmcnt(13)
	ds_write_b128 v146, v[112:115] offset:32768
	global_load_dwordx4 v[112:115], v241, s[6:7]
	s_waitcnt lgkmcnt(2)
	v_mfma_f32_32x32x16_bf16 v[16:31], v[164:167], v[168:171], v[16:31]
	v_mfma_f32_32x32x16_bf16 v[0:15], v[164:167], v[180:183], v[0:15]
	ds_read_b128 v[164:167], v188 offset:28672
	v_add_u32_e32 v188, v145, v151
	ds_read_b128 v[168:171], v188 offset:24576
	s_waitcnt vmcnt(13)
	ds_write_b128 v146, v[116:119] offset:40960
	global_load_dwordx4 v[116:119], v242, s[6:7]
	s_waitcnt lgkmcnt(4)
	v_mfma_f32_32x32x16_bf16 v[80:95], v[172:175], v[184:187], v[80:95]
	s_waitcnt lgkmcnt(2)
	v_mfma_f32_32x32x16_bf16 v[64:79], v[172:175], v[164:167], v[64:79]
	ds_read_b128 v[172:175], v150 offset:4096
	ds_read_b128 v[180:183], v150 offset:8192
	s_waitcnt vmcnt(13)
	ds_write_b128 v146, v[120:123] offset:49152
	global_load_dwordx4 v[120:123], v243, s[6:7]
	s_waitcnt lgkmcnt(2)
	v_mfma_f32_32x32x16_bf16 v[48:63], v[172:175], v[184:187], v[48:63]
	v_mfma_f32_32x32x16_bf16 v[32:47], v[172:175], v[164:167], v[32:47]
	s_waitcnt lgkmcnt(1)
	v_mfma_f32_32x32x16_bf16 v[16:31], v[180:183], v[184:187], v[16:31]
	v_mfma_f32_32x32x16_bf16 v[0:15], v[180:183], v[164:167], v[0:15]
	ds_read_b128 v[164:167], v152
	ds_read_b128 v[172:175], v152 offset:4096
	ds_read_b128 v[180:183], v188 offset:28672
	s_waitcnt lgkmcnt(0)
	s_barrier
	v_mfma_f32_32x32x16_bf16 v[80:95], v[164:167], v[168:171], v[80:95]
	v_mfma_f32_32x32x16_bf16 v[64:79], v[164:167], v[180:183], v[64:79]
	v_mfma_f32_32x32x16_bf16 v[48:63], v[172:175], v[168:171], v[48:63]
	v_mfma_f32_32x32x16_bf16 v[32:47], v[172:175], v[180:183], v[32:47]
	ds_read_b128 v[164:167], v144 offset:57344
	ds_read_b128 v[172:175], v144 offset:61440
	ds_read_b128 v[184:187], v153 offset:8192
	ds_read_b128 v[188:191], v160
	v_mfma_f32_32x32x16_bf16 v[16:31], v[176:179], v[168:171], v[16:31]
	ds_read_b128 v[168:171], v126 offset:4096
	v_add_u32_e32 v240, s98, v124
	v_add_u32_e32 v241, 0x40000, v240
	v_add_u32_e32 v242, 0x80000, v240
	v_add_u32_e32 v243, 0xc0000, v240
	s_waitcnt vmcnt(13)
	ds_write_b128 v142, v[212:215]
	global_load_dwordx4 v[212:215], v240, s[4:5]
	v_mfma_f32_32x32x16_bf16 v[0:15], v[176:179], v[180:183], v[0:15]
	s_waitcnt lgkmcnt(2)
	v_mfma_f32_32x32x16_bf16 v[80:95], v[164:167], v[188:191], v[80:95]
	v_add_u32_e32 v180, v154, v147
	s_mov_b32 s15, s16
	s_waitcnt lgkmcnt(1)
	v_mfma_f32_32x32x16_bf16 v[64:79], v[164:167], v[168:171], v[64:79]
	s_waitcnt vmcnt(13)
	ds_write_b128 v142, v[216:219] offset:8192
	global_load_dwordx4 v[216:219], v241, s[4:5]
	v_mfma_f32_32x32x16_bf16 v[48:63], v[172:175], v[188:191], v[48:63]
	v_mfma_f32_32x32x16_bf16 v[32:47], v[172:175], v[168:171], v[32:47]
	s_waitcnt vmcnt(13)
	ds_write_b128 v142, v[220:223] offset:16384
	global_load_dwordx4 v[220:223], v242, s[4:5]
	v_mfma_f32_32x32x16_bf16 v[16:31], v[184:187], v[188:191], v[16:31]
	v_mfma_f32_32x32x16_bf16 v[0:15], v[184:187], v[168:171], v[0:15]
	ds_read_b128 v[164:167], v148 offset:57344
	ds_read_b128 v[168:171], v161
	ds_read_b128 v[172:175], v148 offset:61440
	ds_read_b128 v[176:179], v157 offset:8192
	ds_read_b128 v[180:183], v180 offset:4096
	ds_read_b128 v[184:187], v162
	s_waitcnt vmcnt(13)
	ds_write_b128 v142, v[224:227] offset:24576
	global_load_dwordx4 v[224:227], v240, s[6:7]
	s_waitcnt lgkmcnt(5)
	v_mfma_f32_32x32x16_bf16 v[80:95], v[164:167], v[168:171], v[80:95]
	s_waitcnt lgkmcnt(2)
	v_mfma_f32_32x32x16_bf16 v[64:79], v[164:167], v[180:183], v[64:79]
	s_waitcnt vmcnt(13)
; #define G_STORE(BUF) do { char* l_ = lds + (BUF) * STAGE + wofs; \
;         *(uint4*)(l_) = ra0; *(uint4*)(l_ + 8192) = ra1; *(uint4*)(l_ + 16384) = ra2; if (MT == 4) *(uint4*)(l_ + 24576) = ra3; \
;         *(uint4*)(l_ + ABYTES) = rb0; *(uint4*)(l_ + ABYTES + 8192) = rb1; *(uint4*)(l_ + ABYTES + 16384) = rb2; *(uint4*)(l_ + ABYTES + 24576) = rb3; } while (0)
; template <int MT, bool PIN, class Epi>
; __device__ __forceinline__ void gemm_phase(const Params& P, const bf16_t* __restrict__ A, const bf16_t* __restrict__ Bt, int nM, int nN, int K, const Epi epi, char* lds) {
;     ...
;         G_LOAD(0);
;         f32x16 acc[MT][2];
; #pragma unroll
;         for (int a = 0; a < MT; ++a)
; #pragma unroll
;             for (int b = 0; b < 2; ++b)
; #pragma unroll
;                 for (int e = 0; e < 16; ++e) acc[a][b][e] = 0.f;
;         bf16x8 fa[2][MT], fb[2][2];
;         __syncthreads();
;         G_STORE(0);
;         G_LOAD(1);
;         __syncthreads();
;         for (int kt = 0; kt < nk; kt += 2) { G_STEP(0, kt); G_STEP(1, kt + 1); }
	ds_write_b128 v142, v[228:231] offset:32768
	global_load_dwordx4 v[228:231], v241, s[6:7]
	v_mfma_f32_32x32x16_bf16 v[48:63], v[172:175], v[168:171], v[48:63]
	v_mfma_f32_32x32x16_bf16 v[32:47], v[172:175], v[180:183], v[32:47]
	ds_read_b128 v[164:167], v155 offset:8192
	ds_read_b128 v[172:175], v156 offset:8192
	s_waitcnt vmcnt(13)
	ds_write_b128 v142, v[232:235] offset:40960
	global_load_dwordx4 v[232:235], v242, s[6:7]
	s_waitcnt lgkmcnt(2)
	v_mfma_f32_32x32x16_bf16 v[16:31], v[164:167], v[168:171], v[16:31]
	v_mfma_f32_32x32x16_bf16 v[0:15], v[164:167], v[180:183], v[0:15]
	ds_read_b128 v[164:167], v150 offset:57344
	ds_read_b128 v[168:171], v150 offset:61440
	v_add_u32_e32 v180, v154, v149
	ds_read_b128 v[180:183], v180 offset:4096
	ds_read_b128 v[188:191], v163
	s_waitcnt vmcnt(13)
	ds_write_b128 v142, v[236:239] offset:49152
	global_load_dwordx4 v[236:239], v243, s[6:7]
	s_waitcnt lgkmcnt(4)
	v_mfma_f32_32x32x16_bf16 v[80:95], v[164:167], v[184:187], v[80:95]
	s_waitcnt lgkmcnt(2)
	v_mfma_f32_32x32x16_bf16 v[64:79], v[164:167], v[180:183], v[64:79]
	v_mfma_f32_32x32x16_bf16 v[48:63], v[168:171], v[184:187], v[48:63]
	v_mfma_f32_32x32x16_bf16 v[32:47], v[168:171], v[180:183], v[32:47]
	ds_read_b128 v[164:167], v152 offset:57344
	ds_read_b128 v[168:171], v152 offset:61440
	v_mfma_f32_32x32x16_bf16 v[16:31], v[172:175], v[184:187], v[16:31]
	v_mfma_f32_32x32x16_bf16 v[0:15], v[172:175], v[180:183], v[0:15]
	v_add_u32_e32 v172, v154, v151
	ds_read_b128 v[172:175], v172 offset:4096
	s_waitcnt lgkmcnt(0)
	s_barrier
	v_mfma_f32_32x32x16_bf16 v[80:95], v[164:167], v[188:191], v[80:95]
	v_mfma_f32_32x32x16_bf16 v[64:79], v[164:167], v[172:175], v[64:79]
	v_mfma_f32_32x32x16_bf16 v[48:63], v[168:171], v[188:191], v[48:63]
	v_mfma_f32_32x32x16_bf16 v[32:47], v[168:171], v[172:175], v[32:47]
	v_mfma_f32_32x32x16_bf16 v[16:31], v[176:179], v[188:191], v[16:31]
	v_mfma_f32_32x32x16_bf16 v[0:15], v[176:179], v[172:175], v[0:15]
	s_cmp_lt_u32 s15, 28
	s_cbranch_scc1 .LBB0_2403
	v_add_u32_e32 v180, v145, v143
	ds_read_b128 v[164:167], v144
	ds_read_b128 v[168:171], v144 offset:4096
	ds_read_b128 v[172:175], v144 offset:8192
	ds_read_b128 v[176:179], v180 offset:24576
	ds_read_b128 v[180:183], v180 offset:28672
	s_add_i32 s16, s15, 2
	s_min_u32 s17, s1, 0xf80
	s_add_i32 s98, s1, 0x80
	s_min_u32 s98, s98, 0xf80
	s_addk_i32 s1, 0x100
	v_add_u32_e32 v240, s17, v124
	v_add_u32_e32 v241, 0x40000, v240
	v_add_u32_e32 v242, 0x80000, v240
	v_add_u32_e32 v243, 0xc0000, v240
	s_waitcnt lgkmcnt(1)
	v_mfma_f32_32x32x16_bf16 v[80:95], v[164:167], v[176:179], v[80:95]
	v_add_u32_e32 v188, v145, v149
	v_add_u32_e32 v126, v154, v143
	s_waitcnt lgkmcnt(0)
	v_mfma_f32_32x32x16_bf16 v[64:79], v[164:167], v[180:183], v[64:79]
	ds_read_b128 v[164:167], v148
	s_waitcnt vmcnt(13)
	ds_write_b128 v142, v[96:99] offset:57344
	global_load_dwordx4 v[96:99], v240, s[4:5]
	v_mfma_f32_32x32x16_bf16 v[48:63], v[168:171], v[176:179], v[48:63]
	v_mfma_f32_32x32x16_bf16 v[32:47], v[168:171], v[180:183], v[32:47]
	s_waitcnt vmcnt(13)
	ds_write_b128 v146, v[100:103] offset:8192
	global_load_dwordx4 v[100:103], v241, s[4:5]
	v_mfma_f32_32x32x16_bf16 v[0:15], v[172:175], v[180:183], v[0:15]
	v_add_u32_e32 v180, v145, v147
	v_mfma_f32_32x32x16_bf16 v[16:31], v[172:175], v[176:179], v[16:31]
	ds_read_b128 v[168:171], v180 offset:24576
	ds_read_b128 v[172:175], v148 offset:4096
	ds_read_b128 v[176:179], v152 offset:8192
	ds_read_b128 v[180:183], v180 offset:28672
	ds_read_b128 v[184:187], v188 offset:24576
	s_waitcnt vmcnt(13)
	ds_write_b128 v146, v[108:111] offset:16384
	global_load_dwordx4 v[108:111], v242, s[4:5]
	s_waitcnt lgkmcnt(5)
	v_mfma_f32_32x32x16_bf16 v[80:95], v[164:167], v[168:171], v[80:95]
	s_waitcnt lgkmcnt(2)
	v_mfma_f32_32x32x16_bf16 v[64:79], v[164:167], v[180:183], v[64:79]
	s_waitcnt vmcnt(13)
	ds_write_b128 v146, v[104:107] offset:24576
	global_load_dwordx4 v[104:107], v240, s[6:7]
	v_mfma_f32_32x32x16_bf16 v[48:63], v[172:175], v[168:171], v[48:63]
	v_mfma_f32_32x32x16_bf16 v[32:47], v[172:175], v[180:183], v[32:47]
	ds_read_b128 v[164:167], v148 offset:8192
	ds_read_b128 v[172:175], v150
	s_waitcnt vmcnt(13)
	ds_write_b128 v146, v[112:115] offset:32768
	global_load_dwordx4 v[112:115], v241, s[6:7]
	s_waitcnt lgkmcnt(2)
	v_mfma_f32_32x32x16_bf16 v[16:31], v[164:167], v[168:171], v[16:31]
	v_mfma_f32_32x32x16_bf16 v[0:15], v[164:167], v[180:183], v[0:15]
	ds_read_b128 v[164:167], v188 offset:28672
	v_add_u32_e32 v188, v145, v151
	ds_read_b128 v[168:171], v188 offset:24576
	s_waitcnt vmcnt(13)
	ds_write_b128 v146, v[116:119] offset:40960
	global_load_dwordx4 v[116:119], v242, s[6:7]
	s_waitcnt lgkmcnt(4)
	v_mfma_f32_32x32x16_bf16 v[80:95], v[172:175], v[184:187], v[80:95]
	s_waitcnt lgkmcnt(2)
	v_mfma_f32_32x32x16_bf16 v[64:79], v[172:175], v[164:167], v[64:79]
	ds_read_b128 v[172:175], v150 offset:4096
	ds_read_b128 v[180:183], v150 offset:8192
	s_waitcnt vmcnt(13)
	ds_write_b128 v146, v[120:123] offset:49152
	global_load_dwordx4 v[120:123], v243, s[6:7]
	s_waitcnt lgkmcnt(2)
	v_mfma_f32_32x32x16_bf16 v[48:63], v[172:175], v[184:187], v[48:63]
	v_mfma_f32_32x32x16_bf16 v[32:47], v[172:175], v[164:167], v[32:47]
	s_waitcnt lgkmcnt(1)
	v_mfma_f32_32x32x16_bf16 v[16:31], v[180:183], v[184:187], v[16:31]
	v_mfma_f32_32x32x16_bf16 v[0:15], v[180:183], v[164:167], v[0:15]
	ds_read_b128 v[164:167], v152
	ds_read_b128 v[172:175], v152 offset:4096
	ds_read_b128 v[180:183], v188 offset:28672
	s_waitcnt lgkmcnt(0)
	s_barrier
; #define G_STORE(BUF) do { char* l_ = lds + (BUF) * STAGE + wofs; \
;         *(uint4*)(l_) = ra0; *(uint4*)(l_ + 8192) = ra1; *(uint4*)(l_ + 16384) = ra2; if (MT == 4) *(uint4*)(l_ + 24576) = ra3; \
;         *(uint4*)(l_ + ABYTES) = rb0; *(uint4*)(l_ + ABYTES + 8192) = rb1; *(uint4*)(l_ + ABYTES + 16384) = rb2; *(uint4*)(l_ + ABYTES + 24576) = rb3; } while (0)
; template <int MT, bool PIN, class Epi>
; __device__ __forceinline__ void gemm_phase(const Params& P, const bf16_t* __restrict__ A, const bf16_t* __restrict__ Bt, int nM, int nN, int K, const Epi epi, char* lds) {
;     ...
;         G_LOAD(0);
;         f32x16 acc[MT][2];
; #pragma unroll
;         for (int a = 0; a < MT; ++a)
; #pragma unroll
;             for (int b = 0; b < 2; ++b)
; #pragma unroll
;                 for (int e = 0; e < 16; ++e) acc[a][b][e] = 0.f;
;         bf16x8 fa[2][MT], fb[2][2];
;         __syncthreads();
;         G_STORE(0);
;         G_LOAD(1);
;         __syncthreads();
;         for (int kt = 0; kt < nk; kt += 2) { G_STEP(0, kt); G_STEP(1, kt + 1); }
	v_mfma_f32_32x32x16_bf16 v[80:95], v[164:167], v[168:171], v[80:95]
	v_mfma_f32_32x32x16_bf16 v[64:79], v[164:167], v[180:183], v[64:79]
	v_mfma_f32_32x32x16_bf16 v[48:63], v[172:175], v[168:171], v[48:63]
	v_mfma_f32_32x32x16_bf16 v[32:47], v[172:175], v[180:183], v[32:47]
	ds_read_b128 v[164:167], v144 offset:57344
	ds_read_b128 v[172:175], v144 offset:61440
	ds_read_b128 v[184:187], v153 offset:8192
	ds_read_b128 v[188:191], v160
	v_mfma_f32_32x32x16_bf16 v[16:31], v[176:179], v[168:171], v[16:31]
	ds_read_b128 v[168:171], v126 offset:4096
	v_add_u32_e32 v240, s98, v124
	v_add_u32_e32 v241, 0x40000, v240
	v_add_u32_e32 v242, 0x80000, v240
	v_add_u32_e32 v243, 0xc0000, v240
	s_waitcnt vmcnt(13)
	ds_write_b128 v142, v[212:215]
	v_mfma_f32_32x32x16_bf16 v[0:15], v[176:179], v[180:183], v[0:15]
	s_waitcnt lgkmcnt(2)
	v_mfma_f32_32x32x16_bf16 v[80:95], v[164:167], v[188:191], v[80:95]
	v_add_u32_e32 v180, v154, v147
	s_mov_b32 s15, s16
	s_waitcnt lgkmcnt(1)
	v_mfma_f32_32x32x16_bf16 v[64:79], v[164:167], v[168:171], v[64:79]
	s_waitcnt vmcnt(12)
	ds_write_b128 v142, v[216:219] offset:8192
	v_mfma_f32_32x32x16_bf16 v[48:63], v[172:175], v[188:191], v[48:63]
	v_mfma_f32_32x32x16_bf16 v[32:47], v[172:175], v[168:171], v[32:47]
	s_waitcnt vmcnt(11)
	ds_write_b128 v142, v[220:223] offset:16384
	v_mfma_f32_32x32x16_bf16 v[16:31], v[184:187], v[188:191], v[16:31]
	v_mfma_f32_32x32x16_bf16 v[0:15], v[184:187], v[168:171], v[0:15]
	ds_read_b128 v[164:167], v148 offset:57344
	ds_read_b128 v[168:171], v161
	ds_read_b128 v[172:175], v148 offset:61440
	ds_read_b128 v[176:179], v157 offset:8192
	ds_read_b128 v[180:183], v180 offset:4096
	ds_read_b128 v[184:187], v162
	s_waitcnt vmcnt(10)
	ds_write_b128 v142, v[224:227] offset:24576
	s_waitcnt lgkmcnt(5)
	v_mfma_f32_32x32x16_bf16 v[80:95], v[164:167], v[168:171], v[80:95]
	s_waitcnt lgkmcnt(2)
	v_mfma_f32_32x32x16_bf16 v[64:79], v[164:167], v[180:183], v[64:79]
	s_waitcnt vmcnt(9)
	ds_write_b128 v142, v[228:231] offset:32768
	v_mfma_f32_32x32x16_bf16 v[48:63], v[172:175], v[168:171], v[48:63]
	v_mfma_f32_32x32x16_bf16 v[32:47], v[172:175], v[180:183], v[32:47]
	ds_read_b128 v[164:167], v155 offset:8192
	ds_read_b128 v[172:175], v156 offset:8192
	s_waitcnt vmcnt(8)
	ds_write_b128 v142, v[232:235] offset:40960
	s_waitcnt lgkmcnt(2)
	v_mfma_f32_32x32x16_bf16 v[16:31], v[164:167], v[168:171], v[16:31]
	v_mfma_f32_32x32x16_bf16 v[0:15], v[164:167], v[180:183], v[0:15]
	ds_read_b128 v[164:167], v150 offset:57344
	ds_read_b128 v[168:171], v150 offset:61440
	v_add_u32_e32 v180, v154, v149
	ds_read_b128 v[180:183], v180 offset:4096
	ds_read_b128 v[188:191], v163
	s_waitcnt vmcnt(7)
	ds_write_b128 v142, v[236:239] offset:49152
	s_waitcnt lgkmcnt(4)
	v_mfma_f32_32x32x16_bf16 v[80:95], v[164:167], v[184:187], v[80:95]
	s_waitcnt lgkmcnt(2)
	v_mfma_f32_32x32x16_bf16 v[64:79], v[164:167], v[180:183], v[64:79]
	v_mfma_f32_32x32x16_bf16 v[48:63], v[168:171], v[184:187], v[48:63]
	v_mfma_f32_32x32x16_bf16 v[32:47], v[168:171], v[180:183], v[32:47]
	ds_read_b128 v[164:167], v152 offset:57344
	ds_read_b128 v[168:171], v152 offset:61440
	v_mfma_f32_32x32x16_bf16 v[16:31], v[172:175], v[184:187], v[16:31]
	v_mfma_f32_32x32x16_bf16 v[0:15], v[172:175], v[180:183], v[0:15]
	v_add_u32_e32 v172, v154, v151
	ds_read_b128 v[172:175], v172 offset:4096
	s_waitcnt lgkmcnt(0)
	s_barrier
	v_mfma_f32_32x32x16_bf16 v[80:95], v[164:167], v[188:191], v[80:95]
	v_mfma_f32_32x32x16_bf16 v[64:79], v[164:167], v[172:175], v[64:79]
	v_mfma_f32_32x32x16_bf16 v[48:63], v[168:171], v[188:191], v[48:63]
	v_mfma_f32_32x32x16_bf16 v[32:47], v[168:171], v[172:175], v[32:47]
	v_mfma_f32_32x32x16_bf16 v[16:31], v[176:179], v[188:191], v[16:31]
	v_mfma_f32_32x32x16_bf16 v[0:15], v[176:179], v[172:175], v[0:15]
	v_add_u32_e32 v180, v145, v143
	ds_read_b128 v[164:167], v144
	ds_read_b128 v[168:171], v144 offset:4096
	ds_read_b128 v[172:175], v144 offset:8192
	ds_read_b128 v[176:179], v180 offset:24576
	ds_read_b128 v[180:183], v180 offset:28672
	s_add_i32 s16, s15, 2
	s_min_u32 s17, s1, 0xf80
	s_add_i32 s98, s1, 0x80
	s_min_u32 s98, s98, 0xf80
	s_addk_i32 s1, 0x100
	v_add_u32_e32 v240, s17, v124
	v_add_u32_e32 v241, 0x40000, v240
	v_add_u32_e32 v242, 0x80000, v240
	v_add_u32_e32 v243, 0xc0000, v240
	s_waitcnt lgkmcnt(1)
	v_mfma_f32_32x32x16_bf16 v[80:95], v[164:167], v[176:179], v[80:95]
	v_add_u32_e32 v188, v145, v149
	v_add_u32_e32 v126, v154, v143
	s_waitcnt lgkmcnt(0)
	v_mfma_f32_32x32x16_bf16 v[64:79], v[164:167], v[180:183], v[64:79]
	ds_read_b128 v[164:167], v148
	s_waitcnt vmcnt(6)
	ds_write_b128 v142, v[96:99] offset:57344
	v_mfma_f32_32x32x16_bf16 v[48:63], v[168:171], v[176:179], v[48:63]
	v_mfma_f32_32x32x16_bf16 v[32:47], v[168:171], v[180:183], v[32:47]
	s_waitcnt vmcnt(5)
	ds_write_b128 v146, v[100:103] offset:8192
	v_mfma_f32_32x32x16_bf16 v[0:15], v[172:175], v[180:183], v[0:15]
	v_add_u32_e32 v180, v145, v147
	v_mfma_f32_32x32x16_bf16 v[16:31], v[172:175], v[176:179], v[16:31]
	ds_read_b128 v[168:171], v180 offset:24576
	ds_read_b128 v[172:175], v148 offset:4096
	ds_read_b128 v[176:179], v152 offset:8192
	ds_read_b128 v[180:183], v180 offset:28672
	ds_read_b128 v[184:187], v188 offset:24576
	s_waitcnt vmcnt(4)
	ds_write_b128 v146, v[108:111] offset:16384
	s_waitcnt lgkmcnt(5)
	v_mfma_f32_32x32x16_bf16 v[80:95], v[164:167], v[168:171], v[80:95]
	s_waitcnt lgkmcnt(2)
	v_mfma_f32_32x32x16_bf16 v[64:79], v[164:167], v[180:183], v[64:79]
	s_waitcnt vmcnt(3)
	ds_write_b128 v146, v[104:107] offset:24576
	v_mfma_f32_32x32x16_bf16 v[48:63], v[172:175], v[168:171], v[48:63]
	v_mfma_f32_32x32x16_bf16 v[32:47], v[172:175], v[180:183], v[32:47]
	ds_read_b128 v[164:167], v148 offset:8192
	ds_read_b128 v[172:175], v150
	s_waitcnt vmcnt(2)
	ds_write_b128 v146, v[112:115] offset:32768
	s_waitcnt lgkmcnt(2)
	v_mfma_f32_32x32x16_bf16 v[16:31], v[164:167], v[168:171], v[16:31]
	v_mfma_f32_32x32x16_bf16 v[0:15], v[164:167], v[180:183], v[0:15]
	ds_read_b128 v[164:167], v188 offset:28672
	v_add_u32_e32 v188, v145, v151
	ds_read_b128 v[168:171], v188 offset:24576
	s_waitcnt vmcnt(1)
	ds_write_b128 v146, v[116:119] offset:40960
	s_waitcnt lgkmcnt(4)
	v_mfma_f32_32x32x16_bf16 v[80:95], v[172:175], v[184:187], v[80:95]
	s_waitcnt lgkmcnt(2)
	v_mfma_f32_32x32x16_bf16 v[64:79], v[172:175], v[164:167], v[64:79]
	ds_read_b128 v[172:175], v150 offset:4096
	ds_read_b128 v[180:183], v150 offset:8192
	s_waitcnt vmcnt(0)
	ds_write_b128 v146, v[120:123] offset:49152
	s_waitcnt lgkmcnt(2)
	v_mfma_f32_32x32x16_bf16 v[48:63], v[172:175], v[184:187], v[48:63]
	v_mfma_f32_32x32x16_bf16 v[32:47], v[172:175], v[164:167], v[32:47]
	s_waitcnt lgkmcnt(1)
	v_mfma_f32_32x32x16_bf16 v[16:31], v[180:183], v[184:187], v[16:31]
	v_mfma_f32_32x32x16_bf16 v[0:15], v[180:183], v[164:167], v[0:15]
	ds_read_b128 v[164:167], v152
	ds_read_b128 v[172:175], v152 offset:4096
	ds_read_b128 v[180:183], v188 offset:28672
	s_waitcnt lgkmcnt(0)
	s_barrier
; #define G_STORE(BUF) do { char* l_ = lds + (BUF) * STAGE + wofs; \
;         *(uint4*)(l_) = ra0; *(uint4*)(l_ + 8192) = ra1; *(uint4*)(l_ + 16384) = ra2; if (MT == 4) *(uint4*)(l_ + 24576) = ra3; \
;         *(uint4*)(l_ + ABYTES) = rb0; *(uint4*)(l_ + ABYTES + 8192) = rb1; *(uint4*)(l_ + ABYTES + 16384) = rb2; *(uint4*)(l_ + ABYTES + 24576) = rb3; } while (0)
; template <int MT, bool PIN, class Epi>
; __device__ __forceinline__ void gemm_phase(const Params& P, const bf16_t* __restrict__ A, const bf16_t* __restrict__ Bt, int nM, int nN, int K, const Epi epi, char* lds) {
;     ...
;         G_LOAD(0);
;         f32x16 acc[MT][2];
; #pragma unroll
;         for (int a = 0; a < MT; ++a)
; #pragma unroll
;             for (int b = 0; b < 2; ++b)
; #pragma unroll
;                 for (int e = 0; e < 16; ++e) acc[a][b][e] = 0.f;
;         bf16x8 fa[2][MT], fb[2][2];
;         __syncthreads();
;         G_STORE(0);
;         G_LOAD(1);
;         __syncthreads();
;         for (int kt = 0; kt < nk; kt += 2) { G_STEP(0, kt); G_STEP(1, kt + 1); }
;     template <int MT> __device__ __forceinline__ void run(const Params& P, f32x16 (&acc)[MT][2], int rbase, int pn, int wc, int lane) const {
;     ...
;             for (int rg = 0; rg < 16; ++rg) { const int r = ROWOF(rb, mt, rg);
;                 const float* x = (r < NPR ? P.xp + (size_t)r * 2048 : P.xs + (size_t)(r - NPR) * 2048) + c0;
;                 float* y = P.out + O_Y + (size_t)r * 2048 + c0;
;                 y[0] = ALPHA * x[0] + acc[mt][0][rg]; y[32] = ALPHA * x[32] + acc[mt][1][rg]; }
	v_mfma_f32_32x32x16_bf16 v[80:95], v[164:167], v[168:171], v[80:95]
	v_mfma_f32_32x32x16_bf16 v[64:79], v[164:167], v[180:183], v[64:79]
	v_mfma_f32_32x32x16_bf16 v[48:63], v[172:175], v[168:171], v[48:63]
	v_mfma_f32_32x32x16_bf16 v[32:47], v[172:175], v[180:183], v[32:47]
	ds_read_b128 v[164:167], v144 offset:57344
	ds_read_b128 v[172:175], v144 offset:61440
	ds_read_b128 v[184:187], v153 offset:8192
	ds_read_b128 v[188:191], v160
	v_mfma_f32_32x32x16_bf16 v[16:31], v[176:179], v[168:171], v[16:31]
	ds_read_b128 v[168:171], v126 offset:4096
	v_add_u32_e32 v240, s98, v124
	v_add_u32_e32 v241, 0x40000, v240
	v_add_u32_e32 v242, 0x80000, v240
	v_add_u32_e32 v243, 0xc0000, v240
	v_mfma_f32_32x32x16_bf16 v[0:15], v[176:179], v[180:183], v[0:15]
	s_waitcnt lgkmcnt(1)
	v_mfma_f32_32x32x16_bf16 v[80:95], v[164:167], v[188:191], v[80:95]
	v_add_u32_e32 v180, v154, v147
	s_mov_b32 s15, s16
	s_waitcnt lgkmcnt(0)
	v_mfma_f32_32x32x16_bf16 v[64:79], v[164:167], v[168:171], v[64:79]
	v_mfma_f32_32x32x16_bf16 v[48:63], v[172:175], v[188:191], v[48:63]
	v_mfma_f32_32x32x16_bf16 v[32:47], v[172:175], v[168:171], v[32:47]
	v_mfma_f32_32x32x16_bf16 v[16:31], v[184:187], v[188:191], v[16:31]
	v_mfma_f32_32x32x16_bf16 v[0:15], v[184:187], v[168:171], v[0:15]
	ds_read_b128 v[164:167], v148 offset:57344
	ds_read_b128 v[168:171], v161
	ds_read_b128 v[172:175], v148 offset:61440
	ds_read_b128 v[176:179], v157 offset:8192
	ds_read_b128 v[180:183], v180 offset:4096
	ds_read_b128 v[184:187], v162
	s_waitcnt lgkmcnt(4)
	v_mfma_f32_32x32x16_bf16 v[80:95], v[164:167], v[168:171], v[80:95]
	s_waitcnt lgkmcnt(1)
	v_mfma_f32_32x32x16_bf16 v[64:79], v[164:167], v[180:183], v[64:79]
	v_mfma_f32_32x32x16_bf16 v[48:63], v[172:175], v[168:171], v[48:63]
	v_mfma_f32_32x32x16_bf16 v[32:47], v[172:175], v[180:183], v[32:47]
	ds_read_b128 v[164:167], v155 offset:8192
	ds_read_b128 v[172:175], v156 offset:8192
	s_waitcnt lgkmcnt(1)
	v_mfma_f32_32x32x16_bf16 v[16:31], v[164:167], v[168:171], v[16:31]
	v_mfma_f32_32x32x16_bf16 v[0:15], v[164:167], v[180:183], v[0:15]
	ds_read_b128 v[164:167], v150 offset:57344
	ds_read_b128 v[168:171], v150 offset:61440
	v_add_u32_e32 v180, v154, v149
	ds_read_b128 v[180:183], v180 offset:4096
	ds_read_b128 v[188:191], v163
	s_waitcnt lgkmcnt(3)
	v_mfma_f32_32x32x16_bf16 v[80:95], v[164:167], v[184:187], v[80:95]
	s_waitcnt lgkmcnt(1)
	v_mfma_f32_32x32x16_bf16 v[64:79], v[164:167], v[180:183], v[64:79]
	v_mfma_f32_32x32x16_bf16 v[48:63], v[168:171], v[184:187], v[48:63]
	v_mfma_f32_32x32x16_bf16 v[32:47], v[168:171], v[180:183], v[32:47]
	ds_read_b128 v[164:167], v152 offset:57344
	ds_read_b128 v[168:171], v152 offset:61440
	v_mfma_f32_32x32x16_bf16 v[16:31], v[172:175], v[184:187], v[16:31]
	v_mfma_f32_32x32x16_bf16 v[0:15], v[172:175], v[180:183], v[0:15]
	v_add_u32_e32 v172, v154, v151
	ds_read_b128 v[172:175], v172 offset:4096
	s_waitcnt lgkmcnt(0)
	s_barrier
	v_mfma_f32_32x32x16_bf16 v[80:95], v[164:167], v[188:191], v[80:95]
	v_mfma_f32_32x32x16_bf16 v[64:79], v[164:167], v[172:175], v[64:79]
	v_mfma_f32_32x32x16_bf16 v[48:63], v[168:171], v[188:191], v[48:63]
	v_mfma_f32_32x32x16_bf16 v[32:47], v[168:171], v[172:175], v[32:47]
	v_mfma_f32_32x32x16_bf16 v[16:31], v[176:179], v[188:191], v[16:31]
	v_mfma_f32_32x32x16_bf16 v[0:15], v[176:179], v[172:175], v[0:15]
	s_nop 1
	s_mulk_i32 s14, 0xc0
	s_waitcnt vmcnt(0)
	v_add_u32_e32 v96, s14, v158
	v_cmp_lt_i32_e32 vcc, s11, v96
	s_and_saveexec_b64 s[4:5], vcc
	s_xor_b64 s[4:5], exec, s[4:5]
	s_cbranch_execz .LBB0_2406
	v_add_u32_e32 v126, 0xffffc000, v96
	v_lshlrev_b64 v[98:99], 13, v[126:127]
	v_mov_b32_e32 v97, v127
	s_waitcnt vmcnt(4)
	v_lshl_add_u64 v[100:101], s[66:67], 0, v[98:99]
	v_lshlrev_b64 v[102:103], 13, v[96:97]

; #define G_STORE(BUF) do { char* l_ = lds + (BUF) * STAGE + wofs; \
;         *(uint4*)(l_) = ra0; *(uint4*)(l_ + 8192) = ra1; *(uint4*)(l_ + 16384) = ra2; if (MT == 4) *(uint4*)(l_ + 24576) = ra3; \
;         *(uint4*)(l_ + ABYTES) = rb0; *(uint4*)(l_ + ABYTES + 8192) = rb1; *(uint4*)(l_ + ABYTES + 16384) = rb2; *(uint4*)(l_ + ABYTES + 24576) = rb3; } while (0)
; template <int MT, bool PIN, class Epi>
; __device__ __forceinline__ void gemm_phase(const Params& P, const bf16_t* __restrict__ A, const bf16_t* __restrict__ Bt, int nM, int nN, int K, const Epi epi, char* lds) {
;     ...
;         G_LOAD(0);
;         f32x16 acc[MT][2];
; #pragma unroll
;         for (int a = 0; a < MT; ++a)
; #pragma unroll
;             for (int b = 0; b < 2; ++b)
; #pragma unroll
;                 for (int e = 0; e < 16; ++e) acc[a][b][e] = 0.f;
;         bf16x8 fa[2][MT], fb[2][2];
;         __syncthreads();
;         G_STORE(0);
;         G_LOAD(1);
;         __syncthreads();
;         for (int kt = 0; kt < nk; kt += 2) { G_STEP(0, kt); G_STEP(1, kt + 1); }
.LBB0_2723:
	v_add_u32_e32 v182, v148, v146
	ds_read_b128 v[166:169], v147
	ds_read_b128 v[170:173], v147 offset:4096
	ds_read_b128 v[174:177], v147 offset:8192
	ds_read_b128 v[178:181], v182 offset:24576
	ds_read_b128 v[182:185], v182 offset:28672
	s_add_i32 s17, s16, 2
	s_min_u32 s18, s7, 0xf80
	s_add_i32 s19, s7, 0x80
	s_min_u32 s19, s19, 0xf80
	s_addk_i32 s7, 0x100
	v_add_u32_e32 v240, s18, v126
	v_add_u32_e32 v241, 0x40000, v240
	v_add_u32_e32 v242, 0x80000, v240
	v_add_u32_e32 v243, 0xc0000, v240
	s_waitcnt lgkmcnt(1)
	v_mfma_f32_32x32x16_bf16 v[80:95], v[166:169], v[178:181], v[80:95]
	v_add_u32_e32 v190, v148, v152
	v_add_u32_e32 v194, v157, v146
	s_waitcnt lgkmcnt(0)
	v_mfma_f32_32x32x16_bf16 v[64:79], v[166:169], v[182:185], v[64:79]
	ds_read_b128 v[166:169], v151
	s_waitcnt vmcnt(13)
	ds_write_b128 v145, v[96:99] offset:57344
	global_load_dwordx4 v[96:99], v240, s[8:9]
	v_mfma_f32_32x32x16_bf16 v[48:63], v[170:173], v[178:181], v[48:63]
	v_mfma_f32_32x32x16_bf16 v[32:47], v[170:173], v[182:185], v[32:47]
	s_waitcnt vmcnt(13)
	ds_write_b128 v149, v[100:103] offset:8192
	global_load_dwordx4 v[100:103], v241, s[8:9]
	v_mfma_f32_32x32x16_bf16 v[0:15], v[174:177], v[182:185], v[0:15]
	v_add_u32_e32 v182, v148, v150
	v_mfma_f32_32x32x16_bf16 v[16:31], v[174:177], v[178:181], v[16:31]
	ds_read_b128 v[170:173], v182 offset:24576
	ds_read_b128 v[174:177], v151 offset:4096
	ds_read_b128 v[178:181], v155 offset:8192
	ds_read_b128 v[182:185], v182 offset:28672
	ds_read_b128 v[186:189], v190 offset:24576
	s_waitcnt vmcnt(13)
	ds_write_b128 v149, v[104:107] offset:16384
	global_load_dwordx4 v[104:107], v242, s[8:9]
	s_waitcnt lgkmcnt(5)
	v_mfma_f32_32x32x16_bf16 v[80:95], v[166:169], v[170:173], v[80:95]
	s_waitcnt lgkmcnt(2)
	v_mfma_f32_32x32x16_bf16 v[64:79], v[166:169], v[182:185], v[64:79]
	s_waitcnt vmcnt(13)
	ds_write_b128 v149, v[108:111] offset:24576
	global_load_dwordx4 v[108:111], v240, s[10:11]
	v_mfma_f32_32x32x16_bf16 v[48:63], v[174:177], v[170:173], v[48:63]
	v_mfma_f32_32x32x16_bf16 v[32:47], v[174:177], v[182:185], v[32:47]
	ds_read_b128 v[166:169], v151 offset:8192
	ds_read_b128 v[174:177], v153
	s_waitcnt vmcnt(13)
	ds_write_b128 v149, v[112:115] offset:32768
	global_load_dwordx4 v[112:115], v241, s[10:11]
	s_waitcnt lgkmcnt(2)
	v_mfma_f32_32x32x16_bf16 v[16:31], v[166:169], v[170:173], v[16:31]
	v_mfma_f32_32x32x16_bf16 v[0:15], v[166:169], v[182:185], v[0:15]
	ds_read_b128 v[166:169], v190 offset:28672
	v_add_u32_e32 v190, v148, v154
	ds_read_b128 v[170:173], v190 offset:24576
	s_waitcnt vmcnt(13)
	ds_write_b128 v149, v[116:119] offset:40960
	global_load_dwordx4 v[116:119], v242, s[10:11]
	s_waitcnt lgkmcnt(4)
	v_mfma_f32_32x32x16_bf16 v[80:95], v[174:177], v[186:189], v[80:95]
	s_waitcnt lgkmcnt(2)
	v_mfma_f32_32x32x16_bf16 v[64:79], v[174:177], v[166:169], v[64:79]
	ds_read_b128 v[174:177], v153 offset:4096
	ds_read_b128 v[182:185], v153 offset:8192
	s_waitcnt vmcnt(13)
	ds_write_b128 v149, v[120:123] offset:49152
	global_load_dwordx4 v[120:123], v243, s[10:11]
	s_waitcnt lgkmcnt(2)
	v_mfma_f32_32x32x16_bf16 v[48:63], v[174:177], v[186:189], v[48:63]
	v_mfma_f32_32x32x16_bf16 v[32:47], v[174:177], v[166:169], v[32:47]
	s_waitcnt lgkmcnt(1)
	v_mfma_f32_32x32x16_bf16 v[16:31], v[182:185], v[186:189], v[16:31]
	v_mfma_f32_32x32x16_bf16 v[0:15], v[182:185], v[166:169], v[0:15]
	ds_read_b128 v[166:169], v155
	ds_read_b128 v[174:177], v155 offset:4096
	ds_read_b128 v[182:185], v190 offset:28672
	s_waitcnt lgkmcnt(0)
	s_barrier
	v_mfma_f32_32x32x16_bf16 v[80:95], v[166:169], v[170:173], v[80:95]
	v_mfma_f32_32x32x16_bf16 v[64:79], v[166:169], v[182:185], v[64:79]
	v_mfma_f32_32x32x16_bf16 v[48:63], v[174:177], v[170:173], v[48:63]
	v_mfma_f32_32x32x16_bf16 v[32:47], v[174:177], v[182:185], v[32:47]
	ds_read_b128 v[166:169], v147 offset:57344
	ds_read_b128 v[174:177], v147 offset:61440
	ds_read_b128 v[186:189], v156 offset:8192
	ds_read_b128 v[190:193], v162
	v_mfma_f32_32x32x16_bf16 v[16:31], v[178:181], v[170:173], v[16:31]
	ds_read_b128 v[170:173], v194 offset:4096
	v_add_u32_e32 v240, s19, v126
	v_add_u32_e32 v241, 0x40000, v240
	v_add_u32_e32 v242, 0x80000, v240
	v_add_u32_e32 v243, 0xc0000, v240
	s_waitcnt vmcnt(13)
	ds_write_b128 v145, v[212:215]
	global_load_dwordx4 v[212:215], v240, s[8:9]
	v_mfma_f32_32x32x16_bf16 v[0:15], v[178:181], v[182:185], v[0:15]
	s_waitcnt lgkmcnt(2)
	v_mfma_f32_32x32x16_bf16 v[80:95], v[166:169], v[190:193], v[80:95]
	v_add_u32_e32 v182, v157, v150
	s_mov_b32 s16, s17
	s_waitcnt lgkmcnt(1)
	v_mfma_f32_32x32x16_bf16 v[64:79], v[166:169], v[170:173], v[64:79]
	s_waitcnt vmcnt(13)
	ds_write_b128 v145, v[216:219] offset:8192
	global_load_dwordx4 v[216:219], v241, s[8:9]
	v_mfma_f32_32x32x16_bf16 v[48:63], v[174:177], v[190:193], v[48:63]
	v_mfma_f32_32x32x16_bf16 v[32:47], v[174:177], v[170:173], v[32:47]
	s_waitcnt vmcnt(13)
	ds_write_b128 v145, v[220:223] offset:16384
	global_load_dwordx4 v[220:223], v242, s[8:9]
	v_mfma_f32_32x32x16_bf16 v[16:31], v[186:189], v[190:193], v[16:31]
	v_mfma_f32_32x32x16_bf16 v[0:15], v[186:189], v[170:173], v[0:15]
	ds_read_b128 v[166:169], v151 offset:57344
	ds_read_b128 v[170:173], v163
	ds_read_b128 v[174:177], v151 offset:61440
	ds_read_b128 v[178:181], v160 offset:8192
	ds_read_b128 v[182:185], v182 offset:4096
	ds_read_b128 v[186:189], v164
	s_waitcnt vmcnt(13)
	ds_write_b128 v145, v[224:227] offset:24576
	global_load_dwordx4 v[224:227], v240, s[10:11]
	s_waitcnt lgkmcnt(5)
	v_mfma_f32_32x32x16_bf16 v[80:95], v[166:169], v[170:173], v[80:95]
	s_waitcnt lgkmcnt(2)
	v_mfma_f32_32x32x16_bf16 v[64:79], v[166:169], v[182:185], v[64:79]
	s_waitcnt vmcnt(13)
; #define G_STORE(BUF) do { char* l_ = lds + (BUF) * STAGE + wofs; \
;         *(uint4*)(l_) = ra0; *(uint4*)(l_ + 8192) = ra1; *(uint4*)(l_ + 16384) = ra2; if (MT == 4) *(uint4*)(l_ + 24576) = ra3; \
;         *(uint4*)(l_ + ABYTES) = rb0; *(uint4*)(l_ + ABYTES + 8192) = rb1; *(uint4*)(l_ + ABYTES + 16384) = rb2; *(uint4*)(l_ + ABYTES + 24576) = rb3; } while (0)
; template <int MT, bool PIN, class Epi>
; __device__ __forceinline__ void gemm_phase(const Params& P, const bf16_t* __restrict__ A, const bf16_t* __restrict__ Bt, int nM, int nN, int K, const Epi epi, char* lds) {
;     ...
;         G_LOAD(0);
;         f32x16 acc[MT][2];
; #pragma unroll
;         for (int a = 0; a < MT; ++a)
; #pragma unroll
;             for (int b = 0; b < 2; ++b)
; #pragma unroll
;                 for (int e = 0; e < 16; ++e) acc[a][b][e] = 0.f;
;         bf16x8 fa[2][MT], fb[2][2];
;         __syncthreads();
;         G_STORE(0);
;         G_LOAD(1);
;         __syncthreads();
;         for (int kt = 0; kt < nk; kt += 2) { G_STEP(0, kt); G_STEP(1, kt + 1); }
	ds_write_b128 v145, v[228:231] offset:32768
	global_load_dwordx4 v[228:231], v241, s[10:11]
	v_mfma_f32_32x32x16_bf16 v[48:63], v[174:177], v[170:173], v[48:63]
	v_mfma_f32_32x32x16_bf16 v[32:47], v[174:177], v[182:185], v[32:47]
	ds_read_b128 v[166:169], v158 offset:8192
	ds_read_b128 v[174:177], v159 offset:8192
	s_waitcnt vmcnt(13)
	ds_write_b128 v145, v[232:235] offset:40960
	global_load_dwordx4 v[232:235], v242, s[10:11]
	s_waitcnt lgkmcnt(2)
	v_mfma_f32_32x32x16_bf16 v[16:31], v[166:169], v[170:173], v[16:31]
	v_mfma_f32_32x32x16_bf16 v[0:15], v[166:169], v[182:185], v[0:15]
	ds_read_b128 v[166:169], v153 offset:57344
	ds_read_b128 v[170:173], v153 offset:61440
	v_add_u32_e32 v182, v157, v152
	ds_read_b128 v[182:185], v182 offset:4096
	ds_read_b128 v[190:193], v165
	s_waitcnt vmcnt(13)
	ds_write_b128 v145, v[236:239] offset:49152
	global_load_dwordx4 v[236:239], v243, s[10:11]
	s_waitcnt lgkmcnt(4)
	v_mfma_f32_32x32x16_bf16 v[80:95], v[166:169], v[186:189], v[80:95]
	s_waitcnt lgkmcnt(2)
	v_mfma_f32_32x32x16_bf16 v[64:79], v[166:169], v[182:185], v[64:79]
	v_mfma_f32_32x32x16_bf16 v[48:63], v[170:173], v[186:189], v[48:63]
	v_mfma_f32_32x32x16_bf16 v[32:47], v[170:173], v[182:185], v[32:47]
	ds_read_b128 v[166:169], v155 offset:57344
	ds_read_b128 v[170:173], v155 offset:61440
	v_mfma_f32_32x32x16_bf16 v[16:31], v[174:177], v[186:189], v[16:31]
	v_mfma_f32_32x32x16_bf16 v[0:15], v[174:177], v[182:185], v[0:15]
	v_add_u32_e32 v174, v157, v154
	ds_read_b128 v[174:177], v174 offset:4096
	s_waitcnt lgkmcnt(0)
	s_barrier
	v_mfma_f32_32x32x16_bf16 v[80:95], v[166:169], v[190:193], v[80:95]
	v_mfma_f32_32x32x16_bf16 v[64:79], v[166:169], v[174:177], v[64:79]
	v_mfma_f32_32x32x16_bf16 v[48:63], v[170:173], v[190:193], v[48:63]
	v_mfma_f32_32x32x16_bf16 v[32:47], v[170:173], v[174:177], v[32:47]
	v_mfma_f32_32x32x16_bf16 v[16:31], v[178:181], v[190:193], v[16:31]
	v_mfma_f32_32x32x16_bf16 v[0:15], v[178:181], v[174:177], v[0:15]
	s_cmp_lt_u32 s16, 28
	s_cbranch_scc1 .LBB0_2723
	v_add_u32_e32 v182, v148, v146
	ds_read_b128 v[166:169], v147
	ds_read_b128 v[170:173], v147 offset:4096
	ds_read_b128 v[174:177], v147 offset:8192
	ds_read_b128 v[178:181], v182 offset:24576
	ds_read_b128 v[182:185], v182 offset:28672
	s_add_i32 s17, s16, 2
	s_min_u32 s18, s7, 0xf80
	s_add_i32 s19, s7, 0x80
	s_min_u32 s19, s19, 0xf80
	s_addk_i32 s7, 0x100
	v_add_u32_e32 v240, s18, v126
	v_add_u32_e32 v241, 0x40000, v240
	v_add_u32_e32 v242, 0x80000, v240
	v_add_u32_e32 v243, 0xc0000, v240
	s_waitcnt lgkmcnt(1)
	v_mfma_f32_32x32x16_bf16 v[80:95], v[166:169], v[178:181], v[80:95]
	v_add_u32_e32 v190, v148, v152
	v_add_u32_e32 v194, v157, v146
	s_waitcnt lgkmcnt(0)
	v_mfma_f32_32x32x16_bf16 v[64:79], v[166:169], v[182:185], v[64:79]
	ds_read_b128 v[166:169], v151
	s_waitcnt vmcnt(13)
	ds_write_b128 v145, v[96:99] offset:57344
	global_load_dwordx4 v[96:99], v240, s[8:9]
	v_mfma_f32_32x32x16_bf16 v[48:63], v[170:173], v[178:181], v[48:63]
	v_mfma_f32_32x32x16_bf16 v[32:47], v[170:173], v[182:185], v[32:47]
	s_waitcnt vmcnt(13)
	ds_write_b128 v149, v[100:103] offset:8192
	global_load_dwordx4 v[100:103], v241, s[8:9]
	v_mfma_f32_32x32x16_bf16 v[0:15], v[174:177], v[182:185], v[0:15]
	v_add_u32_e32 v182, v148, v150
	v_mfma_f32_32x32x16_bf16 v[16:31], v[174:177], v[178:181], v[16:31]
	ds_read_b128 v[170:173], v182 offset:24576
	ds_read_b128 v[174:177], v151 offset:4096
	ds_read_b128 v[178:181], v155 offset:8192
	ds_read_b128 v[182:185], v182 offset:28672
	ds_read_b128 v[186:189], v190 offset:24576
	s_waitcnt vmcnt(13)
	ds_write_b128 v149, v[104:107] offset:16384
	global_load_dwordx4 v[104:107], v242, s[8:9]
	s_waitcnt lgkmcnt(5)
	v_mfma_f32_32x32x16_bf16 v[80:95], v[166:169], v[170:173], v[80:95]
	s_waitcnt lgkmcnt(2)
	v_mfma_f32_32x32x16_bf16 v[64:79], v[166:169], v[182:185], v[64:79]
	s_waitcnt vmcnt(13)
	ds_write_b128 v149, v[108:111] offset:24576
	global_load_dwordx4 v[108:111], v240, s[10:11]
	v_mfma_f32_32x32x16_bf16 v[48:63], v[174:177], v[170:173], v[48:63]
	v_mfma_f32_32x32x16_bf16 v[32:47], v[174:177], v[182:185], v[32:47]
	ds_read_b128 v[166:169], v151 offset:8192
	ds_read_b128 v[174:177], v153
	s_waitcnt vmcnt(13)
	ds_write_b128 v149, v[112:115] offset:32768
	global_load_dwordx4 v[112:115], v241, s[10:11]
	s_waitcnt lgkmcnt(2)
	v_mfma_f32_32x32x16_bf16 v[16:31], v[166:169], v[170:173], v[16:31]
	v_mfma_f32_32x32x16_bf16 v[0:15], v[166:169], v[182:185], v[0:15]
	ds_read_b128 v[166:169], v190 offset:28672
	v_add_u32_e32 v190, v148, v154
	ds_read_b128 v[170:173], v190 offset:24576
	s_waitcnt vmcnt(13)
	ds_write_b128 v149, v[116:119] offset:40960
	global_load_dwordx4 v[116:119], v242, s[10:11]
	s_waitcnt lgkmcnt(4)
	v_mfma_f32_32x32x16_bf16 v[80:95], v[174:177], v[186:189], v[80:95]
	s_waitcnt lgkmcnt(2)
	v_mfma_f32_32x32x16_bf16 v[64:79], v[174:177], v[166:169], v[64:79]
	ds_read_b128 v[174:177], v153 offset:4096
	ds_read_b128 v[182:185], v153 offset:8192
	s_waitcnt vmcnt(13)
	ds_write_b128 v149, v[120:123] offset:49152
	global_load_dwordx4 v[120:123], v243, s[10:11]
	s_waitcnt lgkmcnt(2)
	v_mfma_f32_32x32x16_bf16 v[48:63], v[174:177], v[186:189], v[48:63]
	v_mfma_f32_32x32x16_bf16 v[32:47], v[174:177], v[166:169], v[32:47]
	s_waitcnt lgkmcnt(1)
	v_mfma_f32_32x32x16_bf16 v[16:31], v[182:185], v[186:189], v[16:31]
	v_mfma_f32_32x32x16_bf16 v[0:15], v[182:185], v[166:169], v[0:15]
	ds_read_b128 v[166:169], v155
	ds_read_b128 v[174:177], v155 offset:4096
	ds_read_b128 v[182:185], v190 offset:28672
	s_waitcnt lgkmcnt(0)
	s_barrier
; #define G_STORE(BUF) do { char* l_ = lds + (BUF) * STAGE + wofs; \
;         *(uint4*)(l_) = ra0; *(uint4*)(l_ + 8192) = ra1; *(uint4*)(l_ + 16384) = ra2; if (MT == 4) *(uint4*)(l_ + 24576) = ra3; \
;         *(uint4*)(l_ + ABYTES) = rb0; *(uint4*)(l_ + ABYTES + 8192) = rb1; *(uint4*)(l_ + ABYTES + 16384) = rb2; *(uint4*)(l_ + ABYTES + 24576) = rb3; } while (0)
; template <int MT, bool PIN, class Epi>
; __device__ __forceinline__ void gemm_phase(const Params& P, const bf16_t* __restrict__ A, const bf16_t* __restrict__ Bt, int nM, int nN, int K, const Epi epi, char* lds) {
;     ...
;         G_LOAD(0);
;         f32x16 acc[MT][2];
; #pragma unroll
;         for (int a = 0; a < MT; ++a)
; #pragma unroll
;             for (int b = 0; b < 2; ++b)
; #pragma unroll
;                 for (int e = 0; e < 16; ++e) acc[a][b][e] = 0.f;
;         bf16x8 fa[2][MT], fb[2][2];
;         __syncthreads();
;         G_STORE(0);
;         G_LOAD(1);
;         __syncthreads();
;         for (int kt = 0; kt < nk; kt += 2) { G_STEP(0, kt); G_STEP(1, kt + 1); }
	v_mfma_f32_32x32x16_bf16 v[80:95], v[166:169], v[170:173], v[80:95]
	v_mfma_f32_32x32x16_bf16 v[64:79], v[166:169], v[182:185], v[64:79]
	v_mfma_f32_32x32x16_bf16 v[48:63], v[174:177], v[170:173], v[48:63]
	v_mfma_f32_32x32x16_bf16 v[32:47], v[174:177], v[182:185], v[32:47]
	ds_read_b128 v[166:169], v147 offset:57344
	ds_read_b128 v[174:177], v147 offset:61440
	ds_read_b128 v[186:189], v156 offset:8192
	ds_read_b128 v[190:193], v162
	v_mfma_f32_32x32x16_bf16 v[16:31], v[178:181], v[170:173], v[16:31]
	ds_read_b128 v[170:173], v194 offset:4096
	v_add_u32_e32 v240, s19, v126
	v_add_u32_e32 v241, 0x40000, v240
	v_add_u32_e32 v242, 0x80000, v240
	v_add_u32_e32 v243, 0xc0000, v240
	s_waitcnt vmcnt(13)
	ds_write_b128 v145, v[212:215]
	v_mfma_f32_32x32x16_bf16 v[0:15], v[178:181], v[182:185], v[0:15]
	s_waitcnt lgkmcnt(2)
	v_mfma_f32_32x32x16_bf16 v[80:95], v[166:169], v[190:193], v[80:95]
	v_add_u32_e32 v182, v157, v150
	s_mov_b32 s16, s17
	s_waitcnt lgkmcnt(1)
	v_mfma_f32_32x32x16_bf16 v[64:79], v[166:169], v[170:173], v[64:79]
	s_waitcnt vmcnt(12)
	ds_write_b128 v145, v[216:219] offset:8192
	v_mfma_f32_32x32x16_bf16 v[48:63], v[174:177], v[190:193], v[48:63]
	v_mfma_f32_32x32x16_bf16 v[32:47], v[174:177], v[170:173], v[32:47]
	s_waitcnt vmcnt(11)
	ds_write_b128 v145, v[220:223] offset:16384
	v_mfma_f32_32x32x16_bf16 v[16:31], v[186:189], v[190:193], v[16:31]
	v_mfma_f32_32x32x16_bf16 v[0:15], v[186:189], v[170:173], v[0:15]
	ds_read_b128 v[166:169], v151 offset:57344
	ds_read_b128 v[170:173], v163
	ds_read_b128 v[174:177], v151 offset:61440
	ds_read_b128 v[178:181], v160 offset:8192
	ds_read_b128 v[182:185], v182 offset:4096
	ds_read_b128 v[186:189], v164
	s_waitcnt vmcnt(10)
	ds_write_b128 v145, v[224:227] offset:24576
	s_waitcnt lgkmcnt(5)
	v_mfma_f32_32x32x16_bf16 v[80:95], v[166:169], v[170:173], v[80:95]
	s_waitcnt lgkmcnt(2)
	v_mfma_f32_32x32x16_bf16 v[64:79], v[166:169], v[182:185], v[64:79]
	s_waitcnt vmcnt(9)
	ds_write_b128 v145, v[228:231] offset:32768
	v_mfma_f32_32x32x16_bf16 v[48:63], v[174:177], v[170:173], v[48:63]
	v_mfma_f32_32x32x16_bf16 v[32:47], v[174:177], v[182:185], v[32:47]
	ds_read_b128 v[166:169], v158 offset:8192
	ds_read_b128 v[174:177], v159 offset:8192
	s_waitcnt vmcnt(8)
	ds_write_b128 v145, v[232:235] offset:40960
	s_waitcnt lgkmcnt(2)
	v_mfma_f32_32x32x16_bf16 v[16:31], v[166:169], v[170:173], v[16:31]
	v_mfma_f32_32x32x16_bf16 v[0:15], v[166:169], v[182:185], v[0:15]
	ds_read_b128 v[166:169], v153 offset:57344
	ds_read_b128 v[170:173], v153 offset:61440
	v_add_u32_e32 v182, v157, v152
	ds_read_b128 v[182:185], v182 offset:4096
	ds_read_b128 v[190:193], v165
	s_waitcnt vmcnt(7)
	ds_write_b128 v145, v[236:239] offset:49152
	s_waitcnt lgkmcnt(4)
	v_mfma_f32_32x32x16_bf16 v[80:95], v[166:169], v[186:189], v[80:95]
	s_waitcnt lgkmcnt(2)
	v_mfma_f32_32x32x16_bf16 v[64:79], v[166:169], v[182:185], v[64:79]
	v_mfma_f32_32x32x16_bf16 v[48:63], v[170:173], v[186:189], v[48:63]
	v_mfma_f32_32x32x16_bf16 v[32:47], v[170:173], v[182:185], v[32:47]
	ds_read_b128 v[166:169], v155 offset:57344
	ds_read_b128 v[170:173], v155 offset:61440
	v_mfma_f32_32x32x16_bf16 v[16:31], v[174:177], v[186:189], v[16:31]
	v_mfma_f32_32x32x16_bf16 v[0:15], v[174:177], v[182:185], v[0:15]
	v_add_u32_e32 v174, v157, v154
	ds_read_b128 v[174:177], v174 offset:4096
	s_waitcnt lgkmcnt(0)
	s_barrier
	v_mfma_f32_32x32x16_bf16 v[80:95], v[166:169], v[190:193], v[80:95]
	v_mfma_f32_32x32x16_bf16 v[64:79], v[166:169], v[174:177], v[64:79]
	v_mfma_f32_32x32x16_bf16 v[48:63], v[170:173], v[190:193], v[48:63]
	v_mfma_f32_32x32x16_bf16 v[32:47], v[170:173], v[174:177], v[32:47]
	v_mfma_f32_32x32x16_bf16 v[16:31], v[178:181], v[190:193], v[16:31]
	v_mfma_f32_32x32x16_bf16 v[0:15], v[178:181], v[174:177], v[0:15]
	v_add_u32_e32 v182, v148, v146
	ds_read_b128 v[166:169], v147
	ds_read_b128 v[170:173], v147 offset:4096
	ds_read_b128 v[174:177], v147 offset:8192
	ds_read_b128 v[178:181], v182 offset:24576
	ds_read_b128 v[182:185], v182 offset:28672
	s_add_i32 s17, s16, 2
	s_min_u32 s18, s7, 0xf80
	s_add_i32 s19, s7, 0x80
	s_min_u32 s19, s19, 0xf80
	s_addk_i32 s7, 0x100
	v_add_u32_e32 v240, s18, v126
	v_add_u32_e32 v241, 0x40000, v240
	v_add_u32_e32 v242, 0x80000, v240
	v_add_u32_e32 v243, 0xc0000, v240
	s_waitcnt lgkmcnt(1)
	v_mfma_f32_32x32x16_bf16 v[80:95], v[166:169], v[178:181], v[80:95]
	v_add_u32_e32 v190, v148, v152
	v_add_u32_e32 v194, v157, v146
	s_waitcnt lgkmcnt(0)
	v_mfma_f32_32x32x16_bf16 v[64:79], v[166:169], v[182:185], v[64:79]
	ds_read_b128 v[166:169], v151
	s_waitcnt vmcnt(6)
	ds_write_b128 v145, v[96:99] offset:57344
	v_mfma_f32_32x32x16_bf16 v[48:63], v[170:173], v[178:181], v[48:63]
	v_mfma_f32_32x32x16_bf16 v[32:47], v[170:173], v[182:185], v[32:47]
	s_waitcnt vmcnt(5)
	ds_write_b128 v149, v[100:103] offset:8192
	v_mfma_f32_32x32x16_bf16 v[0:15], v[174:177], v[182:185], v[0:15]
	v_add_u32_e32 v182, v148, v150
	v_mfma_f32_32x32x16_bf16 v[16:31], v[174:177], v[178:181], v[16:31]
	ds_read_b128 v[170:173], v182 offset:24576
	ds_read_b128 v[174:177], v151 offset:4096
	ds_read_b128 v[178:181], v155 offset:8192
	ds_read_b128 v[182:185], v182 offset:28672
	ds_read_b128 v[186:189], v190 offset:24576
	s_waitcnt vmcnt(4)
	ds_write_b128 v149, v[104:107] offset:16384
	s_waitcnt lgkmcnt(5)
	v_mfma_f32_32x32x16_bf16 v[80:95], v[166:169], v[170:173], v[80:95]
	s_waitcnt lgkmcnt(2)
	v_mfma_f32_32x32x16_bf16 v[64:79], v[166:169], v[182:185], v[64:79]
	s_waitcnt vmcnt(3)
	ds_write_b128 v149, v[108:111] offset:24576
	v_mfma_f32_32x32x16_bf16 v[48:63], v[174:177], v[170:173], v[48:63]
	v_mfma_f32_32x32x16_bf16 v[32:47], v[174:177], v[182:185], v[32:47]
	ds_read_b128 v[166:169], v151 offset:8192
	ds_read_b128 v[174:177], v153
	s_waitcnt vmcnt(2)
	ds_write_b128 v149, v[112:115] offset:32768
	s_waitcnt lgkmcnt(2)
	v_mfma_f32_32x32x16_bf16 v[16:31], v[166:169], v[170:173], v[16:31]
	v_mfma_f32_32x32x16_bf16 v[0:15], v[166:169], v[182:185], v[0:15]
	ds_read_b128 v[166:169], v190 offset:28672
	v_add_u32_e32 v190, v148, v154
	ds_read_b128 v[170:173], v190 offset:24576
	s_waitcnt vmcnt(1)
	ds_write_b128 v149, v[116:119] offset:40960
	s_waitcnt lgkmcnt(4)
	v_mfma_f32_32x32x16_bf16 v[80:95], v[174:177], v[186:189], v[80:95]
	s_waitcnt lgkmcnt(2)
	v_mfma_f32_32x32x16_bf16 v[64:79], v[174:177], v[166:169], v[64:79]
	ds_read_b128 v[174:177], v153 offset:4096
	ds_read_b128 v[182:185], v153 offset:8192
	s_waitcnt vmcnt(0)
	ds_write_b128 v149, v[120:123] offset:49152
	s_waitcnt lgkmcnt(2)
	v_mfma_f32_32x32x16_bf16 v[48:63], v[174:177], v[186:189], v[48:63]
	v_mfma_f32_32x32x16_bf16 v[32:47], v[174:177], v[166:169], v[32:47]
	s_waitcnt lgkmcnt(1)
	v_mfma_f32_32x32x16_bf16 v[16:31], v[182:185], v[186:189], v[16:31]
	v_mfma_f32_32x32x16_bf16 v[0:15], v[182:185], v[166:169], v[0:15]
	ds_read_b128 v[166:169], v155
	ds_read_b128 v[174:177], v155 offset:4096
	ds_read_b128 v[182:185], v190 offset:28672
	s_waitcnt lgkmcnt(0)
	s_barrier
; __device__ __forceinline__ bf16_t f2bf(float f) { return (bf16_t)(pk_bf16(f, f) & 0xffffu); }
; #define G_STORE(BUF) do { char* l_ = lds + (BUF) * STAGE + wofs; \
;         *(uint4*)(l_) = ra0; *(uint4*)(l_ + 8192) = ra1; *(uint4*)(l_ + 16384) = ra2; if (MT == 4) *(uint4*)(l_ + 24576) = ra3; \
;         *(uint4*)(l_ + ABYTES) = rb0; *(uint4*)(l_ + ABYTES + 8192) = rb1; *(uint4*)(l_ + ABYTES + 16384) = rb2; *(uint4*)(l_ + ABYTES + 24576) = rb3; } while (0)
; template <int MT, bool PIN, class Epi>
; __device__ __forceinline__ void gemm_phase(const Params& P, const bf16_t* __restrict__ A, const bf16_t* __restrict__ Bt, int nM, int nN, int K, const Epi epi, char* lds) {
;     ...
;         G_LOAD(0);
;         f32x16 acc[MT][2];
; #pragma unroll
;         for (int a = 0; a < MT; ++a)
; #pragma unroll
;             for (int b = 0; b < 2; ++b)
; #pragma unroll
;                 for (int e = 0; e < 16; ++e) acc[a][b][e] = 0.f;
;         bf16x8 fa[2][MT], fb[2][2];
;         __syncthreads();
;         G_STORE(0);
;         G_LOAD(1);
;         __syncthreads();
;         for (int kt = 0; kt < nk; kt += 2) { G_STEP(0, kt); G_STEP(1, kt + 1); }
;     template <int MT> __device__ __forceinline__ void run(const Params& P, f32x16 (&acc)[MT][2], int rbase, int pn, int wc, int lane) const {
;     ...
;             for (int rg = 0; rg < 16; ++rg) { const int r = ROWOF(rb, mt, rg); const float g = acc[mt][0][rg], u = acc[mt][1][rg];
;                 const float sg = g * __builtin_amdgcn_rcpf(1.0f + __builtin_amdgcn_exp2f(-1.4426950408889634f * g));
;                 H[(size_t)r * 5632] = f2bf(sg * u); }
	v_mfma_f32_32x32x16_bf16 v[80:95], v[166:169], v[170:173], v[80:95]
	v_mfma_f32_32x32x16_bf16 v[64:79], v[166:169], v[182:185], v[64:79]
	v_mfma_f32_32x32x16_bf16 v[48:63], v[174:177], v[170:173], v[48:63]
	v_mfma_f32_32x32x16_bf16 v[32:47], v[174:177], v[182:185], v[32:47]
	ds_read_b128 v[166:169], v147 offset:57344
	ds_read_b128 v[174:177], v147 offset:61440
	ds_read_b128 v[186:189], v156 offset:8192
	ds_read_b128 v[190:193], v162
	v_mfma_f32_32x32x16_bf16 v[16:31], v[178:181], v[170:173], v[16:31]
	ds_read_b128 v[170:173], v194 offset:4096
	v_add_u32_e32 v240, s19, v126
	v_add_u32_e32 v241, 0x40000, v240
	v_add_u32_e32 v242, 0x80000, v240
	v_add_u32_e32 v243, 0xc0000, v240
	v_mfma_f32_32x32x16_bf16 v[0:15], v[178:181], v[182:185], v[0:15]
	s_waitcnt lgkmcnt(1)
	v_mfma_f32_32x32x16_bf16 v[80:95], v[166:169], v[190:193], v[80:95]
	v_add_u32_e32 v182, v157, v150
	s_mov_b32 s16, s17
	s_waitcnt lgkmcnt(0)
	v_mfma_f32_32x32x16_bf16 v[64:79], v[166:169], v[170:173], v[64:79]
	v_mfma_f32_32x32x16_bf16 v[48:63], v[174:177], v[190:193], v[48:63]
	v_mfma_f32_32x32x16_bf16 v[32:47], v[174:177], v[170:173], v[32:47]
	v_mfma_f32_32x32x16_bf16 v[16:31], v[186:189], v[190:193], v[16:31]
	v_mfma_f32_32x32x16_bf16 v[0:15], v[186:189], v[170:173], v[0:15]
	ds_read_b128 v[166:169], v151 offset:57344
	ds_read_b128 v[170:173], v163
	ds_read_b128 v[174:177], v151 offset:61440
	ds_read_b128 v[178:181], v160 offset:8192
	ds_read_b128 v[182:185], v182 offset:4096
	ds_read_b128 v[186:189], v164
	s_waitcnt lgkmcnt(4)
	v_mfma_f32_32x32x16_bf16 v[80:95], v[166:169], v[170:173], v[80:95]
	s_waitcnt lgkmcnt(1)
	v_mfma_f32_32x32x16_bf16 v[64:79], v[166:169], v[182:185], v[64:79]
	v_mfma_f32_32x32x16_bf16 v[48:63], v[174:177], v[170:173], v[48:63]
	v_mfma_f32_32x32x16_bf16 v[32:47], v[174:177], v[182:185], v[32:47]
	ds_read_b128 v[166:169], v158 offset:8192
	ds_read_b128 v[174:177], v159 offset:8192
	s_waitcnt lgkmcnt(1)
	v_mfma_f32_32x32x16_bf16 v[16:31], v[166:169], v[170:173], v[16:31]
	v_mfma_f32_32x32x16_bf16 v[0:15], v[166:169], v[182:185], v[0:15]
	ds_read_b128 v[166:169], v153 offset:57344
	ds_read_b128 v[170:173], v153 offset:61440
	v_add_u32_e32 v182, v157, v152
	ds_read_b128 v[182:185], v182 offset:4096
	ds_read_b128 v[190:193], v165
	s_waitcnt lgkmcnt(3)
	v_mfma_f32_32x32x16_bf16 v[80:95], v[166:169], v[186:189], v[80:95]
	s_waitcnt lgkmcnt(1)
	v_mfma_f32_32x32x16_bf16 v[64:79], v[166:169], v[182:185], v[64:79]
	v_mfma_f32_32x32x16_bf16 v[48:63], v[170:173], v[186:189], v[48:63]
	v_mfma_f32_32x32x16_bf16 v[32:47], v[170:173], v[182:185], v[32:47]
	ds_read_b128 v[166:169], v155 offset:57344
	ds_read_b128 v[170:173], v155 offset:61440
	v_mfma_f32_32x32x16_bf16 v[16:31], v[174:177], v[186:189], v[16:31]
	v_mfma_f32_32x32x16_bf16 v[0:15], v[174:177], v[182:185], v[0:15]
	v_add_u32_e32 v174, v157, v154
	ds_read_b128 v[174:177], v174 offset:4096
	s_waitcnt lgkmcnt(0)
	s_barrier
	v_mfma_f32_32x32x16_bf16 v[80:95], v[166:169], v[190:193], v[80:95]
	v_mfma_f32_32x32x16_bf16 v[64:79], v[166:169], v[174:177], v[64:79]
	v_mfma_f32_32x32x16_bf16 v[48:63], v[170:173], v[190:193], v[48:63]
	v_mfma_f32_32x32x16_bf16 v[32:47], v[170:173], v[174:177], v[32:47]
	v_mfma_f32_32x32x16_bf16 v[16:31], v[178:181], v[190:193], v[16:31]
	v_mfma_f32_32x32x16_bf16 v[0:15], v[178:181], v[174:177], v[0:15]
	s_nop 1
	s_waitcnt vmcnt(0)
	s_nop 4
	v_mul_f32_e32 v96, 0xbfb8aa3b, v80
	v_exp_f32_e32 v96, v96
	s_waitcnt vmcnt(4)
	v_mul_f32_e32 v100, 0xbfb8aa3b, v81
	v_exp_f32_e32 v100, v100
	s_lshl_b32 s6, s6, 7
	v_add_f32_e32 v96, 1.0, v96
	v_rcp_f32_e32 v99, v96
	s_or_b32 s6, s6, s13
	s_mulk_i32 s15, 0xc0
	s_ashr_i32 s7, s6, 31
	v_mul_f32_e32 v80, v80, v99
	v_mul_f32_e32 v64, v64, v80
	v_add_f32_e32 v80, 1.0, v100
	v_rcp_f32_e32 v80, v80
	v_add_u32_e32 v98, s15, v161
	v_lshl_add_u64 v[96:97], s[6:7], 1, v[140:141]
	v_cvt_pk_bf16_f32 v64, v64, v64
	v_mul_f32_e32 v80, v81, v80
	v_mul_f32_e32 v65, v65, v80
	v_cvt_pk_bf16_f32 v80, v65, v65
	v_mul_f32_e32 v65, 0xbfb8aa3b, v82
	v_exp_f32_e32 v81, v65
	v_mad_i64_i32 v[100:101], s[6:7], v98, s14, v[96:97]
	global_store_short v[100:101], v64, off
	v_or_b32_e32 v64, 1, v98
	v_mad_i64_i32 v[64:65], s[6:7], v64, s14, v[96:97]
	global_store_short v[64:65], v80, off
	v_add_f32_e32 v64, 1.0, v81
	v_rcp_f32_e32 v64, v64
	v_mul_f32_e32 v80, 0xbfb8aa3b, v83
	v_exp_f32_e32 v80, v80
	v_or_b32_e32 v65, 2, v98
	v_mul_f32_e32 v64, v82, v64
	v_mul_f32_e32 v64, v66, v64
	v_cvt_pk_bf16_f32 v66, v64, v64
	v_add_f32_e32 v64, 1.0, v80
	v_rcp_f32_e32 v80, v64
	v_mad_i64_i32 v[64:65], s[6:7], v65, s14, v[96:97]
	global_store_short v[64:65], v66, off
	v_mul_f32_e32 v65, v83, v80
	v_mul_f32_e32 v65, v67, v65
	v_cvt_pk_bf16_f32 v66, v65, v65
	v_mul_f32_e32 v65, 0xbfb8aa3b, v84
	v_exp_f32_e32 v67, v65
	v_or_b32_e32 v64, 3, v98
	v_mad_i64_i32 v[64:65], s[6:7], v64, s14, v[96:97]
	global_store_short v[64:65], v66, off
	v_add_f32_e32 v64, 1.0, v67
	v_rcp_f32_e32 v64, v64
	v_mul_f32_e32 v66, 0xbfb8aa3b, v85
	v_exp_f32_e32 v66, v66
	v_or_b32_e32 v65, 8, v98
	v_mul_f32_e32 v64, v84, v64
	v_mul_f32_e32 v64, v68, v64
	v_cvt_pk_bf16_f32 v67, v64, v64
	v_add_f32_e32 v64, 1.0, v66
	v_rcp_f32_e32 v66, v64
	v_mad_i64_i32 v[64:65], s[6:7], v65, s14, v[96:97]
	global_store_short v[64:65], v67, off
	v_mul_f32_e32 v65, v85, v66
	v_mul_f32_e32 v65, v69, v65
	v_cvt_pk_bf16_f32 v66, v65, v65
	v_mul_f32_e32 v65, 0xbfb8aa3b, v86
	v_exp_f32_e32 v67, v65
	v_or_b32_e32 v64, 9, v98
	v_mad_i64_i32 v[64:65], s[6:7], v64, s14, v[96:97]
	global_store_short v[64:65], v66, off
	v_add_f32_e32 v64, 1.0, v67
	v_rcp_f32_e32 v64, v64
	v_mul_f32_e32 v66, 0xbfb8aa3b, v87
	v_exp_f32_e32 v66, v66
	v_or_b32_e32 v65, 10, v98
; __device__ __forceinline__ bf16_t f2bf(float f) { return (bf16_t)(pk_bf16(f, f) & 0xffffu); }
;     template <int MT> __device__ __forceinline__ void run(const Params& P, f32x16 (&acc)[MT][2], int rbase, int pn, int wc, int lane) const {
;         const int n = lane & 31, hh = lane >> 5; const int rb = rbase + 4 * hh;
;         bf16_t* H = (bf16_t*)(P.ws + OFF_HFF) + pn * 64 + 32 * wc + n;
; #pragma unroll
;         for (int mt = 0; mt < MT; ++mt)
; #pragma unroll
;             for (int rg = 0; rg < 16; ++rg) { const int r = ROWOF(rb, mt, rg); const float g = acc[mt][0][rg], u = acc[mt][1][rg];
;                 const float sg = g * __builtin_amdgcn_rcpf(1.0f + __builtin_amdgcn_exp2f(-1.4426950408889634f * g));
;                 H[(size_t)r * 5632] = f2bf(sg * u); }
;     }
	v_mul_f32_e32 v64, v86, v64
	v_mul_f32_e32 v64, v70, v64
	v_cvt_pk_bf16_f32 v67, v64, v64
	v_add_f32_e32 v64, 1.0, v66
	v_rcp_f32_e32 v66, v64
	v_mad_i64_i32 v[64:65], s[6:7], v65, s14, v[96:97]
	global_store_short v[64:65], v67, off
	v_mul_f32_e32 v65, v87, v66
	v_mul_f32_e32 v65, v71, v65
	v_cvt_pk_bf16_f32 v66, v65, v65
	v_mul_f32_e32 v65, 0xbfb8aa3b, v88
	v_exp_f32_e32 v67, v65
	v_or_b32_e32 v64, 11, v98
	v_mad_i64_i32 v[64:65], s[6:7], v64, s14, v[96:97]
	global_store_short v[64:65], v66, off
	v_add_f32_e32 v64, 1.0, v67
	v_rcp_f32_e32 v64, v64
	v_mul_f32_e32 v66, 0xbfb8aa3b, v89
	v_exp_f32_e32 v66, v66
	v_or_b32_e32 v65, 16, v98
	v_mul_f32_e32 v64, v88, v64
	v_mul_f32_e32 v64, v72, v64
	v_cvt_pk_bf16_f32 v67, v64, v64
	v_add_f32_e32 v64, 1.0, v66
	v_rcp_f32_e32 v66, v64
	v_mad_i64_i32 v[64:65], s[6:7], v65, s14, v[96:97]
	global_store_short v[64:65], v67, off
	v_mul_f32_e32 v65, v89, v66
	v_mul_f32_e32 v65, v73, v65
	v_cvt_pk_bf16_f32 v66, v65, v65
	v_mul_f32_e32 v65, 0xbfb8aa3b, v90
	v_exp_f32_e32 v67, v65
	v_or_b32_e32 v64, 17, v98
	v_mad_i64_i32 v[64:65], s[6:7], v64, s14, v[96:97]
	global_store_short v[64:65], v66, off
	v_add_f32_e32 v64, 1.0, v67
	v_rcp_f32_e32 v64, v64
	v_mul_f32_e32 v66, 0xbfb8aa3b, v91
	v_exp_f32_e32 v66, v66
	v_or_b32_e32 v65, 18, v98
	v_mul_f32_e32 v64, v90, v64
	v_mul_f32_e32 v64, v74, v64
	v_cvt_pk_bf16_f32 v67, v64, v64
	v_add_f32_e32 v64, 1.0, v66
	v_rcp_f32_e32 v66, v64
	v_mad_i64_i32 v[64:65], s[6:7], v65, s14, v[96:97]
	global_store_short v[64:65], v67, off
	v_mul_f32_e32 v65, v91, v66
	v_mul_f32_e32 v65, v75, v65
	v_cvt_pk_bf16_f32 v66, v65, v65
	v_mul_f32_e32 v65, 0xbfb8aa3b, v92
	v_exp_f32_e32 v67, v65
	v_or_b32_e32 v64, 19, v98
	v_mad_i64_i32 v[64:65], s[6:7], v64, s14, v[96:97]
	global_store_short v[64:65], v66, off
	v_add_f32_e32 v64, 1.0, v67
	v_rcp_f32_e32 v64, v64
	v_mul_f32_e32 v66, 0xbfb8aa3b, v93
	v_exp_f32_e32 v66, v66
	v_or_b32_e32 v65, 24, v98
	v_mul_f32_e32 v64, v92, v64
	v_mul_f32_e32 v64, v76, v64
	v_cvt_pk_bf16_f32 v67, v64, v64
	v_add_f32_e32 v64, 1.0, v66
	v_rcp_f32_e32 v66, v64
	v_mad_i64_i32 v[64:65], s[6:7], v65, s14, v[96:97]
	global_store_short v[64:65], v67, off
	v_mul_f32_e32 v65, v93, v66
	v_mul_f32_e32 v65, v77, v65
	v_cvt_pk_bf16_f32 v66, v65, v65
	v_mul_f32_e32 v65, 0xbfb8aa3b, v94
	v_exp_f32_e32 v67, v65
	v_or_b32_e32 v64, 25, v98
	v_mad_i64_i32 v[64:65], s[6:7], v64, s14, v[96:97]
	global_store_short v[64:65], v66, off
	v_add_f32_e32 v64, 1.0, v67
	v_rcp_f32_e32 v64, v64
	v_mul_f32_e32 v66, 0xbfb8aa3b, v95
	v_exp_f32_e32 v66, v66
	v_or_b32_e32 v65, 26, v98
	v_mul_f32_e32 v64, v94, v64
	v_mul_f32_e32 v64, v78, v64
	v_cvt_pk_bf16_f32 v67, v64, v64
	v_add_f32_e32 v64, 1.0, v66
	v_rcp_f32_e32 v66, v64
	v_mad_i64_i32 v[64:65], s[6:7], v65, s14, v[96:97]
	global_store_short v[64:65], v67, off
	v_mul_f32_e32 v65, v95, v66
	v_mul_f32_e32 v65, v79, v65
	v_cvt_pk_bf16_f32 v66, v65, v65
	v_mul_f32_e32 v65, 0xbfb8aa3b, v48
	v_exp_f32_e32 v67, v65
	v_or_b32_e32 v64, 27, v98
	v_mad_i64_i32 v[64:65], s[6:7], v64, s14, v[96:97]
	global_store_short v[64:65], v66, off
	v_add_f32_e32 v64, 1.0, v67
	v_rcp_f32_e32 v64, v64
	v_mul_f32_e32 v66, 0xbfb8aa3b, v49
	v_exp_f32_e32 v66, v66
	v_add_u32_e32 v65, 32, v98
	v_mul_f32_e32 v48, v48, v64
	v_mul_f32_e32 v32, v32, v48
	v_add_f32_e32 v48, 1.0, v66
	v_rcp_f32_e32 v48, v48
	v_cvt_pk_bf16_f32 v32, v32, v32
	v_mad_i64_i32 v[64:65], s[6:7], v65, s14, v[96:97]
	v_mul_f32_e32 v48, v49, v48
	v_mul_f32_e32 v33, v33, v48
	v_cvt_pk_bf16_f32 v48, v33, v33
	v_mul_f32_e32 v33, 0xbfb8aa3b, v50
	v_exp_f32_e32 v49, v33
	global_store_short v[64:65], v32, off
	v_add_u32_e32 v32, 33, v98
	v_mad_i64_i32 v[32:33], s[6:7], v32, s14, v[96:97]
	global_store_short v[32:33], v48, off
	v_add_f32_e32 v32, 1.0, v49
	v_rcp_f32_e32 v32, v32
	v_mul_f32_e32 v48, 0xbfb8aa3b, v51
	v_exp_f32_e32 v48, v48
	v_add_u32_e32 v33, 34, v98
	v_mul_f32_e32 v32, v50, v32
	v_mul_f32_e32 v32, v34, v32
	v_cvt_pk_bf16_f32 v34, v32, v32
	v_add_f32_e32 v32, 1.0, v48
	v_rcp_f32_e32 v48, v32
	v_mad_i64_i32 v[32:33], s[6:7], v33, s14, v[96:97]
	global_store_short v[32:33], v34, off
	v_mul_f32_e32 v33, v51, v48
	v_mul_f32_e32 v33, v35, v33
	v_cvt_pk_bf16_f32 v34, v33, v33
	v_mul_f32_e32 v33, 0xbfb8aa3b, v52
	v_exp_f32_e32 v35, v33
	v_add_u32_e32 v32, 35, v98
	v_mad_i64_i32 v[32:33], s[6:7], v32, s14, v[96:97]
	global_store_short v[32:33], v34, off
	v_add_f32_e32 v32, 1.0, v35
	v_rcp_f32_e32 v32, v32
	v_mul_f32_e32 v34, 0xbfb8aa3b, v53
	v_exp_f32_e32 v34, v34
	v_add_u32_e32 v33, 40, v98
	v_mul_f32_e32 v32, v52, v32
	v_mul_f32_e32 v32, v36, v32
	v_cvt_pk_bf16_f32 v35, v32, v32
	v_add_f32_e32 v32, 1.0, v34
	v_rcp_f32_e32 v34, v32
	v_mad_i64_i32 v[32:33], s[6:7], v33, s14, v[96:97]
	global_store_short v[32:33], v35, off
	v_mul_f32_e32 v33, v53, v34
	v_mul_f32_e32 v33, v37, v33
	v_cvt_pk_bf16_f32 v34, v33, v33
	v_mul_f32_e32 v33, 0xbfb8aa3b, v54
	v_exp_f32_e32 v35, v33
	v_add_u32_e32 v32, 41, v98
	v_mad_i64_i32 v[32:33], s[6:7], v32, s14, v[96:97]
	global_store_short v[32:33], v34, off
	v_add_f32_e32 v32, 1.0, v35
	v_rcp_f32_e32 v32, v32
	v_mul_f32_e32 v34, 0xbfb8aa3b, v55
	v_exp_f32_e32 v34, v34
	v_add_u32_e32 v33, 42, v98
	v_mul_f32_e32 v32, v54, v32
	v_mul_f32_e32 v32, v38, v32
	v_cvt_pk_bf16_f32 v35, v32, v32
	v_add_f32_e32 v32, 1.0, v34
	v_rcp_f32_e32 v34, v32
	v_mad_i64_i32 v[32:33], s[6:7], v33, s14, v[96:97]
	global_store_short v[32:33], v35, off
	v_mul_f32_e32 v33, v55, v34
	v_mul_f32_e32 v33, v39, v33
	v_cvt_pk_bf16_f32 v34, v33, v33
	v_mul_f32_e32 v33, 0xbfb8aa3b, v56
	v_exp_f32_e32 v35, v33
	v_add_u32_e32 v32, 43, v98
	v_mad_i64_i32 v[32:33], s[6:7], v32, s14, v[96:97]
; __device__ __forceinline__ bf16_t f2bf(float f) { return (bf16_t)(pk_bf16(f, f) & 0xffffu); }
;     template <int MT> __device__ __forceinline__ void run(const Params& P, f32x16 (&acc)[MT][2], int rbase, int pn, int wc, int lane) const {
;         const int n = lane & 31, hh = lane >> 5; const int rb = rbase + 4 * hh;
;         bf16_t* H = (bf16_t*)(P.ws + OFF_HFF) + pn * 64 + 32 * wc + n;
; #pragma unroll
;         for (int mt = 0; mt < MT; ++mt)
; #pragma unroll
;             for (int rg = 0; rg < 16; ++rg) { const int r = ROWOF(rb, mt, rg); const float g = acc[mt][0][rg], u = acc[mt][1][rg];
;                 const float sg = g * __builtin_amdgcn_rcpf(1.0f + __builtin_amdgcn_exp2f(-1.4426950408889634f * g));
;                 H[(size_t)r * 5632] = f2bf(sg * u); }
;     }
	global_store_short v[32:33], v34, off
	v_add_f32_e32 v32, 1.0, v35
	v_rcp_f32_e32 v32, v32
	v_mul_f32_e32 v34, 0xbfb8aa3b, v57
	v_exp_f32_e32 v34, v34
	v_add_u32_e32 v33, 48, v98
	v_mul_f32_e32 v32, v56, v32
	v_mul_f32_e32 v32, v40, v32
	v_cvt_pk_bf16_f32 v35, v32, v32
	v_add_f32_e32 v32, 1.0, v34
	v_rcp_f32_e32 v34, v32
	v_mad_i64_i32 v[32:33], s[6:7], v33, s14, v[96:97]
	global_store_short v[32:33], v35, off
	v_mul_f32_e32 v33, v57, v34
	v_mul_f32_e32 v33, v41, v33
	v_cvt_pk_bf16_f32 v34, v33, v33
	v_mul_f32_e32 v33, 0xbfb8aa3b, v58
	v_exp_f32_e32 v35, v33
	v_add_u32_e32 v32, 49, v98
	v_mad_i64_i32 v[32:33], s[6:7], v32, s14, v[96:97]
	global_store_short v[32:33], v34, off
	v_add_f32_e32 v32, 1.0, v35
	v_rcp_f32_e32 v32, v32
	v_mul_f32_e32 v34, 0xbfb8aa3b, v59
	v_exp_f32_e32 v34, v34
	v_add_u32_e32 v33, 50, v98
	v_mul_f32_e32 v32, v58, v32
	v_mul_f32_e32 v32, v42, v32
	v_cvt_pk_bf16_f32 v35, v32, v32
	v_add_f32_e32 v32, 1.0, v34
	v_rcp_f32_e32 v34, v32
	v_mad_i64_i32 v[32:33], s[6:7], v33, s14, v[96:97]
	global_store_short v[32:33], v35, off
	v_mul_f32_e32 v33, v59, v34
	v_mul_f32_e32 v33, v43, v33
	v_cvt_pk_bf16_f32 v34, v33, v33
	v_mul_f32_e32 v33, 0xbfb8aa3b, v60
	v_exp_f32_e32 v35, v33
	v_add_u32_e32 v32, 51, v98
	v_mad_i64_i32 v[32:33], s[6:7], v32, s14, v[96:97]
	global_store_short v[32:33], v34, off
	v_add_f32_e32 v32, 1.0, v35
	v_rcp_f32_e32 v32, v32
	v_mul_f32_e32 v34, 0xbfb8aa3b, v61
	v_exp_f32_e32 v34, v34
	v_add_u32_e32 v33, 56, v98
	v_mul_f32_e32 v32, v60, v32
	v_mul_f32_e32 v32, v44, v32
	v_cvt_pk_bf16_f32 v35, v32, v32
	v_add_f32_e32 v32, 1.0, v34
	v_rcp_f32_e32 v34, v32
	v_mad_i64_i32 v[32:33], s[6:7], v33, s14, v[96:97]
	global_store_short v[32:33], v35, off
	v_mul_f32_e32 v33, v61, v34
	v_mul_f32_e32 v33, v45, v33
	v_cvt_pk_bf16_f32 v34, v33, v33
	v_mul_f32_e32 v33, 0xbfb8aa3b, v62
	v_exp_f32_e32 v35, v33
	v_add_u32_e32 v32, 57, v98
	v_mad_i64_i32 v[32:33], s[6:7], v32, s14, v[96:97]
	global_store_short v[32:33], v34, off
	v_add_f32_e32 v32, 1.0, v35
	v_rcp_f32_e32 v32, v32
	v_mul_f32_e32 v34, 0xbfb8aa3b, v63
	v_exp_f32_e32 v34, v34
	v_add_u32_e32 v33, 58, v98
	v_mul_f32_e32 v32, v62, v32
	v_mul_f32_e32 v32, v46, v32
	v_cvt_pk_bf16_f32 v35, v32, v32
	v_add_f32_e32 v32, 1.0, v34
	v_rcp_f32_e32 v34, v32
	v_mad_i64_i32 v[32:33], s[6:7], v33, s14, v[96:97]
	global_store_short v[32:33], v35, off
	v_mul_f32_e32 v33, v63, v34
	v_mul_f32_e32 v33, v47, v33
	v_cvt_pk_bf16_f32 v34, v33, v33
	v_mul_f32_e32 v33, 0xbfb8aa3b, v16
	v_exp_f32_e32 v35, v33
	v_add_u32_e32 v32, 59, v98
	v_mad_i64_i32 v[32:33], s[6:7], v32, s14, v[96:97]
	global_store_short v[32:33], v34, off
	v_add_f32_e32 v32, 1.0, v35
	v_rcp_f32_e32 v32, v32
	v_mul_f32_e32 v34, 0xbfb8aa3b, v17
	v_exp_f32_e32 v34, v34
	v_add_u32_e32 v33, 64, v98
	v_mul_f32_e32 v16, v16, v32
	v_mul_f32_e32 v0, v0, v16
	v_add_f32_e32 v16, 1.0, v34
	v_rcp_f32_e32 v16, v16
	v_cvt_pk_bf16_f32 v0, v0, v0
	v_mad_i64_i32 v[32:33], s[6:7], v33, s14, v[96:97]
	v_mul_f32_e32 v16, v17, v16
	v_mul_f32_e32 v1, v1, v16
	v_cvt_pk_bf16_f32 v16, v1, v1
	v_mul_f32_e32 v1, 0xbfb8aa3b, v18
	v_exp_f32_e32 v17, v1
	global_store_short v[32:33], v0, off
	v_add_u32_e32 v0, 0x41, v98
	v_mad_i64_i32 v[0:1], s[6:7], v0, s14, v[96:97]
	global_store_short v[0:1], v16, off
	v_add_f32_e32 v0, 1.0, v17
	v_rcp_f32_e32 v0, v0
	v_mul_f32_e32 v16, 0xbfb8aa3b, v19
	v_exp_f32_e32 v16, v16
	v_add_u32_e32 v1, 0x42, v98
	v_mul_f32_e32 v0, v18, v0
	v_mul_f32_e32 v0, v2, v0
	v_cvt_pk_bf16_f32 v2, v0, v0
	v_add_f32_e32 v0, 1.0, v16
	v_rcp_f32_e32 v16, v0
	v_mad_i64_i32 v[0:1], s[6:7], v1, s14, v[96:97]
	global_store_short v[0:1], v2, off
	v_mul_f32_e32 v1, v19, v16
	v_mul_f32_e32 v1, v3, v1
	v_cvt_pk_bf16_f32 v2, v1, v1
	v_mul_f32_e32 v1, 0xbfb8aa3b, v20
	v_exp_f32_e32 v3, v1
; __device__ __forceinline__ bf16_t f2bf(float f) { return (bf16_t)(pk_bf16(f, f) & 0xffffu); }
; template <int MT, bool PIN, class Epi>
; __device__ __forceinline__ void gemm_phase(const Params& P, const bf16_t* __restrict__ A, const bf16_t* __restrict__ Bt, int nM, int nN, int K, const Epi epi, char* lds) {
;     ...
;     for (int it = 0;; ++it) {
;         const long L = (long)it * G + blockIdx.x; if (L >= nT) break;
;     template <int MT> __device__ __forceinline__ void run(const Params& P, f32x16 (&acc)[MT][2], int rbase, int pn, int wc, int lane) const {
;         const int n = lane & 31, hh = lane >> 5; const int rb = rbase + 4 * hh;
;         bf16_t* H = (bf16_t*)(P.ws + OFF_HFF) + pn * 64 + 32 * wc + n;
; #pragma unroll
;         for (int mt = 0; mt < MT; ++mt)
; #pragma unroll
;             for (int rg = 0; rg < 16; ++rg) { const int r = ROWOF(rb, mt, rg); const float g = acc[mt][0][rg], u = acc[mt][1][rg];
;                 const float sg = g * __builtin_amdgcn_rcpf(1.0f + __builtin_amdgcn_exp2f(-1.4426950408889634f * g));
;                 H[(size_t)r * 5632] = f2bf(sg * u); }
;     }
	v_add_u32_e32 v0, 0x43, v98
	v_mad_i64_i32 v[0:1], s[6:7], v0, s14, v[96:97]
	global_store_short v[0:1], v2, off
	v_add_f32_e32 v0, 1.0, v3
	v_rcp_f32_e32 v0, v0
	v_mul_f32_e32 v2, 0xbfb8aa3b, v21
	v_exp_f32_e32 v2, v2
	v_add_u32_e32 v1, 0x48, v98
	v_mul_f32_e32 v0, v20, v0
	v_mul_f32_e32 v0, v4, v0
	v_cvt_pk_bf16_f32 v3, v0, v0
	v_add_f32_e32 v0, 1.0, v2
	v_rcp_f32_e32 v2, v0
	v_mad_i64_i32 v[0:1], s[6:7], v1, s14, v[96:97]
	global_store_short v[0:1], v3, off
	v_mul_f32_e32 v1, v21, v2
	v_mul_f32_e32 v1, v5, v1
	v_cvt_pk_bf16_f32 v2, v1, v1
	v_mul_f32_e32 v1, 0xbfb8aa3b, v22
	v_exp_f32_e32 v3, v1
	v_add_u32_e32 v0, 0x49, v98
	v_mad_i64_i32 v[0:1], s[6:7], v0, s14, v[96:97]
	global_store_short v[0:1], v2, off
	v_add_f32_e32 v0, 1.0, v3
	v_rcp_f32_e32 v0, v0
	v_mul_f32_e32 v2, 0xbfb8aa3b, v23
	v_exp_f32_e32 v2, v2
	v_add_u32_e32 v1, 0x4a, v98
	v_mul_f32_e32 v0, v22, v0
	v_mul_f32_e32 v0, v6, v0
	v_cvt_pk_bf16_f32 v3, v0, v0
	v_add_f32_e32 v0, 1.0, v2
	v_rcp_f32_e32 v2, v0
	v_mad_i64_i32 v[0:1], s[6:7], v1, s14, v[96:97]
	global_store_short v[0:1], v3, off
	v_mul_f32_e32 v1, v23, v2
	v_mul_f32_e32 v1, v7, v1
	v_cvt_pk_bf16_f32 v2, v1, v1
	v_mul_f32_e32 v1, 0xbfb8aa3b, v24
	v_exp_f32_e32 v3, v1
	v_add_u32_e32 v0, 0x4b, v98
	v_mad_i64_i32 v[0:1], s[6:7], v0, s14, v[96:97]
	global_store_short v[0:1], v2, off
	v_add_f32_e32 v0, 1.0, v3
	v_rcp_f32_e32 v0, v0
	v_mul_f32_e32 v2, 0xbfb8aa3b, v25
	v_exp_f32_e32 v2, v2
	v_add_u32_e32 v1, 0x50, v98
	v_mul_f32_e32 v0, v24, v0
	v_mul_f32_e32 v0, v8, v0
	v_cvt_pk_bf16_f32 v3, v0, v0
	v_add_f32_e32 v0, 1.0, v2
	v_rcp_f32_e32 v2, v0
	v_mad_i64_i32 v[0:1], s[6:7], v1, s14, v[96:97]
	global_store_short v[0:1], v3, off
	v_mul_f32_e32 v1, v25, v2
	v_mul_f32_e32 v1, v9, v1
	v_cvt_pk_bf16_f32 v2, v1, v1
	v_mul_f32_e32 v1, 0xbfb8aa3b, v26
	v_exp_f32_e32 v3, v1
	v_add_u32_e32 v0, 0x51, v98
	v_mad_i64_i32 v[0:1], s[6:7], v0, s14, v[96:97]
	global_store_short v[0:1], v2, off
	v_add_f32_e32 v0, 1.0, v3
	v_rcp_f32_e32 v0, v0
	v_mul_f32_e32 v2, 0xbfb8aa3b, v27
	v_exp_f32_e32 v2, v2
	v_add_u32_e32 v1, 0x52, v98
	v_mul_f32_e32 v0, v26, v0
	v_mul_f32_e32 v0, v10, v0
	v_cvt_pk_bf16_f32 v3, v0, v0
	v_add_f32_e32 v0, 1.0, v2
	v_rcp_f32_e32 v2, v0
	v_mad_i64_i32 v[0:1], s[6:7], v1, s14, v[96:97]
	global_store_short v[0:1], v3, off
	v_mul_f32_e32 v1, v27, v2
	v_mul_f32_e32 v1, v11, v1
	v_cvt_pk_bf16_f32 v2, v1, v1
	v_mul_f32_e32 v1, 0xbfb8aa3b, v28
	v_exp_f32_e32 v3, v1
	v_add_u32_e32 v0, 0x53, v98
	v_mad_i64_i32 v[0:1], s[6:7], v0, s14, v[96:97]
	global_store_short v[0:1], v2, off
	v_add_f32_e32 v0, 1.0, v3
	v_rcp_f32_e32 v0, v0
	v_mul_f32_e32 v2, 0xbfb8aa3b, v29
	v_exp_f32_e32 v2, v2
	v_add_u32_e32 v1, 0x58, v98
	v_mul_f32_e32 v0, v28, v0
	v_mul_f32_e32 v0, v12, v0
	v_cvt_pk_bf16_f32 v3, v0, v0
	v_add_f32_e32 v0, 1.0, v2
	v_rcp_f32_e32 v2, v0
	v_mad_i64_i32 v[0:1], s[6:7], v1, s14, v[96:97]
	global_store_short v[0:1], v3, off
	v_mul_f32_e32 v1, v29, v2
	v_mul_f32_e32 v1, v13, v1
	v_cvt_pk_bf16_f32 v2, v1, v1
	v_mul_f32_e32 v1, 0xbfb8aa3b, v30
	v_exp_f32_e32 v3, v1
	v_add_u32_e32 v0, 0x59, v98
	v_mad_i64_i32 v[0:1], s[6:7], v0, s14, v[96:97]
	global_store_short v[0:1], v2, off
	v_add_f32_e32 v0, 1.0, v3
	v_rcp_f32_e32 v0, v0
	v_mul_f32_e32 v2, 0xbfb8aa3b, v31
	v_exp_f32_e32 v2, v2
	v_add_u32_e32 v1, 0x5a, v98
	v_mul_f32_e32 v0, v30, v0
	v_mul_f32_e32 v0, v14, v0
	v_cvt_pk_bf16_f32 v3, v0, v0
	v_add_f32_e32 v0, 1.0, v2
	v_rcp_f32_e32 v2, v0
	v_mad_i64_i32 v[0:1], s[6:7], v1, s14, v[96:97]
	global_store_short v[0:1], v3, off
	v_mul_f32_e32 v1, v31, v2
	v_add_u32_e32 v0, 0x5b, v98
	v_mul_f32_e32 v1, v15, v1
	v_cvt_pk_bf16_f32 v2, v1, v1
	v_mad_i64_i32 v[0:1], s[6:7], v0, s14, v[96:97]
	s_add_i32 s12, s12, 1
	s_mov_b64 s[8:9], 0
	global_store_short v[0:1], v2, off
	s_branch .LBB0_2720

; #define G_STORE(BUF) do { char* l_ = lds + (BUF) * STAGE + wofs; \
;         *(uint4*)(l_) = ra0; *(uint4*)(l_ + 8192) = ra1; *(uint4*)(l_ + 16384) = ra2; if (MT == 4) *(uint4*)(l_ + 24576) = ra3; \
;         *(uint4*)(l_ + ABYTES) = rb0; *(uint4*)(l_ + ABYTES + 8192) = rb1; *(uint4*)(l_ + ABYTES + 16384) = rb2; *(uint4*)(l_ + ABYTES + 24576) = rb3; } while (0)
; template <int MT, bool PIN, class Epi>
; __device__ __forceinline__ void gemm_phase(const Params& P, const bf16_t* __restrict__ A, const bf16_t* __restrict__ Bt, int nM, int nN, int K, const Epi epi, char* lds) {
;     ...
;         G_LOAD(0);
;         f32x16 acc[MT][2];
; #pragma unroll
;         for (int a = 0; a < MT; ++a)
; #pragma unroll
;             for (int b = 0; b < 2; ++b)
; #pragma unroll
;                 for (int e = 0; e < 16; ++e) acc[a][b][e] = 0.f;
;         bf16x8 fa[2][MT], fb[2][2];
;         __syncthreads();
;         G_STORE(0);
;         G_LOAD(1);
;         __syncthreads();
;         for (int kt = 0; kt < nk; kt += 2) { G_STEP(0, kt); G_STEP(1, kt + 1); }
.LBB0_2781:
	v_add_u32_e32 v182, v146, v143
	ds_read_b128 v[166:169], v145
	ds_read_b128 v[170:173], v145 offset:4096
	ds_read_b128 v[174:177], v145 offset:8192
	ds_read_b128 v[178:181], v182 offset:24576
	ds_read_b128 v[182:185], v182 offset:28672
	s_add_i32 s21, s20, 2
	s_min_u32 s22, s19, 0x2b80
	s_add_i32 s98, s19, 0x80
	s_min_u32 s98, s98, 0x2b80
	s_addk_i32 s19, 0x100
	v_add_u32_e32 v240, s22, v126
	v_add_u32_e32 v241, 0xb0000, v240
	v_add_u32_e32 v242, 0x160000, v240
	v_add_u32_e32 v243, 0x210000, v240
	s_waitcnt lgkmcnt(1)
	v_mfma_f32_32x32x16_bf16 v[80:95], v[166:169], v[178:181], v[80:95]
	v_add_u32_e32 v190, v146, v150
	v_add_u32_e32 v198, v155, v143
	s_waitcnt lgkmcnt(0)
	v_mfma_f32_32x32x16_bf16 v[64:79], v[166:169], v[182:185], v[64:79]
	ds_read_b128 v[166:169], v149
	s_waitcnt vmcnt(13)
	ds_write_b128 v142, v[96:99] offset:57344
	global_load_dwordx4 v[96:99], v240, s[10:11]
	v_mfma_f32_32x32x16_bf16 v[48:63], v[170:173], v[178:181], v[48:63]
	v_mfma_f32_32x32x16_bf16 v[32:47], v[170:173], v[182:185], v[32:47]
	s_waitcnt vmcnt(13)
	ds_write_b128 v147, v[100:103] offset:8192
	global_load_dwordx4 v[100:103], v241, s[10:11]
	v_mfma_f32_32x32x16_bf16 v[0:15], v[174:177], v[182:185], v[0:15]
	v_add_u32_e32 v182, v146, v148
	v_mfma_f32_32x32x16_bf16 v[16:31], v[174:177], v[178:181], v[16:31]
	ds_read_b128 v[170:173], v182 offset:24576
	ds_read_b128 v[174:177], v149 offset:4096
	ds_read_b128 v[178:181], v153 offset:8192
	ds_read_b128 v[182:185], v182 offset:28672
	ds_read_b128 v[186:189], v190 offset:24576
	s_waitcnt vmcnt(13)
	ds_write_b128 v147, v[108:111] offset:16384
	global_load_dwordx4 v[108:111], v242, s[10:11]
	s_waitcnt lgkmcnt(5)
	v_mfma_f32_32x32x16_bf16 v[80:95], v[166:169], v[170:173], v[80:95]
	s_waitcnt lgkmcnt(2)
	v_mfma_f32_32x32x16_bf16 v[64:79], v[166:169], v[182:185], v[64:79]
	s_waitcnt vmcnt(13)
	ds_write_b128 v147, v[104:107] offset:24576
	global_load_dwordx4 v[104:107], v240, s[12:13]
	v_mfma_f32_32x32x16_bf16 v[48:63], v[174:177], v[170:173], v[48:63]
	v_mfma_f32_32x32x16_bf16 v[32:47], v[174:177], v[182:185], v[32:47]
	ds_read_b128 v[166:169], v149 offset:8192
	ds_read_b128 v[174:177], v151
	s_waitcnt vmcnt(13)
	ds_write_b128 v147, v[112:115] offset:32768
	global_load_dwordx4 v[112:115], v241, s[12:13]
	s_waitcnt lgkmcnt(2)
	v_mfma_f32_32x32x16_bf16 v[16:31], v[166:169], v[170:173], v[16:31]
	v_mfma_f32_32x32x16_bf16 v[0:15], v[166:169], v[182:185], v[0:15]
	ds_read_b128 v[166:169], v190 offset:28672
	v_add_u32_e32 v190, v146, v152
	ds_read_b128 v[170:173], v190 offset:24576
	s_waitcnt vmcnt(13)
	ds_write_b128 v147, v[116:119] offset:40960
	global_load_dwordx4 v[116:119], v242, s[12:13]
	s_waitcnt lgkmcnt(4)
	v_mfma_f32_32x32x16_bf16 v[80:95], v[174:177], v[186:189], v[80:95]
	s_waitcnt lgkmcnt(2)
	v_mfma_f32_32x32x16_bf16 v[64:79], v[174:177], v[166:169], v[64:79]
	ds_read_b128 v[174:177], v151 offset:4096
	ds_read_b128 v[182:185], v151 offset:8192
	s_waitcnt vmcnt(13)
	ds_write_b128 v147, v[120:123] offset:49152
	global_load_dwordx4 v[120:123], v243, s[12:13]
	s_waitcnt lgkmcnt(2)
	v_mfma_f32_32x32x16_bf16 v[48:63], v[174:177], v[186:189], v[48:63]
	v_mfma_f32_32x32x16_bf16 v[32:47], v[174:177], v[166:169], v[32:47]
	s_waitcnt lgkmcnt(1)
	v_mfma_f32_32x32x16_bf16 v[16:31], v[182:185], v[186:189], v[16:31]
	v_mfma_f32_32x32x16_bf16 v[0:15], v[182:185], v[166:169], v[0:15]
	ds_read_b128 v[166:169], v153
	ds_read_b128 v[174:177], v153 offset:4096
	ds_read_b128 v[182:185], v190 offset:28672
	s_waitcnt lgkmcnt(0)
	s_barrier
	v_mfma_f32_32x32x16_bf16 v[80:95], v[166:169], v[170:173], v[80:95]
	v_mfma_f32_32x32x16_bf16 v[64:79], v[166:169], v[182:185], v[64:79]
	v_mfma_f32_32x32x16_bf16 v[48:63], v[174:177], v[170:173], v[48:63]
	v_mfma_f32_32x32x16_bf16 v[32:47], v[174:177], v[182:185], v[32:47]
	ds_read_b128 v[166:169], v145 offset:57344
	ds_read_b128 v[174:177], v145 offset:61440
	ds_read_b128 v[186:189], v154 offset:8192
	ds_read_b128 v[190:193], v161
	v_mfma_f32_32x32x16_bf16 v[16:31], v[178:181], v[170:173], v[16:31]
	ds_read_b128 v[170:173], v198 offset:4096
	v_add_u32_e32 v240, s98, v126
	v_add_u32_e32 v241, 0xb0000, v240
	v_add_u32_e32 v242, 0x160000, v240
	v_add_u32_e32 v243, 0x210000, v240
	s_waitcnt vmcnt(13)
	ds_write_b128 v142, v[212:215]
	global_load_dwordx4 v[212:215], v240, s[10:11]
	v_mfma_f32_32x32x16_bf16 v[0:15], v[178:181], v[182:185], v[0:15]
	s_waitcnt lgkmcnt(2)
	v_mfma_f32_32x32x16_bf16 v[80:95], v[166:169], v[190:193], v[80:95]
	v_add_u32_e32 v182, v155, v148
	s_mov_b32 s20, s21
	s_waitcnt lgkmcnt(1)
	v_mfma_f32_32x32x16_bf16 v[64:79], v[166:169], v[170:173], v[64:79]
	s_waitcnt vmcnt(13)
	ds_write_b128 v142, v[216:219] offset:8192
	global_load_dwordx4 v[216:219], v241, s[10:11]
	v_mfma_f32_32x32x16_bf16 v[48:63], v[174:177], v[190:193], v[48:63]
	v_mfma_f32_32x32x16_bf16 v[32:47], v[174:177], v[170:173], v[32:47]
	s_waitcnt vmcnt(13)
	ds_write_b128 v142, v[220:223] offset:16384
	global_load_dwordx4 v[220:223], v242, s[10:11]
	v_mfma_f32_32x32x16_bf16 v[16:31], v[186:189], v[190:193], v[16:31]
	v_mfma_f32_32x32x16_bf16 v[0:15], v[186:189], v[170:173], v[0:15]
	ds_read_b128 v[166:169], v149 offset:57344
	ds_read_b128 v[170:173], v162
	ds_read_b128 v[174:177], v149 offset:61440
	ds_read_b128 v[178:181], v158 offset:8192
	ds_read_b128 v[182:185], v182 offset:4096
	ds_read_b128 v[186:189], v163
	s_waitcnt vmcnt(13)
	ds_write_b128 v142, v[224:227] offset:24576
	global_load_dwordx4 v[224:227], v240, s[12:13]
	s_waitcnt lgkmcnt(5)
	v_mfma_f32_32x32x16_bf16 v[80:95], v[166:169], v[170:173], v[80:95]
	s_waitcnt lgkmcnt(2)
	v_mfma_f32_32x32x16_bf16 v[64:79], v[166:169], v[182:185], v[64:79]
	s_waitcnt vmcnt(13)
; #define G_STORE(BUF) do { char* l_ = lds + (BUF) * STAGE + wofs; \
;         *(uint4*)(l_) = ra0; *(uint4*)(l_ + 8192) = ra1; *(uint4*)(l_ + 16384) = ra2; if (MT == 4) *(uint4*)(l_ + 24576) = ra3; \
;         *(uint4*)(l_ + ABYTES) = rb0; *(uint4*)(l_ + ABYTES + 8192) = rb1; *(uint4*)(l_ + ABYTES + 16384) = rb2; *(uint4*)(l_ + ABYTES + 24576) = rb3; } while (0)
; template <int MT, bool PIN, class Epi>
; __device__ __forceinline__ void gemm_phase(const Params& P, const bf16_t* __restrict__ A, const bf16_t* __restrict__ Bt, int nM, int nN, int K, const Epi epi, char* lds) {
;     ...
;         G_LOAD(0);
;         f32x16 acc[MT][2];
; #pragma unroll
;         for (int a = 0; a < MT; ++a)
; #pragma unroll
;             for (int b = 0; b < 2; ++b)
; #pragma unroll
;                 for (int e = 0; e < 16; ++e) acc[a][b][e] = 0.f;
;         bf16x8 fa[2][MT], fb[2][2];
;         __syncthreads();
;         G_STORE(0);
;         G_LOAD(1);
;         __syncthreads();
;         for (int kt = 0; kt < nk; kt += 2) { G_STEP(0, kt); G_STEP(1, kt + 1); }
	ds_write_b128 v142, v[228:231] offset:32768
	global_load_dwordx4 v[228:231], v241, s[12:13]
	v_mfma_f32_32x32x16_bf16 v[48:63], v[174:177], v[170:173], v[48:63]
	v_mfma_f32_32x32x16_bf16 v[32:47], v[174:177], v[182:185], v[32:47]
	ds_read_b128 v[166:169], v156 offset:8192
	ds_read_b128 v[174:177], v157 offset:8192
	s_waitcnt vmcnt(13)
	ds_write_b128 v142, v[232:235] offset:40960
	global_load_dwordx4 v[232:235], v242, s[12:13]
	s_waitcnt lgkmcnt(2)
	v_mfma_f32_32x32x16_bf16 v[16:31], v[166:169], v[170:173], v[16:31]
	v_mfma_f32_32x32x16_bf16 v[0:15], v[166:169], v[182:185], v[0:15]
	ds_read_b128 v[166:169], v151 offset:57344
	ds_read_b128 v[170:173], v151 offset:61440
	v_add_u32_e32 v182, v155, v150
	ds_read_b128 v[182:185], v182 offset:4096
	ds_read_b128 v[190:193], v164
	s_waitcnt vmcnt(13)
	ds_write_b128 v142, v[236:239] offset:49152
	global_load_dwordx4 v[236:239], v243, s[12:13]
	s_waitcnt lgkmcnt(4)
	v_mfma_f32_32x32x16_bf16 v[80:95], v[166:169], v[186:189], v[80:95]
	s_waitcnt lgkmcnt(2)
	v_mfma_f32_32x32x16_bf16 v[64:79], v[166:169], v[182:185], v[64:79]
	v_mfma_f32_32x32x16_bf16 v[48:63], v[170:173], v[186:189], v[48:63]
	v_mfma_f32_32x32x16_bf16 v[32:47], v[170:173], v[182:185], v[32:47]
	ds_read_b128 v[166:169], v153 offset:57344
	ds_read_b128 v[170:173], v153 offset:61440
	v_mfma_f32_32x32x16_bf16 v[16:31], v[174:177], v[186:189], v[16:31]
	v_mfma_f32_32x32x16_bf16 v[0:15], v[174:177], v[182:185], v[0:15]
	v_add_u32_e32 v174, v155, v152
	ds_read_b128 v[174:177], v174 offset:4096
	s_waitcnt lgkmcnt(0)
	s_barrier
	v_mfma_f32_32x32x16_bf16 v[80:95], v[166:169], v[190:193], v[80:95]
	v_mfma_f32_32x32x16_bf16 v[64:79], v[166:169], v[174:177], v[64:79]
	v_mfma_f32_32x32x16_bf16 v[48:63], v[170:173], v[190:193], v[48:63]
	v_mfma_f32_32x32x16_bf16 v[32:47], v[170:173], v[174:177], v[32:47]
	v_mfma_f32_32x32x16_bf16 v[16:31], v[178:181], v[190:193], v[16:31]
	v_mfma_f32_32x32x16_bf16 v[0:15], v[178:181], v[174:177], v[0:15]
	s_cmp_lt_u32 s20, 84
	s_cbranch_scc1 .LBB0_2781
	v_add_u32_e32 v182, v146, v143
	ds_read_b128 v[166:169], v145
	ds_read_b128 v[170:173], v145 offset:4096
	ds_read_b128 v[174:177], v145 offset:8192
	ds_read_b128 v[178:181], v182 offset:24576
	ds_read_b128 v[182:185], v182 offset:28672
	s_add_i32 s21, s20, 2
	s_min_u32 s22, s19, 0x2b80
	s_add_i32 s98, s19, 0x80
	s_min_u32 s98, s98, 0x2b80
	s_addk_i32 s19, 0x100
	v_add_u32_e32 v240, s22, v126
	v_add_u32_e32 v241, 0xb0000, v240
	v_add_u32_e32 v242, 0x160000, v240
	v_add_u32_e32 v243, 0x210000, v240
	s_waitcnt lgkmcnt(1)
	v_mfma_f32_32x32x16_bf16 v[80:95], v[166:169], v[178:181], v[80:95]
	v_add_u32_e32 v190, v146, v150
	v_add_u32_e32 v198, v155, v143
	s_waitcnt lgkmcnt(0)
	v_mfma_f32_32x32x16_bf16 v[64:79], v[166:169], v[182:185], v[64:79]
	ds_read_b128 v[166:169], v149
	s_waitcnt vmcnt(13)
	ds_write_b128 v142, v[96:99] offset:57344
	global_load_dwordx4 v[96:99], v240, s[10:11]
	v_mfma_f32_32x32x16_bf16 v[48:63], v[170:173], v[178:181], v[48:63]
	v_mfma_f32_32x32x16_bf16 v[32:47], v[170:173], v[182:185], v[32:47]
	s_waitcnt vmcnt(13)
	ds_write_b128 v147, v[100:103] offset:8192
	global_load_dwordx4 v[100:103], v241, s[10:11]
	v_mfma_f32_32x32x16_bf16 v[0:15], v[174:177], v[182:185], v[0:15]
	v_add_u32_e32 v182, v146, v148
	v_mfma_f32_32x32x16_bf16 v[16:31], v[174:177], v[178:181], v[16:31]
	ds_read_b128 v[170:173], v182 offset:24576
	ds_read_b128 v[174:177], v149 offset:4096
	ds_read_b128 v[178:181], v153 offset:8192
	ds_read_b128 v[182:185], v182 offset:28672
	ds_read_b128 v[186:189], v190 offset:24576
	s_waitcnt vmcnt(13)
	ds_write_b128 v147, v[108:111] offset:16384
	global_load_dwordx4 v[108:111], v242, s[10:11]
	s_waitcnt lgkmcnt(5)
	v_mfma_f32_32x32x16_bf16 v[80:95], v[166:169], v[170:173], v[80:95]
	s_waitcnt lgkmcnt(2)
	v_mfma_f32_32x32x16_bf16 v[64:79], v[166:169], v[182:185], v[64:79]
	s_waitcnt vmcnt(13)
	ds_write_b128 v147, v[104:107] offset:24576
	global_load_dwordx4 v[104:107], v240, s[12:13]
	v_mfma_f32_32x32x16_bf16 v[48:63], v[174:177], v[170:173], v[48:63]
	v_mfma_f32_32x32x16_bf16 v[32:47], v[174:177], v[182:185], v[32:47]
	ds_read_b128 v[166:169], v149 offset:8192
	ds_read_b128 v[174:177], v151
	s_waitcnt vmcnt(13)
	ds_write_b128 v147, v[112:115] offset:32768
	global_load_dwordx4 v[112:115], v241, s[12:13]
	s_waitcnt lgkmcnt(2)
	v_mfma_f32_32x32x16_bf16 v[16:31], v[166:169], v[170:173], v[16:31]
	v_mfma_f32_32x32x16_bf16 v[0:15], v[166:169], v[182:185], v[0:15]
	ds_read_b128 v[166:169], v190 offset:28672
	v_add_u32_e32 v190, v146, v152
	ds_read_b128 v[170:173], v190 offset:24576
	s_waitcnt vmcnt(13)
	ds_write_b128 v147, v[116:119] offset:40960
	global_load_dwordx4 v[116:119], v242, s[12:13]
	s_waitcnt lgkmcnt(4)
	v_mfma_f32_32x32x16_bf16 v[80:95], v[174:177], v[186:189], v[80:95]
	s_waitcnt lgkmcnt(2)
	v_mfma_f32_32x32x16_bf16 v[64:79], v[174:177], v[166:169], v[64:79]
	ds_read_b128 v[174:177], v151 offset:4096
	ds_read_b128 v[182:185], v151 offset:8192
	s_waitcnt vmcnt(13)
	ds_write_b128 v147, v[120:123] offset:49152
	global_load_dwordx4 v[120:123], v243, s[12:13]
	s_waitcnt lgkmcnt(2)
	v_mfma_f32_32x32x16_bf16 v[48:63], v[174:177], v[186:189], v[48:63]
	v_mfma_f32_32x32x16_bf16 v[32:47], v[174:177], v[166:169], v[32:47]
	s_waitcnt lgkmcnt(1)
	v_mfma_f32_32x32x16_bf16 v[16:31], v[182:185], v[186:189], v[16:31]
	v_mfma_f32_32x32x16_bf16 v[0:15], v[182:185], v[166:169], v[0:15]
	ds_read_b128 v[166:169], v153
	ds_read_b128 v[174:177], v153 offset:4096
	ds_read_b128 v[182:185], v190 offset:28672
	s_waitcnt lgkmcnt(0)
	s_barrier
	v_mfma_f32_32x32x16_bf16 v[80:95], v[166:169], v[170:173], v[80:95]
	v_mfma_f32_32x32x16_bf16 v[64:79], v[166:169], v[182:185], v[64:79]
	v_mfma_f32_32x32x16_bf16 v[48:63], v[174:177], v[170:173], v[48:63]
	v_mfma_f32_32x32x16_bf16 v[32:47], v[174:177], v[182:185], v[32:47]
	ds_read_b128 v[166:169], v145 offset:57344
	ds_read_b128 v[174:177], v145 offset:61440
	ds_read_b128 v[186:189], v154 offset:8192
	ds_read_b128 v[190:193], v161
	v_mfma_f32_32x32x16_bf16 v[16:31], v[178:181], v[170:173], v[16:31]
	ds_read_b128 v[170:173], v198 offset:4096
	v_add_u32_e32 v240, s98, v126
	v_add_u32_e32 v241, 0xb0000, v240
	v_add_u32_e32 v242, 0x160000, v240
	v_add_u32_e32 v243, 0x210000, v240
	s_waitcnt vmcnt(13)
	ds_write_b128 v142, v[212:215]
	v_mfma_f32_32x32x16_bf16 v[0:15], v[178:181], v[182:185], v[0:15]
	s_waitcnt lgkmcnt(2)
	v_mfma_f32_32x32x16_bf16 v[80:95], v[166:169], v[190:193], v[80:95]
	v_add_u32_e32 v182, v155, v148
	s_mov_b32 s20, s21
	s_waitcnt lgkmcnt(1)
	v_mfma_f32_32x32x16_bf16 v[64:79], v[166:169], v[170:173], v[64:79]
	s_waitcnt vmcnt(12)
	ds_write_b128 v142, v[216:219] offset:8192
	v_mfma_f32_32x32x16_bf16 v[48:63], v[174:177], v[190:193], v[48:63]
	v_mfma_f32_32x32x16_bf16 v[32:47], v[174:177], v[170:173], v[32:47]
	s_waitcnt vmcnt(11)
	ds_write_b128 v142, v[220:223] offset:16384
	v_mfma_f32_32x32x16_bf16 v[16:31], v[186:189], v[190:193], v[16:31]
	v_mfma_f32_32x32x16_bf16 v[0:15], v[186:189], v[170:173], v[0:15]
	ds_read_b128 v[166:169], v149 offset:57344
	ds_read_b128 v[170:173], v162
	ds_read_b128 v[174:177], v149 offset:61440
	ds_read_b128 v[178:181], v158 offset:8192
	ds_read_b128 v[182:185], v182 offset:4096
	ds_read_b128 v[186:189], v163
	s_waitcnt vmcnt(10)
	ds_write_b128 v142, v[224:227] offset:24576
	s_waitcnt lgkmcnt(5)
	v_mfma_f32_32x32x16_bf16 v[80:95], v[166:169], v[170:173], v[80:95]
	s_waitcnt lgkmcnt(2)
	v_mfma_f32_32x32x16_bf16 v[64:79], v[166:169], v[182:185], v[64:79]
	s_waitcnt vmcnt(9)
	ds_write_b128 v142, v[228:231] offset:32768
	v_mfma_f32_32x32x16_bf16 v[48:63], v[174:177], v[170:173], v[48:63]
	v_mfma_f32_32x32x16_bf16 v[32:47], v[174:177], v[182:185], v[32:47]
	ds_read_b128 v[166:169], v156 offset:8192
	ds_read_b128 v[174:177], v157 offset:8192
	s_waitcnt vmcnt(8)
	ds_write_b128 v142, v[232:235] offset:40960
	s_waitcnt lgkmcnt(2)
	v_mfma_f32_32x32x16_bf16 v[16:31], v[166:169], v[170:173], v[16:31]
	v_mfma_f32_32x32x16_bf16 v[0:15], v[166:169], v[182:185], v[0:15]
	ds_read_b128 v[166:169], v151 offset:57344
	ds_read_b128 v[170:173], v151 offset:61440
	v_add_u32_e32 v182, v155, v150
	ds_read_b128 v[182:185], v182 offset:4096
	ds_read_b128 v[190:193], v164
	s_waitcnt vmcnt(7)
	ds_write_b128 v142, v[236:239] offset:49152
	s_waitcnt lgkmcnt(4)
	v_mfma_f32_32x32x16_bf16 v[80:95], v[166:169], v[186:189], v[80:95]
	s_waitcnt lgkmcnt(2)
	v_mfma_f32_32x32x16_bf16 v[64:79], v[166:169], v[182:185], v[64:79]
	v_mfma_f32_32x32x16_bf16 v[48:63], v[170:173], v[186:189], v[48:63]
	v_mfma_f32_32x32x16_bf16 v[32:47], v[170:173], v[182:185], v[32:47]
	ds_read_b128 v[166:169], v153 offset:57344
	ds_read_b128 v[170:173], v153 offset:61440
	v_mfma_f32_32x32x16_bf16 v[16:31], v[174:177], v[186:189], v[16:31]
	v_mfma_f32_32x32x16_bf16 v[0:15], v[174:177], v[182:185], v[0:15]
	v_add_u32_e32 v174, v155, v152
	ds_read_b128 v[174:177], v174 offset:4096
	s_waitcnt lgkmcnt(0)
	s_barrier
	v_mfma_f32_32x32x16_bf16 v[80:95], v[166:169], v[190:193], v[80:95]
	v_mfma_f32_32x32x16_bf16 v[64:79], v[166:169], v[174:177], v[64:79]
	v_mfma_f32_32x32x16_bf16 v[48:63], v[170:173], v[190:193], v[48:63]
	v_mfma_f32_32x32x16_bf16 v[32:47], v[170:173], v[174:177], v[32:47]
	v_mfma_f32_32x32x16_bf16 v[16:31], v[178:181], v[190:193], v[16:31]
	v_mfma_f32_32x32x16_bf16 v[0:15], v[178:181], v[174:177], v[0:15]
	v_add_u32_e32 v182, v146, v143
	ds_read_b128 v[166:169], v145
	ds_read_b128 v[170:173], v145 offset:4096
	ds_read_b128 v[174:177], v145 offset:8192
	ds_read_b128 v[178:181], v182 offset:24576
	ds_read_b128 v[182:185], v182 offset:28672
	s_add_i32 s21, s20, 2
	s_min_u32 s22, s19, 0x2b80
	s_add_i32 s98, s19, 0x80
	s_min_u32 s98, s98, 0x2b80
	s_addk_i32 s19, 0x100
	v_add_u32_e32 v240, s22, v126
	v_add_u32_e32 v241, 0xb0000, v240
	v_add_u32_e32 v242, 0x160000, v240
	v_add_u32_e32 v243, 0x210000, v240
	s_waitcnt lgkmcnt(1)
	v_mfma_f32_32x32x16_bf16 v[80:95], v[166:169], v[178:181], v[80:95]
	v_add_u32_e32 v190, v146, v150
	v_add_u32_e32 v198, v155, v143
	s_waitcnt lgkmcnt(0)
	v_mfma_f32_32x32x16_bf16 v[64:79], v[166:169], v[182:185], v[64:79]
	ds_read_b128 v[166:169], v149
	s_waitcnt vmcnt(6)
	ds_write_b128 v142, v[96:99] offset:57344
	v_mfma_f32_32x32x16_bf16 v[48:63], v[170:173], v[178:181], v[48:63]
	v_mfma_f32_32x32x16_bf16 v[32:47], v[170:173], v[182:185], v[32:47]
	s_waitcnt vmcnt(5)
	ds_write_b128 v147, v[100:103] offset:8192
	v_mfma_f32_32x32x16_bf16 v[0:15], v[174:177], v[182:185], v[0:15]
	v_add_u32_e32 v182, v146, v148
	v_mfma_f32_32x32x16_bf16 v[16:31], v[174:177], v[178:181], v[16:31]
	ds_read_b128 v[170:173], v182 offset:24576
	ds_read_b128 v[174:177], v149 offset:4096
	ds_read_b128 v[178:181], v153 offset:8192
	ds_read_b128 v[182:185], v182 offset:28672
	ds_read_b128 v[186:189], v190 offset:24576
	s_waitcnt vmcnt(4)
	ds_write_b128 v147, v[108:111] offset:16384
	s_waitcnt lgkmcnt(5)
	v_mfma_f32_32x32x16_bf16 v[80:95], v[166:169], v[170:173], v[80:95]
	s_waitcnt lgkmcnt(2)
	v_mfma_f32_32x32x16_bf16 v[64:79], v[166:169], v[182:185], v[64:79]
	s_waitcnt vmcnt(3)
	ds_write_b128 v147, v[104:107] offset:24576
	v_mfma_f32_32x32x16_bf16 v[48:63], v[174:177], v[170:173], v[48:63]
	v_mfma_f32_32x32x16_bf16 v[32:47], v[174:177], v[182:185], v[32:47]
	ds_read_b128 v[166:169], v149 offset:8192
	ds_read_b128 v[174:177], v151
	s_waitcnt vmcnt(2)
	ds_write_b128 v147, v[112:115] offset:32768
	s_waitcnt lgkmcnt(2)
	v_mfma_f32_32x32x16_bf16 v[16:31], v[166:169], v[170:173], v[16:31]
	v_mfma_f32_32x32x16_bf16 v[0:15], v[166:169], v[182:185], v[0:15]
	ds_read_b128 v[166:169], v190 offset:28672
	v_add_u32_e32 v190, v146, v152
	ds_read_b128 v[170:173], v190 offset:24576
	s_waitcnt vmcnt(1)
	ds_write_b128 v147, v[116:119] offset:40960
	s_waitcnt lgkmcnt(4)
	v_mfma_f32_32x32x16_bf16 v[80:95], v[174:177], v[186:189], v[80:95]
	s_waitcnt lgkmcnt(2)
	v_mfma_f32_32x32x16_bf16 v[64:79], v[174:177], v[166:169], v[64:79]
	ds_read_b128 v[174:177], v151 offset:4096
	ds_read_b128 v[182:185], v151 offset:8192
	s_waitcnt vmcnt(0)
	ds_write_b128 v147, v[120:123] offset:49152
	s_waitcnt lgkmcnt(2)
	v_mfma_f32_32x32x16_bf16 v[48:63], v[174:177], v[186:189], v[48:63]
	v_mfma_f32_32x32x16_bf16 v[32:47], v[174:177], v[166:169], v[32:47]
	s_waitcnt lgkmcnt(1)
	v_mfma_f32_32x32x16_bf16 v[16:31], v[182:185], v[186:189], v[16:31]
	v_mfma_f32_32x32x16_bf16 v[0:15], v[182:185], v[166:169], v[0:15]
	ds_read_b128 v[166:169], v153
	ds_read_b128 v[174:177], v153 offset:4096
	ds_read_b128 v[182:185], v190 offset:28672
	s_waitcnt lgkmcnt(0)
	s_barrier
;     template <int MT> __device__ __forceinline__ void run(const Params& P, f32x16 (&acc)[MT][2], int rbase, int pn, int wc, int lane) const {
;         const int n = lane & 31, hh = lane >> 5; const int rb = rbase + 4 * hh;
;         const int c0 = pn * 128 + wc * 64 + n;
; #pragma unroll
;         for (int mt = 0; mt < MT; ++mt)
; #pragma unroll
;             for (int rg = 0; rg < 16; ++rg) { const int r = ROWOF(rb, mt, rg);
;                 float* y = P.out + O_Y + (size_t)r * 2048 + c0;
;                 y[0] = ALPHA * y[0] + acc[mt][0][rg]; y[32] = ALPHA * y[32] + acc[mt][1][rg]; }
	v_mfma_f32_32x32x16_bf16 v[80:95], v[166:169], v[170:173], v[80:95]
	v_mfma_f32_32x32x16_bf16 v[64:79], v[166:169], v[182:185], v[64:79]
	v_mfma_f32_32x32x16_bf16 v[48:63], v[174:177], v[170:173], v[48:63]
	v_mfma_f32_32x32x16_bf16 v[32:47], v[174:177], v[182:185], v[32:47]
	ds_read_b128 v[166:169], v145 offset:57344
	ds_read_b128 v[174:177], v145 offset:61440
	ds_read_b128 v[186:189], v154 offset:8192
	ds_read_b128 v[190:193], v161
	v_mfma_f32_32x32x16_bf16 v[16:31], v[178:181], v[170:173], v[16:31]
	ds_read_b128 v[170:173], v198 offset:4096
	v_add_u32_e32 v240, s98, v126
	v_add_u32_e32 v241, 0xb0000, v240
	v_add_u32_e32 v242, 0x160000, v240
	v_add_u32_e32 v243, 0x210000, v240
	v_mfma_f32_32x32x16_bf16 v[0:15], v[178:181], v[182:185], v[0:15]
	s_waitcnt lgkmcnt(1)
	v_mfma_f32_32x32x16_bf16 v[80:95], v[166:169], v[190:193], v[80:95]
	v_add_u32_e32 v182, v155, v148
	s_mov_b32 s20, s21
	s_waitcnt lgkmcnt(0)
	v_mfma_f32_32x32x16_bf16 v[64:79], v[166:169], v[170:173], v[64:79]
	v_mfma_f32_32x32x16_bf16 v[48:63], v[174:177], v[190:193], v[48:63]
	v_mfma_f32_32x32x16_bf16 v[32:47], v[174:177], v[170:173], v[32:47]
	v_mfma_f32_32x32x16_bf16 v[16:31], v[186:189], v[190:193], v[16:31]
	v_mfma_f32_32x32x16_bf16 v[0:15], v[186:189], v[170:173], v[0:15]
	ds_read_b128 v[166:169], v149 offset:57344
	ds_read_b128 v[170:173], v162
	ds_read_b128 v[174:177], v149 offset:61440
	ds_read_b128 v[178:181], v158 offset:8192
	ds_read_b128 v[182:185], v182 offset:4096
	ds_read_b128 v[186:189], v163
	s_waitcnt lgkmcnt(4)
	v_mfma_f32_32x32x16_bf16 v[80:95], v[166:169], v[170:173], v[80:95]
	s_waitcnt lgkmcnt(1)
	v_mfma_f32_32x32x16_bf16 v[64:79], v[166:169], v[182:185], v[64:79]
	v_mfma_f32_32x32x16_bf16 v[48:63], v[174:177], v[170:173], v[48:63]
	v_mfma_f32_32x32x16_bf16 v[32:47], v[174:177], v[182:185], v[32:47]
	ds_read_b128 v[166:169], v156 offset:8192
	ds_read_b128 v[174:177], v157 offset:8192
	s_waitcnt lgkmcnt(1)
	v_mfma_f32_32x32x16_bf16 v[16:31], v[166:169], v[170:173], v[16:31]
	v_mfma_f32_32x32x16_bf16 v[0:15], v[166:169], v[182:185], v[0:15]
	ds_read_b128 v[166:169], v151 offset:57344
	ds_read_b128 v[170:173], v151 offset:61440
	v_add_u32_e32 v182, v155, v150
	ds_read_b128 v[182:185], v182 offset:4096
	ds_read_b128 v[190:193], v164
	s_waitcnt lgkmcnt(3)
	v_mfma_f32_32x32x16_bf16 v[80:95], v[166:169], v[186:189], v[80:95]
	s_waitcnt lgkmcnt(1)
	v_mfma_f32_32x32x16_bf16 v[64:79], v[166:169], v[182:185], v[64:79]
	v_mfma_f32_32x32x16_bf16 v[48:63], v[170:173], v[186:189], v[48:63]
	v_mfma_f32_32x32x16_bf16 v[32:47], v[170:173], v[182:185], v[32:47]
	ds_read_b128 v[166:169], v153 offset:57344
	ds_read_b128 v[170:173], v153 offset:61440
	v_mfma_f32_32x32x16_bf16 v[16:31], v[174:177], v[186:189], v[16:31]
	v_mfma_f32_32x32x16_bf16 v[0:15], v[174:177], v[182:185], v[0:15]
	v_add_u32_e32 v174, v155, v152
	ds_read_b128 v[174:177], v174 offset:4096
	s_waitcnt lgkmcnt(0)
	s_barrier
	v_mfma_f32_32x32x16_bf16 v[80:95], v[166:169], v[190:193], v[80:95]
	v_mfma_f32_32x32x16_bf16 v[64:79], v[166:169], v[174:177], v[64:79]
	v_mfma_f32_32x32x16_bf16 v[48:63], v[170:173], v[190:193], v[48:63]
	v_mfma_f32_32x32x16_bf16 v[32:47], v[170:173], v[174:177], v[32:47]
	v_mfma_f32_32x32x16_bf16 v[16:31], v[178:181], v[190:193], v[16:31]
	v_mfma_f32_32x32x16_bf16 v[0:15], v[178:181], v[174:177], v[0:15]
	s_nop 1
	s_mulk_i32 s18, 0xc0
	s_waitcnt vmcnt(0)
	v_add_u32_e32 v98, s18, v159
	v_lshl_or_b32 v96, s17, 8, v160
	v_ashrrev_i32_e32 v97, 31, v96
	v_ashrrev_i32_e32 v99, 31, v98
	s_waitcnt vmcnt(4)
	v_or_b32_e32 v102, 1, v98
	v_or_b32_e32 v104, 2, v98
	v_or_b32_e32 v106, 3, v98
	v_lshl_add_u64 v[96:97], v[96:97], 2, s[88:89]
	v_lshlrev_b64 v[100:101], 13, v[98:99]
	v_ashrrev_i32_e32 v103, 31, v102
	v_ashrrev_i32_e32 v105, 31, v104
	v_ashrrev_i32_e32 v107, 31, v106
	v_lshl_add_u64 v[100:101], v[96:97], 0, v[100:101]
	v_lshlrev_b64 v[102:103], 13, v[102:103]
	v_lshlrev_b64 v[104:105], 13, v[104:105]
	v_lshlrev_b64 v[106:107], 13, v[106:107]
	v_lshl_add_u64 v[102:103], v[96:97], 0, v[102:103]
	v_lshl_add_u64 v[104:105], v[96:97], 0, v[104:105]
	v_lshl_add_u64 v[106:107], v[96:97], 0, v[106:107]
	global_load_dword v99, v[100:101], off
	global_load_dword v165, v[100:101], off offset:128
	global_load_dword v166, v[102:103], off
	global_load_dword v167, v[102:103], off offset:128
	global_load_dword v168, v[104:105], off
	global_load_dword v169, v[104:105], off offset:128
	global_load_dword v170, v[106:107], off
	global_load_dword v171, v[106:107], off offset:128
	s_waitcnt vmcnt(10)
	v_or_b32_e32 v108, 8, v98
	v_ashrrev_i32_e32 v109, 31, v108
	v_or_b32_e32 v110, 9, v98
	v_or_b32_e32 v112, 10, v98
	v_or_b32_e32 v114, 11, v98
	v_lshlrev_b64 v[108:109], 13, v[108:109]
	v_ashrrev_i32_e32 v111, 31, v110
	v_ashrrev_i32_e32 v113, 31, v112
	v_ashrrev_i32_e32 v115, 31, v114
	v_lshl_add_u64 v[108:109], v[96:97], 0, v[108:109]
	v_lshlrev_b64 v[110:111], 13, v[110:111]
	v_lshlrev_b64 v[112:113], 13, v[112:113]
	v_lshlrev_b64 v[114:115], 13, v[114:115]
	v_lshl_add_u64 v[110:111], v[96:97], 0, v[110:111]
	v_lshl_add_u64 v[112:113], v[96:97], 0, v[112:113]
	v_lshl_add_u64 v[114:115], v[96:97], 0, v[114:115]
	global_load_dword v172, v[108:109], off
	global_load_dword v173, v[108:109], off offset:128
	global_load_dword v174, v[110:111], off
	global_load_dword v175, v[110:111], off offset:128
	global_load_dword v176, v[112:113], off
	global_load_dword v177, v[112:113], off offset:128
	global_load_dword v178, v[114:115], off
	global_load_dword v179, v[114:115], off offset:128
	s_waitcnt vmcnt(17)
;     template <int MT> __device__ __forceinline__ void run(const Params& P, f32x16 (&acc)[MT][2], int rbase, int pn, int wc, int lane) const {
;         const int n = lane & 31, hh = lane >> 5; const int rb = rbase + 4 * hh;
;         const int c0 = pn * 128 + wc * 64 + n;
; #pragma unroll
;         for (int mt = 0; mt < MT; ++mt)
; #pragma unroll
;             for (int rg = 0; rg < 16; ++rg) { const int r = ROWOF(rb, mt, rg);
;                 float* y = P.out + O_Y + (size_t)r * 2048 + c0;
;                 y[0] = ALPHA * y[0] + acc[mt][0][rg]; y[32] = ALPHA * y[32] + acc[mt][1][rg]; }
	v_or_b32_e32 v116, 16, v98
	v_ashrrev_i32_e32 v117, 31, v116
	v_lshlrev_b64 v[116:117], 13, v[116:117]
	v_lshl_add_u64 v[116:117], v[96:97], 0, v[116:117]
	global_load_dword v180, v[116:117], off
	global_load_dword v181, v[116:117], off offset:128
	v_or_b32_e32 v118, 17, v98
	v_ashrrev_i32_e32 v119, 31, v118
	s_waitcnt vmcnt(18)
	v_or_b32_e32 v120, 18, v98
	v_lshlrev_b64 v[118:119], 13, v[118:119]
	v_ashrrev_i32_e32 v121, 31, v120
	v_or_b32_e32 v122, 19, v98
	v_lshl_add_u64 v[118:119], v[96:97], 0, v[118:119]
	v_lshlrev_b64 v[120:121], 13, v[120:121]
	v_ashrrev_i32_e32 v123, 31, v122
	v_lshl_add_u64 v[120:121], v[96:97], 0, v[120:121]
	global_load_dword v182, v[118:119], off
	global_load_dword v183, v[118:119], off offset:128
	global_load_dword v184, v[120:121], off
	global_load_dword v185, v[120:121], off offset:128
	v_lshlrev_b64 v[122:123], 13, v[122:123]
	v_lshl_add_u64 v[122:123], v[96:97], 0, v[122:123]
	global_load_dword v186, v[122:123], off
	global_load_dword v187, v[122:123], off offset:128
	s_add_i32 s14, s14, 1
	s_mov_b64 s[12:13], 0
	s_waitcnt vmcnt(23)
	v_fmamk_f32 v80, v99, 0x3f9837f0, v80
	s_waitcnt vmcnt(22)
	v_fmamk_f32 v64, v165, 0x3f9837f0, v64
	global_store_dword v[100:101], v80, off
	global_store_dword v[100:101], v64, off offset:128
	s_waitcnt vmcnt(23)
	v_fmamk_f32 v64, v166, 0x3f9837f0, v81
	s_waitcnt vmcnt(22)
	v_fmamk_f32 v65, v167, 0x3f9837f0, v65
	s_waitcnt vmcnt(21)
	v_fmamk_f32 v80, v168, 0x3f9837f0, v82
	s_waitcnt vmcnt(20)
	v_fmamk_f32 v66, v169, 0x3f9837f0, v66
	global_store_dword v[102:103], v64, off
	global_store_dword v[102:103], v65, off offset:128
	global_store_dword v[104:105], v80, off
	global_store_dword v[104:105], v66, off offset:128
	s_waitcnt vmcnt(23)
	v_fmamk_f32 v64, v170, 0x3f9837f0, v83
	global_store_dword v[106:107], v64, off
	s_waitcnt vmcnt(23)
	v_fmamk_f32 v64, v171, 0x3f9837f0, v67
	global_store_dword v[106:107], v64, off offset:128
	v_or_b32_e32 v66, 25, v98
	v_ashrrev_i32_e32 v67, 31, v66
	v_lshlrev_b64 v[66:67], 13, v[66:67]
	v_lshl_add_u64 v[66:67], v[96:97], 0, v[66:67]
	s_waitcnt vmcnt(23)
	v_fmamk_f32 v64, v172, 0x3f9837f0, v84
	global_store_dword v[108:109], v64, off
	s_waitcnt vmcnt(23)
	v_fmamk_f32 v64, v173, 0x3f9837f0, v68
	global_store_dword v[108:109], v64, off offset:128
	s_waitcnt vmcnt(23)
	v_fmamk_f32 v64, v174, 0x3f9837f0, v85
	global_store_dword v[110:111], v64, off
	s_waitcnt vmcnt(23)
	v_fmamk_f32 v64, v175, 0x3f9837f0, v69
	global_store_dword v[110:111], v64, off offset:128
	s_waitcnt vmcnt(23)
	v_fmamk_f32 v64, v176, 0x3f9837f0, v86
	global_store_dword v[112:113], v64, off
	s_waitcnt vmcnt(23)
	v_fmamk_f32 v64, v177, 0x3f9837f0, v70
	global_store_dword v[112:113], v64, off offset:128
	s_waitcnt vmcnt(23)
	v_fmamk_f32 v64, v178, 0x3f9837f0, v87
	v_add_u32_e32 v70, 33, v98
	global_store_dword v[114:115], v64, off
	s_waitcnt vmcnt(23)
	v_fmamk_f32 v64, v179, 0x3f9837f0, v71
	v_ashrrev_i32_e32 v71, 31, v70
	v_lshlrev_b64 v[70:71], 13, v[70:71]
	v_lshl_add_u64 v[80:81], v[96:97], 0, v[70:71]
	v_add_u32_e32 v70, 34, v98
	v_ashrrev_i32_e32 v71, 31, v70
	v_lshlrev_b64 v[70:71], 13, v[70:71]
	v_lshl_add_u64 v[82:83], v[96:97], 0, v[70:71]
	v_add_u32_e32 v70, 35, v98
	global_store_dword v[114:115], v64, off offset:128
	s_waitcnt vmcnt(23)
	v_fmamk_f32 v64, v180, 0x3f9837f0, v88
	v_ashrrev_i32_e32 v71, 31, v70
	global_store_dword v[116:117], v64, off
	s_waitcnt vmcnt(23)
	v_fmamk_f32 v64, v181, 0x3f9837f0, v72
	v_lshlrev_b64 v[70:71], 13, v[70:71]
	global_store_dword v[116:117], v64, off offset:128
	s_waitcnt vmcnt(23)
	v_fmamk_f32 v64, v182, 0x3f9837f0, v89
	v_lshl_add_u64 v[84:85], v[96:97], 0, v[70:71]
	v_add_u32_e32 v70, 40, v98
	global_store_dword v[118:119], v64, off
	s_waitcnt vmcnt(23)
	v_fmamk_f32 v64, v183, 0x3f9837f0, v73
	v_ashrrev_i32_e32 v71, 31, v70
	global_store_dword v[118:119], v64, off offset:128
	s_waitcnt vmcnt(23)
	v_fmamk_f32 v64, v184, 0x3f9837f0, v90
	v_lshlrev_b64 v[70:71], 13, v[70:71]
	global_store_dword v[120:121], v64, off
	s_waitcnt vmcnt(23)
	v_fmamk_f32 v64, v185, 0x3f9837f0, v74
	v_lshl_add_u64 v[86:87], v[96:97], 0, v[70:71]
	v_add_u32_e32 v70, 41, v98
	global_store_dword v[120:121], v64, off offset:128
	s_waitcnt vmcnt(23)
	v_fmamk_f32 v64, v186, 0x3f9837f0, v91
	v_ashrrev_i32_e32 v71, 31, v70
	global_store_dword v[122:123], v64, off
	s_waitcnt vmcnt(23)
;     template <int MT> __device__ __forceinline__ void run(const Params& P, f32x16 (&acc)[MT][2], int rbase, int pn, int wc, int lane) const {
;         const int n = lane & 31, hh = lane >> 5; const int rb = rbase + 4 * hh;
;         const int c0 = pn * 128 + wc * 64 + n;
; #pragma unroll
;         for (int mt = 0; mt < MT; ++mt)
; #pragma unroll
;             for (int rg = 0; rg < 16; ++rg) { const int r = ROWOF(rb, mt, rg);
;                 float* y = P.out + O_Y + (size_t)r * 2048 + c0;
;                 y[0] = ALPHA * y[0] + acc[mt][0][rg]; y[32] = ALPHA * y[32] + acc[mt][1][rg]; }
	v_fmamk_f32 v64, v187, 0x3f9837f0, v75
	v_lshlrev_b64 v[70:71], 13, v[70:71]
	global_store_dword v[122:123], v64, off offset:128
	v_or_b32_e32 v64, 24, v98
	v_lshl_add_u64 v[88:89], v[96:97], 0, v[70:71]
	v_add_u32_e32 v70, 42, v98
	v_ashrrev_i32_e32 v65, 31, v64
	v_ashrrev_i32_e32 v71, 31, v70
	v_lshlrev_b64 v[64:65], 13, v[64:65]
	v_lshlrev_b64 v[70:71], 13, v[70:71]
	v_lshl_add_u64 v[64:65], v[96:97], 0, v[64:65]
	v_lshl_add_u64 v[90:91], v[96:97], 0, v[70:71]
	v_add_u32_e32 v70, 43, v98
	global_load_dword v72, v[64:65], off
	v_ashrrev_i32_e32 v71, 31, v70
	v_lshlrev_b64 v[70:71], 13, v[70:71]
	v_lshl_add_u64 v[102:103], v[96:97], 0, v[70:71]
	v_add_u32_e32 v70, 48, v98
	v_ashrrev_i32_e32 v71, 31, v70
	v_lshlrev_b64 v[70:71], 13, v[70:71]
	global_load_dword v99, v[80:81], off
	global_load_dword v120, v[80:81], off offset:128
	global_load_dword v121, v[82:83], off
	global_load_dword v122, v[82:83], off offset:128
	global_load_dword v123, v[84:85], off
	global_load_dword v165, v[84:85], off offset:128
	v_lshl_add_u64 v[104:105], v[96:97], 0, v[70:71]
	v_add_u32_e32 v70, 49, v98
	v_ashrrev_i32_e32 v71, 31, v70
	v_lshlrev_b64 v[70:71], 13, v[70:71]
	v_lshl_add_u64 v[106:107], v[96:97], 0, v[70:71]
	v_add_u32_e32 v70, 50, v98
	v_ashrrev_i32_e32 v71, 31, v70
	v_lshlrev_b64 v[70:71], 13, v[70:71]
	v_lshl_add_u64 v[108:109], v[96:97], 0, v[70:71]
	v_add_u32_e32 v70, 51, v98
	v_ashrrev_i32_e32 v71, 31, v70
	global_load_dword v166, v[86:87], off
	global_load_dword v167, v[86:87], off offset:128
	global_load_dword v168, v[88:89], off
	global_load_dword v169, v[88:89], off offset:128
	global_load_dword v170, v[90:91], off
	global_load_dword v171, v[90:91], off offset:128
	global_load_dword v172, v[102:103], off
	global_load_dword v173, v[102:103], off offset:128
	v_lshlrev_b64 v[70:71], 13, v[70:71]
	v_lshl_add_u64 v[110:111], v[96:97], 0, v[70:71]
	v_add_u32_e32 v70, 56, v98
	v_ashrrev_i32_e32 v71, 31, v70
	v_lshlrev_b64 v[70:71], 13, v[70:71]
	v_lshl_add_u64 v[112:113], v[96:97], 0, v[70:71]
	v_add_u32_e32 v70, 57, v98
	v_ashrrev_i32_e32 v71, 31, v70
	v_lshlrev_b64 v[70:71], 13, v[70:71]
	v_lshl_add_u64 v[114:115], v[96:97], 0, v[70:71]
	v_add_u32_e32 v70, 58, v98
	global_load_dword v174, v[104:105], off
	global_load_dword v175, v[104:105], off offset:128
	global_load_dword v176, v[106:107], off
	global_load_dword v177, v[106:107], off offset:128
	global_load_dword v178, v[108:109], off
	global_load_dword v179, v[108:109], off offset:128
	global_load_dword v180, v[110:111], off
	global_load_dword v181, v[110:111], off offset:128
	v_ashrrev_i32_e32 v71, 31, v70
	v_lshlrev_b64 v[70:71], 13, v[70:71]
	global_load_dword v182, v[112:113], off
	global_load_dword v183, v[112:113], off offset:128
	v_lshl_add_u64 v[116:117], v[96:97], 0, v[70:71]
	v_add_u32_e32 v70, 59, v98
	v_ashrrev_i32_e32 v71, 31, v70
	v_lshlrev_b64 v[70:71], 13, v[70:71]
	v_lshl_add_u64 v[118:119], v[96:97], 0, v[70:71]
	global_load_dword v184, v[114:115], off
	global_load_dword v185, v[114:115], off offset:128
	global_load_dword v186, v[116:117], off
	global_load_dword v187, v[116:117], off offset:128
	global_load_dword v188, v[118:119], off
	global_load_dword v189, v[118:119], off offset:128
	v_or_b32_e32 v68, 26, v98
	v_or_b32_e32 v70, 27, v98
	v_ashrrev_i32_e32 v69, 31, v68
	v_ashrrev_i32_e32 v71, 31, v70
	v_lshlrev_b64 v[68:69], 13, v[68:69]
	v_lshlrev_b64 v[70:71], 13, v[70:71]
	v_add_co_u32_e32 v74, vcc, s15, v100
	v_lshl_add_u64 v[68:69], v[96:97], 0, v[68:69]
	v_lshl_add_u64 v[70:71], v[96:97], 0, v[70:71]
	global_load_dword v190, v[64:65], off offset:128
	global_load_dword v191, v[66:67], off
	global_load_dword v192, v[66:67], off offset:128
	global_load_dword v193, v[68:69], off
	global_load_dword v194, v[68:69], off offset:128
	global_load_dword v195, v[70:71], off
	global_load_dword v196, v[70:71], off offset:128
	v_addc_co_u32_e32 v75, vcc, 0, v101, vcc
	s_waitcnt vmcnt(37)
	v_fmamk_f32 v72, v72, 0x3f9837f0, v92
	global_store_dword v[64:65], v72, off
	v_lshl_add_u64 v[72:73], v[100:101], 0, s[6:7]
	s_waitcnt vmcnt(36)
	v_fmamk_f32 v33, v120, 0x3f9837f0, v33
	global_load_dword v92, v[74:75], off
	global_load_dword v197, v[72:73], off offset:128
	v_fmamk_f32 v49, v99, 0x3f9837f0, v49
	global_store_dword v[80:81], v33, off offset:128
	s_waitcnt vmcnt(38)
	v_fmamk_f32 v33, v121, 0x3f9837f0, v50
	global_store_dword v[82:83], v33, off
	s_waitcnt vmcnt(38)
	v_fmamk_f32 v33, v122, 0x3f9837f0, v34
	global_store_dword v[82:83], v33, off offset:128
	s_waitcnt vmcnt(38)
	v_fmamk_f32 v33, v123, 0x3f9837f0, v51
	global_store_dword v[84:85], v33, off
	s_waitcnt vmcnt(38)
	v_fmamk_f32 v33, v165, 0x3f9837f0, v35
	global_store_dword v[84:85], v33, off offset:128
	s_waitcnt vmcnt(38)
	v_fmamk_f32 v33, v166, 0x3f9837f0, v52
	global_store_dword v[86:87], v33, off
	s_waitcnt vmcnt(38)
	v_fmamk_f32 v33, v167, 0x3f9837f0, v36
	global_store_dword v[86:87], v33, off offset:128
	s_waitcnt vmcnt(38)
	v_fmamk_f32 v33, v168, 0x3f9837f0, v53
	global_store_dword v[88:89], v33, off
	s_waitcnt vmcnt(38)
	v_fmamk_f32 v33, v169, 0x3f9837f0, v37
	global_store_dword v[88:89], v33, off offset:128
	s_waitcnt vmcnt(38)
	v_fmamk_f32 v33, v170, 0x3f9837f0, v54
	global_store_dword v[90:91], v33, off
	s_waitcnt vmcnt(38)
	v_fmamk_f32 v33, v171, 0x3f9837f0, v38
	global_store_dword v[90:91], v33, off offset:128
	s_waitcnt vmcnt(38)
	v_fmamk_f32 v33, v172, 0x3f9837f0, v55
	global_store_dword v[102:103], v33, off
	s_waitcnt vmcnt(38)
	v_fmamk_f32 v33, v173, 0x3f9837f0, v39
	global_store_dword v[102:103], v33, off offset:128
	s_waitcnt vmcnt(38)
	v_fmamk_f32 v33, v174, 0x3f9837f0, v56
	global_store_dword v[104:105], v33, off
	s_waitcnt vmcnt(38)
;     template <int MT> __device__ __forceinline__ void run(const Params& P, f32x16 (&acc)[MT][2], int rbase, int pn, int wc, int lane) const {
;         const int n = lane & 31, hh = lane >> 5; const int rb = rbase + 4 * hh;
;         const int c0 = pn * 128 + wc * 64 + n;
; #pragma unroll
;         for (int mt = 0; mt < MT; ++mt)
; #pragma unroll
;             for (int rg = 0; rg < 16; ++rg) { const int r = ROWOF(rb, mt, rg);
;                 float* y = P.out + O_Y + (size_t)r * 2048 + c0;
;                 y[0] = ALPHA * y[0] + acc[mt][0][rg]; y[32] = ALPHA * y[32] + acc[mt][1][rg]; }
	v_fmamk_f32 v33, v175, 0x3f9837f0, v40
	global_store_dword v[104:105], v33, off offset:128
	s_waitcnt vmcnt(38)
	v_fmamk_f32 v33, v176, 0x3f9837f0, v57
	global_store_dword v[106:107], v33, off
	s_waitcnt vmcnt(38)
	v_fmamk_f32 v33, v177, 0x3f9837f0, v41
	global_store_dword v[106:107], v33, off offset:128
	s_waitcnt vmcnt(38)
	v_fmamk_f32 v33, v178, 0x3f9837f0, v58
	global_store_dword v[108:109], v33, off
	s_waitcnt vmcnt(38)
	v_fmamk_f32 v33, v179, 0x3f9837f0, v42
	global_store_dword v[108:109], v33, off offset:128
	s_waitcnt vmcnt(38)
	v_fmamk_f32 v33, v180, 0x3f9837f0, v59
	global_store_dword v[110:111], v33, off
	s_waitcnt vmcnt(38)
	v_fmamk_f32 v33, v181, 0x3f9837f0, v43
	global_store_dword v[110:111], v33, off offset:128
	s_waitcnt vmcnt(38)
	v_fmamk_f32 v33, v182, 0x3f9837f0, v60
	global_store_dword v[112:113], v33, off
	s_waitcnt vmcnt(38)
	v_fmamk_f32 v33, v183, 0x3f9837f0, v44
	global_store_dword v[112:113], v33, off offset:128
	s_waitcnt vmcnt(38)
	v_fmamk_f32 v33, v184, 0x3f9837f0, v61
	global_store_dword v[114:115], v33, off
	s_waitcnt vmcnt(38)
	v_fmamk_f32 v33, v185, 0x3f9837f0, v45
	global_store_dword v[114:115], v33, off offset:128
	s_waitcnt vmcnt(38)
	v_fmamk_f32 v33, v186, 0x3f9837f0, v62
	v_add_u32_e32 v38, 0x41, v98
	v_add_u32_e32 v40, 0x42, v98
	v_add_u32_e32 v42, 0x43, v98
	global_store_dword v[116:117], v33, off
	s_waitcnt vmcnt(38)
	v_fmamk_f32 v33, v187, 0x3f9837f0, v46
	s_waitcnt vmcnt(37)
	v_fmac_f32_e32 v63, 0x3f9837f0, v188
	s_waitcnt vmcnt(36)
	v_fmac_f32_e32 v47, 0x3f9837f0, v189
	v_add_co_u32_e32 v36, vcc, s16, v100
	v_ashrrev_i32_e32 v39, 31, v38
	v_ashrrev_i32_e32 v41, 31, v40
	v_ashrrev_i32_e32 v43, 31, v42
	global_store_dword v[80:81], v49, off
	global_store_dword v[116:117], v33, off offset:128
	global_store_dword v[118:119], v63, off
	global_store_dword v[118:119], v47, off offset:128
	v_addc_co_u32_e32 v37, vcc, 0, v101, vcc
	v_lshlrev_b64 v[38:39], 13, v[38:39]
	v_lshlrev_b64 v[40:41], 13, v[40:41]
	v_lshlrev_b64 v[42:43], 13, v[42:43]
	v_lshl_add_u64 v[34:35], v[100:101], 0, s[8:9]
	v_lshl_add_u64 v[38:39], v[96:97], 0, v[38:39]
	v_lshl_add_u64 v[40:41], v[96:97], 0, v[40:41]
	v_lshl_add_u64 v[42:43], v[96:97], 0, v[42:43]
	global_load_dword v33, v[36:37], off
	global_load_dword v49, v[38:39], off
	global_load_dword v86, v[38:39], off offset:128
	global_load_dword v87, v[40:41], off
	global_load_dword v88, v[40:41], off offset:128
	global_load_dword v89, v[42:43], off
	global_load_dword v90, v[42:43], off offset:128
	global_load_dword v91, v[34:35], off offset:128
	v_add_u32_e32 v44, 0x48, v98
	v_ashrrev_i32_e32 v45, 31, v44
	v_add_u32_e32 v46, 0x49, v98
	v_add_u32_e32 v50, 0x4a, v98
	v_add_u32_e32 v52, 0x4b, v98
	v_lshlrev_b64 v[44:45], 13, v[44:45]
	v_ashrrev_i32_e32 v47, 31, v46
	v_ashrrev_i32_e32 v51, 31, v50
	v_ashrrev_i32_e32 v53, 31, v52
	v_lshl_add_u64 v[44:45], v[96:97], 0, v[44:45]
	v_lshlrev_b64 v[46:47], 13, v[46:47]
	v_lshlrev_b64 v[50:51], 13, v[50:51]
	v_lshlrev_b64 v[52:53], 13, v[52:53]
	v_lshl_add_u64 v[46:47], v[96:97], 0, v[46:47]
	v_lshl_add_u64 v[50:51], v[96:97], 0, v[50:51]
	v_lshl_add_u64 v[52:53], v[96:97], 0, v[52:53]
	global_load_dword v99, v[44:45], off
	global_load_dword v100, v[44:45], off offset:128
	global_load_dword v101, v[46:47], off
	global_load_dword v102, v[46:47], off offset:128
	global_load_dword v103, v[50:51], off
	global_load_dword v104, v[50:51], off offset:128
	global_load_dword v105, v[52:53], off
	global_load_dword v106, v[52:53], off offset:128
	v_add_u32_e32 v54, 0x50, v98
	v_ashrrev_i32_e32 v55, 31, v54
	v_add_u32_e32 v56, 0x51, v98
	v_add_u32_e32 v58, 0x52, v98
	v_add_u32_e32 v60, 0x53, v98
	v_lshlrev_b64 v[54:55], 13, v[54:55]
	v_ashrrev_i32_e32 v57, 31, v56
	v_ashrrev_i32_e32 v59, 31, v58
	v_ashrrev_i32_e32 v61, 31, v60
	v_add_u32_e32 v62, 0x58, v98
	v_lshl_add_u64 v[54:55], v[96:97], 0, v[54:55]
	v_lshlrev_b64 v[56:57], 13, v[56:57]
	v_lshlrev_b64 v[58:59], 13, v[58:59]
	v_lshlrev_b64 v[60:61], 13, v[60:61]
	v_ashrrev_i32_e32 v63, 31, v62
	v_lshl_add_u64 v[56:57], v[96:97], 0, v[56:57]
	v_lshl_add_u64 v[58:59], v[96:97], 0, v[58:59]
	v_lshl_add_u64 v[60:61], v[96:97], 0, v[60:61]
	global_load_dword v107, v[54:55], off
	global_load_dword v108, v[54:55], off offset:128
	global_load_dword v109, v[56:57], off
	global_load_dword v110, v[56:57], off offset:128
	global_load_dword v111, v[58:59], off
	global_load_dword v112, v[58:59], off offset:128
	global_load_dword v113, v[60:61], off
	global_load_dword v114, v[60:61], off offset:128
	v_lshlrev_b64 v[62:63], 13, v[62:63]
	v_lshl_add_u64 v[62:63], v[96:97], 0, v[62:63]
	global_load_dword v115, v[62:63], off
	global_load_dword v116, v[62:63], off offset:128
	v_add_u32_e32 v80, 0x59, v98
	v_add_u32_e32 v84, 0x5b, v98
	v_ashrrev_i32_e32 v81, 31, v80
	v_add_u32_e32 v82, 0x5a, v98
	v_ashrrev_i32_e32 v85, 31, v84
	v_lshlrev_b64 v[80:81], 13, v[80:81]
	v_ashrrev_i32_e32 v83, 31, v82
	v_lshlrev_b64 v[84:85], 13, v[84:85]
	v_lshl_add_u64 v[80:81], v[96:97], 0, v[80:81]
	v_lshlrev_b64 v[82:83], 13, v[82:83]
	v_lshl_add_u64 v[84:85], v[96:97], 0, v[84:85]
	v_lshl_add_u64 v[82:83], v[96:97], 0, v[82:83]
	global_load_dword v117, v[80:81], off
	global_load_dword v118, v[80:81], off offset:128
	global_load_dword v119, v[82:83], off
	global_load_dword v120, v[82:83], off offset:128
	global_load_dword v96, v[84:85], off
	global_load_dword v97, v[84:85], off offset:128
	s_waitcnt vmcnt(62)
;     template <int MT> __device__ __forceinline__ void run(const Params& P, f32x16 (&acc)[MT][2], int rbase, int pn, int wc, int lane) const {
;         const int n = lane & 31, hh = lane >> 5; const int rb = rbase + 4 * hh;
;         const int c0 = pn * 128 + wc * 64 + n;
; #pragma unroll
;         for (int mt = 0; mt < MT; ++mt)
; #pragma unroll
;             for (int rg = 0; rg < 16; ++rg) { const int r = ROWOF(rb, mt, rg);
;                 float* y = P.out + O_Y + (size_t)r * 2048 + c0;
;                 y[0] = ALPHA * y[0] + acc[mt][0][rg]; y[32] = ALPHA * y[32] + acc[mt][1][rg]; }
	v_fmamk_f32 v76, v190, 0x3f9837f0, v76
	global_store_dword v[64:65], v76, off offset:128
	v_fmamk_f32 v64, v191, 0x3f9837f0, v93
	global_store_dword v[66:67], v64, off
	v_fmamk_f32 v64, v192, 0x3f9837f0, v77
	global_store_dword v[66:67], v64, off offset:128
	v_fmamk_f32 v64, v193, 0x3f9837f0, v94
	global_store_dword v[68:69], v64, off
	v_fmamk_f32 v64, v194, 0x3f9837f0, v78
	v_fmac_f32_e32 v95, 0x3f9837f0, v195
	v_fmac_f32_e32 v79, 0x3f9837f0, v196
	v_fmamk_f32 v48, v92, 0x3f9837f0, v48
	v_fmamk_f32 v32, v197, 0x3f9837f0, v32
	global_store_dword v[68:69], v64, off offset:128
	global_store_dword v[70:71], v95, off
	global_store_dword v[70:71], v79, off offset:128
	global_store_dword v[74:75], v48, off
	global_store_dword v[72:73], v32, off offset:128
	s_waitcnt vmcnt(40)
	v_fmamk_f32 v16, v33, 0x3f9837f0, v16
	global_store_dword v[36:37], v16, off
	s_waitcnt vmcnt(34)
	v_fmamk_f32 v0, v91, 0x3f9837f0, v0
	global_store_dword v[34:35], v0, off offset:128
	v_fmamk_f32 v0, v49, 0x3f9837f0, v17
	global_store_dword v[38:39], v0, off
	v_fmamk_f32 v0, v86, 0x3f9837f0, v1
	global_store_dword v[38:39], v0, off offset:128
	v_fmamk_f32 v0, v87, 0x3f9837f0, v18
	global_store_dword v[40:41], v0, off
	v_fmamk_f32 v0, v88, 0x3f9837f0, v2
	global_store_dword v[40:41], v0, off offset:128
	v_fmamk_f32 v0, v89, 0x3f9837f0, v19
	global_store_dword v[42:43], v0, off
	v_fmamk_f32 v0, v90, 0x3f9837f0, v3
	global_store_dword v[42:43], v0, off offset:128
	s_waitcnt vmcnt(40)
	v_fmamk_f32 v0, v99, 0x3f9837f0, v20
	global_store_dword v[44:45], v0, off
	s_waitcnt vmcnt(40)
	v_fmamk_f32 v0, v100, 0x3f9837f0, v4
	global_store_dword v[44:45], v0, off offset:128
	s_waitcnt vmcnt(40)
	v_fmamk_f32 v0, v101, 0x3f9837f0, v21
	global_store_dword v[46:47], v0, off
	s_waitcnt vmcnt(40)
	v_fmamk_f32 v0, v102, 0x3f9837f0, v5
	global_store_dword v[46:47], v0, off offset:128
	s_waitcnt vmcnt(40)
	v_fmamk_f32 v0, v103, 0x3f9837f0, v22
	global_store_dword v[50:51], v0, off
	s_waitcnt vmcnt(40)
	v_fmamk_f32 v0, v104, 0x3f9837f0, v6
	global_store_dword v[50:51], v0, off offset:128
	s_waitcnt vmcnt(40)
	v_fmamk_f32 v0, v105, 0x3f9837f0, v23
	global_store_dword v[52:53], v0, off
	s_waitcnt vmcnt(40)
	v_fmamk_f32 v0, v106, 0x3f9837f0, v7
	global_store_dword v[52:53], v0, off offset:128
	s_waitcnt vmcnt(40)
	v_fmamk_f32 v0, v107, 0x3f9837f0, v24
	global_store_dword v[54:55], v0, off
	s_waitcnt vmcnt(40)
	v_fmamk_f32 v0, v108, 0x3f9837f0, v8
	global_store_dword v[54:55], v0, off offset:128
	s_waitcnt vmcnt(40)
	v_fmamk_f32 v0, v109, 0x3f9837f0, v25
	global_store_dword v[56:57], v0, off
	s_waitcnt vmcnt(40)
	v_fmamk_f32 v0, v110, 0x3f9837f0, v9
	global_store_dword v[56:57], v0, off offset:128
	s_waitcnt vmcnt(40)
	v_fmamk_f32 v0, v111, 0x3f9837f0, v26
	global_store_dword v[58:59], v0, off
	s_waitcnt vmcnt(40)
	v_fmamk_f32 v0, v112, 0x3f9837f0, v10
	global_store_dword v[58:59], v0, off offset:128
	s_waitcnt vmcnt(40)
	v_fmamk_f32 v0, v113, 0x3f9837f0, v27
	global_store_dword v[60:61], v0, off
	s_waitcnt vmcnt(40)
	v_fmamk_f32 v0, v114, 0x3f9837f0, v11
	global_store_dword v[60:61], v0, off offset:128
	s_waitcnt vmcnt(40)
	v_fmamk_f32 v0, v115, 0x3f9837f0, v28
	global_store_dword v[62:63], v0, off
	s_waitcnt vmcnt(40)
	v_fmamk_f32 v0, v116, 0x3f9837f0, v12
	global_store_dword v[62:63], v0, off offset:128
	s_waitcnt vmcnt(40)
	v_fmamk_f32 v0, v117, 0x3f9837f0, v29
	global_store_dword v[80:81], v0, off
	s_waitcnt vmcnt(40)
	v_fmamk_f32 v0, v118, 0x3f9837f0, v13
	global_store_dword v[80:81], v0, off offset:128
	s_waitcnt vmcnt(40)
	v_fmamk_f32 v0, v119, 0x3f9837f0, v30
	global_store_dword v[82:83], v0, off
	s_waitcnt vmcnt(40)
	v_fmamk_f32 v0, v120, 0x3f9837f0, v14
	s_waitcnt vmcnt(39)
	v_fmac_f32_e32 v31, 0x3f9837f0, v96
	s_waitcnt vmcnt(38)
	v_fmac_f32_e32 v15, 0x3f9837f0, v97
	global_store_dword v[82:83], v0, off offset:128
	global_store_dword v[84:85], v31, off
	global_store_dword v[84:85], v15, off offset:128
	s_branch .LBB0_2778
